# GEMM K loops: remaining 64-bit VGPR DMA addresses as scalar base pairs + lane offsets (8 fewer 64-bit VALU adds per 2 K-tiles)
# baseline (speedup 1.0000x reference)
.LBB0_271:
	s_ashr_i32 s37, s36, 31
	s_lshl_b64 s[38:39], s[36:37], 19
	s_add_u32 s38, s58, s38
	s_addc_u32 s39, s59, s39
	s_and_b64 s[40:41], s[4:5], exec
	s_cselect_b32 s37, s39, s61
	s_cselect_b32 s43, s38, s60
	s_ashr_i32 s35, s34, 31
	s_lshl_b64 s[40:41], s[34:35], 19
	s_add_u32 s40, s66, s40
	s_addc_u32 s41, s67, s41
	s_and_b64 s[64:65], s[4:5], exec
	s_cselect_b32 s35, s41, s63
	s_cselect_b32 s55, s40, s62
	s_add_u32 s60, s60, 0x40080
	s_addc_u32 s61, s61, 0
	s_add_u32 s84, s62, 0x100
	s_addc_u32 s85, s63, 0
	s_mov_b32 s86, -2
	ds_read_b128 v[146:149], v153
	ds_read_b128 v[156:159], v153 offset:1024
	ds_read_b128 v[160:163], v153 offset:2048
	ds_read_b128 v[164:167], v153 offset:3072
	ds_read_b128 v[168:171], v154
	ds_read_b128 v[172:175], v154 offset:1024
	ds_read_b128 v[176:179], v154 offset:2048
	ds_read_b128 v[180:183], v154 offset:3072
	s_add_u32 s62, s60, 0xfffc0080
	s_addc_u32 s63, s61, -1
	s_cmp_eq_u32 s86, 12
	s_cselect_b32 s65, s37, s63
	s_cselect_b32 s64, s43, s62
	s_cselect_b32 s63, s35, s85
	s_cselect_b32 s62, s55, s84
	s_add_i32 m0, s69, 0xc000
	ds_read_b128 v[184:187], v155
	ds_read_b128 v[192:195], v155 offset:1024
	ds_read_b128 v[196:199], v155 offset:2048
	ds_read_b128 v[200:203], v155 offset:3072
	ds_read_b128 v[204:207], v155 offset:4096
	ds_read_b128 v[208:211], v155 offset:5120
	ds_read_b128 v[212:215], v155 offset:6144
	ds_read_b128 v[216:219], v155 offset:7168
	global_load_lds_dwordx4 v138, s[60:61]
	v_lshl_add_u64 v[188:189], s[60:61], 0, v[140:141]
	s_add_i32 m0, s69, 0xe000
	s_nop 0
	global_load_lds_dwordx4 v[188:189], off
	s_waitcnt vmcnt(8)
	s_waitcnt lgkmcnt(0)
	s_barrier
	s_setprio 1
	s_waitcnt lgkmcnt(0)
	v_mfma_f32_16x16x32_bf16 v[124:127], v[146:149], v[184:187], 0
	v_mfma_f32_16x16x32_bf16 v[120:123], v[160:163], v[184:187], 0
	v_mfma_f32_16x16x32_bf16 v[116:119], v[146:149], v[196:199], 0
	v_mfma_f32_16x16x32_bf16 v[108:111], v[160:163], v[196:199], 0
	v_mfma_f32_16x16x32_bf16 v[100:103], v[146:149], v[204:207], 0
	v_mfma_f32_16x16x32_bf16 v[92:95], v[160:163], v[204:207], 0
	v_mfma_f32_16x16x32_bf16 v[84:87], v[146:149], v[212:215], 0
	v_mfma_f32_16x16x32_bf16 v[76:79], v[160:163], v[212:215], 0
	v_mfma_f32_16x16x32_bf16 v[124:127], v[156:159], v[192:195], v[124:127]
	v_mfma_f32_16x16x32_bf16 v[120:123], v[164:167], v[192:195], v[120:123]
	v_mfma_f32_16x16x32_bf16 v[116:119], v[156:159], v[200:203], v[116:119]
	v_mfma_f32_16x16x32_bf16 v[108:111], v[164:167], v[200:203], v[108:111]
	v_mfma_f32_16x16x32_bf16 v[100:103], v[156:159], v[208:211], v[100:103]
	v_mfma_f32_16x16x32_bf16 v[92:95], v[164:167], v[208:211], v[92:95]
	v_mfma_f32_16x16x32_bf16 v[84:87], v[156:159], v[216:219], v[84:87]
	v_mfma_f32_16x16x32_bf16 v[76:79], v[164:167], v[216:219], v[76:79]
	s_setprio 0
	s_setprio 1
	v_mfma_f32_16x16x32_bf16 v[112:115], v[168:171], v[184:187], 0
	v_mfma_f32_16x16x32_bf16 v[104:107], v[176:179], v[184:187], 0
	v_mfma_f32_16x16x32_bf16 v[96:99], v[168:171], v[196:199], 0
	v_mfma_f32_16x16x32_bf16 v[88:91], v[176:179], v[196:199], 0
	v_mfma_f32_16x16x32_bf16 v[80:83], v[168:171], v[204:207], 0
	v_mfma_f32_16x16x32_bf16 v[72:75], v[176:179], v[204:207], 0
	v_mfma_f32_16x16x32_bf16 v[68:71], v[168:171], v[212:215], 0
	v_mfma_f32_16x16x32_bf16 v[64:67], v[176:179], v[212:215], 0
	v_mfma_f32_16x16x32_bf16 v[112:115], v[172:175], v[192:195], v[112:115]
	v_mfma_f32_16x16x32_bf16 v[104:107], v[180:183], v[192:195], v[104:107]
	v_mfma_f32_16x16x32_bf16 v[96:99], v[172:175], v[200:203], v[96:99]
	v_mfma_f32_16x16x32_bf16 v[88:91], v[180:183], v[200:203], v[88:91]
	v_mfma_f32_16x16x32_bf16 v[80:83], v[172:175], v[208:211], v[80:83]
	v_mfma_f32_16x16x32_bf16 v[72:75], v[180:183], v[208:211], v[72:75]
	v_mfma_f32_16x16x32_bf16 v[68:71], v[172:175], v[216:219], v[68:71]
	v_mfma_f32_16x16x32_bf16 v[64:67], v[180:183], v[216:219], v[64:67]
	s_setprio 0
	s_barrier
	s_add_i32 s87, s76, s68
	s_add_u32 s98, s62, 0x80
	s_addc_u32 s99, s63, 0
	s_mov_b32 m0, s87
	ds_read_b128 v[184:187], v155 offset:16384
	ds_read_b128 v[192:195], v155 offset:17408
	ds_read_b128 v[196:199], v155 offset:18432
	ds_read_b128 v[200:203], v155 offset:19456
	ds_read_b128 v[204:207], v155 offset:20480
	ds_read_b128 v[208:211], v155 offset:21504
	ds_read_b128 v[212:215], v155 offset:22528
	ds_read_b128 v[216:219], v155 offset:23552
	global_load_lds_dwordx4 v132, s[62:63]
	s_add_i32 m0, s87, 0x2000
	s_add_u32 s88, s62, 0x40000
	s_addc_u32 s89, s63, 0
	s_add_i32 s87, s77, s68
	global_load_lds_dwordx4 v128, s[62:63]
	s_mov_b32 m0, s87
	s_add_u32 s100, s64, 0x80
	s_addc_u32 s101, s65, 0
	global_load_lds_dwordx4 v132, s[88:89]
	s_add_i32 m0, s87, 0x2000
	s_nop 0
	global_load_lds_dwordx4 v128, s[88:89]
	s_mov_b32 m0, s69
	s_nop 0
	global_load_lds_dwordx4 v134, s[64:65]
	s_mov_b32 m0, s70
	s_nop 0
	global_load_lds_dwordx4 v130, s[64:65]
	s_waitcnt vmcnt(8)
	s_waitcnt lgkmcnt(0)
	s_barrier
	s_setprio 1
	s_waitcnt lgkmcnt(0)
	v_mfma_f32_16x16x32_bf16 v[60:63], v[146:149], v[184:187], 0
	v_mfma_f32_16x16x32_bf16 v[56:59], v[160:163], v[184:187], 0
	v_mfma_f32_16x16x32_bf16 v[52:55], v[146:149], v[196:199], 0
	v_mfma_f32_16x16x32_bf16 v[44:47], v[160:163], v[196:199], 0
	v_mfma_f32_16x16x32_bf16 v[36:39], v[146:149], v[204:207], 0
	v_mfma_f32_16x16x32_bf16 v[28:31], v[160:163], v[204:207], 0
	v_mfma_f32_16x16x32_bf16 v[20:23], v[146:149], v[212:215], 0
	v_mfma_f32_16x16x32_bf16 v[12:15], v[160:163], v[212:215], 0
	v_mfma_f32_16x16x32_bf16 v[60:63], v[156:159], v[192:195], v[60:63]
	v_mfma_f32_16x16x32_bf16 v[56:59], v[164:167], v[192:195], v[56:59]
	v_mfma_f32_16x16x32_bf16 v[52:55], v[156:159], v[200:203], v[52:55]
	v_mfma_f32_16x16x32_bf16 v[44:47], v[164:167], v[200:203], v[44:47]
	v_mfma_f32_16x16x32_bf16 v[36:39], v[156:159], v[208:211], v[36:39]
	v_mfma_f32_16x16x32_bf16 v[28:31], v[164:167], v[208:211], v[28:31]
	v_mfma_f32_16x16x32_bf16 v[20:23], v[156:159], v[216:219], v[20:23]
	v_mfma_f32_16x16x32_bf16 v[12:15], v[164:167], v[216:219], v[12:15]
	s_setprio 0
	s_setprio 1
	v_mfma_f32_16x16x32_bf16 v[48:51], v[168:171], v[184:187], 0
	v_mfma_f32_16x16x32_bf16 v[40:43], v[176:179], v[184:187], 0
	v_mfma_f32_16x16x32_bf16 v[32:35], v[168:171], v[196:199], 0
	v_mfma_f32_16x16x32_bf16 v[24:27], v[176:179], v[196:199], 0
	v_mfma_f32_16x16x32_bf16 v[16:19], v[168:171], v[204:207], 0
	v_mfma_f32_16x16x32_bf16 v[8:11], v[176:179], v[204:207], 0
	v_mfma_f32_16x16x32_bf16 v[4:7], v[168:171], v[212:215], 0
	v_mfma_f32_16x16x32_bf16 v[0:3], v[176:179], v[212:215], 0
	v_mfma_f32_16x16x32_bf16 v[48:51], v[172:175], v[192:195], v[48:51]
	v_mfma_f32_16x16x32_bf16 v[40:43], v[180:183], v[192:195], v[40:43]
	v_mfma_f32_16x16x32_bf16 v[32:35], v[172:175], v[200:203], v[32:35]
	v_mfma_f32_16x16x32_bf16 v[24:27], v[180:183], v[200:203], v[24:27]
	v_mfma_f32_16x16x32_bf16 v[16:19], v[172:175], v[208:211], v[16:19]
	v_mfma_f32_16x16x32_bf16 v[8:11], v[180:183], v[208:211], v[8:11]
	v_mfma_f32_16x16x32_bf16 v[4:7], v[172:175], v[216:219], v[4:7]
	v_mfma_f32_16x16x32_bf16 v[0:3], v[180:183], v[216:219], v[0:3]
	s_setprio 0
	s_barrier
	s_add_i32 s87, 0, 0x18000
	s_add_i32 s88, 0, 0x1c000
	v_add_u32_e32 v164, s87, v151
	v_add_u32_e32 v180, s88, v151
	ds_read_b128 v[146:149], v164
	ds_read_b128 v[156:159], v164 offset:1024
	ds_read_b128 v[160:163], v164 offset:2048
	ds_read_b128 v[164:167], v164 offset:3072
	ds_read_b128 v[168:171], v180
	ds_read_b128 v[172:175], v180 offset:1024
	ds_read_b128 v[176:179], v180 offset:2048
	ds_read_b128 v[180:183], v180 offset:3072
	s_add_u32 s64, s64, 0x40000
	s_addc_u32 s65, s65, 0
	s_mov_b32 m0, s71
	ds_read_b128 v[184:187], v155 offset:32768
	ds_read_b128 v[192:195], v155 offset:33792
	ds_read_b128 v[196:199], v155 offset:34816
	ds_read_b128 v[200:203], v155 offset:35840
	ds_read_b128 v[204:207], v155 offset:36864
	ds_read_b128 v[208:211], v155 offset:37888
	ds_read_b128 v[212:215], v155 offset:38912
	ds_read_b128 v[216:219], v155 offset:39936
	global_load_lds_dwordx4 v134, s[64:65]
	s_mov_b32 m0, s72
	s_nop 0
	global_load_lds_dwordx4 v130, s[64:65]
	s_waitcnt vmcnt(8)
	s_waitcnt lgkmcnt(0)
	s_barrier
	s_setprio 1
	s_waitcnt lgkmcnt(0)
	v_mfma_f32_16x16x32_bf16 v[124:127], v[146:149], v[184:187], v[124:127]
	v_mfma_f32_16x16x32_bf16 v[120:123], v[160:163], v[184:187], v[120:123]
	v_mfma_f32_16x16x32_bf16 v[116:119], v[146:149], v[196:199], v[116:119]
	v_mfma_f32_16x16x32_bf16 v[108:111], v[160:163], v[196:199], v[108:111]
	v_mfma_f32_16x16x32_bf16 v[100:103], v[146:149], v[204:207], v[100:103]
	v_mfma_f32_16x16x32_bf16 v[92:95], v[160:163], v[204:207], v[92:95]
	v_mfma_f32_16x16x32_bf16 v[84:87], v[146:149], v[212:215], v[84:87]
	v_mfma_f32_16x16x32_bf16 v[76:79], v[160:163], v[212:215], v[76:79]
	v_mfma_f32_16x16x32_bf16 v[124:127], v[156:159], v[192:195], v[124:127]
	v_mfma_f32_16x16x32_bf16 v[120:123], v[164:167], v[192:195], v[120:123]
	v_mfma_f32_16x16x32_bf16 v[116:119], v[156:159], v[200:203], v[116:119]
	v_mfma_f32_16x16x32_bf16 v[108:111], v[164:167], v[200:203], v[108:111]
	v_mfma_f32_16x16x32_bf16 v[100:103], v[156:159], v[208:211], v[100:103]
	v_mfma_f32_16x16x32_bf16 v[92:95], v[164:167], v[208:211], v[92:95]
	v_mfma_f32_16x16x32_bf16 v[84:87], v[156:159], v[216:219], v[84:87]
	v_mfma_f32_16x16x32_bf16 v[76:79], v[164:167], v[216:219], v[76:79]
	s_setprio 0
	s_setprio 1
	v_mfma_f32_16x16x32_bf16 v[112:115], v[168:171], v[184:187], v[112:115]
	v_mfma_f32_16x16x32_bf16 v[104:107], v[176:179], v[184:187], v[104:107]
	v_mfma_f32_16x16x32_bf16 v[96:99], v[168:171], v[196:199], v[96:99]
	v_mfma_f32_16x16x32_bf16 v[88:91], v[176:179], v[196:199], v[88:91]
	v_mfma_f32_16x16x32_bf16 v[80:83], v[168:171], v[204:207], v[80:83]
	v_mfma_f32_16x16x32_bf16 v[72:75], v[176:179], v[204:207], v[72:75]
	v_mfma_f32_16x16x32_bf16 v[68:71], v[168:171], v[212:215], v[68:71]
	v_mfma_f32_16x16x32_bf16 v[64:67], v[176:179], v[212:215], v[64:67]
	v_mfma_f32_16x16x32_bf16 v[112:115], v[172:175], v[192:195], v[112:115]
	v_mfma_f32_16x16x32_bf16 v[104:107], v[180:183], v[192:195], v[104:107]
	v_mfma_f32_16x16x32_bf16 v[96:99], v[172:175], v[200:203], v[96:99]
	v_mfma_f32_16x16x32_bf16 v[88:91], v[180:183], v[200:203], v[88:91]
	v_mfma_f32_16x16x32_bf16 v[80:83], v[172:175], v[208:211], v[80:83]
	v_mfma_f32_16x16x32_bf16 v[72:75], v[180:183], v[208:211], v[72:75]
	v_mfma_f32_16x16x32_bf16 v[68:71], v[172:175], v[216:219], v[68:71]
	v_mfma_f32_16x16x32_bf16 v[64:67], v[180:183], v[216:219], v[64:67]
	s_setprio 0
	s_barrier
	s_add_i32 s64, s87, s68
	s_mov_b32 m0, s64
	ds_read_b128 v[184:187], v155 offset:49152
	ds_read_b128 v[192:195], v155 offset:50176
	ds_read_b128 v[196:199], v155 offset:51200
	ds_read_b128 v[200:203], v155 offset:52224
	ds_read_b128 v[204:207], v155 offset:53248
	ds_read_b128 v[208:211], v155 offset:54272
	ds_read_b128 v[212:215], v155 offset:55296
	ds_read_b128 v[216:219], v155 offset:56320
	global_load_lds_dwordx4 v132, s[98:99]
	s_add_i32 m0, s64, 0x2000
	s_add_u32 s62, s62, 0x40080
	s_addc_u32 s63, s63, 0
	s_add_i32 s64, s88, s68
	global_load_lds_dwordx4 v128, s[98:99]
	s_mov_b32 m0, s64
	s_nop 0
	global_load_lds_dwordx4 v132, s[62:63]
	s_add_i32 m0, s64, 0x2000
	s_nop 0
	global_load_lds_dwordx4 v128, s[62:63]
	s_mov_b32 m0, s33
	s_nop 0
	global_load_lds_dwordx4 v134, s[100:101]
	s_mov_b32 m0, s74
	s_nop 0
	global_load_lds_dwordx4 v130, s[100:101]
	s_waitcnt vmcnt(8)
	s_waitcnt lgkmcnt(0)
	s_barrier
	s_setprio 1
	s_waitcnt lgkmcnt(0)
	v_mfma_f32_16x16x32_bf16 v[60:63], v[146:149], v[184:187], v[60:63]
	v_mfma_f32_16x16x32_bf16 v[56:59], v[160:163], v[184:187], v[56:59]
	v_mfma_f32_16x16x32_bf16 v[52:55], v[146:149], v[196:199], v[52:55]
	v_mfma_f32_16x16x32_bf16 v[44:47], v[160:163], v[196:199], v[44:47]
	v_mfma_f32_16x16x32_bf16 v[36:39], v[146:149], v[204:207], v[36:39]
	v_mfma_f32_16x16x32_bf16 v[28:31], v[160:163], v[204:207], v[28:31]
	v_mfma_f32_16x16x32_bf16 v[20:23], v[146:149], v[212:215], v[20:23]
	v_mfma_f32_16x16x32_bf16 v[12:15], v[160:163], v[212:215], v[12:15]
	v_mfma_f32_16x16x32_bf16 v[60:63], v[156:159], v[192:195], v[60:63]
	v_mfma_f32_16x16x32_bf16 v[56:59], v[164:167], v[192:195], v[56:59]
	v_mfma_f32_16x16x32_bf16 v[52:55], v[156:159], v[200:203], v[52:55]
	v_mfma_f32_16x16x32_bf16 v[44:47], v[164:167], v[200:203], v[44:47]
	v_mfma_f32_16x16x32_bf16 v[36:39], v[156:159], v[208:211], v[36:39]
	v_mfma_f32_16x16x32_bf16 v[28:31], v[164:167], v[208:211], v[28:31]
	v_mfma_f32_16x16x32_bf16 v[20:23], v[156:159], v[216:219], v[20:23]
	v_mfma_f32_16x16x32_bf16 v[12:15], v[164:167], v[216:219], v[12:15]
	s_setprio 0
	s_setprio 1
	v_mfma_f32_16x16x32_bf16 v[48:51], v[168:171], v[184:187], v[48:51]
	v_mfma_f32_16x16x32_bf16 v[40:43], v[176:179], v[184:187], v[40:43]
	v_mfma_f32_16x16x32_bf16 v[32:35], v[168:171], v[196:199], v[32:35]
	v_mfma_f32_16x16x32_bf16 v[24:27], v[176:179], v[196:199], v[24:27]
	v_mfma_f32_16x16x32_bf16 v[16:19], v[168:171], v[204:207], v[16:19]
	v_mfma_f32_16x16x32_bf16 v[8:11], v[176:179], v[204:207], v[8:11]
	v_mfma_f32_16x16x32_bf16 v[4:7], v[168:171], v[212:215], v[4:7]
	v_mfma_f32_16x16x32_bf16 v[0:3], v[176:179], v[212:215], v[0:3]
	v_mfma_f32_16x16x32_bf16 v[48:51], v[172:175], v[192:195], v[48:51]
	v_mfma_f32_16x16x32_bf16 v[40:43], v[180:183], v[192:195], v[40:43]
	v_mfma_f32_16x16x32_bf16 v[32:35], v[172:175], v[200:203], v[32:35]
	v_mfma_f32_16x16x32_bf16 v[24:27], v[180:183], v[200:203], v[24:27]
	v_mfma_f32_16x16x32_bf16 v[16:19], v[172:175], v[208:211], v[16:19]
	v_mfma_f32_16x16x32_bf16 v[8:11], v[180:183], v[208:211], v[8:11]
	v_mfma_f32_16x16x32_bf16 v[4:7], v[172:175], v[216:219], v[4:7]
	v_mfma_f32_16x16x32_bf16 v[0:3], v[180:183], v[216:219], v[0:3]
	s_setprio 0
	s_barrier
	s_add_i32 s86, s86, 2
	s_add_u32 s60, s60, 0x100
	s_addc_u32 s61, s61, 0
	s_add_u32 s84, s84, 0x100
	s_addc_u32 s85, s85, 0
	s_cmp_gt_u32 s86, 13
	s_cbranch_scc0 .LBB0_272
	s_branch .Lpeel_exit0
.LBB0_272:
	ds_read_b128 v[146:149], v153
	ds_read_b128 v[156:159], v153 offset:1024
	ds_read_b128 v[160:163], v153 offset:2048
	ds_read_b128 v[164:167], v153 offset:3072
	ds_read_b128 v[168:171], v154
	ds_read_b128 v[172:175], v154 offset:1024
	ds_read_b128 v[176:179], v154 offset:2048
	ds_read_b128 v[180:183], v154 offset:3072
	s_add_u32 s62, s60, 0xfffc0080
	s_addc_u32 s63, s61, -1
	s_cmp_eq_u32 s86, 12
	s_cselect_b32 s65, s37, s63
	s_cselect_b32 s64, s43, s62
	s_cselect_b32 s63, s35, s85
	s_cselect_b32 s62, s55, s84
	s_add_i32 m0, s69, 0xc000
	ds_read_b128 v[184:187], v155
	ds_read_b128 v[192:195], v155 offset:1024
	ds_read_b128 v[196:199], v155 offset:2048
	ds_read_b128 v[200:203], v155 offset:3072
	ds_read_b128 v[204:207], v155 offset:4096
	ds_read_b128 v[208:211], v155 offset:5120
	ds_read_b128 v[212:215], v155 offset:6144
	ds_read_b128 v[216:219], v155 offset:7168
	global_load_lds_dwordx4 v138, s[60:61]
	v_lshl_add_u64 v[188:189], s[60:61], 0, v[140:141]
	s_add_i32 m0, s69, 0xe000
	s_nop 0
	global_load_lds_dwordx4 v[188:189], off
	s_waitcnt vmcnt(8)
	s_waitcnt lgkmcnt(0)
	s_barrier
	s_setprio 1
	s_waitcnt lgkmcnt(0)
	v_mfma_f32_16x16x32_bf16 v[124:127], v[146:149], v[184:187], v[124:127]
	v_mfma_f32_16x16x32_bf16 v[120:123], v[160:163], v[184:187], v[120:123]
	v_mfma_f32_16x16x32_bf16 v[116:119], v[146:149], v[196:199], v[116:119]
	v_mfma_f32_16x16x32_bf16 v[108:111], v[160:163], v[196:199], v[108:111]
	v_mfma_f32_16x16x32_bf16 v[100:103], v[146:149], v[204:207], v[100:103]
	v_mfma_f32_16x16x32_bf16 v[92:95], v[160:163], v[204:207], v[92:95]
	v_mfma_f32_16x16x32_bf16 v[84:87], v[146:149], v[212:215], v[84:87]
	v_mfma_f32_16x16x32_bf16 v[76:79], v[160:163], v[212:215], v[76:79]
	v_mfma_f32_16x16x32_bf16 v[124:127], v[156:159], v[192:195], v[124:127]
	v_mfma_f32_16x16x32_bf16 v[120:123], v[164:167], v[192:195], v[120:123]
	v_mfma_f32_16x16x32_bf16 v[116:119], v[156:159], v[200:203], v[116:119]
	v_mfma_f32_16x16x32_bf16 v[108:111], v[164:167], v[200:203], v[108:111]
	v_mfma_f32_16x16x32_bf16 v[100:103], v[156:159], v[208:211], v[100:103]
	v_mfma_f32_16x16x32_bf16 v[92:95], v[164:167], v[208:211], v[92:95]
	v_mfma_f32_16x16x32_bf16 v[84:87], v[156:159], v[216:219], v[84:87]
	v_mfma_f32_16x16x32_bf16 v[76:79], v[164:167], v[216:219], v[76:79]
	s_setprio 0
	s_setprio 1
	v_mfma_f32_16x16x32_bf16 v[112:115], v[168:171], v[184:187], v[112:115]
	v_mfma_f32_16x16x32_bf16 v[104:107], v[176:179], v[184:187], v[104:107]
	v_mfma_f32_16x16x32_bf16 v[96:99], v[168:171], v[196:199], v[96:99]
	v_mfma_f32_16x16x32_bf16 v[88:91], v[176:179], v[196:199], v[88:91]
	v_mfma_f32_16x16x32_bf16 v[80:83], v[168:171], v[204:207], v[80:83]
	v_mfma_f32_16x16x32_bf16 v[72:75], v[176:179], v[204:207], v[72:75]
	v_mfma_f32_16x16x32_bf16 v[68:71], v[168:171], v[212:215], v[68:71]
	v_mfma_f32_16x16x32_bf16 v[64:67], v[176:179], v[212:215], v[64:67]
	v_mfma_f32_16x16x32_bf16 v[112:115], v[172:175], v[192:195], v[112:115]
	v_mfma_f32_16x16x32_bf16 v[104:107], v[180:183], v[192:195], v[104:107]
	v_mfma_f32_16x16x32_bf16 v[96:99], v[172:175], v[200:203], v[96:99]
	v_mfma_f32_16x16x32_bf16 v[88:91], v[180:183], v[200:203], v[88:91]
	v_mfma_f32_16x16x32_bf16 v[80:83], v[172:175], v[208:211], v[80:83]
	v_mfma_f32_16x16x32_bf16 v[72:75], v[180:183], v[208:211], v[72:75]
	v_mfma_f32_16x16x32_bf16 v[68:71], v[172:175], v[216:219], v[68:71]
	v_mfma_f32_16x16x32_bf16 v[64:67], v[180:183], v[216:219], v[64:67]
	s_setprio 0
	s_barrier
	s_add_i32 s87, s76, s68
	s_add_u32 s98, s62, 0x80
	s_addc_u32 s99, s63, 0
	s_mov_b32 m0, s87
	ds_read_b128 v[184:187], v155 offset:16384
	ds_read_b128 v[192:195], v155 offset:17408
	ds_read_b128 v[196:199], v155 offset:18432
	ds_read_b128 v[200:203], v155 offset:19456
	ds_read_b128 v[204:207], v155 offset:20480
	ds_read_b128 v[208:211], v155 offset:21504
	ds_read_b128 v[212:215], v155 offset:22528
	ds_read_b128 v[216:219], v155 offset:23552
	global_load_lds_dwordx4 v132, s[62:63]
	s_add_i32 m0, s87, 0x2000
	s_add_u32 s88, s62, 0x40000
	s_addc_u32 s89, s63, 0
	s_add_i32 s87, s77, s68
	global_load_lds_dwordx4 v128, s[62:63]
	s_mov_b32 m0, s87
	s_add_u32 s100, s64, 0x80
	s_addc_u32 s101, s65, 0
	global_load_lds_dwordx4 v132, s[88:89]
	s_add_i32 m0, s87, 0x2000
	s_nop 0
	global_load_lds_dwordx4 v128, s[88:89]
	s_mov_b32 m0, s69
	s_nop 0
	global_load_lds_dwordx4 v134, s[64:65]
	s_mov_b32 m0, s70
	s_nop 0
	global_load_lds_dwordx4 v130, s[64:65]
	s_waitcnt vmcnt(8)
	s_waitcnt lgkmcnt(0)
	s_barrier
	s_setprio 1
	s_waitcnt lgkmcnt(0)
	v_mfma_f32_16x16x32_bf16 v[60:63], v[146:149], v[184:187], v[60:63]
	v_mfma_f32_16x16x32_bf16 v[56:59], v[160:163], v[184:187], v[56:59]
	v_mfma_f32_16x16x32_bf16 v[52:55], v[146:149], v[196:199], v[52:55]
	v_mfma_f32_16x16x32_bf16 v[44:47], v[160:163], v[196:199], v[44:47]
	v_mfma_f32_16x16x32_bf16 v[36:39], v[146:149], v[204:207], v[36:39]
	v_mfma_f32_16x16x32_bf16 v[28:31], v[160:163], v[204:207], v[28:31]
	v_mfma_f32_16x16x32_bf16 v[20:23], v[146:149], v[212:215], v[20:23]
	v_mfma_f32_16x16x32_bf16 v[12:15], v[160:163], v[212:215], v[12:15]
	v_mfma_f32_16x16x32_bf16 v[60:63], v[156:159], v[192:195], v[60:63]
	v_mfma_f32_16x16x32_bf16 v[56:59], v[164:167], v[192:195], v[56:59]
	v_mfma_f32_16x16x32_bf16 v[52:55], v[156:159], v[200:203], v[52:55]
	v_mfma_f32_16x16x32_bf16 v[44:47], v[164:167], v[200:203], v[44:47]
	v_mfma_f32_16x16x32_bf16 v[36:39], v[156:159], v[208:211], v[36:39]
	v_mfma_f32_16x16x32_bf16 v[28:31], v[164:167], v[208:211], v[28:31]
	v_mfma_f32_16x16x32_bf16 v[20:23], v[156:159], v[216:219], v[20:23]
	v_mfma_f32_16x16x32_bf16 v[12:15], v[164:167], v[216:219], v[12:15]
	s_setprio 0
	s_setprio 1
	v_mfma_f32_16x16x32_bf16 v[48:51], v[168:171], v[184:187], v[48:51]
	v_mfma_f32_16x16x32_bf16 v[40:43], v[176:179], v[184:187], v[40:43]
	v_mfma_f32_16x16x32_bf16 v[32:35], v[168:171], v[196:199], v[32:35]
	v_mfma_f32_16x16x32_bf16 v[24:27], v[176:179], v[196:199], v[24:27]
	v_mfma_f32_16x16x32_bf16 v[16:19], v[168:171], v[204:207], v[16:19]
	v_mfma_f32_16x16x32_bf16 v[8:11], v[176:179], v[204:207], v[8:11]
	v_mfma_f32_16x16x32_bf16 v[4:7], v[168:171], v[212:215], v[4:7]
	v_mfma_f32_16x16x32_bf16 v[0:3], v[176:179], v[212:215], v[0:3]
	v_mfma_f32_16x16x32_bf16 v[48:51], v[172:175], v[192:195], v[48:51]
	v_mfma_f32_16x16x32_bf16 v[40:43], v[180:183], v[192:195], v[40:43]
	v_mfma_f32_16x16x32_bf16 v[32:35], v[172:175], v[200:203], v[32:35]
	v_mfma_f32_16x16x32_bf16 v[24:27], v[180:183], v[200:203], v[24:27]
	v_mfma_f32_16x16x32_bf16 v[16:19], v[172:175], v[208:211], v[16:19]
	v_mfma_f32_16x16x32_bf16 v[8:11], v[180:183], v[208:211], v[8:11]
	v_mfma_f32_16x16x32_bf16 v[4:7], v[172:175], v[216:219], v[4:7]
	v_mfma_f32_16x16x32_bf16 v[0:3], v[180:183], v[216:219], v[0:3]
	s_setprio 0
	s_barrier
	s_add_i32 s87, 0, 0x18000
	s_add_i32 s88, 0, 0x1c000
	v_add_u32_e32 v164, s87, v151
	v_add_u32_e32 v180, s88, v151
	ds_read_b128 v[146:149], v164
	ds_read_b128 v[156:159], v164 offset:1024
	ds_read_b128 v[160:163], v164 offset:2048
	ds_read_b128 v[164:167], v164 offset:3072
	ds_read_b128 v[168:171], v180
	ds_read_b128 v[172:175], v180 offset:1024
	ds_read_b128 v[176:179], v180 offset:2048
	ds_read_b128 v[180:183], v180 offset:3072
	s_add_u32 s64, s64, 0x40000
	s_addc_u32 s65, s65, 0
	s_mov_b32 m0, s71
	ds_read_b128 v[184:187], v155 offset:32768
	ds_read_b128 v[192:195], v155 offset:33792
	ds_read_b128 v[196:199], v155 offset:34816
	ds_read_b128 v[200:203], v155 offset:35840
	ds_read_b128 v[204:207], v155 offset:36864
	ds_read_b128 v[208:211], v155 offset:37888
	ds_read_b128 v[212:215], v155 offset:38912
	ds_read_b128 v[216:219], v155 offset:39936
	global_load_lds_dwordx4 v134, s[64:65]
	s_mov_b32 m0, s72
	s_nop 0
	global_load_lds_dwordx4 v130, s[64:65]
	s_waitcnt vmcnt(8)
	s_waitcnt lgkmcnt(0)
	s_barrier
	s_setprio 1
	s_waitcnt lgkmcnt(0)
	v_mfma_f32_16x16x32_bf16 v[124:127], v[146:149], v[184:187], v[124:127]
	v_mfma_f32_16x16x32_bf16 v[120:123], v[160:163], v[184:187], v[120:123]
	v_mfma_f32_16x16x32_bf16 v[116:119], v[146:149], v[196:199], v[116:119]
	v_mfma_f32_16x16x32_bf16 v[108:111], v[160:163], v[196:199], v[108:111]
	v_mfma_f32_16x16x32_bf16 v[100:103], v[146:149], v[204:207], v[100:103]
	v_mfma_f32_16x16x32_bf16 v[92:95], v[160:163], v[204:207], v[92:95]
	v_mfma_f32_16x16x32_bf16 v[84:87], v[146:149], v[212:215], v[84:87]
	v_mfma_f32_16x16x32_bf16 v[76:79], v[160:163], v[212:215], v[76:79]
	v_mfma_f32_16x16x32_bf16 v[124:127], v[156:159], v[192:195], v[124:127]
	v_mfma_f32_16x16x32_bf16 v[120:123], v[164:167], v[192:195], v[120:123]
	v_mfma_f32_16x16x32_bf16 v[116:119], v[156:159], v[200:203], v[116:119]
	v_mfma_f32_16x16x32_bf16 v[108:111], v[164:167], v[200:203], v[108:111]
	v_mfma_f32_16x16x32_bf16 v[100:103], v[156:159], v[208:211], v[100:103]
	v_mfma_f32_16x16x32_bf16 v[92:95], v[164:167], v[208:211], v[92:95]
	v_mfma_f32_16x16x32_bf16 v[84:87], v[156:159], v[216:219], v[84:87]
	v_mfma_f32_16x16x32_bf16 v[76:79], v[164:167], v[216:219], v[76:79]
	s_setprio 0
	s_setprio 1
	v_mfma_f32_16x16x32_bf16 v[112:115], v[168:171], v[184:187], v[112:115]
	v_mfma_f32_16x16x32_bf16 v[104:107], v[176:179], v[184:187], v[104:107]
	v_mfma_f32_16x16x32_bf16 v[96:99], v[168:171], v[196:199], v[96:99]
	v_mfma_f32_16x16x32_bf16 v[88:91], v[176:179], v[196:199], v[88:91]
	v_mfma_f32_16x16x32_bf16 v[80:83], v[168:171], v[204:207], v[80:83]
	v_mfma_f32_16x16x32_bf16 v[72:75], v[176:179], v[204:207], v[72:75]
	v_mfma_f32_16x16x32_bf16 v[68:71], v[168:171], v[212:215], v[68:71]
	v_mfma_f32_16x16x32_bf16 v[64:67], v[176:179], v[212:215], v[64:67]
	v_mfma_f32_16x16x32_bf16 v[112:115], v[172:175], v[192:195], v[112:115]
	v_mfma_f32_16x16x32_bf16 v[104:107], v[180:183], v[192:195], v[104:107]
	v_mfma_f32_16x16x32_bf16 v[96:99], v[172:175], v[200:203], v[96:99]
	v_mfma_f32_16x16x32_bf16 v[88:91], v[180:183], v[200:203], v[88:91]
	v_mfma_f32_16x16x32_bf16 v[80:83], v[172:175], v[208:211], v[80:83]
	v_mfma_f32_16x16x32_bf16 v[72:75], v[180:183], v[208:211], v[72:75]
	v_mfma_f32_16x16x32_bf16 v[68:71], v[172:175], v[216:219], v[68:71]
	v_mfma_f32_16x16x32_bf16 v[64:67], v[180:183], v[216:219], v[64:67]
	s_setprio 0
	s_barrier
	s_add_i32 s64, s87, s68
	s_mov_b32 m0, s64
	ds_read_b128 v[184:187], v155 offset:49152
	ds_read_b128 v[192:195], v155 offset:50176
	ds_read_b128 v[196:199], v155 offset:51200
	ds_read_b128 v[200:203], v155 offset:52224
	ds_read_b128 v[204:207], v155 offset:53248
	ds_read_b128 v[208:211], v155 offset:54272
	ds_read_b128 v[212:215], v155 offset:55296
	ds_read_b128 v[216:219], v155 offset:56320
	global_load_lds_dwordx4 v132, s[98:99]
	s_add_i32 m0, s64, 0x2000
	s_add_u32 s62, s62, 0x40080
	s_addc_u32 s63, s63, 0
	s_add_i32 s64, s88, s68
	global_load_lds_dwordx4 v128, s[98:99]
	s_mov_b32 m0, s64
	s_nop 0
	global_load_lds_dwordx4 v132, s[62:63]
	s_add_i32 m0, s64, 0x2000
	s_nop 0
	global_load_lds_dwordx4 v128, s[62:63]
	s_mov_b32 m0, s33
	s_nop 0
	global_load_lds_dwordx4 v134, s[100:101]
	s_mov_b32 m0, s74
	s_nop 0
	global_load_lds_dwordx4 v130, s[100:101]
	s_waitcnt vmcnt(8)
	s_waitcnt lgkmcnt(0)
	s_barrier
	s_setprio 1
	s_waitcnt lgkmcnt(0)
	v_mfma_f32_16x16x32_bf16 v[60:63], v[146:149], v[184:187], v[60:63]
	v_mfma_f32_16x16x32_bf16 v[56:59], v[160:163], v[184:187], v[56:59]
	v_mfma_f32_16x16x32_bf16 v[52:55], v[146:149], v[196:199], v[52:55]
	v_mfma_f32_16x16x32_bf16 v[44:47], v[160:163], v[196:199], v[44:47]
	v_mfma_f32_16x16x32_bf16 v[36:39], v[146:149], v[204:207], v[36:39]
	v_mfma_f32_16x16x32_bf16 v[28:31], v[160:163], v[204:207], v[28:31]
	v_mfma_f32_16x16x32_bf16 v[20:23], v[146:149], v[212:215], v[20:23]
	v_mfma_f32_16x16x32_bf16 v[12:15], v[160:163], v[212:215], v[12:15]
	v_mfma_f32_16x16x32_bf16 v[60:63], v[156:159], v[192:195], v[60:63]
	v_mfma_f32_16x16x32_bf16 v[56:59], v[164:167], v[192:195], v[56:59]
	v_mfma_f32_16x16x32_bf16 v[52:55], v[156:159], v[200:203], v[52:55]
	v_mfma_f32_16x16x32_bf16 v[44:47], v[164:167], v[200:203], v[44:47]
	v_mfma_f32_16x16x32_bf16 v[36:39], v[156:159], v[208:211], v[36:39]
	v_mfma_f32_16x16x32_bf16 v[28:31], v[164:167], v[208:211], v[28:31]
	v_mfma_f32_16x16x32_bf16 v[20:23], v[156:159], v[216:219], v[20:23]
	v_mfma_f32_16x16x32_bf16 v[12:15], v[164:167], v[216:219], v[12:15]
	s_setprio 0
	s_setprio 1
	v_mfma_f32_16x16x32_bf16 v[48:51], v[168:171], v[184:187], v[48:51]
	v_mfma_f32_16x16x32_bf16 v[40:43], v[176:179], v[184:187], v[40:43]
	v_mfma_f32_16x16x32_bf16 v[32:35], v[168:171], v[196:199], v[32:35]
	v_mfma_f32_16x16x32_bf16 v[24:27], v[176:179], v[196:199], v[24:27]
	v_mfma_f32_16x16x32_bf16 v[16:19], v[168:171], v[204:207], v[16:19]
	v_mfma_f32_16x16x32_bf16 v[8:11], v[176:179], v[204:207], v[8:11]
	v_mfma_f32_16x16x32_bf16 v[4:7], v[168:171], v[212:215], v[4:7]
	v_mfma_f32_16x16x32_bf16 v[0:3], v[176:179], v[212:215], v[0:3]
	v_mfma_f32_16x16x32_bf16 v[48:51], v[172:175], v[192:195], v[48:51]
	v_mfma_f32_16x16x32_bf16 v[40:43], v[180:183], v[192:195], v[40:43]
	v_mfma_f32_16x16x32_bf16 v[32:35], v[172:175], v[200:203], v[32:35]
	v_mfma_f32_16x16x32_bf16 v[24:27], v[180:183], v[200:203], v[24:27]
	v_mfma_f32_16x16x32_bf16 v[16:19], v[172:175], v[208:211], v[16:19]
	v_mfma_f32_16x16x32_bf16 v[8:11], v[180:183], v[208:211], v[8:11]
	v_mfma_f32_16x16x32_bf16 v[4:7], v[172:175], v[216:219], v[4:7]
	v_mfma_f32_16x16x32_bf16 v[0:3], v[180:183], v[216:219], v[0:3]
	s_setprio 0
	s_barrier
	s_add_i32 s86, s86, 2
	s_add_u32 s60, s60, 0x100
	s_addc_u32 s61, s61, 0
	s_add_u32 s84, s84, 0x100
	s_addc_u32 s85, s85, 0
	s_cmp_gt_u32 s86, 13
	s_cbranch_scc0 .LBB0_272

.LBB0_301:
	s_ashr_i32 s27, s26, 31
	s_lshl_b64 s[28:29], s[26:27], 19
	s_add_u32 s28, s43, s28
	s_addc_u32 s29, s52, s29
	s_and_b64 s[30:31], s[4:5], exec
	s_cselect_b32 s27, s29, s37
	s_cselect_b32 s55, s28, s36
	s_ashr_i32 s25, s24, 31
	s_lshl_b64 s[30:31], s[24:25], 19
	s_add_u32 s30, s58, s30
	s_addc_u32 s31, s59, s31
	s_and_b64 s[40:41], s[4:5], exec
	s_cselect_b32 s25, s31, s39
	s_cselect_b32 s72, s30, s38
	s_add_u32 s36, s36, 0x40080
	s_addc_u32 s37, s37, 0
	s_add_u32 s73, s38, 0x100
	s_addc_u32 s74, s39, 0
	s_mov_b32 s75, -2
	ds_read_b128 v[152:155], v149
	ds_read_b128 v[156:159], v149 offset:1024
	ds_read_b128 v[160:163], v149 offset:2048
	ds_read_b128 v[164:167], v149 offset:3072
	ds_read_b128 v[168:171], v150
	ds_read_b128 v[172:175], v150 offset:1024
	ds_read_b128 v[176:179], v150 offset:2048
	ds_read_b128 v[180:183], v150 offset:3072
	s_add_u32 s38, s36, 0xfffc0080
	s_addc_u32 s39, s37, -1
	s_cmp_eq_u32 s75, 12
	s_cselect_b32 s41, s27, s39
	s_cselect_b32 s40, s55, s38
	s_cselect_b32 s39, s25, s74
	s_cselect_b32 s38, s72, s73
	v_lshl_add_u64 v[144:145], s[36:37], 0, v[136:137]
	s_add_i32 m0, s35, 0xc000
	ds_read_b128 v[184:187], v151
	ds_read_b128 v[192:195], v151 offset:1024
	ds_read_b128 v[196:199], v151 offset:2048
	ds_read_b128 v[200:203], v151 offset:3072
	ds_read_b128 v[204:207], v151 offset:4096
	ds_read_b128 v[208:211], v151 offset:5120
	ds_read_b128 v[212:215], v151 offset:6144
	ds_read_b128 v[216:219], v151 offset:7168
	global_load_lds_dwordx4 v[144:145], off
	s_add_i32 m0, s35, 0xe000
	s_nop 0
	global_load_lds_dwordx4 v138, s[36:37]
	s_waitcnt vmcnt(8)
	s_waitcnt lgkmcnt(0)
	s_barrier
	s_setprio 1
	s_waitcnt lgkmcnt(0)
	v_mfma_f32_16x16x32_bf16 v[124:127], v[152:155], v[184:187], 0
	v_mfma_f32_16x16x32_bf16 v[120:123], v[160:163], v[184:187], 0
	v_mfma_f32_16x16x32_bf16 v[116:119], v[152:155], v[196:199], 0
	v_mfma_f32_16x16x32_bf16 v[108:111], v[160:163], v[196:199], 0
	v_mfma_f32_16x16x32_bf16 v[100:103], v[152:155], v[204:207], 0
	v_mfma_f32_16x16x32_bf16 v[92:95], v[160:163], v[204:207], 0
	v_mfma_f32_16x16x32_bf16 v[84:87], v[152:155], v[212:215], 0
	v_mfma_f32_16x16x32_bf16 v[76:79], v[160:163], v[212:215], 0
	v_mfma_f32_16x16x32_bf16 v[124:127], v[156:159], v[192:195], v[124:127]
	v_mfma_f32_16x16x32_bf16 v[120:123], v[164:167], v[192:195], v[120:123]
	v_mfma_f32_16x16x32_bf16 v[116:119], v[156:159], v[200:203], v[116:119]
	v_mfma_f32_16x16x32_bf16 v[108:111], v[164:167], v[200:203], v[108:111]
	v_mfma_f32_16x16x32_bf16 v[100:103], v[156:159], v[208:211], v[100:103]
	v_mfma_f32_16x16x32_bf16 v[92:95], v[164:167], v[208:211], v[92:95]
	v_mfma_f32_16x16x32_bf16 v[84:87], v[156:159], v[216:219], v[84:87]
	v_mfma_f32_16x16x32_bf16 v[76:79], v[164:167], v[216:219], v[76:79]
	s_setprio 0
	s_setprio 1
	v_mfma_f32_16x16x32_bf16 v[112:115], v[168:171], v[184:187], 0
	v_mfma_f32_16x16x32_bf16 v[104:107], v[176:179], v[184:187], 0
	v_mfma_f32_16x16x32_bf16 v[96:99], v[168:171], v[196:199], 0
	v_mfma_f32_16x16x32_bf16 v[88:91], v[176:179], v[196:199], 0
	v_mfma_f32_16x16x32_bf16 v[80:83], v[168:171], v[204:207], 0
	v_mfma_f32_16x16x32_bf16 v[72:75], v[176:179], v[204:207], 0
	v_mfma_f32_16x16x32_bf16 v[68:71], v[168:171], v[212:215], 0
	v_mfma_f32_16x16x32_bf16 v[64:67], v[176:179], v[212:215], 0
	v_mfma_f32_16x16x32_bf16 v[112:115], v[172:175], v[192:195], v[112:115]
	v_mfma_f32_16x16x32_bf16 v[104:107], v[180:183], v[192:195], v[104:107]
	v_mfma_f32_16x16x32_bf16 v[96:99], v[172:175], v[200:203], v[96:99]
	v_mfma_f32_16x16x32_bf16 v[88:91], v[180:183], v[200:203], v[88:91]
	v_mfma_f32_16x16x32_bf16 v[80:83], v[172:175], v[208:211], v[80:83]
	v_mfma_f32_16x16x32_bf16 v[72:75], v[180:183], v[208:211], v[72:75]
	v_mfma_f32_16x16x32_bf16 v[68:71], v[172:175], v[216:219], v[68:71]
	v_mfma_f32_16x16x32_bf16 v[64:67], v[180:183], v[216:219], v[64:67]
	s_setprio 0
	s_barrier
	s_add_i32 s76, s66, s53
	s_add_u32 s98, s38, 0x80
	s_addc_u32 s99, s39, 0
	s_mov_b32 m0, s76
	ds_read_b128 v[184:187], v151 offset:16384
	ds_read_b128 v[192:195], v151 offset:17408
	ds_read_b128 v[196:199], v151 offset:18432
	ds_read_b128 v[200:203], v151 offset:19456
	ds_read_b128 v[204:207], v151 offset:20480
	ds_read_b128 v[208:211], v151 offset:21504
	ds_read_b128 v[212:215], v151 offset:22528
	ds_read_b128 v[216:219], v151 offset:23552
	global_load_lds_dwordx4 v130, s[38:39]
	s_add_i32 m0, s76, 0x2000
	s_add_u32 s76, s38, 0x40000
	s_addc_u32 s77, s39, 0
	s_add_i32 s80, s67, s53
	global_load_lds_dwordx4 v134, s[38:39]
	s_mov_b32 m0, s80
	s_add_u32 s100, s40, 0x80
	s_addc_u32 s101, s41, 0
	global_load_lds_dwordx4 v130, s[76:77]
	s_add_i32 m0, s80, 0x2000
	s_nop 0
	global_load_lds_dwordx4 v134, s[76:77]
	s_mov_b32 m0, s35
	s_nop 0
	global_load_lds_dwordx4 v128, s[40:41]
	s_mov_b32 m0, s33
	s_nop 0
	global_load_lds_dwordx4 v132, s[40:41]
	s_waitcnt vmcnt(8)
	s_waitcnt lgkmcnt(0)
	s_barrier
	s_setprio 1
	s_waitcnt lgkmcnt(0)
	v_mfma_f32_16x16x32_bf16 v[60:63], v[152:155], v[184:187], 0
	v_mfma_f32_16x16x32_bf16 v[56:59], v[160:163], v[184:187], 0
	v_mfma_f32_16x16x32_bf16 v[52:55], v[152:155], v[196:199], 0
	v_mfma_f32_16x16x32_bf16 v[44:47], v[160:163], v[196:199], 0
	v_mfma_f32_16x16x32_bf16 v[36:39], v[152:155], v[204:207], 0
	v_mfma_f32_16x16x32_bf16 v[28:31], v[160:163], v[204:207], 0
	v_mfma_f32_16x16x32_bf16 v[20:23], v[152:155], v[212:215], 0
	v_mfma_f32_16x16x32_bf16 v[12:15], v[160:163], v[212:215], 0
	v_mfma_f32_16x16x32_bf16 v[60:63], v[156:159], v[192:195], v[60:63]
	v_mfma_f32_16x16x32_bf16 v[56:59], v[164:167], v[192:195], v[56:59]
	v_mfma_f32_16x16x32_bf16 v[52:55], v[156:159], v[200:203], v[52:55]
	v_mfma_f32_16x16x32_bf16 v[44:47], v[164:167], v[200:203], v[44:47]
	v_mfma_f32_16x16x32_bf16 v[36:39], v[156:159], v[208:211], v[36:39]
	v_mfma_f32_16x16x32_bf16 v[28:31], v[164:167], v[208:211], v[28:31]
	v_mfma_f32_16x16x32_bf16 v[20:23], v[156:159], v[216:219], v[20:23]
	v_mfma_f32_16x16x32_bf16 v[12:15], v[164:167], v[216:219], v[12:15]
	s_setprio 0
	s_setprio 1
	v_mfma_f32_16x16x32_bf16 v[48:51], v[168:171], v[184:187], 0
	v_mfma_f32_16x16x32_bf16 v[40:43], v[176:179], v[184:187], 0
	v_mfma_f32_16x16x32_bf16 v[32:35], v[168:171], v[196:199], 0
	v_mfma_f32_16x16x32_bf16 v[24:27], v[176:179], v[196:199], 0
	v_mfma_f32_16x16x32_bf16 v[16:19], v[168:171], v[204:207], 0
	v_mfma_f32_16x16x32_bf16 v[8:11], v[176:179], v[204:207], 0
	v_mfma_f32_16x16x32_bf16 v[4:7], v[168:171], v[212:215], 0
	v_mfma_f32_16x16x32_bf16 v[0:3], v[176:179], v[212:215], 0
	v_mfma_f32_16x16x32_bf16 v[48:51], v[172:175], v[192:195], v[48:51]
	v_mfma_f32_16x16x32_bf16 v[40:43], v[180:183], v[192:195], v[40:43]
	v_mfma_f32_16x16x32_bf16 v[32:35], v[172:175], v[200:203], v[32:35]
	v_mfma_f32_16x16x32_bf16 v[24:27], v[180:183], v[200:203], v[24:27]
	v_mfma_f32_16x16x32_bf16 v[16:19], v[172:175], v[208:211], v[16:19]
	v_mfma_f32_16x16x32_bf16 v[8:11], v[180:183], v[208:211], v[8:11]
	v_mfma_f32_16x16x32_bf16 v[4:7], v[172:175], v[216:219], v[4:7]
	v_mfma_f32_16x16x32_bf16 v[0:3], v[180:183], v[216:219], v[0:3]
	s_setprio 0
	s_barrier
	s_add_i32 s76, 0, 0x18000
	s_add_i32 s77, 0, 0x1c000
	v_add_u32_e32 v164, s76, v147
	v_add_u32_e32 v180, s77, v147
	ds_read_b128 v[152:155], v164
	ds_read_b128 v[156:159], v164 offset:1024
	ds_read_b128 v[160:163], v164 offset:2048
	ds_read_b128 v[164:167], v164 offset:3072
	ds_read_b128 v[168:171], v180
	ds_read_b128 v[172:175], v180 offset:1024
	ds_read_b128 v[176:179], v180 offset:2048
	ds_read_b128 v[180:183], v180 offset:3072
	s_add_u32 s40, s40, 0x40000
	s_addc_u32 s41, s41, 0
	s_mov_b32 m0, s60
	ds_read_b128 v[184:187], v151 offset:32768
	ds_read_b128 v[192:195], v151 offset:33792
	ds_read_b128 v[196:199], v151 offset:34816
	ds_read_b128 v[200:203], v151 offset:35840
	ds_read_b128 v[204:207], v151 offset:36864
	ds_read_b128 v[208:211], v151 offset:37888
	ds_read_b128 v[212:215], v151 offset:38912
	ds_read_b128 v[216:219], v151 offset:39936
	global_load_lds_dwordx4 v128, s[40:41]
	s_mov_b32 m0, s61
	s_nop 0
	global_load_lds_dwordx4 v132, s[40:41]
	s_waitcnt vmcnt(8)
	s_waitcnt lgkmcnt(0)
	s_barrier
	s_setprio 1
	s_waitcnt lgkmcnt(0)
	v_mfma_f32_16x16x32_bf16 v[124:127], v[152:155], v[184:187], v[124:127]
	v_mfma_f32_16x16x32_bf16 v[120:123], v[160:163], v[184:187], v[120:123]
	v_mfma_f32_16x16x32_bf16 v[116:119], v[152:155], v[196:199], v[116:119]
	v_mfma_f32_16x16x32_bf16 v[108:111], v[160:163], v[196:199], v[108:111]
	v_mfma_f32_16x16x32_bf16 v[100:103], v[152:155], v[204:207], v[100:103]
	v_mfma_f32_16x16x32_bf16 v[92:95], v[160:163], v[204:207], v[92:95]
	v_mfma_f32_16x16x32_bf16 v[84:87], v[152:155], v[212:215], v[84:87]
	v_mfma_f32_16x16x32_bf16 v[76:79], v[160:163], v[212:215], v[76:79]
	v_mfma_f32_16x16x32_bf16 v[124:127], v[156:159], v[192:195], v[124:127]
	v_mfma_f32_16x16x32_bf16 v[120:123], v[164:167], v[192:195], v[120:123]
	v_mfma_f32_16x16x32_bf16 v[116:119], v[156:159], v[200:203], v[116:119]
	v_mfma_f32_16x16x32_bf16 v[108:111], v[164:167], v[200:203], v[108:111]
	v_mfma_f32_16x16x32_bf16 v[100:103], v[156:159], v[208:211], v[100:103]
	v_mfma_f32_16x16x32_bf16 v[92:95], v[164:167], v[208:211], v[92:95]
	v_mfma_f32_16x16x32_bf16 v[84:87], v[156:159], v[216:219], v[84:87]
	v_mfma_f32_16x16x32_bf16 v[76:79], v[164:167], v[216:219], v[76:79]
	s_setprio 0
	s_setprio 1
	v_mfma_f32_16x16x32_bf16 v[112:115], v[168:171], v[184:187], v[112:115]
	v_mfma_f32_16x16x32_bf16 v[104:107], v[176:179], v[184:187], v[104:107]
	v_mfma_f32_16x16x32_bf16 v[96:99], v[168:171], v[196:199], v[96:99]
	v_mfma_f32_16x16x32_bf16 v[88:91], v[176:179], v[196:199], v[88:91]
	v_mfma_f32_16x16x32_bf16 v[80:83], v[168:171], v[204:207], v[80:83]
	v_mfma_f32_16x16x32_bf16 v[72:75], v[176:179], v[204:207], v[72:75]
	v_mfma_f32_16x16x32_bf16 v[68:71], v[168:171], v[212:215], v[68:71]
	v_mfma_f32_16x16x32_bf16 v[64:67], v[176:179], v[212:215], v[64:67]
	v_mfma_f32_16x16x32_bf16 v[112:115], v[172:175], v[192:195], v[112:115]
	v_mfma_f32_16x16x32_bf16 v[104:107], v[180:183], v[192:195], v[104:107]
	v_mfma_f32_16x16x32_bf16 v[96:99], v[172:175], v[200:203], v[96:99]
	v_mfma_f32_16x16x32_bf16 v[88:91], v[180:183], v[200:203], v[88:91]
	v_mfma_f32_16x16x32_bf16 v[80:83], v[172:175], v[208:211], v[80:83]
	v_mfma_f32_16x16x32_bf16 v[72:75], v[180:183], v[208:211], v[72:75]
	v_mfma_f32_16x16x32_bf16 v[68:71], v[172:175], v[216:219], v[68:71]
	v_mfma_f32_16x16x32_bf16 v[64:67], v[180:183], v[216:219], v[64:67]
	s_setprio 0
	s_barrier
	s_add_i32 s40, s76, s53
	s_mov_b32 m0, s40
	ds_read_b128 v[184:187], v151 offset:49152
	ds_read_b128 v[192:195], v151 offset:50176
	ds_read_b128 v[196:199], v151 offset:51200
	ds_read_b128 v[200:203], v151 offset:52224
	ds_read_b128 v[204:207], v151 offset:53248
	ds_read_b128 v[208:211], v151 offset:54272
	ds_read_b128 v[212:215], v151 offset:55296
	ds_read_b128 v[216:219], v151 offset:56320
	global_load_lds_dwordx4 v130, s[98:99]
	s_add_i32 m0, s40, 0x2000
	s_add_u32 s38, s38, 0x40080
	s_addc_u32 s39, s39, 0
	s_add_i32 s40, s77, s53
	global_load_lds_dwordx4 v134, s[98:99]
	s_mov_b32 m0, s40
	s_nop 0
	global_load_lds_dwordx4 v130, s[38:39]
	s_add_i32 m0, s40, 0x2000
	s_nop 0
	global_load_lds_dwordx4 v134, s[38:39]
	s_mov_b32 m0, s63
	s_nop 0
	global_load_lds_dwordx4 v128, s[100:101]
	s_mov_b32 m0, s64
	s_nop 0
	global_load_lds_dwordx4 v132, s[100:101]
	s_waitcnt vmcnt(8)
	s_waitcnt lgkmcnt(0)
	s_barrier
	s_setprio 1
	s_waitcnt lgkmcnt(0)
	v_mfma_f32_16x16x32_bf16 v[60:63], v[152:155], v[184:187], v[60:63]
	v_mfma_f32_16x16x32_bf16 v[56:59], v[160:163], v[184:187], v[56:59]
	v_mfma_f32_16x16x32_bf16 v[52:55], v[152:155], v[196:199], v[52:55]
	v_mfma_f32_16x16x32_bf16 v[44:47], v[160:163], v[196:199], v[44:47]
	v_mfma_f32_16x16x32_bf16 v[36:39], v[152:155], v[204:207], v[36:39]
	v_mfma_f32_16x16x32_bf16 v[28:31], v[160:163], v[204:207], v[28:31]
	v_mfma_f32_16x16x32_bf16 v[20:23], v[152:155], v[212:215], v[20:23]
	v_mfma_f32_16x16x32_bf16 v[12:15], v[160:163], v[212:215], v[12:15]
	v_mfma_f32_16x16x32_bf16 v[60:63], v[156:159], v[192:195], v[60:63]
	v_mfma_f32_16x16x32_bf16 v[56:59], v[164:167], v[192:195], v[56:59]
	v_mfma_f32_16x16x32_bf16 v[52:55], v[156:159], v[200:203], v[52:55]
	v_mfma_f32_16x16x32_bf16 v[44:47], v[164:167], v[200:203], v[44:47]
	v_mfma_f32_16x16x32_bf16 v[36:39], v[156:159], v[208:211], v[36:39]
	v_mfma_f32_16x16x32_bf16 v[28:31], v[164:167], v[208:211], v[28:31]
	v_mfma_f32_16x16x32_bf16 v[20:23], v[156:159], v[216:219], v[20:23]
	v_mfma_f32_16x16x32_bf16 v[12:15], v[164:167], v[216:219], v[12:15]
	s_setprio 0
	s_setprio 1
	v_mfma_f32_16x16x32_bf16 v[48:51], v[168:171], v[184:187], v[48:51]
	v_mfma_f32_16x16x32_bf16 v[40:43], v[176:179], v[184:187], v[40:43]
	v_mfma_f32_16x16x32_bf16 v[32:35], v[168:171], v[196:199], v[32:35]
	v_mfma_f32_16x16x32_bf16 v[24:27], v[176:179], v[196:199], v[24:27]
	v_mfma_f32_16x16x32_bf16 v[16:19], v[168:171], v[204:207], v[16:19]
	v_mfma_f32_16x16x32_bf16 v[8:11], v[176:179], v[204:207], v[8:11]
	v_mfma_f32_16x16x32_bf16 v[4:7], v[168:171], v[212:215], v[4:7]
	v_mfma_f32_16x16x32_bf16 v[0:3], v[176:179], v[212:215], v[0:3]
	v_mfma_f32_16x16x32_bf16 v[48:51], v[172:175], v[192:195], v[48:51]
	v_mfma_f32_16x16x32_bf16 v[40:43], v[180:183], v[192:195], v[40:43]
	v_mfma_f32_16x16x32_bf16 v[32:35], v[172:175], v[200:203], v[32:35]
	v_mfma_f32_16x16x32_bf16 v[24:27], v[180:183], v[200:203], v[24:27]
	v_mfma_f32_16x16x32_bf16 v[16:19], v[172:175], v[208:211], v[16:19]
	v_mfma_f32_16x16x32_bf16 v[8:11], v[180:183], v[208:211], v[8:11]
	v_mfma_f32_16x16x32_bf16 v[4:7], v[172:175], v[216:219], v[4:7]
	v_mfma_f32_16x16x32_bf16 v[0:3], v[180:183], v[216:219], v[0:3]
	s_setprio 0
	s_barrier
	s_add_i32 s75, s75, 2
	s_add_u32 s36, s36, 0x100
	s_addc_u32 s37, s37, 0
	s_add_u32 s73, s73, 0x100
	s_addc_u32 s74, s74, 0
	s_cmp_gt_u32 s75, 13
	s_cbranch_scc0 .LBB0_302
	s_branch .Lpeel_exit1
.LBB0_302:
	ds_read_b128 v[152:155], v149
	ds_read_b128 v[156:159], v149 offset:1024
	ds_read_b128 v[160:163], v149 offset:2048
	ds_read_b128 v[164:167], v149 offset:3072
	ds_read_b128 v[168:171], v150
	ds_read_b128 v[172:175], v150 offset:1024
	ds_read_b128 v[176:179], v150 offset:2048
	ds_read_b128 v[180:183], v150 offset:3072
	s_add_u32 s38, s36, 0xfffc0080
	s_addc_u32 s39, s37, -1
	s_cmp_eq_u32 s75, 12
	s_cselect_b32 s41, s27, s39
	s_cselect_b32 s40, s55, s38
	s_cselect_b32 s39, s25, s74
	s_cselect_b32 s38, s72, s73
	v_lshl_add_u64 v[144:145], s[36:37], 0, v[136:137]
	s_add_i32 m0, s35, 0xc000
	ds_read_b128 v[184:187], v151
	ds_read_b128 v[192:195], v151 offset:1024
	ds_read_b128 v[196:199], v151 offset:2048
	ds_read_b128 v[200:203], v151 offset:3072
	ds_read_b128 v[204:207], v151 offset:4096
	ds_read_b128 v[208:211], v151 offset:5120
	ds_read_b128 v[212:215], v151 offset:6144
	ds_read_b128 v[216:219], v151 offset:7168
	global_load_lds_dwordx4 v[144:145], off
	s_add_i32 m0, s35, 0xe000
	s_nop 0
	global_load_lds_dwordx4 v138, s[36:37]
	s_waitcnt vmcnt(8)
	s_waitcnt lgkmcnt(0)
	s_barrier
	s_setprio 1
	s_waitcnt lgkmcnt(0)
	v_mfma_f32_16x16x32_bf16 v[124:127], v[152:155], v[184:187], v[124:127]
	v_mfma_f32_16x16x32_bf16 v[120:123], v[160:163], v[184:187], v[120:123]
	v_mfma_f32_16x16x32_bf16 v[116:119], v[152:155], v[196:199], v[116:119]
	v_mfma_f32_16x16x32_bf16 v[108:111], v[160:163], v[196:199], v[108:111]
	v_mfma_f32_16x16x32_bf16 v[100:103], v[152:155], v[204:207], v[100:103]
	v_mfma_f32_16x16x32_bf16 v[92:95], v[160:163], v[204:207], v[92:95]
	v_mfma_f32_16x16x32_bf16 v[84:87], v[152:155], v[212:215], v[84:87]
	v_mfma_f32_16x16x32_bf16 v[76:79], v[160:163], v[212:215], v[76:79]
	v_mfma_f32_16x16x32_bf16 v[124:127], v[156:159], v[192:195], v[124:127]
	v_mfma_f32_16x16x32_bf16 v[120:123], v[164:167], v[192:195], v[120:123]
	v_mfma_f32_16x16x32_bf16 v[116:119], v[156:159], v[200:203], v[116:119]
	v_mfma_f32_16x16x32_bf16 v[108:111], v[164:167], v[200:203], v[108:111]
	v_mfma_f32_16x16x32_bf16 v[100:103], v[156:159], v[208:211], v[100:103]
	v_mfma_f32_16x16x32_bf16 v[92:95], v[164:167], v[208:211], v[92:95]
	v_mfma_f32_16x16x32_bf16 v[84:87], v[156:159], v[216:219], v[84:87]
	v_mfma_f32_16x16x32_bf16 v[76:79], v[164:167], v[216:219], v[76:79]
	s_setprio 0
	s_setprio 1
	v_mfma_f32_16x16x32_bf16 v[112:115], v[168:171], v[184:187], v[112:115]
	v_mfma_f32_16x16x32_bf16 v[104:107], v[176:179], v[184:187], v[104:107]
	v_mfma_f32_16x16x32_bf16 v[96:99], v[168:171], v[196:199], v[96:99]
	v_mfma_f32_16x16x32_bf16 v[88:91], v[176:179], v[196:199], v[88:91]
	v_mfma_f32_16x16x32_bf16 v[80:83], v[168:171], v[204:207], v[80:83]
	v_mfma_f32_16x16x32_bf16 v[72:75], v[176:179], v[204:207], v[72:75]
	v_mfma_f32_16x16x32_bf16 v[68:71], v[168:171], v[212:215], v[68:71]
	v_mfma_f32_16x16x32_bf16 v[64:67], v[176:179], v[212:215], v[64:67]
	v_mfma_f32_16x16x32_bf16 v[112:115], v[172:175], v[192:195], v[112:115]
	v_mfma_f32_16x16x32_bf16 v[104:107], v[180:183], v[192:195], v[104:107]
	v_mfma_f32_16x16x32_bf16 v[96:99], v[172:175], v[200:203], v[96:99]
	v_mfma_f32_16x16x32_bf16 v[88:91], v[180:183], v[200:203], v[88:91]
	v_mfma_f32_16x16x32_bf16 v[80:83], v[172:175], v[208:211], v[80:83]
	v_mfma_f32_16x16x32_bf16 v[72:75], v[180:183], v[208:211], v[72:75]
	v_mfma_f32_16x16x32_bf16 v[68:71], v[172:175], v[216:219], v[68:71]
	v_mfma_f32_16x16x32_bf16 v[64:67], v[180:183], v[216:219], v[64:67]
	s_setprio 0
	s_barrier
	s_add_i32 s76, s66, s53
	s_add_u32 s98, s38, 0x80
	s_addc_u32 s99, s39, 0
	s_mov_b32 m0, s76
	ds_read_b128 v[184:187], v151 offset:16384
	ds_read_b128 v[192:195], v151 offset:17408
	ds_read_b128 v[196:199], v151 offset:18432
	ds_read_b128 v[200:203], v151 offset:19456
	ds_read_b128 v[204:207], v151 offset:20480
	ds_read_b128 v[208:211], v151 offset:21504
	ds_read_b128 v[212:215], v151 offset:22528
	ds_read_b128 v[216:219], v151 offset:23552
	global_load_lds_dwordx4 v130, s[38:39]
	s_add_i32 m0, s76, 0x2000
	s_add_u32 s76, s38, 0x40000
	s_addc_u32 s77, s39, 0
	s_add_i32 s80, s67, s53
	global_load_lds_dwordx4 v134, s[38:39]
	s_mov_b32 m0, s80
	s_add_u32 s100, s40, 0x80
	s_addc_u32 s101, s41, 0
	global_load_lds_dwordx4 v130, s[76:77]
	s_add_i32 m0, s80, 0x2000
	s_nop 0
	global_load_lds_dwordx4 v134, s[76:77]
	s_mov_b32 m0, s35
	s_nop 0
	global_load_lds_dwordx4 v128, s[40:41]
	s_mov_b32 m0, s33
	s_nop 0
	global_load_lds_dwordx4 v132, s[40:41]
	s_waitcnt vmcnt(8)
	s_waitcnt lgkmcnt(0)
	s_barrier
	s_setprio 1
	s_waitcnt lgkmcnt(0)
	v_mfma_f32_16x16x32_bf16 v[60:63], v[152:155], v[184:187], v[60:63]
	v_mfma_f32_16x16x32_bf16 v[56:59], v[160:163], v[184:187], v[56:59]
	v_mfma_f32_16x16x32_bf16 v[52:55], v[152:155], v[196:199], v[52:55]
	v_mfma_f32_16x16x32_bf16 v[44:47], v[160:163], v[196:199], v[44:47]
	v_mfma_f32_16x16x32_bf16 v[36:39], v[152:155], v[204:207], v[36:39]
	v_mfma_f32_16x16x32_bf16 v[28:31], v[160:163], v[204:207], v[28:31]
	v_mfma_f32_16x16x32_bf16 v[20:23], v[152:155], v[212:215], v[20:23]
	v_mfma_f32_16x16x32_bf16 v[12:15], v[160:163], v[212:215], v[12:15]
	v_mfma_f32_16x16x32_bf16 v[60:63], v[156:159], v[192:195], v[60:63]
	v_mfma_f32_16x16x32_bf16 v[56:59], v[164:167], v[192:195], v[56:59]
	v_mfma_f32_16x16x32_bf16 v[52:55], v[156:159], v[200:203], v[52:55]
	v_mfma_f32_16x16x32_bf16 v[44:47], v[164:167], v[200:203], v[44:47]
	v_mfma_f32_16x16x32_bf16 v[36:39], v[156:159], v[208:211], v[36:39]
	v_mfma_f32_16x16x32_bf16 v[28:31], v[164:167], v[208:211], v[28:31]
	v_mfma_f32_16x16x32_bf16 v[20:23], v[156:159], v[216:219], v[20:23]
	v_mfma_f32_16x16x32_bf16 v[12:15], v[164:167], v[216:219], v[12:15]
	s_setprio 0
	s_setprio 1
	v_mfma_f32_16x16x32_bf16 v[48:51], v[168:171], v[184:187], v[48:51]
	v_mfma_f32_16x16x32_bf16 v[40:43], v[176:179], v[184:187], v[40:43]
	v_mfma_f32_16x16x32_bf16 v[32:35], v[168:171], v[196:199], v[32:35]
	v_mfma_f32_16x16x32_bf16 v[24:27], v[176:179], v[196:199], v[24:27]
	v_mfma_f32_16x16x32_bf16 v[16:19], v[168:171], v[204:207], v[16:19]
	v_mfma_f32_16x16x32_bf16 v[8:11], v[176:179], v[204:207], v[8:11]
	v_mfma_f32_16x16x32_bf16 v[4:7], v[168:171], v[212:215], v[4:7]
	v_mfma_f32_16x16x32_bf16 v[0:3], v[176:179], v[212:215], v[0:3]
	v_mfma_f32_16x16x32_bf16 v[48:51], v[172:175], v[192:195], v[48:51]
	v_mfma_f32_16x16x32_bf16 v[40:43], v[180:183], v[192:195], v[40:43]
	v_mfma_f32_16x16x32_bf16 v[32:35], v[172:175], v[200:203], v[32:35]
	v_mfma_f32_16x16x32_bf16 v[24:27], v[180:183], v[200:203], v[24:27]
	v_mfma_f32_16x16x32_bf16 v[16:19], v[172:175], v[208:211], v[16:19]
	v_mfma_f32_16x16x32_bf16 v[8:11], v[180:183], v[208:211], v[8:11]
	v_mfma_f32_16x16x32_bf16 v[4:7], v[172:175], v[216:219], v[4:7]
	v_mfma_f32_16x16x32_bf16 v[0:3], v[180:183], v[216:219], v[0:3]
	s_setprio 0
	s_barrier
	s_add_i32 s76, 0, 0x18000
	s_add_i32 s77, 0, 0x1c000
	v_add_u32_e32 v164, s76, v147
	v_add_u32_e32 v180, s77, v147
	ds_read_b128 v[152:155], v164
	ds_read_b128 v[156:159], v164 offset:1024
	ds_read_b128 v[160:163], v164 offset:2048
	ds_read_b128 v[164:167], v164 offset:3072
	ds_read_b128 v[168:171], v180
	ds_read_b128 v[172:175], v180 offset:1024
	ds_read_b128 v[176:179], v180 offset:2048
	ds_read_b128 v[180:183], v180 offset:3072
	s_add_u32 s40, s40, 0x40000
	s_addc_u32 s41, s41, 0
	s_mov_b32 m0, s60
	ds_read_b128 v[184:187], v151 offset:32768
	ds_read_b128 v[192:195], v151 offset:33792
	ds_read_b128 v[196:199], v151 offset:34816
	ds_read_b128 v[200:203], v151 offset:35840
	ds_read_b128 v[204:207], v151 offset:36864
	ds_read_b128 v[208:211], v151 offset:37888
	ds_read_b128 v[212:215], v151 offset:38912
	ds_read_b128 v[216:219], v151 offset:39936
	global_load_lds_dwordx4 v128, s[40:41]
	s_mov_b32 m0, s61
	s_nop 0
	global_load_lds_dwordx4 v132, s[40:41]
	s_waitcnt vmcnt(8)
	s_waitcnt lgkmcnt(0)
	s_barrier
	s_setprio 1
	s_waitcnt lgkmcnt(0)
	v_mfma_f32_16x16x32_bf16 v[124:127], v[152:155], v[184:187], v[124:127]
	v_mfma_f32_16x16x32_bf16 v[120:123], v[160:163], v[184:187], v[120:123]
	v_mfma_f32_16x16x32_bf16 v[116:119], v[152:155], v[196:199], v[116:119]
	v_mfma_f32_16x16x32_bf16 v[108:111], v[160:163], v[196:199], v[108:111]
	v_mfma_f32_16x16x32_bf16 v[100:103], v[152:155], v[204:207], v[100:103]
	v_mfma_f32_16x16x32_bf16 v[92:95], v[160:163], v[204:207], v[92:95]
	v_mfma_f32_16x16x32_bf16 v[84:87], v[152:155], v[212:215], v[84:87]
	v_mfma_f32_16x16x32_bf16 v[76:79], v[160:163], v[212:215], v[76:79]
	v_mfma_f32_16x16x32_bf16 v[124:127], v[156:159], v[192:195], v[124:127]
	v_mfma_f32_16x16x32_bf16 v[120:123], v[164:167], v[192:195], v[120:123]
	v_mfma_f32_16x16x32_bf16 v[116:119], v[156:159], v[200:203], v[116:119]
	v_mfma_f32_16x16x32_bf16 v[108:111], v[164:167], v[200:203], v[108:111]
	v_mfma_f32_16x16x32_bf16 v[100:103], v[156:159], v[208:211], v[100:103]
	v_mfma_f32_16x16x32_bf16 v[92:95], v[164:167], v[208:211], v[92:95]
	v_mfma_f32_16x16x32_bf16 v[84:87], v[156:159], v[216:219], v[84:87]
	v_mfma_f32_16x16x32_bf16 v[76:79], v[164:167], v[216:219], v[76:79]
	s_setprio 0
	s_setprio 1
	v_mfma_f32_16x16x32_bf16 v[112:115], v[168:171], v[184:187], v[112:115]
	v_mfma_f32_16x16x32_bf16 v[104:107], v[176:179], v[184:187], v[104:107]
	v_mfma_f32_16x16x32_bf16 v[96:99], v[168:171], v[196:199], v[96:99]
	v_mfma_f32_16x16x32_bf16 v[88:91], v[176:179], v[196:199], v[88:91]
	v_mfma_f32_16x16x32_bf16 v[80:83], v[168:171], v[204:207], v[80:83]
	v_mfma_f32_16x16x32_bf16 v[72:75], v[176:179], v[204:207], v[72:75]
	v_mfma_f32_16x16x32_bf16 v[68:71], v[168:171], v[212:215], v[68:71]
	v_mfma_f32_16x16x32_bf16 v[64:67], v[176:179], v[212:215], v[64:67]
	v_mfma_f32_16x16x32_bf16 v[112:115], v[172:175], v[192:195], v[112:115]
	v_mfma_f32_16x16x32_bf16 v[104:107], v[180:183], v[192:195], v[104:107]
	v_mfma_f32_16x16x32_bf16 v[96:99], v[172:175], v[200:203], v[96:99]
	v_mfma_f32_16x16x32_bf16 v[88:91], v[180:183], v[200:203], v[88:91]
	v_mfma_f32_16x16x32_bf16 v[80:83], v[172:175], v[208:211], v[80:83]
	v_mfma_f32_16x16x32_bf16 v[72:75], v[180:183], v[208:211], v[72:75]
	v_mfma_f32_16x16x32_bf16 v[68:71], v[172:175], v[216:219], v[68:71]
	v_mfma_f32_16x16x32_bf16 v[64:67], v[180:183], v[216:219], v[64:67]
	s_setprio 0
	s_barrier
	s_add_i32 s40, s76, s53
	s_mov_b32 m0, s40
	ds_read_b128 v[184:187], v151 offset:49152
	ds_read_b128 v[192:195], v151 offset:50176
	ds_read_b128 v[196:199], v151 offset:51200
	ds_read_b128 v[200:203], v151 offset:52224
	ds_read_b128 v[204:207], v151 offset:53248
	ds_read_b128 v[208:211], v151 offset:54272
	ds_read_b128 v[212:215], v151 offset:55296
	ds_read_b128 v[216:219], v151 offset:56320
	global_load_lds_dwordx4 v130, s[98:99]
	s_add_i32 m0, s40, 0x2000
	s_add_u32 s38, s38, 0x40080
	s_addc_u32 s39, s39, 0
	s_add_i32 s40, s77, s53
	global_load_lds_dwordx4 v134, s[98:99]
	s_mov_b32 m0, s40
	s_nop 0
	global_load_lds_dwordx4 v130, s[38:39]
	s_add_i32 m0, s40, 0x2000
	s_nop 0
	global_load_lds_dwordx4 v134, s[38:39]
	s_mov_b32 m0, s63
	s_nop 0
	global_load_lds_dwordx4 v128, s[100:101]
	s_mov_b32 m0, s64
	s_nop 0
	global_load_lds_dwordx4 v132, s[100:101]
	s_waitcnt vmcnt(8)
	s_waitcnt lgkmcnt(0)
	s_barrier
	s_setprio 1
	s_waitcnt lgkmcnt(0)
	v_mfma_f32_16x16x32_bf16 v[60:63], v[152:155], v[184:187], v[60:63]
	v_mfma_f32_16x16x32_bf16 v[56:59], v[160:163], v[184:187], v[56:59]
	v_mfma_f32_16x16x32_bf16 v[52:55], v[152:155], v[196:199], v[52:55]
	v_mfma_f32_16x16x32_bf16 v[44:47], v[160:163], v[196:199], v[44:47]
	v_mfma_f32_16x16x32_bf16 v[36:39], v[152:155], v[204:207], v[36:39]
	v_mfma_f32_16x16x32_bf16 v[28:31], v[160:163], v[204:207], v[28:31]
	v_mfma_f32_16x16x32_bf16 v[20:23], v[152:155], v[212:215], v[20:23]
	v_mfma_f32_16x16x32_bf16 v[12:15], v[160:163], v[212:215], v[12:15]
	v_mfma_f32_16x16x32_bf16 v[60:63], v[156:159], v[192:195], v[60:63]
	v_mfma_f32_16x16x32_bf16 v[56:59], v[164:167], v[192:195], v[56:59]
	v_mfma_f32_16x16x32_bf16 v[52:55], v[156:159], v[200:203], v[52:55]
	v_mfma_f32_16x16x32_bf16 v[44:47], v[164:167], v[200:203], v[44:47]
	v_mfma_f32_16x16x32_bf16 v[36:39], v[156:159], v[208:211], v[36:39]
	v_mfma_f32_16x16x32_bf16 v[28:31], v[164:167], v[208:211], v[28:31]
	v_mfma_f32_16x16x32_bf16 v[20:23], v[156:159], v[216:219], v[20:23]
	v_mfma_f32_16x16x32_bf16 v[12:15], v[164:167], v[216:219], v[12:15]
	s_setprio 0
	s_setprio 1
	v_mfma_f32_16x16x32_bf16 v[48:51], v[168:171], v[184:187], v[48:51]
	v_mfma_f32_16x16x32_bf16 v[40:43], v[176:179], v[184:187], v[40:43]
	v_mfma_f32_16x16x32_bf16 v[32:35], v[168:171], v[196:199], v[32:35]
	v_mfma_f32_16x16x32_bf16 v[24:27], v[176:179], v[196:199], v[24:27]
	v_mfma_f32_16x16x32_bf16 v[16:19], v[168:171], v[204:207], v[16:19]
	v_mfma_f32_16x16x32_bf16 v[8:11], v[176:179], v[204:207], v[8:11]
	v_mfma_f32_16x16x32_bf16 v[4:7], v[168:171], v[212:215], v[4:7]
	v_mfma_f32_16x16x32_bf16 v[0:3], v[176:179], v[212:215], v[0:3]
	v_mfma_f32_16x16x32_bf16 v[48:51], v[172:175], v[192:195], v[48:51]
	v_mfma_f32_16x16x32_bf16 v[40:43], v[180:183], v[192:195], v[40:43]
	v_mfma_f32_16x16x32_bf16 v[32:35], v[172:175], v[200:203], v[32:35]
	v_mfma_f32_16x16x32_bf16 v[24:27], v[180:183], v[200:203], v[24:27]
	v_mfma_f32_16x16x32_bf16 v[16:19], v[172:175], v[208:211], v[16:19]
	v_mfma_f32_16x16x32_bf16 v[8:11], v[180:183], v[208:211], v[8:11]
	v_mfma_f32_16x16x32_bf16 v[4:7], v[172:175], v[216:219], v[4:7]
	v_mfma_f32_16x16x32_bf16 v[0:3], v[180:183], v[216:219], v[0:3]
	s_setprio 0
	s_barrier
	s_add_i32 s75, s75, 2
	s_add_u32 s36, s36, 0x100
	s_addc_u32 s37, s37, 0
	s_add_u32 s73, s73, 0x100
	s_addc_u32 s74, s74, 0
	s_cmp_gt_u32 s75, 13
	s_cbranch_scc0 .LBB0_302

.LBB0_699:
	s_ashr_i32 s25, s24, 31
	s_lshl_b64 s[26:27], s[24:25], 19
	s_add_u32 s26, s58, s26
	s_addc_u32 s27, s59, s27
	s_and_b64 s[28:29], s[4:5], exec
	s_cselect_b32 s25, s27, s35
	s_cselect_b32 s55, s26, s34
	s_ashr_i32 s23, s22, 31
	s_lshl_b64 s[28:29], s[22:23], 19
	s_add_u32 s28, s43, s28
	s_addc_u32 s29, s52, s29
	s_and_b64 s[40:41], s[4:5], exec
	s_cselect_b32 s23, s29, s39
	s_cselect_b32 s72, s28, s38
	s_add_u32 s34, s34, 0x40080
	s_addc_u32 s35, s35, 0
	s_add_u32 s73, s38, 0x100
	s_addc_u32 s74, s39, 0
	s_mov_b32 s75, -2
	ds_read_b128 v[152:155], v149
	ds_read_b128 v[156:159], v149 offset:1024
	ds_read_b128 v[160:163], v149 offset:2048
	ds_read_b128 v[164:167], v149 offset:3072
	ds_read_b128 v[168:171], v150
	ds_read_b128 v[172:175], v150 offset:1024
	ds_read_b128 v[176:179], v150 offset:2048
	ds_read_b128 v[180:183], v150 offset:3072
	s_add_u32 s38, s34, 0xfffc0080
	s_addc_u32 s39, s35, -1
	s_cmp_eq_u32 s75, 12
	s_cselect_b32 s41, s25, s39
	s_cselect_b32 s40, s55, s38
	s_cselect_b32 s39, s23, s74
	s_cselect_b32 s38, s72, s73
	s_add_i32 m0, s31, 0xc000
	ds_read_b128 v[184:187], v151
	ds_read_b128 v[192:195], v151 offset:1024
	ds_read_b128 v[196:199], v151 offset:2048
	ds_read_b128 v[200:203], v151 offset:3072
	ds_read_b128 v[204:207], v151 offset:4096
	ds_read_b128 v[208:211], v151 offset:5120
	ds_read_b128 v[212:215], v151 offset:6144
	ds_read_b128 v[216:219], v151 offset:7168
	global_load_lds_dwordx4 v136, s[34:35]
	s_add_i32 m0, s31, 0xe000
	s_nop 0
	global_load_lds_dwordx4 v138, s[34:35]
	s_waitcnt vmcnt(8)
	s_waitcnt lgkmcnt(0)
	s_barrier
	s_setprio 1
	s_waitcnt lgkmcnt(0)
	v_mfma_f32_16x16x32_bf16 v[124:127], v[152:155], v[184:187], 0
	v_mfma_f32_16x16x32_bf16 v[120:123], v[160:163], v[184:187], 0
	v_mfma_f32_16x16x32_bf16 v[116:119], v[152:155], v[196:199], 0
	v_mfma_f32_16x16x32_bf16 v[108:111], v[160:163], v[196:199], 0
	v_mfma_f32_16x16x32_bf16 v[100:103], v[152:155], v[204:207], 0
	v_mfma_f32_16x16x32_bf16 v[92:95], v[160:163], v[204:207], 0
	v_mfma_f32_16x16x32_bf16 v[84:87], v[152:155], v[212:215], 0
	v_mfma_f32_16x16x32_bf16 v[76:79], v[160:163], v[212:215], 0
	v_mfma_f32_16x16x32_bf16 v[124:127], v[156:159], v[192:195], v[124:127]
	v_mfma_f32_16x16x32_bf16 v[120:123], v[164:167], v[192:195], v[120:123]
	v_mfma_f32_16x16x32_bf16 v[116:119], v[156:159], v[200:203], v[116:119]
	v_mfma_f32_16x16x32_bf16 v[108:111], v[164:167], v[200:203], v[108:111]
	v_mfma_f32_16x16x32_bf16 v[100:103], v[156:159], v[208:211], v[100:103]
	v_mfma_f32_16x16x32_bf16 v[92:95], v[164:167], v[208:211], v[92:95]
	v_mfma_f32_16x16x32_bf16 v[84:87], v[156:159], v[216:219], v[84:87]
	v_mfma_f32_16x16x32_bf16 v[76:79], v[164:167], v[216:219], v[76:79]
	s_setprio 0
	s_setprio 1
	v_mfma_f32_16x16x32_bf16 v[112:115], v[168:171], v[184:187], 0
	v_mfma_f32_16x16x32_bf16 v[104:107], v[176:179], v[184:187], 0
	v_mfma_f32_16x16x32_bf16 v[96:99], v[168:171], v[196:199], 0
	v_mfma_f32_16x16x32_bf16 v[88:91], v[176:179], v[196:199], 0
	v_mfma_f32_16x16x32_bf16 v[80:83], v[168:171], v[204:207], 0
	v_mfma_f32_16x16x32_bf16 v[72:75], v[176:179], v[204:207], 0
	v_mfma_f32_16x16x32_bf16 v[68:71], v[168:171], v[212:215], 0
	v_mfma_f32_16x16x32_bf16 v[64:67], v[176:179], v[212:215], 0
	v_mfma_f32_16x16x32_bf16 v[112:115], v[172:175], v[192:195], v[112:115]
	v_mfma_f32_16x16x32_bf16 v[104:107], v[180:183], v[192:195], v[104:107]
	v_mfma_f32_16x16x32_bf16 v[96:99], v[172:175], v[200:203], v[96:99]
	v_mfma_f32_16x16x32_bf16 v[88:91], v[180:183], v[200:203], v[88:91]
	v_mfma_f32_16x16x32_bf16 v[80:83], v[172:175], v[208:211], v[80:83]
	v_mfma_f32_16x16x32_bf16 v[72:75], v[180:183], v[208:211], v[72:75]
	v_mfma_f32_16x16x32_bf16 v[68:71], v[172:175], v[216:219], v[68:71]
	v_mfma_f32_16x16x32_bf16 v[64:67], v[180:183], v[216:219], v[64:67]
	s_setprio 0
	s_barrier
	s_add_i32 s76, s66, s53
	s_add_u32 s98, s38, 0x80
	s_addc_u32 s99, s39, 0
	s_mov_b32 m0, s76
	ds_read_b128 v[184:187], v151 offset:16384
	ds_read_b128 v[192:195], v151 offset:17408
	ds_read_b128 v[196:199], v151 offset:18432
	ds_read_b128 v[200:203], v151 offset:19456
	ds_read_b128 v[204:207], v151 offset:20480
	ds_read_b128 v[208:211], v151 offset:21504
	ds_read_b128 v[212:215], v151 offset:22528
	ds_read_b128 v[216:219], v151 offset:23552
	global_load_lds_dwordx4 v130, s[38:39]
	s_add_i32 m0, s76, 0x2000
	s_add_u32 s76, s38, 0x40000
	s_addc_u32 s77, s39, 0
	s_add_i32 s79, s67, s53
	global_load_lds_dwordx4 v134, s[38:39]
	s_mov_b32 m0, s79
	s_add_u32 s100, s40, 0x80
	s_addc_u32 s101, s41, 0
	global_load_lds_dwordx4 v130, s[76:77]
	s_add_i32 m0, s79, 0x2000
	s_nop 0
	global_load_lds_dwordx4 v134, s[76:77]
	s_mov_b32 m0, s31
	s_nop 0
	global_load_lds_dwordx4 v128, s[40:41]
	s_mov_b32 m0, s33
	s_nop 0
	global_load_lds_dwordx4 v132, s[40:41]
	s_waitcnt vmcnt(8)
	s_waitcnt lgkmcnt(0)
	s_barrier
	s_setprio 1
	s_waitcnt lgkmcnt(0)
	v_mfma_f32_16x16x32_bf16 v[60:63], v[152:155], v[184:187], 0
	v_mfma_f32_16x16x32_bf16 v[56:59], v[160:163], v[184:187], 0
	v_mfma_f32_16x16x32_bf16 v[52:55], v[152:155], v[196:199], 0
	v_mfma_f32_16x16x32_bf16 v[44:47], v[160:163], v[196:199], 0
	v_mfma_f32_16x16x32_bf16 v[36:39], v[152:155], v[204:207], 0
	v_mfma_f32_16x16x32_bf16 v[28:31], v[160:163], v[204:207], 0
	v_mfma_f32_16x16x32_bf16 v[20:23], v[152:155], v[212:215], 0
	v_mfma_f32_16x16x32_bf16 v[12:15], v[160:163], v[212:215], 0
	v_mfma_f32_16x16x32_bf16 v[60:63], v[156:159], v[192:195], v[60:63]
	v_mfma_f32_16x16x32_bf16 v[56:59], v[164:167], v[192:195], v[56:59]
	v_mfma_f32_16x16x32_bf16 v[52:55], v[156:159], v[200:203], v[52:55]
	v_mfma_f32_16x16x32_bf16 v[44:47], v[164:167], v[200:203], v[44:47]
	v_mfma_f32_16x16x32_bf16 v[36:39], v[156:159], v[208:211], v[36:39]
	v_mfma_f32_16x16x32_bf16 v[28:31], v[164:167], v[208:211], v[28:31]
	v_mfma_f32_16x16x32_bf16 v[20:23], v[156:159], v[216:219], v[20:23]
	v_mfma_f32_16x16x32_bf16 v[12:15], v[164:167], v[216:219], v[12:15]
	s_setprio 0
	s_setprio 1
	v_mfma_f32_16x16x32_bf16 v[48:51], v[168:171], v[184:187], 0
	v_mfma_f32_16x16x32_bf16 v[40:43], v[176:179], v[184:187], 0
	v_mfma_f32_16x16x32_bf16 v[32:35], v[168:171], v[196:199], 0
	v_mfma_f32_16x16x32_bf16 v[24:27], v[176:179], v[196:199], 0
	v_mfma_f32_16x16x32_bf16 v[16:19], v[168:171], v[204:207], 0
	v_mfma_f32_16x16x32_bf16 v[8:11], v[176:179], v[204:207], 0
	v_mfma_f32_16x16x32_bf16 v[4:7], v[168:171], v[212:215], 0
	v_mfma_f32_16x16x32_bf16 v[0:3], v[176:179], v[212:215], 0
	v_mfma_f32_16x16x32_bf16 v[48:51], v[172:175], v[192:195], v[48:51]
	v_mfma_f32_16x16x32_bf16 v[40:43], v[180:183], v[192:195], v[40:43]
	v_mfma_f32_16x16x32_bf16 v[32:35], v[172:175], v[200:203], v[32:35]
	v_mfma_f32_16x16x32_bf16 v[24:27], v[180:183], v[200:203], v[24:27]
	v_mfma_f32_16x16x32_bf16 v[16:19], v[172:175], v[208:211], v[16:19]
	v_mfma_f32_16x16x32_bf16 v[8:11], v[180:183], v[208:211], v[8:11]
	v_mfma_f32_16x16x32_bf16 v[4:7], v[172:175], v[216:219], v[4:7]
	v_mfma_f32_16x16x32_bf16 v[0:3], v[180:183], v[216:219], v[0:3]
	s_setprio 0
	s_barrier
	s_add_i32 s76, 0, 0x18000
	s_add_i32 s77, 0, 0x1c000
	v_add_u32_e32 v164, s76, v147
	v_add_u32_e32 v180, s77, v147
	ds_read_b128 v[152:155], v164
	ds_read_b128 v[156:159], v164 offset:1024
	ds_read_b128 v[160:163], v164 offset:2048
	ds_read_b128 v[164:167], v164 offset:3072
	ds_read_b128 v[168:171], v180
	ds_read_b128 v[172:175], v180 offset:1024
	ds_read_b128 v[176:179], v180 offset:2048
	ds_read_b128 v[180:183], v180 offset:3072
	s_add_u32 s40, s40, 0x40000
	s_addc_u32 s41, s41, 0
	s_mov_b32 m0, s60
	ds_read_b128 v[184:187], v151 offset:32768
	ds_read_b128 v[192:195], v151 offset:33792
	ds_read_b128 v[196:199], v151 offset:34816
	ds_read_b128 v[200:203], v151 offset:35840
	ds_read_b128 v[204:207], v151 offset:36864
	ds_read_b128 v[208:211], v151 offset:37888
	ds_read_b128 v[212:215], v151 offset:38912
	ds_read_b128 v[216:219], v151 offset:39936
	global_load_lds_dwordx4 v128, s[40:41]
	s_mov_b32 m0, s61
	s_nop 0
	global_load_lds_dwordx4 v132, s[40:41]
	s_waitcnt vmcnt(8)
	s_waitcnt lgkmcnt(0)
	s_barrier
	s_setprio 1
	s_waitcnt lgkmcnt(0)
	v_mfma_f32_16x16x32_bf16 v[124:127], v[152:155], v[184:187], v[124:127]
	v_mfma_f32_16x16x32_bf16 v[120:123], v[160:163], v[184:187], v[120:123]
	v_mfma_f32_16x16x32_bf16 v[116:119], v[152:155], v[196:199], v[116:119]
	v_mfma_f32_16x16x32_bf16 v[108:111], v[160:163], v[196:199], v[108:111]
	v_mfma_f32_16x16x32_bf16 v[100:103], v[152:155], v[204:207], v[100:103]
	v_mfma_f32_16x16x32_bf16 v[92:95], v[160:163], v[204:207], v[92:95]
	v_mfma_f32_16x16x32_bf16 v[84:87], v[152:155], v[212:215], v[84:87]
	v_mfma_f32_16x16x32_bf16 v[76:79], v[160:163], v[212:215], v[76:79]
	v_mfma_f32_16x16x32_bf16 v[124:127], v[156:159], v[192:195], v[124:127]
	v_mfma_f32_16x16x32_bf16 v[120:123], v[164:167], v[192:195], v[120:123]
	v_mfma_f32_16x16x32_bf16 v[116:119], v[156:159], v[200:203], v[116:119]
	v_mfma_f32_16x16x32_bf16 v[108:111], v[164:167], v[200:203], v[108:111]
	v_mfma_f32_16x16x32_bf16 v[100:103], v[156:159], v[208:211], v[100:103]
	v_mfma_f32_16x16x32_bf16 v[92:95], v[164:167], v[208:211], v[92:95]
	v_mfma_f32_16x16x32_bf16 v[84:87], v[156:159], v[216:219], v[84:87]
	v_mfma_f32_16x16x32_bf16 v[76:79], v[164:167], v[216:219], v[76:79]
	s_setprio 0
	s_setprio 1
	v_mfma_f32_16x16x32_bf16 v[112:115], v[168:171], v[184:187], v[112:115]
	v_mfma_f32_16x16x32_bf16 v[104:107], v[176:179], v[184:187], v[104:107]
	v_mfma_f32_16x16x32_bf16 v[96:99], v[168:171], v[196:199], v[96:99]
	v_mfma_f32_16x16x32_bf16 v[88:91], v[176:179], v[196:199], v[88:91]
	v_mfma_f32_16x16x32_bf16 v[80:83], v[168:171], v[204:207], v[80:83]
	v_mfma_f32_16x16x32_bf16 v[72:75], v[176:179], v[204:207], v[72:75]
	v_mfma_f32_16x16x32_bf16 v[68:71], v[168:171], v[212:215], v[68:71]
	v_mfma_f32_16x16x32_bf16 v[64:67], v[176:179], v[212:215], v[64:67]
	v_mfma_f32_16x16x32_bf16 v[112:115], v[172:175], v[192:195], v[112:115]
	v_mfma_f32_16x16x32_bf16 v[104:107], v[180:183], v[192:195], v[104:107]
	v_mfma_f32_16x16x32_bf16 v[96:99], v[172:175], v[200:203], v[96:99]
	v_mfma_f32_16x16x32_bf16 v[88:91], v[180:183], v[200:203], v[88:91]
	v_mfma_f32_16x16x32_bf16 v[80:83], v[172:175], v[208:211], v[80:83]
	v_mfma_f32_16x16x32_bf16 v[72:75], v[180:183], v[208:211], v[72:75]
	v_mfma_f32_16x16x32_bf16 v[68:71], v[172:175], v[216:219], v[68:71]
	v_mfma_f32_16x16x32_bf16 v[64:67], v[180:183], v[216:219], v[64:67]
	s_setprio 0
	s_barrier
	s_add_i32 s40, s76, s53
	s_mov_b32 m0, s40
	ds_read_b128 v[184:187], v151 offset:49152
	ds_read_b128 v[192:195], v151 offset:50176
	ds_read_b128 v[196:199], v151 offset:51200
	ds_read_b128 v[200:203], v151 offset:52224
	ds_read_b128 v[204:207], v151 offset:53248
	ds_read_b128 v[208:211], v151 offset:54272
	ds_read_b128 v[212:215], v151 offset:55296
	ds_read_b128 v[216:219], v151 offset:56320
	global_load_lds_dwordx4 v130, s[98:99]
	s_add_i32 m0, s40, 0x2000
	s_add_u32 s38, s38, 0x40080
	s_addc_u32 s39, s39, 0
	s_add_i32 s40, s77, s53
	global_load_lds_dwordx4 v134, s[98:99]
	s_mov_b32 m0, s40
	s_nop 0
	global_load_lds_dwordx4 v130, s[38:39]
	s_add_i32 m0, s40, 0x2000
	s_nop 0
	global_load_lds_dwordx4 v134, s[38:39]
	s_mov_b32 m0, s63
	s_nop 0
	global_load_lds_dwordx4 v128, s[100:101]
	s_mov_b32 m0, s64
	s_nop 0
	global_load_lds_dwordx4 v132, s[100:101]
	s_waitcnt vmcnt(8)
	s_waitcnt lgkmcnt(0)
	s_barrier
	s_setprio 1
	s_waitcnt lgkmcnt(0)
	v_mfma_f32_16x16x32_bf16 v[60:63], v[152:155], v[184:187], v[60:63]
	v_mfma_f32_16x16x32_bf16 v[56:59], v[160:163], v[184:187], v[56:59]
	v_mfma_f32_16x16x32_bf16 v[52:55], v[152:155], v[196:199], v[52:55]
	v_mfma_f32_16x16x32_bf16 v[44:47], v[160:163], v[196:199], v[44:47]
	v_mfma_f32_16x16x32_bf16 v[36:39], v[152:155], v[204:207], v[36:39]
	v_mfma_f32_16x16x32_bf16 v[28:31], v[160:163], v[204:207], v[28:31]
	v_mfma_f32_16x16x32_bf16 v[20:23], v[152:155], v[212:215], v[20:23]
	v_mfma_f32_16x16x32_bf16 v[12:15], v[160:163], v[212:215], v[12:15]
	v_mfma_f32_16x16x32_bf16 v[60:63], v[156:159], v[192:195], v[60:63]
	v_mfma_f32_16x16x32_bf16 v[56:59], v[164:167], v[192:195], v[56:59]
	v_mfma_f32_16x16x32_bf16 v[52:55], v[156:159], v[200:203], v[52:55]
	v_mfma_f32_16x16x32_bf16 v[44:47], v[164:167], v[200:203], v[44:47]
	v_mfma_f32_16x16x32_bf16 v[36:39], v[156:159], v[208:211], v[36:39]
	v_mfma_f32_16x16x32_bf16 v[28:31], v[164:167], v[208:211], v[28:31]
	v_mfma_f32_16x16x32_bf16 v[20:23], v[156:159], v[216:219], v[20:23]
	v_mfma_f32_16x16x32_bf16 v[12:15], v[164:167], v[216:219], v[12:15]
	s_setprio 0
	s_setprio 1
	v_mfma_f32_16x16x32_bf16 v[48:51], v[168:171], v[184:187], v[48:51]
	v_mfma_f32_16x16x32_bf16 v[40:43], v[176:179], v[184:187], v[40:43]
	v_mfma_f32_16x16x32_bf16 v[32:35], v[168:171], v[196:199], v[32:35]
	v_mfma_f32_16x16x32_bf16 v[24:27], v[176:179], v[196:199], v[24:27]
	v_mfma_f32_16x16x32_bf16 v[16:19], v[168:171], v[204:207], v[16:19]
	v_mfma_f32_16x16x32_bf16 v[8:11], v[176:179], v[204:207], v[8:11]
	v_mfma_f32_16x16x32_bf16 v[4:7], v[168:171], v[212:215], v[4:7]
	v_mfma_f32_16x16x32_bf16 v[0:3], v[176:179], v[212:215], v[0:3]
	v_mfma_f32_16x16x32_bf16 v[48:51], v[172:175], v[192:195], v[48:51]
	v_mfma_f32_16x16x32_bf16 v[40:43], v[180:183], v[192:195], v[40:43]
	v_mfma_f32_16x16x32_bf16 v[32:35], v[172:175], v[200:203], v[32:35]
	v_mfma_f32_16x16x32_bf16 v[24:27], v[180:183], v[200:203], v[24:27]
	v_mfma_f32_16x16x32_bf16 v[16:19], v[172:175], v[208:211], v[16:19]
	v_mfma_f32_16x16x32_bf16 v[8:11], v[180:183], v[208:211], v[8:11]
	v_mfma_f32_16x16x32_bf16 v[4:7], v[172:175], v[216:219], v[4:7]
	v_mfma_f32_16x16x32_bf16 v[0:3], v[180:183], v[216:219], v[0:3]
	s_setprio 0
	s_barrier
	s_add_i32 s75, s75, 2
	s_add_u32 s34, s34, 0x100
	s_addc_u32 s35, s35, 0
	s_add_u32 s73, s73, 0x100
	s_addc_u32 s74, s74, 0
	s_cmp_gt_u32 s75, 13
	s_cbranch_scc0 .LBB0_700
	s_branch .Lpeel_exit2
.LBB0_700:
	ds_read_b128 v[152:155], v149
	ds_read_b128 v[156:159], v149 offset:1024
	ds_read_b128 v[160:163], v149 offset:2048
	ds_read_b128 v[164:167], v149 offset:3072
	ds_read_b128 v[168:171], v150
	ds_read_b128 v[172:175], v150 offset:1024
	ds_read_b128 v[176:179], v150 offset:2048
	ds_read_b128 v[180:183], v150 offset:3072
	s_add_u32 s38, s34, 0xfffc0080
	s_addc_u32 s39, s35, -1
	s_cmp_eq_u32 s75, 12
	s_cselect_b32 s41, s25, s39
	s_cselect_b32 s40, s55, s38
	s_cselect_b32 s39, s23, s74
	s_cselect_b32 s38, s72, s73
	s_add_i32 m0, s31, 0xc000
	ds_read_b128 v[184:187], v151
	ds_read_b128 v[192:195], v151 offset:1024
	ds_read_b128 v[196:199], v151 offset:2048
	ds_read_b128 v[200:203], v151 offset:3072
	ds_read_b128 v[204:207], v151 offset:4096
	ds_read_b128 v[208:211], v151 offset:5120
	ds_read_b128 v[212:215], v151 offset:6144
	ds_read_b128 v[216:219], v151 offset:7168
	global_load_lds_dwordx4 v136, s[34:35]
	s_add_i32 m0, s31, 0xe000
	s_nop 0
	global_load_lds_dwordx4 v138, s[34:35]
	s_waitcnt vmcnt(8)
	s_waitcnt lgkmcnt(0)
	s_barrier
	s_setprio 1
	s_waitcnt lgkmcnt(0)
	v_mfma_f32_16x16x32_bf16 v[124:127], v[152:155], v[184:187], v[124:127]
	v_mfma_f32_16x16x32_bf16 v[120:123], v[160:163], v[184:187], v[120:123]
	v_mfma_f32_16x16x32_bf16 v[116:119], v[152:155], v[196:199], v[116:119]
	v_mfma_f32_16x16x32_bf16 v[108:111], v[160:163], v[196:199], v[108:111]
	v_mfma_f32_16x16x32_bf16 v[100:103], v[152:155], v[204:207], v[100:103]
	v_mfma_f32_16x16x32_bf16 v[92:95], v[160:163], v[204:207], v[92:95]
	v_mfma_f32_16x16x32_bf16 v[84:87], v[152:155], v[212:215], v[84:87]
	v_mfma_f32_16x16x32_bf16 v[76:79], v[160:163], v[212:215], v[76:79]
	v_mfma_f32_16x16x32_bf16 v[124:127], v[156:159], v[192:195], v[124:127]
	v_mfma_f32_16x16x32_bf16 v[120:123], v[164:167], v[192:195], v[120:123]
	v_mfma_f32_16x16x32_bf16 v[116:119], v[156:159], v[200:203], v[116:119]
	v_mfma_f32_16x16x32_bf16 v[108:111], v[164:167], v[200:203], v[108:111]
	v_mfma_f32_16x16x32_bf16 v[100:103], v[156:159], v[208:211], v[100:103]
	v_mfma_f32_16x16x32_bf16 v[92:95], v[164:167], v[208:211], v[92:95]
	v_mfma_f32_16x16x32_bf16 v[84:87], v[156:159], v[216:219], v[84:87]
	v_mfma_f32_16x16x32_bf16 v[76:79], v[164:167], v[216:219], v[76:79]
	s_setprio 0
	s_setprio 1
	v_mfma_f32_16x16x32_bf16 v[112:115], v[168:171], v[184:187], v[112:115]
	v_mfma_f32_16x16x32_bf16 v[104:107], v[176:179], v[184:187], v[104:107]
	v_mfma_f32_16x16x32_bf16 v[96:99], v[168:171], v[196:199], v[96:99]
	v_mfma_f32_16x16x32_bf16 v[88:91], v[176:179], v[196:199], v[88:91]
	v_mfma_f32_16x16x32_bf16 v[80:83], v[168:171], v[204:207], v[80:83]
	v_mfma_f32_16x16x32_bf16 v[72:75], v[176:179], v[204:207], v[72:75]
	v_mfma_f32_16x16x32_bf16 v[68:71], v[168:171], v[212:215], v[68:71]
	v_mfma_f32_16x16x32_bf16 v[64:67], v[176:179], v[212:215], v[64:67]
	v_mfma_f32_16x16x32_bf16 v[112:115], v[172:175], v[192:195], v[112:115]
	v_mfma_f32_16x16x32_bf16 v[104:107], v[180:183], v[192:195], v[104:107]
	v_mfma_f32_16x16x32_bf16 v[96:99], v[172:175], v[200:203], v[96:99]
	v_mfma_f32_16x16x32_bf16 v[88:91], v[180:183], v[200:203], v[88:91]
	v_mfma_f32_16x16x32_bf16 v[80:83], v[172:175], v[208:211], v[80:83]
	v_mfma_f32_16x16x32_bf16 v[72:75], v[180:183], v[208:211], v[72:75]
	v_mfma_f32_16x16x32_bf16 v[68:71], v[172:175], v[216:219], v[68:71]
	v_mfma_f32_16x16x32_bf16 v[64:67], v[180:183], v[216:219], v[64:67]
	s_setprio 0
	s_barrier
	s_add_i32 s76, s66, s53
	s_add_u32 s98, s38, 0x80
	s_addc_u32 s99, s39, 0
	s_mov_b32 m0, s76
	ds_read_b128 v[184:187], v151 offset:16384
	ds_read_b128 v[192:195], v151 offset:17408
	ds_read_b128 v[196:199], v151 offset:18432
	ds_read_b128 v[200:203], v151 offset:19456
	ds_read_b128 v[204:207], v151 offset:20480
	ds_read_b128 v[208:211], v151 offset:21504
	ds_read_b128 v[212:215], v151 offset:22528
	ds_read_b128 v[216:219], v151 offset:23552
	global_load_lds_dwordx4 v130, s[38:39]
	s_add_i32 m0, s76, 0x2000
	s_add_u32 s76, s38, 0x40000
	s_addc_u32 s77, s39, 0
	s_add_i32 s79, s67, s53
	global_load_lds_dwordx4 v134, s[38:39]
	s_mov_b32 m0, s79
	s_add_u32 s100, s40, 0x80
	s_addc_u32 s101, s41, 0
	global_load_lds_dwordx4 v130, s[76:77]
	s_add_i32 m0, s79, 0x2000
	s_nop 0
	global_load_lds_dwordx4 v134, s[76:77]
	s_mov_b32 m0, s31
	s_nop 0
	global_load_lds_dwordx4 v128, s[40:41]
	s_mov_b32 m0, s33
	s_nop 0
	global_load_lds_dwordx4 v132, s[40:41]
	s_waitcnt vmcnt(8)
	s_waitcnt lgkmcnt(0)
	s_barrier
	s_setprio 1
	s_waitcnt lgkmcnt(0)
	v_mfma_f32_16x16x32_bf16 v[60:63], v[152:155], v[184:187], v[60:63]
	v_mfma_f32_16x16x32_bf16 v[56:59], v[160:163], v[184:187], v[56:59]
	v_mfma_f32_16x16x32_bf16 v[52:55], v[152:155], v[196:199], v[52:55]
	v_mfma_f32_16x16x32_bf16 v[44:47], v[160:163], v[196:199], v[44:47]
	v_mfma_f32_16x16x32_bf16 v[36:39], v[152:155], v[204:207], v[36:39]
	v_mfma_f32_16x16x32_bf16 v[28:31], v[160:163], v[204:207], v[28:31]
	v_mfma_f32_16x16x32_bf16 v[20:23], v[152:155], v[212:215], v[20:23]
	v_mfma_f32_16x16x32_bf16 v[12:15], v[160:163], v[212:215], v[12:15]
	v_mfma_f32_16x16x32_bf16 v[60:63], v[156:159], v[192:195], v[60:63]
	v_mfma_f32_16x16x32_bf16 v[56:59], v[164:167], v[192:195], v[56:59]
	v_mfma_f32_16x16x32_bf16 v[52:55], v[156:159], v[200:203], v[52:55]
	v_mfma_f32_16x16x32_bf16 v[44:47], v[164:167], v[200:203], v[44:47]
	v_mfma_f32_16x16x32_bf16 v[36:39], v[156:159], v[208:211], v[36:39]
	v_mfma_f32_16x16x32_bf16 v[28:31], v[164:167], v[208:211], v[28:31]
	v_mfma_f32_16x16x32_bf16 v[20:23], v[156:159], v[216:219], v[20:23]
	v_mfma_f32_16x16x32_bf16 v[12:15], v[164:167], v[216:219], v[12:15]
	s_setprio 0
	s_setprio 1
	v_mfma_f32_16x16x32_bf16 v[48:51], v[168:171], v[184:187], v[48:51]
	v_mfma_f32_16x16x32_bf16 v[40:43], v[176:179], v[184:187], v[40:43]
	v_mfma_f32_16x16x32_bf16 v[32:35], v[168:171], v[196:199], v[32:35]
	v_mfma_f32_16x16x32_bf16 v[24:27], v[176:179], v[196:199], v[24:27]
	v_mfma_f32_16x16x32_bf16 v[16:19], v[168:171], v[204:207], v[16:19]
	v_mfma_f32_16x16x32_bf16 v[8:11], v[176:179], v[204:207], v[8:11]
	v_mfma_f32_16x16x32_bf16 v[4:7], v[168:171], v[212:215], v[4:7]
	v_mfma_f32_16x16x32_bf16 v[0:3], v[176:179], v[212:215], v[0:3]
	v_mfma_f32_16x16x32_bf16 v[48:51], v[172:175], v[192:195], v[48:51]
	v_mfma_f32_16x16x32_bf16 v[40:43], v[180:183], v[192:195], v[40:43]
	v_mfma_f32_16x16x32_bf16 v[32:35], v[172:175], v[200:203], v[32:35]
	v_mfma_f32_16x16x32_bf16 v[24:27], v[180:183], v[200:203], v[24:27]
	v_mfma_f32_16x16x32_bf16 v[16:19], v[172:175], v[208:211], v[16:19]
	v_mfma_f32_16x16x32_bf16 v[8:11], v[180:183], v[208:211], v[8:11]
	v_mfma_f32_16x16x32_bf16 v[4:7], v[172:175], v[216:219], v[4:7]
	v_mfma_f32_16x16x32_bf16 v[0:3], v[180:183], v[216:219], v[0:3]
	s_setprio 0
	s_barrier
	s_add_i32 s76, 0, 0x18000
	s_add_i32 s77, 0, 0x1c000
	v_add_u32_e32 v164, s76, v147
	v_add_u32_e32 v180, s77, v147
	ds_read_b128 v[152:155], v164
	ds_read_b128 v[156:159], v164 offset:1024
	ds_read_b128 v[160:163], v164 offset:2048
	ds_read_b128 v[164:167], v164 offset:3072
	ds_read_b128 v[168:171], v180
	ds_read_b128 v[172:175], v180 offset:1024
	ds_read_b128 v[176:179], v180 offset:2048
	ds_read_b128 v[180:183], v180 offset:3072
	s_add_u32 s40, s40, 0x40000
	s_addc_u32 s41, s41, 0
	s_mov_b32 m0, s60
	ds_read_b128 v[184:187], v151 offset:32768
	ds_read_b128 v[192:195], v151 offset:33792
	ds_read_b128 v[196:199], v151 offset:34816
	ds_read_b128 v[200:203], v151 offset:35840
	ds_read_b128 v[204:207], v151 offset:36864
	ds_read_b128 v[208:211], v151 offset:37888
	ds_read_b128 v[212:215], v151 offset:38912
	ds_read_b128 v[216:219], v151 offset:39936
	global_load_lds_dwordx4 v128, s[40:41]
	s_mov_b32 m0, s61
	s_nop 0
	global_load_lds_dwordx4 v132, s[40:41]
	s_waitcnt vmcnt(8)
	s_waitcnt lgkmcnt(0)
	s_barrier
	s_setprio 1
	s_waitcnt lgkmcnt(0)
	v_mfma_f32_16x16x32_bf16 v[124:127], v[152:155], v[184:187], v[124:127]
	v_mfma_f32_16x16x32_bf16 v[120:123], v[160:163], v[184:187], v[120:123]
	v_mfma_f32_16x16x32_bf16 v[116:119], v[152:155], v[196:199], v[116:119]
	v_mfma_f32_16x16x32_bf16 v[108:111], v[160:163], v[196:199], v[108:111]
	v_mfma_f32_16x16x32_bf16 v[100:103], v[152:155], v[204:207], v[100:103]
	v_mfma_f32_16x16x32_bf16 v[92:95], v[160:163], v[204:207], v[92:95]
	v_mfma_f32_16x16x32_bf16 v[84:87], v[152:155], v[212:215], v[84:87]
	v_mfma_f32_16x16x32_bf16 v[76:79], v[160:163], v[212:215], v[76:79]
	v_mfma_f32_16x16x32_bf16 v[124:127], v[156:159], v[192:195], v[124:127]
	v_mfma_f32_16x16x32_bf16 v[120:123], v[164:167], v[192:195], v[120:123]
	v_mfma_f32_16x16x32_bf16 v[116:119], v[156:159], v[200:203], v[116:119]
	v_mfma_f32_16x16x32_bf16 v[108:111], v[164:167], v[200:203], v[108:111]
	v_mfma_f32_16x16x32_bf16 v[100:103], v[156:159], v[208:211], v[100:103]
	v_mfma_f32_16x16x32_bf16 v[92:95], v[164:167], v[208:211], v[92:95]
	v_mfma_f32_16x16x32_bf16 v[84:87], v[156:159], v[216:219], v[84:87]
	v_mfma_f32_16x16x32_bf16 v[76:79], v[164:167], v[216:219], v[76:79]
	s_setprio 0
	s_setprio 1
	v_mfma_f32_16x16x32_bf16 v[112:115], v[168:171], v[184:187], v[112:115]
	v_mfma_f32_16x16x32_bf16 v[104:107], v[176:179], v[184:187], v[104:107]
	v_mfma_f32_16x16x32_bf16 v[96:99], v[168:171], v[196:199], v[96:99]
	v_mfma_f32_16x16x32_bf16 v[88:91], v[176:179], v[196:199], v[88:91]
	v_mfma_f32_16x16x32_bf16 v[80:83], v[168:171], v[204:207], v[80:83]
	v_mfma_f32_16x16x32_bf16 v[72:75], v[176:179], v[204:207], v[72:75]
	v_mfma_f32_16x16x32_bf16 v[68:71], v[168:171], v[212:215], v[68:71]
	v_mfma_f32_16x16x32_bf16 v[64:67], v[176:179], v[212:215], v[64:67]
	v_mfma_f32_16x16x32_bf16 v[112:115], v[172:175], v[192:195], v[112:115]
	v_mfma_f32_16x16x32_bf16 v[104:107], v[180:183], v[192:195], v[104:107]
	v_mfma_f32_16x16x32_bf16 v[96:99], v[172:175], v[200:203], v[96:99]
	v_mfma_f32_16x16x32_bf16 v[88:91], v[180:183], v[200:203], v[88:91]
	v_mfma_f32_16x16x32_bf16 v[80:83], v[172:175], v[208:211], v[80:83]
	v_mfma_f32_16x16x32_bf16 v[72:75], v[180:183], v[208:211], v[72:75]
	v_mfma_f32_16x16x32_bf16 v[68:71], v[172:175], v[216:219], v[68:71]
	v_mfma_f32_16x16x32_bf16 v[64:67], v[180:183], v[216:219], v[64:67]
	s_setprio 0
	s_barrier
	s_add_i32 s40, s76, s53
	s_mov_b32 m0, s40
	ds_read_b128 v[184:187], v151 offset:49152
	ds_read_b128 v[192:195], v151 offset:50176
	ds_read_b128 v[196:199], v151 offset:51200
	ds_read_b128 v[200:203], v151 offset:52224
	ds_read_b128 v[204:207], v151 offset:53248
	ds_read_b128 v[208:211], v151 offset:54272
	ds_read_b128 v[212:215], v151 offset:55296
	ds_read_b128 v[216:219], v151 offset:56320
	global_load_lds_dwordx4 v130, s[98:99]
	s_add_i32 m0, s40, 0x2000
	s_add_u32 s38, s38, 0x40080
	s_addc_u32 s39, s39, 0
	s_add_i32 s40, s77, s53
	global_load_lds_dwordx4 v134, s[98:99]
	s_mov_b32 m0, s40
	s_nop 0
	global_load_lds_dwordx4 v130, s[38:39]
	s_add_i32 m0, s40, 0x2000
	s_nop 0
	global_load_lds_dwordx4 v134, s[38:39]
	s_mov_b32 m0, s63
	s_nop 0
	global_load_lds_dwordx4 v128, s[100:101]
	s_mov_b32 m0, s64
	s_nop 0
	global_load_lds_dwordx4 v132, s[100:101]
	s_waitcnt vmcnt(8)
	s_waitcnt lgkmcnt(0)
	s_barrier
	s_setprio 1
	s_waitcnt lgkmcnt(0)
	v_mfma_f32_16x16x32_bf16 v[60:63], v[152:155], v[184:187], v[60:63]
	v_mfma_f32_16x16x32_bf16 v[56:59], v[160:163], v[184:187], v[56:59]
	v_mfma_f32_16x16x32_bf16 v[52:55], v[152:155], v[196:199], v[52:55]
	v_mfma_f32_16x16x32_bf16 v[44:47], v[160:163], v[196:199], v[44:47]
	v_mfma_f32_16x16x32_bf16 v[36:39], v[152:155], v[204:207], v[36:39]
	v_mfma_f32_16x16x32_bf16 v[28:31], v[160:163], v[204:207], v[28:31]
	v_mfma_f32_16x16x32_bf16 v[20:23], v[152:155], v[212:215], v[20:23]
	v_mfma_f32_16x16x32_bf16 v[12:15], v[160:163], v[212:215], v[12:15]
	v_mfma_f32_16x16x32_bf16 v[60:63], v[156:159], v[192:195], v[60:63]
	v_mfma_f32_16x16x32_bf16 v[56:59], v[164:167], v[192:195], v[56:59]
	v_mfma_f32_16x16x32_bf16 v[52:55], v[156:159], v[200:203], v[52:55]
	v_mfma_f32_16x16x32_bf16 v[44:47], v[164:167], v[200:203], v[44:47]
	v_mfma_f32_16x16x32_bf16 v[36:39], v[156:159], v[208:211], v[36:39]
	v_mfma_f32_16x16x32_bf16 v[28:31], v[164:167], v[208:211], v[28:31]
	v_mfma_f32_16x16x32_bf16 v[20:23], v[156:159], v[216:219], v[20:23]
	v_mfma_f32_16x16x32_bf16 v[12:15], v[164:167], v[216:219], v[12:15]
	s_setprio 0
	s_setprio 1
	v_mfma_f32_16x16x32_bf16 v[48:51], v[168:171], v[184:187], v[48:51]
	v_mfma_f32_16x16x32_bf16 v[40:43], v[176:179], v[184:187], v[40:43]
	v_mfma_f32_16x16x32_bf16 v[32:35], v[168:171], v[196:199], v[32:35]
	v_mfma_f32_16x16x32_bf16 v[24:27], v[176:179], v[196:199], v[24:27]
	v_mfma_f32_16x16x32_bf16 v[16:19], v[168:171], v[204:207], v[16:19]
	v_mfma_f32_16x16x32_bf16 v[8:11], v[176:179], v[204:207], v[8:11]
	v_mfma_f32_16x16x32_bf16 v[4:7], v[168:171], v[212:215], v[4:7]
	v_mfma_f32_16x16x32_bf16 v[0:3], v[176:179], v[212:215], v[0:3]
	v_mfma_f32_16x16x32_bf16 v[48:51], v[172:175], v[192:195], v[48:51]
	v_mfma_f32_16x16x32_bf16 v[40:43], v[180:183], v[192:195], v[40:43]
	v_mfma_f32_16x16x32_bf16 v[32:35], v[172:175], v[200:203], v[32:35]
	v_mfma_f32_16x16x32_bf16 v[24:27], v[180:183], v[200:203], v[24:27]
	v_mfma_f32_16x16x32_bf16 v[16:19], v[172:175], v[208:211], v[16:19]
	v_mfma_f32_16x16x32_bf16 v[8:11], v[180:183], v[208:211], v[8:11]
	v_mfma_f32_16x16x32_bf16 v[4:7], v[172:175], v[216:219], v[4:7]
	v_mfma_f32_16x16x32_bf16 v[0:3], v[180:183], v[216:219], v[0:3]
	s_setprio 0
	s_barrier
	s_add_i32 s75, s75, 2
	s_add_u32 s34, s34, 0x100
	s_addc_u32 s35, s35, 0
	s_add_u32 s73, s73, 0x100
	s_addc_u32 s74, s74, 0
	s_cmp_gt_u32 s75, 13
	s_cbranch_scc0 .LBB0_700

.LBB0_836:
	s_ashr_i32 s25, s24, 31
	s_lshl_b64 s[26:27], s[24:25], 19
	s_add_u32 s26, s58, s26
	s_addc_u32 s27, s59, s27
	s_and_b64 s[28:29], s[4:5], exec
	s_cselect_b32 s25, s27, s35
	s_cselect_b32 s54, s26, s34
	s_ashr_i32 s23, s22, 31
	s_lshl_b64 s[28:29], s[22:23], 19
	s_add_u32 s28, s61, s28
	s_addc_u32 s29, s62, s29
	s_and_b64 s[42:43], s[4:5], exec
	s_cselect_b32 s23, s29, s41
	s_cselect_b32 s55, s28, s40
	s_add_u32 s34, s34, 0x40080
	s_addc_u32 s35, s35, 0
	s_add_u32 s75, s40, 0x100
	s_addc_u32 s76, s41, 0
	s_mov_b32 s77, -2
	ds_read_b128 v[152:155], v149
	ds_read_b128 v[156:159], v149 offset:1024
	ds_read_b128 v[160:163], v149 offset:2048
	ds_read_b128 v[164:167], v149 offset:3072
	ds_read_b128 v[168:171], v150
	ds_read_b128 v[172:175], v150 offset:1024
	ds_read_b128 v[176:179], v150 offset:2048
	ds_read_b128 v[180:183], v150 offset:3072
	s_add_u32 s40, s34, 0xfffc0080
	s_addc_u32 s41, s35, -1
	s_cmp_eq_u32 s77, 12
	s_cselect_b32 s43, s25, s41
	s_cselect_b32 s42, s54, s40
	s_cselect_b32 s41, s23, s76
	s_cselect_b32 s40, s55, s75
	s_add_i32 m0, s31, 0xc000
	ds_read_b128 v[184:187], v151
	ds_read_b128 v[192:195], v151 offset:1024
	ds_read_b128 v[196:199], v151 offset:2048
	ds_read_b128 v[200:203], v151 offset:3072
	ds_read_b128 v[204:207], v151 offset:4096
	ds_read_b128 v[208:211], v151 offset:5120
	ds_read_b128 v[212:215], v151 offset:6144
	ds_read_b128 v[216:219], v151 offset:7168
	global_load_lds_dwordx4 v136, s[34:35]
	s_add_i32 m0, s31, 0xe000
	s_nop 0
	global_load_lds_dwordx4 v138, s[34:35]
	s_waitcnt vmcnt(8)
	s_waitcnt lgkmcnt(0)
	s_barrier
	s_setprio 1
	s_waitcnt lgkmcnt(0)
	v_mfma_f32_16x16x32_bf16 v[124:127], v[152:155], v[184:187], 0
	v_mfma_f32_16x16x32_bf16 v[120:123], v[160:163], v[184:187], 0
	v_mfma_f32_16x16x32_bf16 v[108:111], v[152:155], v[196:199], 0
	v_mfma_f32_16x16x32_bf16 v[104:107], v[160:163], v[196:199], 0
	v_mfma_f32_16x16x32_bf16 v[92:95], v[152:155], v[204:207], 0
	v_mfma_f32_16x16x32_bf16 v[88:91], v[160:163], v[204:207], 0
	v_mfma_f32_16x16x32_bf16 v[76:79], v[152:155], v[212:215], 0
	v_mfma_f32_16x16x32_bf16 v[72:75], v[160:163], v[212:215], 0
	v_mfma_f32_16x16x32_bf16 v[124:127], v[156:159], v[192:195], v[124:127]
	v_mfma_f32_16x16x32_bf16 v[120:123], v[164:167], v[192:195], v[120:123]
	v_mfma_f32_16x16x32_bf16 v[108:111], v[156:159], v[200:203], v[108:111]
	v_mfma_f32_16x16x32_bf16 v[104:107], v[164:167], v[200:203], v[104:107]
	v_mfma_f32_16x16x32_bf16 v[92:95], v[156:159], v[208:211], v[92:95]
	v_mfma_f32_16x16x32_bf16 v[88:91], v[164:167], v[208:211], v[88:91]
	v_mfma_f32_16x16x32_bf16 v[76:79], v[156:159], v[216:219], v[76:79]
	v_mfma_f32_16x16x32_bf16 v[72:75], v[164:167], v[216:219], v[72:75]
	s_setprio 0
	s_setprio 1
	v_mfma_f32_16x16x32_bf16 v[116:119], v[168:171], v[184:187], 0
	v_mfma_f32_16x16x32_bf16 v[112:115], v[176:179], v[184:187], 0
	v_mfma_f32_16x16x32_bf16 v[100:103], v[168:171], v[196:199], 0
	v_mfma_f32_16x16x32_bf16 v[96:99], v[176:179], v[196:199], 0
	v_mfma_f32_16x16x32_bf16 v[84:87], v[168:171], v[204:207], 0
	v_mfma_f32_16x16x32_bf16 v[80:83], v[176:179], v[204:207], 0
	v_mfma_f32_16x16x32_bf16 v[68:71], v[168:171], v[212:215], 0
	v_mfma_f32_16x16x32_bf16 v[64:67], v[176:179], v[212:215], 0
	v_mfma_f32_16x16x32_bf16 v[116:119], v[172:175], v[192:195], v[116:119]
	v_mfma_f32_16x16x32_bf16 v[112:115], v[180:183], v[192:195], v[112:115]
	v_mfma_f32_16x16x32_bf16 v[100:103], v[172:175], v[200:203], v[100:103]
	v_mfma_f32_16x16x32_bf16 v[96:99], v[180:183], v[200:203], v[96:99]
	v_mfma_f32_16x16x32_bf16 v[84:87], v[172:175], v[208:211], v[84:87]
	v_mfma_f32_16x16x32_bf16 v[80:83], v[180:183], v[208:211], v[80:83]
	v_mfma_f32_16x16x32_bf16 v[68:71], v[172:175], v[216:219], v[68:71]
	v_mfma_f32_16x16x32_bf16 v[64:67], v[180:183], v[216:219], v[64:67]
	s_setprio 0
	s_barrier
	s_add_i32 s79, s69, s63
	s_add_u32 s98, s40, 0x80
	s_addc_u32 s99, s41, 0
	s_mov_b32 m0, s79
	ds_read_b128 v[184:187], v151 offset:16384
	ds_read_b128 v[192:195], v151 offset:17408
	ds_read_b128 v[196:199], v151 offset:18432
	ds_read_b128 v[200:203], v151 offset:19456
	ds_read_b128 v[204:207], v151 offset:20480
	ds_read_b128 v[208:211], v151 offset:21504
	ds_read_b128 v[212:215], v151 offset:22528
	ds_read_b128 v[216:219], v151 offset:23552
	global_load_lds_dwordx4 v130, s[40:41]
	s_add_i32 m0, s79, 0x2000
	s_add_u32 s80, s40, 0x40000
	s_addc_u32 s81, s41, 0
	s_add_i32 s79, s70, s63
	global_load_lds_dwordx4 v134, s[40:41]
	s_mov_b32 m0, s79
	s_add_u32 s100, s42, 0x80
	s_addc_u32 s101, s43, 0
	global_load_lds_dwordx4 v130, s[80:81]
	s_add_i32 m0, s79, 0x2000
	s_nop 0
	global_load_lds_dwordx4 v134, s[80:81]
	s_mov_b32 m0, s31
	s_nop 0
	global_load_lds_dwordx4 v128, s[42:43]
	s_mov_b32 m0, s64
	s_nop 0
	global_load_lds_dwordx4 v132, s[42:43]
	s_waitcnt vmcnt(8)
	s_waitcnt lgkmcnt(0)
	s_barrier
	s_setprio 1
	s_waitcnt lgkmcnt(0)
	v_mfma_f32_16x16x32_bf16 v[60:63], v[152:155], v[184:187], 0
	v_mfma_f32_16x16x32_bf16 v[56:59], v[160:163], v[184:187], 0
	v_mfma_f32_16x16x32_bf16 v[44:47], v[152:155], v[196:199], 0
	v_mfma_f32_16x16x32_bf16 v[40:43], v[160:163], v[196:199], 0
	v_mfma_f32_16x16x32_bf16 v[28:31], v[152:155], v[204:207], 0
	v_mfma_f32_16x16x32_bf16 v[24:27], v[160:163], v[204:207], 0
	v_mfma_f32_16x16x32_bf16 v[12:15], v[152:155], v[212:215], 0
	v_mfma_f32_16x16x32_bf16 v[8:11], v[160:163], v[212:215], 0
	v_mfma_f32_16x16x32_bf16 v[60:63], v[156:159], v[192:195], v[60:63]
	v_mfma_f32_16x16x32_bf16 v[56:59], v[164:167], v[192:195], v[56:59]
	v_mfma_f32_16x16x32_bf16 v[44:47], v[156:159], v[200:203], v[44:47]
	v_mfma_f32_16x16x32_bf16 v[40:43], v[164:167], v[200:203], v[40:43]
	v_mfma_f32_16x16x32_bf16 v[28:31], v[156:159], v[208:211], v[28:31]
	v_mfma_f32_16x16x32_bf16 v[24:27], v[164:167], v[208:211], v[24:27]
	v_mfma_f32_16x16x32_bf16 v[12:15], v[156:159], v[216:219], v[12:15]
	v_mfma_f32_16x16x32_bf16 v[8:11], v[164:167], v[216:219], v[8:11]
	s_setprio 0
	s_setprio 1
	v_mfma_f32_16x16x32_bf16 v[52:55], v[168:171], v[184:187], 0
	v_mfma_f32_16x16x32_bf16 v[48:51], v[176:179], v[184:187], 0
	v_mfma_f32_16x16x32_bf16 v[36:39], v[168:171], v[196:199], 0
	v_mfma_f32_16x16x32_bf16 v[32:35], v[176:179], v[196:199], 0
	v_mfma_f32_16x16x32_bf16 v[20:23], v[168:171], v[204:207], 0
	v_mfma_f32_16x16x32_bf16 v[16:19], v[176:179], v[204:207], 0
	v_mfma_f32_16x16x32_bf16 v[4:7], v[168:171], v[212:215], 0
	v_mfma_f32_16x16x32_bf16 v[0:3], v[176:179], v[212:215], 0
	v_mfma_f32_16x16x32_bf16 v[52:55], v[172:175], v[192:195], v[52:55]
	v_mfma_f32_16x16x32_bf16 v[48:51], v[180:183], v[192:195], v[48:51]
	v_mfma_f32_16x16x32_bf16 v[36:39], v[172:175], v[200:203], v[36:39]
	v_mfma_f32_16x16x32_bf16 v[32:35], v[180:183], v[200:203], v[32:35]
	v_mfma_f32_16x16x32_bf16 v[20:23], v[172:175], v[208:211], v[20:23]
	v_mfma_f32_16x16x32_bf16 v[16:19], v[180:183], v[208:211], v[16:19]
	v_mfma_f32_16x16x32_bf16 v[4:7], v[172:175], v[216:219], v[4:7]
	v_mfma_f32_16x16x32_bf16 v[0:3], v[180:183], v[216:219], v[0:3]
	s_setprio 0
	s_barrier
	s_add_i32 s79, 0, 0x18000
	s_add_i32 s80, 0, 0x1c000
	v_add_u32_e32 v164, s79, v147
	v_add_u32_e32 v180, s80, v147
	ds_read_b128 v[152:155], v164
	ds_read_b128 v[156:159], v164 offset:1024
	ds_read_b128 v[160:163], v164 offset:2048
	ds_read_b128 v[164:167], v164 offset:3072
	ds_read_b128 v[168:171], v180
	ds_read_b128 v[172:175], v180 offset:1024
	ds_read_b128 v[176:179], v180 offset:2048
	ds_read_b128 v[180:183], v180 offset:3072
	s_add_u32 s42, s42, 0x40000
	s_addc_u32 s43, s43, 0
	s_mov_b32 m0, s65
	ds_read_b128 v[184:187], v151 offset:32768
	ds_read_b128 v[192:195], v151 offset:33792
	ds_read_b128 v[196:199], v151 offset:34816
	ds_read_b128 v[200:203], v151 offset:35840
	ds_read_b128 v[204:207], v151 offset:36864
	ds_read_b128 v[208:211], v151 offset:37888
	ds_read_b128 v[212:215], v151 offset:38912
	ds_read_b128 v[216:219], v151 offset:39936
	global_load_lds_dwordx4 v128, s[42:43]
	s_mov_b32 m0, s66
	s_nop 0
	global_load_lds_dwordx4 v132, s[42:43]
	s_waitcnt vmcnt(8)
	s_waitcnt lgkmcnt(0)
	s_barrier
	s_setprio 1
	s_waitcnt lgkmcnt(0)
	v_mfma_f32_16x16x32_bf16 v[124:127], v[152:155], v[184:187], v[124:127]
	v_mfma_f32_16x16x32_bf16 v[120:123], v[160:163], v[184:187], v[120:123]
	v_mfma_f32_16x16x32_bf16 v[108:111], v[152:155], v[196:199], v[108:111]
	v_mfma_f32_16x16x32_bf16 v[104:107], v[160:163], v[196:199], v[104:107]
	v_mfma_f32_16x16x32_bf16 v[92:95], v[152:155], v[204:207], v[92:95]
	v_mfma_f32_16x16x32_bf16 v[88:91], v[160:163], v[204:207], v[88:91]
	v_mfma_f32_16x16x32_bf16 v[76:79], v[152:155], v[212:215], v[76:79]
	v_mfma_f32_16x16x32_bf16 v[72:75], v[160:163], v[212:215], v[72:75]
	v_mfma_f32_16x16x32_bf16 v[124:127], v[156:159], v[192:195], v[124:127]
	v_mfma_f32_16x16x32_bf16 v[120:123], v[164:167], v[192:195], v[120:123]
	v_mfma_f32_16x16x32_bf16 v[108:111], v[156:159], v[200:203], v[108:111]
	v_mfma_f32_16x16x32_bf16 v[104:107], v[164:167], v[200:203], v[104:107]
	v_mfma_f32_16x16x32_bf16 v[92:95], v[156:159], v[208:211], v[92:95]
	v_mfma_f32_16x16x32_bf16 v[88:91], v[164:167], v[208:211], v[88:91]
	v_mfma_f32_16x16x32_bf16 v[76:79], v[156:159], v[216:219], v[76:79]
	v_mfma_f32_16x16x32_bf16 v[72:75], v[164:167], v[216:219], v[72:75]
	s_setprio 0
	s_setprio 1
	v_mfma_f32_16x16x32_bf16 v[116:119], v[168:171], v[184:187], v[116:119]
	v_mfma_f32_16x16x32_bf16 v[112:115], v[176:179], v[184:187], v[112:115]
	v_mfma_f32_16x16x32_bf16 v[100:103], v[168:171], v[196:199], v[100:103]
	v_mfma_f32_16x16x32_bf16 v[96:99], v[176:179], v[196:199], v[96:99]
	v_mfma_f32_16x16x32_bf16 v[84:87], v[168:171], v[204:207], v[84:87]
	v_mfma_f32_16x16x32_bf16 v[80:83], v[176:179], v[204:207], v[80:83]
	v_mfma_f32_16x16x32_bf16 v[68:71], v[168:171], v[212:215], v[68:71]
	v_mfma_f32_16x16x32_bf16 v[64:67], v[176:179], v[212:215], v[64:67]
	v_mfma_f32_16x16x32_bf16 v[116:119], v[172:175], v[192:195], v[116:119]
	v_mfma_f32_16x16x32_bf16 v[112:115], v[180:183], v[192:195], v[112:115]
	v_mfma_f32_16x16x32_bf16 v[100:103], v[172:175], v[200:203], v[100:103]
	v_mfma_f32_16x16x32_bf16 v[96:99], v[180:183], v[200:203], v[96:99]
	v_mfma_f32_16x16x32_bf16 v[84:87], v[172:175], v[208:211], v[84:87]
	v_mfma_f32_16x16x32_bf16 v[80:83], v[180:183], v[208:211], v[80:83]
	v_mfma_f32_16x16x32_bf16 v[68:71], v[172:175], v[216:219], v[68:71]
	v_mfma_f32_16x16x32_bf16 v[64:67], v[180:183], v[216:219], v[64:67]
	s_setprio 0
	s_barrier
	s_add_i32 s42, s79, s63
	s_mov_b32 m0, s42
	ds_read_b128 v[184:187], v151 offset:49152
	ds_read_b128 v[192:195], v151 offset:50176
	ds_read_b128 v[196:199], v151 offset:51200
	ds_read_b128 v[200:203], v151 offset:52224
	ds_read_b128 v[204:207], v151 offset:53248
	ds_read_b128 v[208:211], v151 offset:54272
	ds_read_b128 v[212:215], v151 offset:55296
	ds_read_b128 v[216:219], v151 offset:56320
	global_load_lds_dwordx4 v130, s[98:99]
	s_add_i32 m0, s42, 0x2000
	s_add_u32 s40, s40, 0x40080
	s_addc_u32 s41, s41, 0
	s_add_i32 s42, s80, s63
	global_load_lds_dwordx4 v134, s[98:99]
	s_mov_b32 m0, s42
	s_nop 0
	global_load_lds_dwordx4 v130, s[40:41]
	s_add_i32 m0, s42, 0x2000
	s_nop 0
	global_load_lds_dwordx4 v134, s[40:41]
	s_mov_b32 m0, s52
	s_nop 0
	global_load_lds_dwordx4 v128, s[100:101]
	s_mov_b32 m0, s53
	s_nop 0
	global_load_lds_dwordx4 v132, s[100:101]
	s_waitcnt vmcnt(8)
	s_waitcnt lgkmcnt(0)
	s_barrier
	s_setprio 1
	s_waitcnt lgkmcnt(0)
	v_mfma_f32_16x16x32_bf16 v[60:63], v[152:155], v[184:187], v[60:63]
	v_mfma_f32_16x16x32_bf16 v[56:59], v[160:163], v[184:187], v[56:59]
	v_mfma_f32_16x16x32_bf16 v[44:47], v[152:155], v[196:199], v[44:47]
	v_mfma_f32_16x16x32_bf16 v[40:43], v[160:163], v[196:199], v[40:43]
	v_mfma_f32_16x16x32_bf16 v[28:31], v[152:155], v[204:207], v[28:31]
	v_mfma_f32_16x16x32_bf16 v[24:27], v[160:163], v[204:207], v[24:27]
	v_mfma_f32_16x16x32_bf16 v[12:15], v[152:155], v[212:215], v[12:15]
	v_mfma_f32_16x16x32_bf16 v[8:11], v[160:163], v[212:215], v[8:11]
	v_mfma_f32_16x16x32_bf16 v[60:63], v[156:159], v[192:195], v[60:63]
	v_mfma_f32_16x16x32_bf16 v[56:59], v[164:167], v[192:195], v[56:59]
	v_mfma_f32_16x16x32_bf16 v[44:47], v[156:159], v[200:203], v[44:47]
	v_mfma_f32_16x16x32_bf16 v[40:43], v[164:167], v[200:203], v[40:43]
	v_mfma_f32_16x16x32_bf16 v[28:31], v[156:159], v[208:211], v[28:31]
	v_mfma_f32_16x16x32_bf16 v[24:27], v[164:167], v[208:211], v[24:27]
	v_mfma_f32_16x16x32_bf16 v[12:15], v[156:159], v[216:219], v[12:15]
	v_mfma_f32_16x16x32_bf16 v[8:11], v[164:167], v[216:219], v[8:11]
	s_setprio 0
	s_setprio 1
	v_mfma_f32_16x16x32_bf16 v[52:55], v[168:171], v[184:187], v[52:55]
	v_mfma_f32_16x16x32_bf16 v[48:51], v[176:179], v[184:187], v[48:51]
	v_mfma_f32_16x16x32_bf16 v[36:39], v[168:171], v[196:199], v[36:39]
	v_mfma_f32_16x16x32_bf16 v[32:35], v[176:179], v[196:199], v[32:35]
	v_mfma_f32_16x16x32_bf16 v[20:23], v[168:171], v[204:207], v[20:23]
	v_mfma_f32_16x16x32_bf16 v[16:19], v[176:179], v[204:207], v[16:19]
	v_mfma_f32_16x16x32_bf16 v[4:7], v[168:171], v[212:215], v[4:7]
	v_mfma_f32_16x16x32_bf16 v[0:3], v[176:179], v[212:215], v[0:3]
	v_mfma_f32_16x16x32_bf16 v[52:55], v[172:175], v[192:195], v[52:55]
	v_mfma_f32_16x16x32_bf16 v[48:51], v[180:183], v[192:195], v[48:51]
	v_mfma_f32_16x16x32_bf16 v[36:39], v[172:175], v[200:203], v[36:39]
	v_mfma_f32_16x16x32_bf16 v[32:35], v[180:183], v[200:203], v[32:35]
	v_mfma_f32_16x16x32_bf16 v[20:23], v[172:175], v[208:211], v[20:23]
	v_mfma_f32_16x16x32_bf16 v[16:19], v[180:183], v[208:211], v[16:19]
	v_mfma_f32_16x16x32_bf16 v[4:7], v[172:175], v[216:219], v[4:7]
	v_mfma_f32_16x16x32_bf16 v[0:3], v[180:183], v[216:219], v[0:3]
	s_setprio 0
	s_barrier
	s_add_i32 s77, s77, 2
	s_add_u32 s34, s34, 0x100
	s_addc_u32 s35, s35, 0
	s_add_u32 s75, s75, 0x100
	s_addc_u32 s76, s76, 0
	s_cmp_gt_u32 s77, 13
	s_cbranch_scc0 .LBB0_837
	s_branch .Lpeel_exit3
.LBB0_837:
	ds_read_b128 v[152:155], v149
	ds_read_b128 v[156:159], v149 offset:1024
	ds_read_b128 v[160:163], v149 offset:2048
	ds_read_b128 v[164:167], v149 offset:3072
	ds_read_b128 v[168:171], v150
	ds_read_b128 v[172:175], v150 offset:1024
	ds_read_b128 v[176:179], v150 offset:2048
	ds_read_b128 v[180:183], v150 offset:3072
	s_add_u32 s40, s34, 0xfffc0080
	s_addc_u32 s41, s35, -1
	s_cmp_eq_u32 s77, 12
	s_cselect_b32 s43, s25, s41
	s_cselect_b32 s42, s54, s40
	s_cselect_b32 s41, s23, s76
	s_cselect_b32 s40, s55, s75
	s_add_i32 m0, s31, 0xc000
	ds_read_b128 v[184:187], v151
	ds_read_b128 v[192:195], v151 offset:1024
	ds_read_b128 v[196:199], v151 offset:2048
	ds_read_b128 v[200:203], v151 offset:3072
	ds_read_b128 v[204:207], v151 offset:4096
	ds_read_b128 v[208:211], v151 offset:5120
	ds_read_b128 v[212:215], v151 offset:6144
	ds_read_b128 v[216:219], v151 offset:7168
	global_load_lds_dwordx4 v136, s[34:35]
	s_add_i32 m0, s31, 0xe000
	s_nop 0
	global_load_lds_dwordx4 v138, s[34:35]
	s_waitcnt vmcnt(8)
	s_waitcnt lgkmcnt(0)
	s_barrier
	s_setprio 1
	s_waitcnt lgkmcnt(0)
	v_mfma_f32_16x16x32_bf16 v[124:127], v[152:155], v[184:187], v[124:127]
	v_mfma_f32_16x16x32_bf16 v[120:123], v[160:163], v[184:187], v[120:123]
	v_mfma_f32_16x16x32_bf16 v[108:111], v[152:155], v[196:199], v[108:111]
	v_mfma_f32_16x16x32_bf16 v[104:107], v[160:163], v[196:199], v[104:107]
	v_mfma_f32_16x16x32_bf16 v[92:95], v[152:155], v[204:207], v[92:95]
	v_mfma_f32_16x16x32_bf16 v[88:91], v[160:163], v[204:207], v[88:91]
	v_mfma_f32_16x16x32_bf16 v[76:79], v[152:155], v[212:215], v[76:79]
	v_mfma_f32_16x16x32_bf16 v[72:75], v[160:163], v[212:215], v[72:75]
	v_mfma_f32_16x16x32_bf16 v[124:127], v[156:159], v[192:195], v[124:127]
	v_mfma_f32_16x16x32_bf16 v[120:123], v[164:167], v[192:195], v[120:123]
	v_mfma_f32_16x16x32_bf16 v[108:111], v[156:159], v[200:203], v[108:111]
	v_mfma_f32_16x16x32_bf16 v[104:107], v[164:167], v[200:203], v[104:107]
	v_mfma_f32_16x16x32_bf16 v[92:95], v[156:159], v[208:211], v[92:95]
	v_mfma_f32_16x16x32_bf16 v[88:91], v[164:167], v[208:211], v[88:91]
	v_mfma_f32_16x16x32_bf16 v[76:79], v[156:159], v[216:219], v[76:79]
	v_mfma_f32_16x16x32_bf16 v[72:75], v[164:167], v[216:219], v[72:75]
	s_setprio 0
	s_setprio 1
	v_mfma_f32_16x16x32_bf16 v[116:119], v[168:171], v[184:187], v[116:119]
	v_mfma_f32_16x16x32_bf16 v[112:115], v[176:179], v[184:187], v[112:115]
	v_mfma_f32_16x16x32_bf16 v[100:103], v[168:171], v[196:199], v[100:103]
	v_mfma_f32_16x16x32_bf16 v[96:99], v[176:179], v[196:199], v[96:99]
	v_mfma_f32_16x16x32_bf16 v[84:87], v[168:171], v[204:207], v[84:87]
	v_mfma_f32_16x16x32_bf16 v[80:83], v[176:179], v[204:207], v[80:83]
	v_mfma_f32_16x16x32_bf16 v[68:71], v[168:171], v[212:215], v[68:71]
	v_mfma_f32_16x16x32_bf16 v[64:67], v[176:179], v[212:215], v[64:67]
	v_mfma_f32_16x16x32_bf16 v[116:119], v[172:175], v[192:195], v[116:119]
	v_mfma_f32_16x16x32_bf16 v[112:115], v[180:183], v[192:195], v[112:115]
	v_mfma_f32_16x16x32_bf16 v[100:103], v[172:175], v[200:203], v[100:103]
	v_mfma_f32_16x16x32_bf16 v[96:99], v[180:183], v[200:203], v[96:99]
	v_mfma_f32_16x16x32_bf16 v[84:87], v[172:175], v[208:211], v[84:87]
	v_mfma_f32_16x16x32_bf16 v[80:83], v[180:183], v[208:211], v[80:83]
	v_mfma_f32_16x16x32_bf16 v[68:71], v[172:175], v[216:219], v[68:71]
	v_mfma_f32_16x16x32_bf16 v[64:67], v[180:183], v[216:219], v[64:67]
	s_setprio 0
	s_barrier
	s_add_i32 s79, s69, s63
	s_add_u32 s98, s40, 0x80
	s_addc_u32 s99, s41, 0
	s_mov_b32 m0, s79
	ds_read_b128 v[184:187], v151 offset:16384
	ds_read_b128 v[192:195], v151 offset:17408
	ds_read_b128 v[196:199], v151 offset:18432
	ds_read_b128 v[200:203], v151 offset:19456
	ds_read_b128 v[204:207], v151 offset:20480
	ds_read_b128 v[208:211], v151 offset:21504
	ds_read_b128 v[212:215], v151 offset:22528
	ds_read_b128 v[216:219], v151 offset:23552
	global_load_lds_dwordx4 v130, s[40:41]
	s_add_i32 m0, s79, 0x2000
	s_add_u32 s80, s40, 0x40000
	s_addc_u32 s81, s41, 0
	s_add_i32 s79, s70, s63
	global_load_lds_dwordx4 v134, s[40:41]
	s_mov_b32 m0, s79
	s_add_u32 s100, s42, 0x80
	s_addc_u32 s101, s43, 0
	global_load_lds_dwordx4 v130, s[80:81]
	s_add_i32 m0, s79, 0x2000
	s_nop 0
	global_load_lds_dwordx4 v134, s[80:81]
	s_mov_b32 m0, s31
	s_nop 0
	global_load_lds_dwordx4 v128, s[42:43]
	s_mov_b32 m0, s64
	s_nop 0
	global_load_lds_dwordx4 v132, s[42:43]
	s_waitcnt vmcnt(8)
	s_waitcnt lgkmcnt(0)
	s_barrier
	s_setprio 1
	s_waitcnt lgkmcnt(0)
	v_mfma_f32_16x16x32_bf16 v[60:63], v[152:155], v[184:187], v[60:63]
	v_mfma_f32_16x16x32_bf16 v[56:59], v[160:163], v[184:187], v[56:59]
	v_mfma_f32_16x16x32_bf16 v[44:47], v[152:155], v[196:199], v[44:47]
	v_mfma_f32_16x16x32_bf16 v[40:43], v[160:163], v[196:199], v[40:43]
	v_mfma_f32_16x16x32_bf16 v[28:31], v[152:155], v[204:207], v[28:31]
	v_mfma_f32_16x16x32_bf16 v[24:27], v[160:163], v[204:207], v[24:27]
	v_mfma_f32_16x16x32_bf16 v[12:15], v[152:155], v[212:215], v[12:15]
	v_mfma_f32_16x16x32_bf16 v[8:11], v[160:163], v[212:215], v[8:11]
	v_mfma_f32_16x16x32_bf16 v[60:63], v[156:159], v[192:195], v[60:63]
	v_mfma_f32_16x16x32_bf16 v[56:59], v[164:167], v[192:195], v[56:59]
	v_mfma_f32_16x16x32_bf16 v[44:47], v[156:159], v[200:203], v[44:47]
	v_mfma_f32_16x16x32_bf16 v[40:43], v[164:167], v[200:203], v[40:43]
	v_mfma_f32_16x16x32_bf16 v[28:31], v[156:159], v[208:211], v[28:31]
	v_mfma_f32_16x16x32_bf16 v[24:27], v[164:167], v[208:211], v[24:27]
	v_mfma_f32_16x16x32_bf16 v[12:15], v[156:159], v[216:219], v[12:15]
	v_mfma_f32_16x16x32_bf16 v[8:11], v[164:167], v[216:219], v[8:11]
	s_setprio 0
	s_setprio 1
	v_mfma_f32_16x16x32_bf16 v[52:55], v[168:171], v[184:187], v[52:55]
	v_mfma_f32_16x16x32_bf16 v[48:51], v[176:179], v[184:187], v[48:51]
	v_mfma_f32_16x16x32_bf16 v[36:39], v[168:171], v[196:199], v[36:39]
	v_mfma_f32_16x16x32_bf16 v[32:35], v[176:179], v[196:199], v[32:35]
	v_mfma_f32_16x16x32_bf16 v[20:23], v[168:171], v[204:207], v[20:23]
	v_mfma_f32_16x16x32_bf16 v[16:19], v[176:179], v[204:207], v[16:19]
	v_mfma_f32_16x16x32_bf16 v[4:7], v[168:171], v[212:215], v[4:7]
	v_mfma_f32_16x16x32_bf16 v[0:3], v[176:179], v[212:215], v[0:3]
	v_mfma_f32_16x16x32_bf16 v[52:55], v[172:175], v[192:195], v[52:55]
	v_mfma_f32_16x16x32_bf16 v[48:51], v[180:183], v[192:195], v[48:51]
	v_mfma_f32_16x16x32_bf16 v[36:39], v[172:175], v[200:203], v[36:39]
	v_mfma_f32_16x16x32_bf16 v[32:35], v[180:183], v[200:203], v[32:35]
	v_mfma_f32_16x16x32_bf16 v[20:23], v[172:175], v[208:211], v[20:23]
	v_mfma_f32_16x16x32_bf16 v[16:19], v[180:183], v[208:211], v[16:19]
	v_mfma_f32_16x16x32_bf16 v[4:7], v[172:175], v[216:219], v[4:7]
	v_mfma_f32_16x16x32_bf16 v[0:3], v[180:183], v[216:219], v[0:3]
	s_setprio 0
	s_barrier
	s_add_i32 s79, 0, 0x18000
	s_add_i32 s80, 0, 0x1c000
	v_add_u32_e32 v164, s79, v147
	v_add_u32_e32 v180, s80, v147
	ds_read_b128 v[152:155], v164
	ds_read_b128 v[156:159], v164 offset:1024
	ds_read_b128 v[160:163], v164 offset:2048
	ds_read_b128 v[164:167], v164 offset:3072
	ds_read_b128 v[168:171], v180
	ds_read_b128 v[172:175], v180 offset:1024
	ds_read_b128 v[176:179], v180 offset:2048
	ds_read_b128 v[180:183], v180 offset:3072
	s_add_u32 s42, s42, 0x40000
	s_addc_u32 s43, s43, 0
	s_mov_b32 m0, s65
	ds_read_b128 v[184:187], v151 offset:32768
	ds_read_b128 v[192:195], v151 offset:33792
	ds_read_b128 v[196:199], v151 offset:34816
	ds_read_b128 v[200:203], v151 offset:35840
	ds_read_b128 v[204:207], v151 offset:36864
	ds_read_b128 v[208:211], v151 offset:37888
	ds_read_b128 v[212:215], v151 offset:38912
	ds_read_b128 v[216:219], v151 offset:39936
	global_load_lds_dwordx4 v128, s[42:43]
	s_mov_b32 m0, s66
	s_nop 0
	global_load_lds_dwordx4 v132, s[42:43]
	s_waitcnt vmcnt(8)
	s_waitcnt lgkmcnt(0)
	s_barrier
	s_setprio 1
	s_waitcnt lgkmcnt(0)
	v_mfma_f32_16x16x32_bf16 v[124:127], v[152:155], v[184:187], v[124:127]
	v_mfma_f32_16x16x32_bf16 v[120:123], v[160:163], v[184:187], v[120:123]
	v_mfma_f32_16x16x32_bf16 v[108:111], v[152:155], v[196:199], v[108:111]
	v_mfma_f32_16x16x32_bf16 v[104:107], v[160:163], v[196:199], v[104:107]
	v_mfma_f32_16x16x32_bf16 v[92:95], v[152:155], v[204:207], v[92:95]
	v_mfma_f32_16x16x32_bf16 v[88:91], v[160:163], v[204:207], v[88:91]
	v_mfma_f32_16x16x32_bf16 v[76:79], v[152:155], v[212:215], v[76:79]
	v_mfma_f32_16x16x32_bf16 v[72:75], v[160:163], v[212:215], v[72:75]
	v_mfma_f32_16x16x32_bf16 v[124:127], v[156:159], v[192:195], v[124:127]
	v_mfma_f32_16x16x32_bf16 v[120:123], v[164:167], v[192:195], v[120:123]
	v_mfma_f32_16x16x32_bf16 v[108:111], v[156:159], v[200:203], v[108:111]
	v_mfma_f32_16x16x32_bf16 v[104:107], v[164:167], v[200:203], v[104:107]
	v_mfma_f32_16x16x32_bf16 v[92:95], v[156:159], v[208:211], v[92:95]
	v_mfma_f32_16x16x32_bf16 v[88:91], v[164:167], v[208:211], v[88:91]
	v_mfma_f32_16x16x32_bf16 v[76:79], v[156:159], v[216:219], v[76:79]
	v_mfma_f32_16x16x32_bf16 v[72:75], v[164:167], v[216:219], v[72:75]
	s_setprio 0
	s_setprio 1
	v_mfma_f32_16x16x32_bf16 v[116:119], v[168:171], v[184:187], v[116:119]
	v_mfma_f32_16x16x32_bf16 v[112:115], v[176:179], v[184:187], v[112:115]
	v_mfma_f32_16x16x32_bf16 v[100:103], v[168:171], v[196:199], v[100:103]
	v_mfma_f32_16x16x32_bf16 v[96:99], v[176:179], v[196:199], v[96:99]
	v_mfma_f32_16x16x32_bf16 v[84:87], v[168:171], v[204:207], v[84:87]
	v_mfma_f32_16x16x32_bf16 v[80:83], v[176:179], v[204:207], v[80:83]
	v_mfma_f32_16x16x32_bf16 v[68:71], v[168:171], v[212:215], v[68:71]
	v_mfma_f32_16x16x32_bf16 v[64:67], v[176:179], v[212:215], v[64:67]
	v_mfma_f32_16x16x32_bf16 v[116:119], v[172:175], v[192:195], v[116:119]
	v_mfma_f32_16x16x32_bf16 v[112:115], v[180:183], v[192:195], v[112:115]
	v_mfma_f32_16x16x32_bf16 v[100:103], v[172:175], v[200:203], v[100:103]
	v_mfma_f32_16x16x32_bf16 v[96:99], v[180:183], v[200:203], v[96:99]
	v_mfma_f32_16x16x32_bf16 v[84:87], v[172:175], v[208:211], v[84:87]
	v_mfma_f32_16x16x32_bf16 v[80:83], v[180:183], v[208:211], v[80:83]
	v_mfma_f32_16x16x32_bf16 v[68:71], v[172:175], v[216:219], v[68:71]
	v_mfma_f32_16x16x32_bf16 v[64:67], v[180:183], v[216:219], v[64:67]
	s_setprio 0
	s_barrier
	s_add_i32 s42, s79, s63
	s_mov_b32 m0, s42
	ds_read_b128 v[184:187], v151 offset:49152
	ds_read_b128 v[192:195], v151 offset:50176
	ds_read_b128 v[196:199], v151 offset:51200
	ds_read_b128 v[200:203], v151 offset:52224
	ds_read_b128 v[204:207], v151 offset:53248
	ds_read_b128 v[208:211], v151 offset:54272
	ds_read_b128 v[212:215], v151 offset:55296
	ds_read_b128 v[216:219], v151 offset:56320
	global_load_lds_dwordx4 v130, s[98:99]
	s_add_i32 m0, s42, 0x2000
	s_add_u32 s40, s40, 0x40080
	s_addc_u32 s41, s41, 0
	s_add_i32 s42, s80, s63
	global_load_lds_dwordx4 v134, s[98:99]
	s_mov_b32 m0, s42
	s_nop 0
	global_load_lds_dwordx4 v130, s[40:41]
	s_add_i32 m0, s42, 0x2000
	s_nop 0
	global_load_lds_dwordx4 v134, s[40:41]
	s_mov_b32 m0, s52
	s_nop 0
	global_load_lds_dwordx4 v128, s[100:101]
	s_mov_b32 m0, s53
	s_nop 0
	global_load_lds_dwordx4 v132, s[100:101]
	s_waitcnt vmcnt(8)
	s_waitcnt lgkmcnt(0)
	s_barrier
	s_setprio 1
	s_waitcnt lgkmcnt(0)
	v_mfma_f32_16x16x32_bf16 v[60:63], v[152:155], v[184:187], v[60:63]
	v_mfma_f32_16x16x32_bf16 v[56:59], v[160:163], v[184:187], v[56:59]
	v_mfma_f32_16x16x32_bf16 v[44:47], v[152:155], v[196:199], v[44:47]
	v_mfma_f32_16x16x32_bf16 v[40:43], v[160:163], v[196:199], v[40:43]
	v_mfma_f32_16x16x32_bf16 v[28:31], v[152:155], v[204:207], v[28:31]
	v_mfma_f32_16x16x32_bf16 v[24:27], v[160:163], v[204:207], v[24:27]
	v_mfma_f32_16x16x32_bf16 v[12:15], v[152:155], v[212:215], v[12:15]
	v_mfma_f32_16x16x32_bf16 v[8:11], v[160:163], v[212:215], v[8:11]
	v_mfma_f32_16x16x32_bf16 v[60:63], v[156:159], v[192:195], v[60:63]
	v_mfma_f32_16x16x32_bf16 v[56:59], v[164:167], v[192:195], v[56:59]
	v_mfma_f32_16x16x32_bf16 v[44:47], v[156:159], v[200:203], v[44:47]
	v_mfma_f32_16x16x32_bf16 v[40:43], v[164:167], v[200:203], v[40:43]
	v_mfma_f32_16x16x32_bf16 v[28:31], v[156:159], v[208:211], v[28:31]
	v_mfma_f32_16x16x32_bf16 v[24:27], v[164:167], v[208:211], v[24:27]
	v_mfma_f32_16x16x32_bf16 v[12:15], v[156:159], v[216:219], v[12:15]
	v_mfma_f32_16x16x32_bf16 v[8:11], v[164:167], v[216:219], v[8:11]
	s_setprio 0
	s_setprio 1
	v_mfma_f32_16x16x32_bf16 v[52:55], v[168:171], v[184:187], v[52:55]
	v_mfma_f32_16x16x32_bf16 v[48:51], v[176:179], v[184:187], v[48:51]
	v_mfma_f32_16x16x32_bf16 v[36:39], v[168:171], v[196:199], v[36:39]
	v_mfma_f32_16x16x32_bf16 v[32:35], v[176:179], v[196:199], v[32:35]
	v_mfma_f32_16x16x32_bf16 v[20:23], v[168:171], v[204:207], v[20:23]
	v_mfma_f32_16x16x32_bf16 v[16:19], v[176:179], v[204:207], v[16:19]
	v_mfma_f32_16x16x32_bf16 v[4:7], v[168:171], v[212:215], v[4:7]
	v_mfma_f32_16x16x32_bf16 v[0:3], v[176:179], v[212:215], v[0:3]
	v_mfma_f32_16x16x32_bf16 v[52:55], v[172:175], v[192:195], v[52:55]
	v_mfma_f32_16x16x32_bf16 v[48:51], v[180:183], v[192:195], v[48:51]
	v_mfma_f32_16x16x32_bf16 v[36:39], v[172:175], v[200:203], v[36:39]
	v_mfma_f32_16x16x32_bf16 v[32:35], v[180:183], v[200:203], v[32:35]
	v_mfma_f32_16x16x32_bf16 v[20:23], v[172:175], v[208:211], v[20:23]
	v_mfma_f32_16x16x32_bf16 v[16:19], v[180:183], v[208:211], v[16:19]
	v_mfma_f32_16x16x32_bf16 v[4:7], v[172:175], v[216:219], v[4:7]
	v_mfma_f32_16x16x32_bf16 v[0:3], v[180:183], v[216:219], v[0:3]
	s_setprio 0
	s_barrier
	s_add_i32 s77, s77, 2
	s_add_u32 s34, s34, 0x100
	s_addc_u32 s35, s35, 0
	s_add_u32 s75, s75, 0x100
	s_addc_u32 s76, s76, 0
	s_cmp_gt_u32 s77, 13
	s_cbranch_scc0 .LBB0_837

.LBB0_915:
	s_ashr_i32 s25, s24, 31
	s_lshl_b64 s[26:27], s[24:25], 21
	s_add_u32 s26, s56, s26
	s_addc_u32 s27, s57, s27
	s_and_b64 s[28:29], s[4:5], exec
	s_cselect_b32 s25, s27, s35
	s_cselect_b32 s55, s26, s34
	s_ashr_i32 s23, s22, 31
	s_lshl_b64 s[28:29], s[22:23], 21
	s_add_u32 s28, s53, s28
	s_addc_u32 s29, s60, s29
	s_and_b64 s[42:43], s[4:5], exec
	s_cselect_b32 s23, s29, s41
	s_cselect_b32 s74, s28, s40
	s_add_u32 s34, s34, 0x100080
	s_addc_u32 s35, s35, 0
	s_add_u32 s75, s40, 0x100
	s_addc_u32 s76, s41, 0
	s_mov_b32 s77, -2
	ds_read_b128 v[152:155], v149
	ds_read_b128 v[156:159], v149 offset:1024
	ds_read_b128 v[160:163], v149 offset:2048
	ds_read_b128 v[164:167], v149 offset:3072
	ds_read_b128 v[168:171], v150
	ds_read_b128 v[172:175], v150 offset:1024
	ds_read_b128 v[176:179], v150 offset:2048
	ds_read_b128 v[180:183], v150 offset:3072
	s_add_u32 s40, s34, 0xfff00080
	s_addc_u32 s41, s35, -1
	s_cmp_eq_u32 s77, 60
	s_cselect_b32 s43, s25, s41
	s_cselect_b32 s42, s55, s40
	s_cselect_b32 s41, s23, s76
	s_cselect_b32 s40, s74, s75
	s_add_i32 m0, s31, 0xc000
	ds_read_b128 v[184:187], v151
	ds_read_b128 v[192:195], v151 offset:1024
	ds_read_b128 v[196:199], v151 offset:2048
	ds_read_b128 v[200:203], v151 offset:3072
	ds_read_b128 v[204:207], v151 offset:4096
	ds_read_b128 v[208:211], v151 offset:5120
	ds_read_b128 v[212:215], v151 offset:6144
	ds_read_b128 v[216:219], v151 offset:7168
	global_load_lds_dwordx4 v136, s[34:35]
	s_add_i32 m0, s31, 0xe000
	s_nop 0
	global_load_lds_dwordx4 v138, s[34:35]
	s_waitcnt vmcnt(8)
	s_waitcnt lgkmcnt(0)
	s_barrier
	s_setprio 1
	s_waitcnt lgkmcnt(0)
	v_mfma_f32_16x16x32_bf16 v[124:127], v[152:155], v[184:187], 0
	v_mfma_f32_16x16x32_bf16 v[120:123], v[160:163], v[184:187], 0
	v_mfma_f32_16x16x32_bf16 v[116:119], v[152:155], v[196:199], 0
	v_mfma_f32_16x16x32_bf16 v[108:111], v[160:163], v[196:199], 0
	v_mfma_f32_16x16x32_bf16 v[100:103], v[152:155], v[204:207], 0
	v_mfma_f32_16x16x32_bf16 v[92:95], v[160:163], v[204:207], 0
	v_mfma_f32_16x16x32_bf16 v[84:87], v[152:155], v[212:215], 0
	v_mfma_f32_16x16x32_bf16 v[76:79], v[160:163], v[212:215], 0
	v_mfma_f32_16x16x32_bf16 v[124:127], v[156:159], v[192:195], v[124:127]
	v_mfma_f32_16x16x32_bf16 v[120:123], v[164:167], v[192:195], v[120:123]
	v_mfma_f32_16x16x32_bf16 v[116:119], v[156:159], v[200:203], v[116:119]
	v_mfma_f32_16x16x32_bf16 v[108:111], v[164:167], v[200:203], v[108:111]
	v_mfma_f32_16x16x32_bf16 v[100:103], v[156:159], v[208:211], v[100:103]
	v_mfma_f32_16x16x32_bf16 v[92:95], v[164:167], v[208:211], v[92:95]
	v_mfma_f32_16x16x32_bf16 v[84:87], v[156:159], v[216:219], v[84:87]
	v_mfma_f32_16x16x32_bf16 v[76:79], v[164:167], v[216:219], v[76:79]
	s_setprio 0
	s_setprio 1
	v_mfma_f32_16x16x32_bf16 v[112:115], v[168:171], v[184:187], 0
	v_mfma_f32_16x16x32_bf16 v[104:107], v[176:179], v[184:187], 0
	v_mfma_f32_16x16x32_bf16 v[96:99], v[168:171], v[196:199], 0
	v_mfma_f32_16x16x32_bf16 v[88:91], v[176:179], v[196:199], 0
	v_mfma_f32_16x16x32_bf16 v[80:83], v[168:171], v[204:207], 0
	v_mfma_f32_16x16x32_bf16 v[72:75], v[176:179], v[204:207], 0
	v_mfma_f32_16x16x32_bf16 v[68:71], v[168:171], v[212:215], 0
	v_mfma_f32_16x16x32_bf16 v[64:67], v[176:179], v[212:215], 0
	v_mfma_f32_16x16x32_bf16 v[112:115], v[172:175], v[192:195], v[112:115]
	v_mfma_f32_16x16x32_bf16 v[104:107], v[180:183], v[192:195], v[104:107]
	v_mfma_f32_16x16x32_bf16 v[96:99], v[172:175], v[200:203], v[96:99]
	v_mfma_f32_16x16x32_bf16 v[88:91], v[180:183], v[200:203], v[88:91]
	v_mfma_f32_16x16x32_bf16 v[80:83], v[172:175], v[208:211], v[80:83]
	v_mfma_f32_16x16x32_bf16 v[72:75], v[180:183], v[208:211], v[72:75]
	v_mfma_f32_16x16x32_bf16 v[68:71], v[172:175], v[216:219], v[68:71]
	v_mfma_f32_16x16x32_bf16 v[64:67], v[180:183], v[216:219], v[64:67]
	s_setprio 0
	s_barrier
	s_add_i32 s79, s68, s61
	s_add_u32 s98, s40, 0x80
	s_addc_u32 s99, s41, 0
	s_mov_b32 m0, s79
	ds_read_b128 v[184:187], v151 offset:16384
	ds_read_b128 v[192:195], v151 offset:17408
	ds_read_b128 v[196:199], v151 offset:18432
	ds_read_b128 v[200:203], v151 offset:19456
	ds_read_b128 v[204:207], v151 offset:20480
	ds_read_b128 v[208:211], v151 offset:21504
	ds_read_b128 v[212:215], v151 offset:22528
	ds_read_b128 v[216:219], v151 offset:23552
	global_load_lds_dwordx4 v130, s[40:41]
	s_add_i32 m0, s79, 0x2000
	s_add_u32 s80, s40, 0x100000
	s_addc_u32 s81, s41, 0
	s_add_i32 s79, s69, s61
	global_load_lds_dwordx4 v134, s[40:41]
	s_mov_b32 m0, s79
	s_add_u32 s100, s42, 0x80
	s_addc_u32 s101, s43, 0
	global_load_lds_dwordx4 v130, s[80:81]
	s_add_i32 m0, s79, 0x2000
	s_nop 0
	global_load_lds_dwordx4 v134, s[80:81]
	s_mov_b32 m0, s31
	s_nop 0
	global_load_lds_dwordx4 v128, s[42:43]
	s_mov_b32 m0, s33
	s_nop 0
	global_load_lds_dwordx4 v132, s[42:43]
	s_waitcnt vmcnt(8)
	s_waitcnt lgkmcnt(0)
	s_barrier
	s_setprio 1
	s_waitcnt lgkmcnt(0)
	v_mfma_f32_16x16x32_bf16 v[60:63], v[152:155], v[184:187], 0
	v_mfma_f32_16x16x32_bf16 v[56:59], v[160:163], v[184:187], 0
	v_mfma_f32_16x16x32_bf16 v[52:55], v[152:155], v[196:199], 0
	v_mfma_f32_16x16x32_bf16 v[44:47], v[160:163], v[196:199], 0
	v_mfma_f32_16x16x32_bf16 v[36:39], v[152:155], v[204:207], 0
	v_mfma_f32_16x16x32_bf16 v[28:31], v[160:163], v[204:207], 0
	v_mfma_f32_16x16x32_bf16 v[20:23], v[152:155], v[212:215], 0
	v_mfma_f32_16x16x32_bf16 v[12:15], v[160:163], v[212:215], 0
	v_mfma_f32_16x16x32_bf16 v[60:63], v[156:159], v[192:195], v[60:63]
	v_mfma_f32_16x16x32_bf16 v[56:59], v[164:167], v[192:195], v[56:59]
	v_mfma_f32_16x16x32_bf16 v[52:55], v[156:159], v[200:203], v[52:55]
	v_mfma_f32_16x16x32_bf16 v[44:47], v[164:167], v[200:203], v[44:47]
	v_mfma_f32_16x16x32_bf16 v[36:39], v[156:159], v[208:211], v[36:39]
	v_mfma_f32_16x16x32_bf16 v[28:31], v[164:167], v[208:211], v[28:31]
	v_mfma_f32_16x16x32_bf16 v[20:23], v[156:159], v[216:219], v[20:23]
	v_mfma_f32_16x16x32_bf16 v[12:15], v[164:167], v[216:219], v[12:15]
	s_setprio 0
	s_setprio 1
	v_mfma_f32_16x16x32_bf16 v[48:51], v[168:171], v[184:187], 0
	v_mfma_f32_16x16x32_bf16 v[40:43], v[176:179], v[184:187], 0
	v_mfma_f32_16x16x32_bf16 v[32:35], v[168:171], v[196:199], 0
	v_mfma_f32_16x16x32_bf16 v[24:27], v[176:179], v[196:199], 0
	v_mfma_f32_16x16x32_bf16 v[16:19], v[168:171], v[204:207], 0
	v_mfma_f32_16x16x32_bf16 v[8:11], v[176:179], v[204:207], 0
	v_mfma_f32_16x16x32_bf16 v[4:7], v[168:171], v[212:215], 0
	v_mfma_f32_16x16x32_bf16 v[0:3], v[176:179], v[212:215], 0
	v_mfma_f32_16x16x32_bf16 v[48:51], v[172:175], v[192:195], v[48:51]
	v_mfma_f32_16x16x32_bf16 v[40:43], v[180:183], v[192:195], v[40:43]
	v_mfma_f32_16x16x32_bf16 v[32:35], v[172:175], v[200:203], v[32:35]
	v_mfma_f32_16x16x32_bf16 v[24:27], v[180:183], v[200:203], v[24:27]
	v_mfma_f32_16x16x32_bf16 v[16:19], v[172:175], v[208:211], v[16:19]
	v_mfma_f32_16x16x32_bf16 v[8:11], v[180:183], v[208:211], v[8:11]
	v_mfma_f32_16x16x32_bf16 v[4:7], v[172:175], v[216:219], v[4:7]
	v_mfma_f32_16x16x32_bf16 v[0:3], v[180:183], v[216:219], v[0:3]
	s_setprio 0
	s_barrier
	s_add_i32 s79, 0, 0x18000
	s_add_i32 s80, 0, 0x1c000
	v_add_u32_e32 v164, s79, v147
	v_add_u32_e32 v180, s80, v147
	ds_read_b128 v[152:155], v164
	ds_read_b128 v[156:159], v164 offset:1024
	ds_read_b128 v[160:163], v164 offset:2048
	ds_read_b128 v[164:167], v164 offset:3072
	ds_read_b128 v[168:171], v180
	ds_read_b128 v[172:175], v180 offset:1024
	ds_read_b128 v[176:179], v180 offset:2048
	ds_read_b128 v[180:183], v180 offset:3072
	s_add_u32 s42, s42, 0x100000
	s_addc_u32 s43, s43, 0
	s_mov_b32 m0, s62
	ds_read_b128 v[184:187], v151 offset:32768
	ds_read_b128 v[192:195], v151 offset:33792
	ds_read_b128 v[196:199], v151 offset:34816
	ds_read_b128 v[200:203], v151 offset:35840
	ds_read_b128 v[204:207], v151 offset:36864
	ds_read_b128 v[208:211], v151 offset:37888
	ds_read_b128 v[212:215], v151 offset:38912
	ds_read_b128 v[216:219], v151 offset:39936
	global_load_lds_dwordx4 v128, s[42:43]
	s_mov_b32 m0, s63
	s_nop 0
	global_load_lds_dwordx4 v132, s[42:43]
	s_waitcnt vmcnt(8)
	s_waitcnt lgkmcnt(0)
	s_barrier
	s_setprio 1
	s_waitcnt lgkmcnt(0)
	v_mfma_f32_16x16x32_bf16 v[124:127], v[152:155], v[184:187], v[124:127]
	v_mfma_f32_16x16x32_bf16 v[120:123], v[160:163], v[184:187], v[120:123]
	v_mfma_f32_16x16x32_bf16 v[116:119], v[152:155], v[196:199], v[116:119]
	v_mfma_f32_16x16x32_bf16 v[108:111], v[160:163], v[196:199], v[108:111]
	v_mfma_f32_16x16x32_bf16 v[100:103], v[152:155], v[204:207], v[100:103]
	v_mfma_f32_16x16x32_bf16 v[92:95], v[160:163], v[204:207], v[92:95]
	v_mfma_f32_16x16x32_bf16 v[84:87], v[152:155], v[212:215], v[84:87]
	v_mfma_f32_16x16x32_bf16 v[76:79], v[160:163], v[212:215], v[76:79]
	v_mfma_f32_16x16x32_bf16 v[124:127], v[156:159], v[192:195], v[124:127]
	v_mfma_f32_16x16x32_bf16 v[120:123], v[164:167], v[192:195], v[120:123]
	v_mfma_f32_16x16x32_bf16 v[116:119], v[156:159], v[200:203], v[116:119]
	v_mfma_f32_16x16x32_bf16 v[108:111], v[164:167], v[200:203], v[108:111]
	v_mfma_f32_16x16x32_bf16 v[100:103], v[156:159], v[208:211], v[100:103]
	v_mfma_f32_16x16x32_bf16 v[92:95], v[164:167], v[208:211], v[92:95]
	v_mfma_f32_16x16x32_bf16 v[84:87], v[156:159], v[216:219], v[84:87]
	v_mfma_f32_16x16x32_bf16 v[76:79], v[164:167], v[216:219], v[76:79]
	s_setprio 0
	s_setprio 1
	v_mfma_f32_16x16x32_bf16 v[112:115], v[168:171], v[184:187], v[112:115]
	v_mfma_f32_16x16x32_bf16 v[104:107], v[176:179], v[184:187], v[104:107]
	v_mfma_f32_16x16x32_bf16 v[96:99], v[168:171], v[196:199], v[96:99]
	v_mfma_f32_16x16x32_bf16 v[88:91], v[176:179], v[196:199], v[88:91]
	v_mfma_f32_16x16x32_bf16 v[80:83], v[168:171], v[204:207], v[80:83]
	v_mfma_f32_16x16x32_bf16 v[72:75], v[176:179], v[204:207], v[72:75]
	v_mfma_f32_16x16x32_bf16 v[68:71], v[168:171], v[212:215], v[68:71]
	v_mfma_f32_16x16x32_bf16 v[64:67], v[176:179], v[212:215], v[64:67]
	v_mfma_f32_16x16x32_bf16 v[112:115], v[172:175], v[192:195], v[112:115]
	v_mfma_f32_16x16x32_bf16 v[104:107], v[180:183], v[192:195], v[104:107]
	v_mfma_f32_16x16x32_bf16 v[96:99], v[172:175], v[200:203], v[96:99]
	v_mfma_f32_16x16x32_bf16 v[88:91], v[180:183], v[200:203], v[88:91]
	v_mfma_f32_16x16x32_bf16 v[80:83], v[172:175], v[208:211], v[80:83]
	v_mfma_f32_16x16x32_bf16 v[72:75], v[180:183], v[208:211], v[72:75]
	v_mfma_f32_16x16x32_bf16 v[68:71], v[172:175], v[216:219], v[68:71]
	v_mfma_f32_16x16x32_bf16 v[64:67], v[180:183], v[216:219], v[64:67]
	s_setprio 0
	s_barrier
	s_add_i32 s42, s79, s61
	s_mov_b32 m0, s42
	ds_read_b128 v[184:187], v151 offset:49152
	ds_read_b128 v[192:195], v151 offset:50176
	ds_read_b128 v[196:199], v151 offset:51200
	ds_read_b128 v[200:203], v151 offset:52224
	ds_read_b128 v[204:207], v151 offset:53248
	ds_read_b128 v[208:211], v151 offset:54272
	ds_read_b128 v[212:215], v151 offset:55296
	ds_read_b128 v[216:219], v151 offset:56320
	global_load_lds_dwordx4 v130, s[98:99]
	s_add_i32 m0, s42, 0x2000
	s_add_u32 s40, s40, 0x100080
	s_addc_u32 s41, s41, 0
	s_add_i32 s42, s80, s61
	global_load_lds_dwordx4 v134, s[98:99]
	s_mov_b32 m0, s42
	s_nop 0
	global_load_lds_dwordx4 v130, s[40:41]
	s_add_i32 m0, s42, 0x2000
	s_nop 0
	global_load_lds_dwordx4 v134, s[40:41]
	s_mov_b32 m0, s65
	s_nop 0
	global_load_lds_dwordx4 v128, s[100:101]
	s_mov_b32 m0, s66
	s_nop 0
	global_load_lds_dwordx4 v132, s[100:101]
	s_waitcnt vmcnt(8)
	s_waitcnt lgkmcnt(0)
	s_barrier
	s_setprio 1
	s_waitcnt lgkmcnt(0)
	v_mfma_f32_16x16x32_bf16 v[60:63], v[152:155], v[184:187], v[60:63]
	v_mfma_f32_16x16x32_bf16 v[56:59], v[160:163], v[184:187], v[56:59]
	v_mfma_f32_16x16x32_bf16 v[52:55], v[152:155], v[196:199], v[52:55]
	v_mfma_f32_16x16x32_bf16 v[44:47], v[160:163], v[196:199], v[44:47]
	v_mfma_f32_16x16x32_bf16 v[36:39], v[152:155], v[204:207], v[36:39]
	v_mfma_f32_16x16x32_bf16 v[28:31], v[160:163], v[204:207], v[28:31]
	v_mfma_f32_16x16x32_bf16 v[20:23], v[152:155], v[212:215], v[20:23]
	v_mfma_f32_16x16x32_bf16 v[12:15], v[160:163], v[212:215], v[12:15]
	v_mfma_f32_16x16x32_bf16 v[60:63], v[156:159], v[192:195], v[60:63]
	v_mfma_f32_16x16x32_bf16 v[56:59], v[164:167], v[192:195], v[56:59]
	v_mfma_f32_16x16x32_bf16 v[52:55], v[156:159], v[200:203], v[52:55]
	v_mfma_f32_16x16x32_bf16 v[44:47], v[164:167], v[200:203], v[44:47]
	v_mfma_f32_16x16x32_bf16 v[36:39], v[156:159], v[208:211], v[36:39]
	v_mfma_f32_16x16x32_bf16 v[28:31], v[164:167], v[208:211], v[28:31]
	v_mfma_f32_16x16x32_bf16 v[20:23], v[156:159], v[216:219], v[20:23]
	v_mfma_f32_16x16x32_bf16 v[12:15], v[164:167], v[216:219], v[12:15]
	s_setprio 0
	s_setprio 1
	v_mfma_f32_16x16x32_bf16 v[48:51], v[168:171], v[184:187], v[48:51]
	v_mfma_f32_16x16x32_bf16 v[40:43], v[176:179], v[184:187], v[40:43]
	v_mfma_f32_16x16x32_bf16 v[32:35], v[168:171], v[196:199], v[32:35]
	v_mfma_f32_16x16x32_bf16 v[24:27], v[176:179], v[196:199], v[24:27]
	v_mfma_f32_16x16x32_bf16 v[16:19], v[168:171], v[204:207], v[16:19]
	v_mfma_f32_16x16x32_bf16 v[8:11], v[176:179], v[204:207], v[8:11]
	v_mfma_f32_16x16x32_bf16 v[4:7], v[168:171], v[212:215], v[4:7]
	v_mfma_f32_16x16x32_bf16 v[0:3], v[176:179], v[212:215], v[0:3]
	v_mfma_f32_16x16x32_bf16 v[48:51], v[172:175], v[192:195], v[48:51]
	v_mfma_f32_16x16x32_bf16 v[40:43], v[180:183], v[192:195], v[40:43]
	v_mfma_f32_16x16x32_bf16 v[32:35], v[172:175], v[200:203], v[32:35]
	v_mfma_f32_16x16x32_bf16 v[24:27], v[180:183], v[200:203], v[24:27]
	v_mfma_f32_16x16x32_bf16 v[16:19], v[172:175], v[208:211], v[16:19]
	v_mfma_f32_16x16x32_bf16 v[8:11], v[180:183], v[208:211], v[8:11]
	v_mfma_f32_16x16x32_bf16 v[4:7], v[172:175], v[216:219], v[4:7]
	v_mfma_f32_16x16x32_bf16 v[0:3], v[180:183], v[216:219], v[0:3]
	s_setprio 0
	s_barrier
	s_add_i32 s77, s77, 2
	s_add_u32 s34, s34, 0x100
	s_addc_u32 s35, s35, 0
	s_add_u32 s75, s75, 0x100
	s_addc_u32 s76, s76, 0
	s_cmp_gt_u32 s77, 61
	s_cbranch_scc0 .LBB0_916
	s_branch .Lpeel_exit4
.LBB0_916:
	ds_read_b128 v[152:155], v149
	ds_read_b128 v[156:159], v149 offset:1024
	ds_read_b128 v[160:163], v149 offset:2048
	ds_read_b128 v[164:167], v149 offset:3072
	ds_read_b128 v[168:171], v150
	ds_read_b128 v[172:175], v150 offset:1024
	ds_read_b128 v[176:179], v150 offset:2048
	ds_read_b128 v[180:183], v150 offset:3072
	s_add_u32 s40, s34, 0xfff00080
	s_addc_u32 s41, s35, -1
	s_cmp_eq_u32 s77, 60
	s_cselect_b32 s43, s25, s41
	s_cselect_b32 s42, s55, s40
	s_cselect_b32 s41, s23, s76
	s_cselect_b32 s40, s74, s75
	s_add_i32 m0, s31, 0xc000
	ds_read_b128 v[184:187], v151
	ds_read_b128 v[192:195], v151 offset:1024
	ds_read_b128 v[196:199], v151 offset:2048
	ds_read_b128 v[200:203], v151 offset:3072
	ds_read_b128 v[204:207], v151 offset:4096
	ds_read_b128 v[208:211], v151 offset:5120
	ds_read_b128 v[212:215], v151 offset:6144
	ds_read_b128 v[216:219], v151 offset:7168
	global_load_lds_dwordx4 v136, s[34:35]
	s_add_i32 m0, s31, 0xe000
	s_nop 0
	global_load_lds_dwordx4 v138, s[34:35]
	s_waitcnt vmcnt(8)
	s_waitcnt lgkmcnt(0)
	s_barrier
	s_setprio 1
	s_waitcnt lgkmcnt(0)
	v_mfma_f32_16x16x32_bf16 v[124:127], v[152:155], v[184:187], v[124:127]
	v_mfma_f32_16x16x32_bf16 v[120:123], v[160:163], v[184:187], v[120:123]
	v_mfma_f32_16x16x32_bf16 v[116:119], v[152:155], v[196:199], v[116:119]
	v_mfma_f32_16x16x32_bf16 v[108:111], v[160:163], v[196:199], v[108:111]
	v_mfma_f32_16x16x32_bf16 v[100:103], v[152:155], v[204:207], v[100:103]
	v_mfma_f32_16x16x32_bf16 v[92:95], v[160:163], v[204:207], v[92:95]
	v_mfma_f32_16x16x32_bf16 v[84:87], v[152:155], v[212:215], v[84:87]
	v_mfma_f32_16x16x32_bf16 v[76:79], v[160:163], v[212:215], v[76:79]
	v_mfma_f32_16x16x32_bf16 v[124:127], v[156:159], v[192:195], v[124:127]
	v_mfma_f32_16x16x32_bf16 v[120:123], v[164:167], v[192:195], v[120:123]
	v_mfma_f32_16x16x32_bf16 v[116:119], v[156:159], v[200:203], v[116:119]
	v_mfma_f32_16x16x32_bf16 v[108:111], v[164:167], v[200:203], v[108:111]
	v_mfma_f32_16x16x32_bf16 v[100:103], v[156:159], v[208:211], v[100:103]
	v_mfma_f32_16x16x32_bf16 v[92:95], v[164:167], v[208:211], v[92:95]
	v_mfma_f32_16x16x32_bf16 v[84:87], v[156:159], v[216:219], v[84:87]
	v_mfma_f32_16x16x32_bf16 v[76:79], v[164:167], v[216:219], v[76:79]
	s_setprio 0
	s_setprio 1
	v_mfma_f32_16x16x32_bf16 v[112:115], v[168:171], v[184:187], v[112:115]
	v_mfma_f32_16x16x32_bf16 v[104:107], v[176:179], v[184:187], v[104:107]
	v_mfma_f32_16x16x32_bf16 v[96:99], v[168:171], v[196:199], v[96:99]
	v_mfma_f32_16x16x32_bf16 v[88:91], v[176:179], v[196:199], v[88:91]
	v_mfma_f32_16x16x32_bf16 v[80:83], v[168:171], v[204:207], v[80:83]
	v_mfma_f32_16x16x32_bf16 v[72:75], v[176:179], v[204:207], v[72:75]
	v_mfma_f32_16x16x32_bf16 v[68:71], v[168:171], v[212:215], v[68:71]
	v_mfma_f32_16x16x32_bf16 v[64:67], v[176:179], v[212:215], v[64:67]
	v_mfma_f32_16x16x32_bf16 v[112:115], v[172:175], v[192:195], v[112:115]
	v_mfma_f32_16x16x32_bf16 v[104:107], v[180:183], v[192:195], v[104:107]
	v_mfma_f32_16x16x32_bf16 v[96:99], v[172:175], v[200:203], v[96:99]
	v_mfma_f32_16x16x32_bf16 v[88:91], v[180:183], v[200:203], v[88:91]
	v_mfma_f32_16x16x32_bf16 v[80:83], v[172:175], v[208:211], v[80:83]
	v_mfma_f32_16x16x32_bf16 v[72:75], v[180:183], v[208:211], v[72:75]
	v_mfma_f32_16x16x32_bf16 v[68:71], v[172:175], v[216:219], v[68:71]
	v_mfma_f32_16x16x32_bf16 v[64:67], v[180:183], v[216:219], v[64:67]
	s_setprio 0
	s_barrier
	s_add_i32 s79, s68, s61
	s_add_u32 s98, s40, 0x80
	s_addc_u32 s99, s41, 0
	s_mov_b32 m0, s79
	ds_read_b128 v[184:187], v151 offset:16384
	ds_read_b128 v[192:195], v151 offset:17408
	ds_read_b128 v[196:199], v151 offset:18432
	ds_read_b128 v[200:203], v151 offset:19456
	ds_read_b128 v[204:207], v151 offset:20480
	ds_read_b128 v[208:211], v151 offset:21504
	ds_read_b128 v[212:215], v151 offset:22528
	ds_read_b128 v[216:219], v151 offset:23552
	global_load_lds_dwordx4 v130, s[40:41]
	s_add_i32 m0, s79, 0x2000
	s_add_u32 s80, s40, 0x100000
	s_addc_u32 s81, s41, 0
	s_add_i32 s79, s69, s61
	global_load_lds_dwordx4 v134, s[40:41]
	s_mov_b32 m0, s79
	s_add_u32 s100, s42, 0x80
	s_addc_u32 s101, s43, 0
	global_load_lds_dwordx4 v130, s[80:81]
	s_add_i32 m0, s79, 0x2000
	s_nop 0
	global_load_lds_dwordx4 v134, s[80:81]
	s_mov_b32 m0, s31
	s_nop 0
	global_load_lds_dwordx4 v128, s[42:43]
	s_mov_b32 m0, s33
	s_nop 0
	global_load_lds_dwordx4 v132, s[42:43]
	s_waitcnt vmcnt(8)
	s_waitcnt lgkmcnt(0)
	s_barrier
	s_setprio 1
	s_waitcnt lgkmcnt(0)
	v_mfma_f32_16x16x32_bf16 v[60:63], v[152:155], v[184:187], v[60:63]
	v_mfma_f32_16x16x32_bf16 v[56:59], v[160:163], v[184:187], v[56:59]
	v_mfma_f32_16x16x32_bf16 v[52:55], v[152:155], v[196:199], v[52:55]
	v_mfma_f32_16x16x32_bf16 v[44:47], v[160:163], v[196:199], v[44:47]
	v_mfma_f32_16x16x32_bf16 v[36:39], v[152:155], v[204:207], v[36:39]
	v_mfma_f32_16x16x32_bf16 v[28:31], v[160:163], v[204:207], v[28:31]
	v_mfma_f32_16x16x32_bf16 v[20:23], v[152:155], v[212:215], v[20:23]
	v_mfma_f32_16x16x32_bf16 v[12:15], v[160:163], v[212:215], v[12:15]
	v_mfma_f32_16x16x32_bf16 v[60:63], v[156:159], v[192:195], v[60:63]
	v_mfma_f32_16x16x32_bf16 v[56:59], v[164:167], v[192:195], v[56:59]
	v_mfma_f32_16x16x32_bf16 v[52:55], v[156:159], v[200:203], v[52:55]
	v_mfma_f32_16x16x32_bf16 v[44:47], v[164:167], v[200:203], v[44:47]
	v_mfma_f32_16x16x32_bf16 v[36:39], v[156:159], v[208:211], v[36:39]
	v_mfma_f32_16x16x32_bf16 v[28:31], v[164:167], v[208:211], v[28:31]
	v_mfma_f32_16x16x32_bf16 v[20:23], v[156:159], v[216:219], v[20:23]
	v_mfma_f32_16x16x32_bf16 v[12:15], v[164:167], v[216:219], v[12:15]
	s_setprio 0
	s_setprio 1
	v_mfma_f32_16x16x32_bf16 v[48:51], v[168:171], v[184:187], v[48:51]
	v_mfma_f32_16x16x32_bf16 v[40:43], v[176:179], v[184:187], v[40:43]
	v_mfma_f32_16x16x32_bf16 v[32:35], v[168:171], v[196:199], v[32:35]
	v_mfma_f32_16x16x32_bf16 v[24:27], v[176:179], v[196:199], v[24:27]
	v_mfma_f32_16x16x32_bf16 v[16:19], v[168:171], v[204:207], v[16:19]
	v_mfma_f32_16x16x32_bf16 v[8:11], v[176:179], v[204:207], v[8:11]
	v_mfma_f32_16x16x32_bf16 v[4:7], v[168:171], v[212:215], v[4:7]
	v_mfma_f32_16x16x32_bf16 v[0:3], v[176:179], v[212:215], v[0:3]
	v_mfma_f32_16x16x32_bf16 v[48:51], v[172:175], v[192:195], v[48:51]
	v_mfma_f32_16x16x32_bf16 v[40:43], v[180:183], v[192:195], v[40:43]
	v_mfma_f32_16x16x32_bf16 v[32:35], v[172:175], v[200:203], v[32:35]
	v_mfma_f32_16x16x32_bf16 v[24:27], v[180:183], v[200:203], v[24:27]
	v_mfma_f32_16x16x32_bf16 v[16:19], v[172:175], v[208:211], v[16:19]
	v_mfma_f32_16x16x32_bf16 v[8:11], v[180:183], v[208:211], v[8:11]
	v_mfma_f32_16x16x32_bf16 v[4:7], v[172:175], v[216:219], v[4:7]
	v_mfma_f32_16x16x32_bf16 v[0:3], v[180:183], v[216:219], v[0:3]
	s_setprio 0
	s_barrier
	s_add_i32 s79, 0, 0x18000
	s_add_i32 s80, 0, 0x1c000
	v_add_u32_e32 v164, s79, v147
	v_add_u32_e32 v180, s80, v147
	ds_read_b128 v[152:155], v164
	ds_read_b128 v[156:159], v164 offset:1024
	ds_read_b128 v[160:163], v164 offset:2048
	ds_read_b128 v[164:167], v164 offset:3072
	ds_read_b128 v[168:171], v180
	ds_read_b128 v[172:175], v180 offset:1024
	ds_read_b128 v[176:179], v180 offset:2048
	ds_read_b128 v[180:183], v180 offset:3072
	s_add_u32 s42, s42, 0x100000
	s_addc_u32 s43, s43, 0
	s_mov_b32 m0, s62
	ds_read_b128 v[184:187], v151 offset:32768
	ds_read_b128 v[192:195], v151 offset:33792
	ds_read_b128 v[196:199], v151 offset:34816
	ds_read_b128 v[200:203], v151 offset:35840
	ds_read_b128 v[204:207], v151 offset:36864
	ds_read_b128 v[208:211], v151 offset:37888
	ds_read_b128 v[212:215], v151 offset:38912
	ds_read_b128 v[216:219], v151 offset:39936
	global_load_lds_dwordx4 v128, s[42:43]
	s_mov_b32 m0, s63
	s_nop 0
	global_load_lds_dwordx4 v132, s[42:43]
	s_waitcnt vmcnt(8)
	s_waitcnt lgkmcnt(0)
	s_barrier
	s_setprio 1
	s_waitcnt lgkmcnt(0)
	v_mfma_f32_16x16x32_bf16 v[124:127], v[152:155], v[184:187], v[124:127]
	v_mfma_f32_16x16x32_bf16 v[120:123], v[160:163], v[184:187], v[120:123]
	v_mfma_f32_16x16x32_bf16 v[116:119], v[152:155], v[196:199], v[116:119]
	v_mfma_f32_16x16x32_bf16 v[108:111], v[160:163], v[196:199], v[108:111]
	v_mfma_f32_16x16x32_bf16 v[100:103], v[152:155], v[204:207], v[100:103]
	v_mfma_f32_16x16x32_bf16 v[92:95], v[160:163], v[204:207], v[92:95]
	v_mfma_f32_16x16x32_bf16 v[84:87], v[152:155], v[212:215], v[84:87]
	v_mfma_f32_16x16x32_bf16 v[76:79], v[160:163], v[212:215], v[76:79]
	v_mfma_f32_16x16x32_bf16 v[124:127], v[156:159], v[192:195], v[124:127]
	v_mfma_f32_16x16x32_bf16 v[120:123], v[164:167], v[192:195], v[120:123]
	v_mfma_f32_16x16x32_bf16 v[116:119], v[156:159], v[200:203], v[116:119]
	v_mfma_f32_16x16x32_bf16 v[108:111], v[164:167], v[200:203], v[108:111]
	v_mfma_f32_16x16x32_bf16 v[100:103], v[156:159], v[208:211], v[100:103]
	v_mfma_f32_16x16x32_bf16 v[92:95], v[164:167], v[208:211], v[92:95]
	v_mfma_f32_16x16x32_bf16 v[84:87], v[156:159], v[216:219], v[84:87]
	v_mfma_f32_16x16x32_bf16 v[76:79], v[164:167], v[216:219], v[76:79]
	s_setprio 0
	s_setprio 1
	v_mfma_f32_16x16x32_bf16 v[112:115], v[168:171], v[184:187], v[112:115]
	v_mfma_f32_16x16x32_bf16 v[104:107], v[176:179], v[184:187], v[104:107]
	v_mfma_f32_16x16x32_bf16 v[96:99], v[168:171], v[196:199], v[96:99]
	v_mfma_f32_16x16x32_bf16 v[88:91], v[176:179], v[196:199], v[88:91]
	v_mfma_f32_16x16x32_bf16 v[80:83], v[168:171], v[204:207], v[80:83]
	v_mfma_f32_16x16x32_bf16 v[72:75], v[176:179], v[204:207], v[72:75]
	v_mfma_f32_16x16x32_bf16 v[68:71], v[168:171], v[212:215], v[68:71]
	v_mfma_f32_16x16x32_bf16 v[64:67], v[176:179], v[212:215], v[64:67]
	v_mfma_f32_16x16x32_bf16 v[112:115], v[172:175], v[192:195], v[112:115]
	v_mfma_f32_16x16x32_bf16 v[104:107], v[180:183], v[192:195], v[104:107]
	v_mfma_f32_16x16x32_bf16 v[96:99], v[172:175], v[200:203], v[96:99]
	v_mfma_f32_16x16x32_bf16 v[88:91], v[180:183], v[200:203], v[88:91]
	v_mfma_f32_16x16x32_bf16 v[80:83], v[172:175], v[208:211], v[80:83]
	v_mfma_f32_16x16x32_bf16 v[72:75], v[180:183], v[208:211], v[72:75]
	v_mfma_f32_16x16x32_bf16 v[68:71], v[172:175], v[216:219], v[68:71]
	v_mfma_f32_16x16x32_bf16 v[64:67], v[180:183], v[216:219], v[64:67]
	s_setprio 0
	s_barrier
	s_add_i32 s42, s79, s61
	s_mov_b32 m0, s42
	ds_read_b128 v[184:187], v151 offset:49152
	ds_read_b128 v[192:195], v151 offset:50176
	ds_read_b128 v[196:199], v151 offset:51200
	ds_read_b128 v[200:203], v151 offset:52224
	ds_read_b128 v[204:207], v151 offset:53248
	ds_read_b128 v[208:211], v151 offset:54272
	ds_read_b128 v[212:215], v151 offset:55296
	ds_read_b128 v[216:219], v151 offset:56320
	global_load_lds_dwordx4 v130, s[98:99]
	s_add_i32 m0, s42, 0x2000
	s_add_u32 s40, s40, 0x100080
	s_addc_u32 s41, s41, 0
	s_add_i32 s42, s80, s61
	global_load_lds_dwordx4 v134, s[98:99]
	s_mov_b32 m0, s42
	s_nop 0
	global_load_lds_dwordx4 v130, s[40:41]
	s_add_i32 m0, s42, 0x2000
	s_nop 0
	global_load_lds_dwordx4 v134, s[40:41]
	s_mov_b32 m0, s65
	s_nop 0
	global_load_lds_dwordx4 v128, s[100:101]
	s_mov_b32 m0, s66
	s_nop 0
	global_load_lds_dwordx4 v132, s[100:101]
	s_waitcnt vmcnt(8)
	s_waitcnt lgkmcnt(0)
	s_barrier
	s_setprio 1
	s_waitcnt lgkmcnt(0)
	v_mfma_f32_16x16x32_bf16 v[60:63], v[152:155], v[184:187], v[60:63]
	v_mfma_f32_16x16x32_bf16 v[56:59], v[160:163], v[184:187], v[56:59]
	v_mfma_f32_16x16x32_bf16 v[52:55], v[152:155], v[196:199], v[52:55]
	v_mfma_f32_16x16x32_bf16 v[44:47], v[160:163], v[196:199], v[44:47]
	v_mfma_f32_16x16x32_bf16 v[36:39], v[152:155], v[204:207], v[36:39]
	v_mfma_f32_16x16x32_bf16 v[28:31], v[160:163], v[204:207], v[28:31]
	v_mfma_f32_16x16x32_bf16 v[20:23], v[152:155], v[212:215], v[20:23]
	v_mfma_f32_16x16x32_bf16 v[12:15], v[160:163], v[212:215], v[12:15]
	v_mfma_f32_16x16x32_bf16 v[60:63], v[156:159], v[192:195], v[60:63]
	v_mfma_f32_16x16x32_bf16 v[56:59], v[164:167], v[192:195], v[56:59]
	v_mfma_f32_16x16x32_bf16 v[52:55], v[156:159], v[200:203], v[52:55]
	v_mfma_f32_16x16x32_bf16 v[44:47], v[164:167], v[200:203], v[44:47]
	v_mfma_f32_16x16x32_bf16 v[36:39], v[156:159], v[208:211], v[36:39]
	v_mfma_f32_16x16x32_bf16 v[28:31], v[164:167], v[208:211], v[28:31]
	v_mfma_f32_16x16x32_bf16 v[20:23], v[156:159], v[216:219], v[20:23]
	v_mfma_f32_16x16x32_bf16 v[12:15], v[164:167], v[216:219], v[12:15]
	s_setprio 0
	s_setprio 1
	v_mfma_f32_16x16x32_bf16 v[48:51], v[168:171], v[184:187], v[48:51]
	v_mfma_f32_16x16x32_bf16 v[40:43], v[176:179], v[184:187], v[40:43]
	v_mfma_f32_16x16x32_bf16 v[32:35], v[168:171], v[196:199], v[32:35]
	v_mfma_f32_16x16x32_bf16 v[24:27], v[176:179], v[196:199], v[24:27]
	v_mfma_f32_16x16x32_bf16 v[16:19], v[168:171], v[204:207], v[16:19]
	v_mfma_f32_16x16x32_bf16 v[8:11], v[176:179], v[204:207], v[8:11]
	v_mfma_f32_16x16x32_bf16 v[4:7], v[168:171], v[212:215], v[4:7]
	v_mfma_f32_16x16x32_bf16 v[0:3], v[176:179], v[212:215], v[0:3]
	v_mfma_f32_16x16x32_bf16 v[48:51], v[172:175], v[192:195], v[48:51]
	v_mfma_f32_16x16x32_bf16 v[40:43], v[180:183], v[192:195], v[40:43]
	v_mfma_f32_16x16x32_bf16 v[32:35], v[172:175], v[200:203], v[32:35]
	v_mfma_f32_16x16x32_bf16 v[24:27], v[180:183], v[200:203], v[24:27]
	v_mfma_f32_16x16x32_bf16 v[16:19], v[172:175], v[208:211], v[16:19]
	v_mfma_f32_16x16x32_bf16 v[8:11], v[180:183], v[208:211], v[8:11]
	v_mfma_f32_16x16x32_bf16 v[4:7], v[172:175], v[216:219], v[4:7]
	v_mfma_f32_16x16x32_bf16 v[0:3], v[180:183], v[216:219], v[0:3]
	s_setprio 0
	s_barrier
	s_add_i32 s77, s77, 2
	s_add_u32 s34, s34, 0x100
	s_addc_u32 s35, s35, 0
	s_add_u32 s75, s75, 0x100
	s_addc_u32 s76, s76, 0
	s_cmp_gt_u32 s77, 61
	s_cbranch_scc0 .LBB0_916

.LBB0_1052:
	s_ashr_i32 s27, s26, 31
	s_lshl_b64 s[28:29], s[26:27], 19
	s_add_u32 s28, s58, s28
	s_addc_u32 s29, s59, s29
	s_and_b64 s[30:31], s[4:5], exec
	s_cselect_b32 s27, s29, s43
	s_cselect_b32 s55, s28, s42
	s_ashr_i32 s25, s24, 31
	s_lshl_b64 s[30:31], s[24:25], 19
	s_add_u32 s30, s53, s30
	s_addc_u32 s31, s64, s31
	s_and_b64 s[62:63], s[4:5], exec
	s_cselect_b32 s25, s31, s61
	s_cselect_b32 s79, s30, s60
	s_add_u32 s42, s42, 0x40080
	s_addc_u32 s43, s43, 0
	s_add_u32 s80, s60, 0x100
	s_addc_u32 s81, s61, 0
	s_mov_b32 s82, -2
	ds_read_b128 v[152:155], v149
	ds_read_b128 v[156:159], v149 offset:1024
	ds_read_b128 v[160:163], v149 offset:2048
	ds_read_b128 v[164:167], v149 offset:3072
	ds_read_b128 v[168:171], v150
	ds_read_b128 v[172:175], v150 offset:1024
	ds_read_b128 v[176:179], v150 offset:2048
	ds_read_b128 v[180:183], v150 offset:3072
	s_add_u32 s60, s42, 0xfffc0080
	s_addc_u32 s61, s43, -1
	s_cmp_eq_u32 s82, 12
	s_cselect_b32 s63, s27, s61
	s_cselect_b32 s62, s55, s60
	s_cselect_b32 s61, s25, s81
	s_cselect_b32 s60, s79, s80
	s_add_i32 m0, s35, 0xc000
	ds_read_b128 v[184:187], v151
	ds_read_b128 v[192:195], v151 offset:1024
	ds_read_b128 v[196:199], v151 offset:2048
	ds_read_b128 v[200:203], v151 offset:3072
	ds_read_b128 v[204:207], v151 offset:4096
	ds_read_b128 v[208:211], v151 offset:5120
	ds_read_b128 v[212:215], v151 offset:6144
	ds_read_b128 v[216:219], v151 offset:7168
	global_load_lds_dwordx4 v136, s[42:43]
	s_add_i32 m0, s35, 0xe000
	s_nop 0
	global_load_lds_dwordx4 v138, s[42:43]
	s_waitcnt vmcnt(8)
	s_waitcnt lgkmcnt(0)
	s_barrier
	s_setprio 1
	s_waitcnt lgkmcnt(0)
	v_mfma_f32_16x16x32_bf16 v[124:127], v[152:155], v[184:187], 0
	v_mfma_f32_16x16x32_bf16 v[120:123], v[160:163], v[184:187], 0
	v_mfma_f32_16x16x32_bf16 v[116:119], v[152:155], v[196:199], 0
	v_mfma_f32_16x16x32_bf16 v[108:111], v[160:163], v[196:199], 0
	v_mfma_f32_16x16x32_bf16 v[100:103], v[152:155], v[204:207], 0
	v_mfma_f32_16x16x32_bf16 v[92:95], v[160:163], v[204:207], 0
	v_mfma_f32_16x16x32_bf16 v[84:87], v[152:155], v[212:215], 0
	v_mfma_f32_16x16x32_bf16 v[76:79], v[160:163], v[212:215], 0
	v_mfma_f32_16x16x32_bf16 v[124:127], v[156:159], v[192:195], v[124:127]
	v_mfma_f32_16x16x32_bf16 v[120:123], v[164:167], v[192:195], v[120:123]
	v_mfma_f32_16x16x32_bf16 v[116:119], v[156:159], v[200:203], v[116:119]
	v_mfma_f32_16x16x32_bf16 v[108:111], v[164:167], v[200:203], v[108:111]
	v_mfma_f32_16x16x32_bf16 v[100:103], v[156:159], v[208:211], v[100:103]
	v_mfma_f32_16x16x32_bf16 v[92:95], v[164:167], v[208:211], v[92:95]
	v_mfma_f32_16x16x32_bf16 v[84:87], v[156:159], v[216:219], v[84:87]
	v_mfma_f32_16x16x32_bf16 v[76:79], v[164:167], v[216:219], v[76:79]
	s_setprio 0
	s_setprio 1
	v_mfma_f32_16x16x32_bf16 v[112:115], v[168:171], v[184:187], 0
	v_mfma_f32_16x16x32_bf16 v[104:107], v[176:179], v[184:187], 0
	v_mfma_f32_16x16x32_bf16 v[96:99], v[168:171], v[196:199], 0
	v_mfma_f32_16x16x32_bf16 v[88:91], v[176:179], v[196:199], 0
	v_mfma_f32_16x16x32_bf16 v[80:83], v[168:171], v[204:207], 0
	v_mfma_f32_16x16x32_bf16 v[72:75], v[176:179], v[204:207], 0
	v_mfma_f32_16x16x32_bf16 v[68:71], v[168:171], v[212:215], 0
	v_mfma_f32_16x16x32_bf16 v[64:67], v[176:179], v[212:215], 0
	v_mfma_f32_16x16x32_bf16 v[112:115], v[172:175], v[192:195], v[112:115]
	v_mfma_f32_16x16x32_bf16 v[104:107], v[180:183], v[192:195], v[104:107]
	v_mfma_f32_16x16x32_bf16 v[96:99], v[172:175], v[200:203], v[96:99]
	v_mfma_f32_16x16x32_bf16 v[88:91], v[180:183], v[200:203], v[88:91]
	v_mfma_f32_16x16x32_bf16 v[80:83], v[172:175], v[208:211], v[80:83]
	v_mfma_f32_16x16x32_bf16 v[72:75], v[180:183], v[208:211], v[72:75]
	v_mfma_f32_16x16x32_bf16 v[68:71], v[172:175], v[216:219], v[68:71]
	v_mfma_f32_16x16x32_bf16 v[64:67], v[180:183], v[216:219], v[64:67]
	s_setprio 0
	s_barrier
	s_add_i32 s83, s72, s65
	s_add_u32 s98, s60, 0x80
	s_addc_u32 s99, s61, 0
	s_mov_b32 m0, s83
	ds_read_b128 v[184:187], v151 offset:16384
	ds_read_b128 v[192:195], v151 offset:17408
	ds_read_b128 v[196:199], v151 offset:18432
	ds_read_b128 v[200:203], v151 offset:19456
	ds_read_b128 v[204:207], v151 offset:20480
	ds_read_b128 v[208:211], v151 offset:21504
	ds_read_b128 v[212:215], v151 offset:22528
	ds_read_b128 v[216:219], v151 offset:23552
	global_load_lds_dwordx4 v130, s[60:61]
	s_add_i32 m0, s83, 0x2000
	s_add_u32 s84, s60, 0x40000
	s_addc_u32 s85, s61, 0
	s_add_i32 s83, s73, s65
	global_load_lds_dwordx4 v134, s[60:61]
	s_mov_b32 m0, s83
	s_add_u32 s100, s62, 0x80
	s_addc_u32 s101, s63, 0
	global_load_lds_dwordx4 v130, s[84:85]
	s_add_i32 m0, s83, 0x2000
	s_nop 0
	global_load_lds_dwordx4 v134, s[84:85]
	s_mov_b32 m0, s35
	s_nop 0
	global_load_lds_dwordx4 v128, s[62:63]
	s_mov_b32 m0, s33
	s_nop 0
	global_load_lds_dwordx4 v132, s[62:63]
	s_waitcnt vmcnt(8)
	s_waitcnt lgkmcnt(0)
	s_barrier
	s_setprio 1
	s_waitcnt lgkmcnt(0)
	v_mfma_f32_16x16x32_bf16 v[60:63], v[152:155], v[184:187], 0
	v_mfma_f32_16x16x32_bf16 v[56:59], v[160:163], v[184:187], 0
	v_mfma_f32_16x16x32_bf16 v[52:55], v[152:155], v[196:199], 0
	v_mfma_f32_16x16x32_bf16 v[44:47], v[160:163], v[196:199], 0
	v_mfma_f32_16x16x32_bf16 v[36:39], v[152:155], v[204:207], 0
	v_mfma_f32_16x16x32_bf16 v[28:31], v[160:163], v[204:207], 0
	v_mfma_f32_16x16x32_bf16 v[20:23], v[152:155], v[212:215], 0
	v_mfma_f32_16x16x32_bf16 v[12:15], v[160:163], v[212:215], 0
	v_mfma_f32_16x16x32_bf16 v[60:63], v[156:159], v[192:195], v[60:63]
	v_mfma_f32_16x16x32_bf16 v[56:59], v[164:167], v[192:195], v[56:59]
	v_mfma_f32_16x16x32_bf16 v[52:55], v[156:159], v[200:203], v[52:55]
	v_mfma_f32_16x16x32_bf16 v[44:47], v[164:167], v[200:203], v[44:47]
	v_mfma_f32_16x16x32_bf16 v[36:39], v[156:159], v[208:211], v[36:39]
	v_mfma_f32_16x16x32_bf16 v[28:31], v[164:167], v[208:211], v[28:31]
	v_mfma_f32_16x16x32_bf16 v[20:23], v[156:159], v[216:219], v[20:23]
	v_mfma_f32_16x16x32_bf16 v[12:15], v[164:167], v[216:219], v[12:15]
	s_setprio 0
	s_setprio 1
	v_mfma_f32_16x16x32_bf16 v[48:51], v[168:171], v[184:187], 0
	v_mfma_f32_16x16x32_bf16 v[40:43], v[176:179], v[184:187], 0
	v_mfma_f32_16x16x32_bf16 v[32:35], v[168:171], v[196:199], 0
	v_mfma_f32_16x16x32_bf16 v[24:27], v[176:179], v[196:199], 0
	v_mfma_f32_16x16x32_bf16 v[16:19], v[168:171], v[204:207], 0
	v_mfma_f32_16x16x32_bf16 v[8:11], v[176:179], v[204:207], 0
	v_mfma_f32_16x16x32_bf16 v[4:7], v[168:171], v[212:215], 0
	v_mfma_f32_16x16x32_bf16 v[0:3], v[176:179], v[212:215], 0
	v_mfma_f32_16x16x32_bf16 v[48:51], v[172:175], v[192:195], v[48:51]
	v_mfma_f32_16x16x32_bf16 v[40:43], v[180:183], v[192:195], v[40:43]
	v_mfma_f32_16x16x32_bf16 v[32:35], v[172:175], v[200:203], v[32:35]
	v_mfma_f32_16x16x32_bf16 v[24:27], v[180:183], v[200:203], v[24:27]
	v_mfma_f32_16x16x32_bf16 v[16:19], v[172:175], v[208:211], v[16:19]
	v_mfma_f32_16x16x32_bf16 v[8:11], v[180:183], v[208:211], v[8:11]
	v_mfma_f32_16x16x32_bf16 v[4:7], v[172:175], v[216:219], v[4:7]
	v_mfma_f32_16x16x32_bf16 v[0:3], v[180:183], v[216:219], v[0:3]
	s_setprio 0
	s_barrier
	s_add_i32 s83, 0, 0x18000
	s_add_i32 s84, 0, 0x1c000
	v_add_u32_e32 v164, s83, v147
	v_add_u32_e32 v180, s84, v147
	ds_read_b128 v[152:155], v164
	ds_read_b128 v[156:159], v164 offset:1024
	ds_read_b128 v[160:163], v164 offset:2048
	ds_read_b128 v[164:167], v164 offset:3072
	ds_read_b128 v[168:171], v180
	ds_read_b128 v[172:175], v180 offset:1024
	ds_read_b128 v[176:179], v180 offset:2048
	ds_read_b128 v[180:183], v180 offset:3072
	s_add_u32 s62, s62, 0x40000
	s_addc_u32 s63, s63, 0
	s_mov_b32 m0, s66
	ds_read_b128 v[184:187], v151 offset:32768
	ds_read_b128 v[192:195], v151 offset:33792
	ds_read_b128 v[196:199], v151 offset:34816
	ds_read_b128 v[200:203], v151 offset:35840
	ds_read_b128 v[204:207], v151 offset:36864
	ds_read_b128 v[208:211], v151 offset:37888
	ds_read_b128 v[212:215], v151 offset:38912
	ds_read_b128 v[216:219], v151 offset:39936
	global_load_lds_dwordx4 v128, s[62:63]
	s_mov_b32 m0, s67
	s_nop 0
	global_load_lds_dwordx4 v132, s[62:63]
	s_waitcnt vmcnt(8)
	s_waitcnt lgkmcnt(0)
	s_barrier
	s_setprio 1
	s_waitcnt lgkmcnt(0)
	v_mfma_f32_16x16x32_bf16 v[124:127], v[152:155], v[184:187], v[124:127]
	v_mfma_f32_16x16x32_bf16 v[120:123], v[160:163], v[184:187], v[120:123]
	v_mfma_f32_16x16x32_bf16 v[116:119], v[152:155], v[196:199], v[116:119]
	v_mfma_f32_16x16x32_bf16 v[108:111], v[160:163], v[196:199], v[108:111]
	v_mfma_f32_16x16x32_bf16 v[100:103], v[152:155], v[204:207], v[100:103]
	v_mfma_f32_16x16x32_bf16 v[92:95], v[160:163], v[204:207], v[92:95]
	v_mfma_f32_16x16x32_bf16 v[84:87], v[152:155], v[212:215], v[84:87]
	v_mfma_f32_16x16x32_bf16 v[76:79], v[160:163], v[212:215], v[76:79]
	v_mfma_f32_16x16x32_bf16 v[124:127], v[156:159], v[192:195], v[124:127]
	v_mfma_f32_16x16x32_bf16 v[120:123], v[164:167], v[192:195], v[120:123]
	v_mfma_f32_16x16x32_bf16 v[116:119], v[156:159], v[200:203], v[116:119]
	v_mfma_f32_16x16x32_bf16 v[108:111], v[164:167], v[200:203], v[108:111]
	v_mfma_f32_16x16x32_bf16 v[100:103], v[156:159], v[208:211], v[100:103]
	v_mfma_f32_16x16x32_bf16 v[92:95], v[164:167], v[208:211], v[92:95]
	v_mfma_f32_16x16x32_bf16 v[84:87], v[156:159], v[216:219], v[84:87]
	v_mfma_f32_16x16x32_bf16 v[76:79], v[164:167], v[216:219], v[76:79]
	s_setprio 0
	s_setprio 1
	v_mfma_f32_16x16x32_bf16 v[112:115], v[168:171], v[184:187], v[112:115]
	v_mfma_f32_16x16x32_bf16 v[104:107], v[176:179], v[184:187], v[104:107]
	v_mfma_f32_16x16x32_bf16 v[96:99], v[168:171], v[196:199], v[96:99]
	v_mfma_f32_16x16x32_bf16 v[88:91], v[176:179], v[196:199], v[88:91]
	v_mfma_f32_16x16x32_bf16 v[80:83], v[168:171], v[204:207], v[80:83]
	v_mfma_f32_16x16x32_bf16 v[72:75], v[176:179], v[204:207], v[72:75]
	v_mfma_f32_16x16x32_bf16 v[68:71], v[168:171], v[212:215], v[68:71]
	v_mfma_f32_16x16x32_bf16 v[64:67], v[176:179], v[212:215], v[64:67]
	v_mfma_f32_16x16x32_bf16 v[112:115], v[172:175], v[192:195], v[112:115]
	v_mfma_f32_16x16x32_bf16 v[104:107], v[180:183], v[192:195], v[104:107]
	v_mfma_f32_16x16x32_bf16 v[96:99], v[172:175], v[200:203], v[96:99]
	v_mfma_f32_16x16x32_bf16 v[88:91], v[180:183], v[200:203], v[88:91]
	v_mfma_f32_16x16x32_bf16 v[80:83], v[172:175], v[208:211], v[80:83]
	v_mfma_f32_16x16x32_bf16 v[72:75], v[180:183], v[208:211], v[72:75]
	v_mfma_f32_16x16x32_bf16 v[68:71], v[172:175], v[216:219], v[68:71]
	v_mfma_f32_16x16x32_bf16 v[64:67], v[180:183], v[216:219], v[64:67]
	s_setprio 0
	s_barrier
	s_add_i32 s62, s83, s65
	s_mov_b32 m0, s62
	ds_read_b128 v[184:187], v151 offset:49152
	ds_read_b128 v[192:195], v151 offset:50176
	ds_read_b128 v[196:199], v151 offset:51200
	ds_read_b128 v[200:203], v151 offset:52224
	ds_read_b128 v[204:207], v151 offset:53248
	ds_read_b128 v[208:211], v151 offset:54272
	ds_read_b128 v[212:215], v151 offset:55296
	ds_read_b128 v[216:219], v151 offset:56320
	global_load_lds_dwordx4 v130, s[98:99]
	s_add_i32 m0, s62, 0x2000
	s_add_u32 s60, s60, 0x40080
	s_addc_u32 s61, s61, 0
	s_add_i32 s62, s84, s65
	global_load_lds_dwordx4 v134, s[98:99]
	s_mov_b32 m0, s62
	s_nop 0
	global_load_lds_dwordx4 v130, s[60:61]
	s_add_i32 m0, s62, 0x2000
	s_nop 0
	global_load_lds_dwordx4 v134, s[60:61]
	s_mov_b32 m0, s69
	s_nop 0
	global_load_lds_dwordx4 v128, s[100:101]
	s_mov_b32 m0, s70
	s_nop 0
	global_load_lds_dwordx4 v132, s[100:101]
	s_waitcnt vmcnt(8)
	s_waitcnt lgkmcnt(0)
	s_barrier
	s_setprio 1
	s_waitcnt lgkmcnt(0)
	v_mfma_f32_16x16x32_bf16 v[60:63], v[152:155], v[184:187], v[60:63]
	v_mfma_f32_16x16x32_bf16 v[56:59], v[160:163], v[184:187], v[56:59]
	v_mfma_f32_16x16x32_bf16 v[52:55], v[152:155], v[196:199], v[52:55]
	v_mfma_f32_16x16x32_bf16 v[44:47], v[160:163], v[196:199], v[44:47]
	v_mfma_f32_16x16x32_bf16 v[36:39], v[152:155], v[204:207], v[36:39]
	v_mfma_f32_16x16x32_bf16 v[28:31], v[160:163], v[204:207], v[28:31]
	v_mfma_f32_16x16x32_bf16 v[20:23], v[152:155], v[212:215], v[20:23]
	v_mfma_f32_16x16x32_bf16 v[12:15], v[160:163], v[212:215], v[12:15]
	v_mfma_f32_16x16x32_bf16 v[60:63], v[156:159], v[192:195], v[60:63]
	v_mfma_f32_16x16x32_bf16 v[56:59], v[164:167], v[192:195], v[56:59]
	v_mfma_f32_16x16x32_bf16 v[52:55], v[156:159], v[200:203], v[52:55]
	v_mfma_f32_16x16x32_bf16 v[44:47], v[164:167], v[200:203], v[44:47]
	v_mfma_f32_16x16x32_bf16 v[36:39], v[156:159], v[208:211], v[36:39]
	v_mfma_f32_16x16x32_bf16 v[28:31], v[164:167], v[208:211], v[28:31]
	v_mfma_f32_16x16x32_bf16 v[20:23], v[156:159], v[216:219], v[20:23]
	v_mfma_f32_16x16x32_bf16 v[12:15], v[164:167], v[216:219], v[12:15]
	s_setprio 0
	s_setprio 1
	v_mfma_f32_16x16x32_bf16 v[48:51], v[168:171], v[184:187], v[48:51]
	v_mfma_f32_16x16x32_bf16 v[40:43], v[176:179], v[184:187], v[40:43]
	v_mfma_f32_16x16x32_bf16 v[32:35], v[168:171], v[196:199], v[32:35]
	v_mfma_f32_16x16x32_bf16 v[24:27], v[176:179], v[196:199], v[24:27]
	v_mfma_f32_16x16x32_bf16 v[16:19], v[168:171], v[204:207], v[16:19]
	v_mfma_f32_16x16x32_bf16 v[8:11], v[176:179], v[204:207], v[8:11]
	v_mfma_f32_16x16x32_bf16 v[4:7], v[168:171], v[212:215], v[4:7]
	v_mfma_f32_16x16x32_bf16 v[0:3], v[176:179], v[212:215], v[0:3]
	v_mfma_f32_16x16x32_bf16 v[48:51], v[172:175], v[192:195], v[48:51]
	v_mfma_f32_16x16x32_bf16 v[40:43], v[180:183], v[192:195], v[40:43]
	v_mfma_f32_16x16x32_bf16 v[32:35], v[172:175], v[200:203], v[32:35]
	v_mfma_f32_16x16x32_bf16 v[24:27], v[180:183], v[200:203], v[24:27]
	v_mfma_f32_16x16x32_bf16 v[16:19], v[172:175], v[208:211], v[16:19]
	v_mfma_f32_16x16x32_bf16 v[8:11], v[180:183], v[208:211], v[8:11]
	v_mfma_f32_16x16x32_bf16 v[4:7], v[172:175], v[216:219], v[4:7]
	v_mfma_f32_16x16x32_bf16 v[0:3], v[180:183], v[216:219], v[0:3]
	s_setprio 0
	s_barrier
	s_add_i32 s82, s82, 2
	s_add_u32 s42, s42, 0x100
	s_addc_u32 s43, s43, 0
	s_add_u32 s80, s80, 0x100
	s_addc_u32 s81, s81, 0
	s_cmp_gt_u32 s82, 13
	s_cbranch_scc0 .LBB0_1053
	s_branch .Lpeel_exit5
.LBB0_1053:
	ds_read_b128 v[152:155], v149
	ds_read_b128 v[156:159], v149 offset:1024
	ds_read_b128 v[160:163], v149 offset:2048
	ds_read_b128 v[164:167], v149 offset:3072
	ds_read_b128 v[168:171], v150
	ds_read_b128 v[172:175], v150 offset:1024
	ds_read_b128 v[176:179], v150 offset:2048
	ds_read_b128 v[180:183], v150 offset:3072
	s_add_u32 s60, s42, 0xfffc0080
	s_addc_u32 s61, s43, -1
	s_cmp_eq_u32 s82, 12
	s_cselect_b32 s63, s27, s61
	s_cselect_b32 s62, s55, s60
	s_cselect_b32 s61, s25, s81
	s_cselect_b32 s60, s79, s80
	s_add_i32 m0, s35, 0xc000
	ds_read_b128 v[184:187], v151
	ds_read_b128 v[192:195], v151 offset:1024
	ds_read_b128 v[196:199], v151 offset:2048
	ds_read_b128 v[200:203], v151 offset:3072
	ds_read_b128 v[204:207], v151 offset:4096
	ds_read_b128 v[208:211], v151 offset:5120
	ds_read_b128 v[212:215], v151 offset:6144
	ds_read_b128 v[216:219], v151 offset:7168
	global_load_lds_dwordx4 v136, s[42:43]
	s_add_i32 m0, s35, 0xe000
	s_nop 0
	global_load_lds_dwordx4 v138, s[42:43]
	s_waitcnt vmcnt(8)
	s_waitcnt lgkmcnt(0)
	s_barrier
	s_setprio 1
	s_waitcnt lgkmcnt(0)
	v_mfma_f32_16x16x32_bf16 v[124:127], v[152:155], v[184:187], v[124:127]
	v_mfma_f32_16x16x32_bf16 v[120:123], v[160:163], v[184:187], v[120:123]
	v_mfma_f32_16x16x32_bf16 v[116:119], v[152:155], v[196:199], v[116:119]
	v_mfma_f32_16x16x32_bf16 v[108:111], v[160:163], v[196:199], v[108:111]
	v_mfma_f32_16x16x32_bf16 v[100:103], v[152:155], v[204:207], v[100:103]
	v_mfma_f32_16x16x32_bf16 v[92:95], v[160:163], v[204:207], v[92:95]
	v_mfma_f32_16x16x32_bf16 v[84:87], v[152:155], v[212:215], v[84:87]
	v_mfma_f32_16x16x32_bf16 v[76:79], v[160:163], v[212:215], v[76:79]
	v_mfma_f32_16x16x32_bf16 v[124:127], v[156:159], v[192:195], v[124:127]
	v_mfma_f32_16x16x32_bf16 v[120:123], v[164:167], v[192:195], v[120:123]
	v_mfma_f32_16x16x32_bf16 v[116:119], v[156:159], v[200:203], v[116:119]
	v_mfma_f32_16x16x32_bf16 v[108:111], v[164:167], v[200:203], v[108:111]
	v_mfma_f32_16x16x32_bf16 v[100:103], v[156:159], v[208:211], v[100:103]
	v_mfma_f32_16x16x32_bf16 v[92:95], v[164:167], v[208:211], v[92:95]
	v_mfma_f32_16x16x32_bf16 v[84:87], v[156:159], v[216:219], v[84:87]
	v_mfma_f32_16x16x32_bf16 v[76:79], v[164:167], v[216:219], v[76:79]
	s_setprio 0
	s_setprio 1
	v_mfma_f32_16x16x32_bf16 v[112:115], v[168:171], v[184:187], v[112:115]
	v_mfma_f32_16x16x32_bf16 v[104:107], v[176:179], v[184:187], v[104:107]
	v_mfma_f32_16x16x32_bf16 v[96:99], v[168:171], v[196:199], v[96:99]
	v_mfma_f32_16x16x32_bf16 v[88:91], v[176:179], v[196:199], v[88:91]
	v_mfma_f32_16x16x32_bf16 v[80:83], v[168:171], v[204:207], v[80:83]
	v_mfma_f32_16x16x32_bf16 v[72:75], v[176:179], v[204:207], v[72:75]
	v_mfma_f32_16x16x32_bf16 v[68:71], v[168:171], v[212:215], v[68:71]
	v_mfma_f32_16x16x32_bf16 v[64:67], v[176:179], v[212:215], v[64:67]
	v_mfma_f32_16x16x32_bf16 v[112:115], v[172:175], v[192:195], v[112:115]
	v_mfma_f32_16x16x32_bf16 v[104:107], v[180:183], v[192:195], v[104:107]
	v_mfma_f32_16x16x32_bf16 v[96:99], v[172:175], v[200:203], v[96:99]
	v_mfma_f32_16x16x32_bf16 v[88:91], v[180:183], v[200:203], v[88:91]
	v_mfma_f32_16x16x32_bf16 v[80:83], v[172:175], v[208:211], v[80:83]
	v_mfma_f32_16x16x32_bf16 v[72:75], v[180:183], v[208:211], v[72:75]
	v_mfma_f32_16x16x32_bf16 v[68:71], v[172:175], v[216:219], v[68:71]
	v_mfma_f32_16x16x32_bf16 v[64:67], v[180:183], v[216:219], v[64:67]
	s_setprio 0
	s_barrier
	s_add_i32 s83, s72, s65
	s_add_u32 s98, s60, 0x80
	s_addc_u32 s99, s61, 0
	s_mov_b32 m0, s83
	ds_read_b128 v[184:187], v151 offset:16384
	ds_read_b128 v[192:195], v151 offset:17408
	ds_read_b128 v[196:199], v151 offset:18432
	ds_read_b128 v[200:203], v151 offset:19456
	ds_read_b128 v[204:207], v151 offset:20480
	ds_read_b128 v[208:211], v151 offset:21504
	ds_read_b128 v[212:215], v151 offset:22528
	ds_read_b128 v[216:219], v151 offset:23552
	global_load_lds_dwordx4 v130, s[60:61]
	s_add_i32 m0, s83, 0x2000
	s_add_u32 s84, s60, 0x40000
	s_addc_u32 s85, s61, 0
	s_add_i32 s83, s73, s65
	global_load_lds_dwordx4 v134, s[60:61]
	s_mov_b32 m0, s83
	s_add_u32 s100, s62, 0x80
	s_addc_u32 s101, s63, 0
	global_load_lds_dwordx4 v130, s[84:85]
	s_add_i32 m0, s83, 0x2000
	s_nop 0
	global_load_lds_dwordx4 v134, s[84:85]
	s_mov_b32 m0, s35
	s_nop 0
	global_load_lds_dwordx4 v128, s[62:63]
	s_mov_b32 m0, s33
	s_nop 0
	global_load_lds_dwordx4 v132, s[62:63]
	s_waitcnt vmcnt(8)
	s_waitcnt lgkmcnt(0)
	s_barrier
	s_setprio 1
	s_waitcnt lgkmcnt(0)
	v_mfma_f32_16x16x32_bf16 v[60:63], v[152:155], v[184:187], v[60:63]
	v_mfma_f32_16x16x32_bf16 v[56:59], v[160:163], v[184:187], v[56:59]
	v_mfma_f32_16x16x32_bf16 v[52:55], v[152:155], v[196:199], v[52:55]
	v_mfma_f32_16x16x32_bf16 v[44:47], v[160:163], v[196:199], v[44:47]
	v_mfma_f32_16x16x32_bf16 v[36:39], v[152:155], v[204:207], v[36:39]
	v_mfma_f32_16x16x32_bf16 v[28:31], v[160:163], v[204:207], v[28:31]
	v_mfma_f32_16x16x32_bf16 v[20:23], v[152:155], v[212:215], v[20:23]
	v_mfma_f32_16x16x32_bf16 v[12:15], v[160:163], v[212:215], v[12:15]
	v_mfma_f32_16x16x32_bf16 v[60:63], v[156:159], v[192:195], v[60:63]
	v_mfma_f32_16x16x32_bf16 v[56:59], v[164:167], v[192:195], v[56:59]
	v_mfma_f32_16x16x32_bf16 v[52:55], v[156:159], v[200:203], v[52:55]
	v_mfma_f32_16x16x32_bf16 v[44:47], v[164:167], v[200:203], v[44:47]
	v_mfma_f32_16x16x32_bf16 v[36:39], v[156:159], v[208:211], v[36:39]
	v_mfma_f32_16x16x32_bf16 v[28:31], v[164:167], v[208:211], v[28:31]
	v_mfma_f32_16x16x32_bf16 v[20:23], v[156:159], v[216:219], v[20:23]
	v_mfma_f32_16x16x32_bf16 v[12:15], v[164:167], v[216:219], v[12:15]
	s_setprio 0
	s_setprio 1
	v_mfma_f32_16x16x32_bf16 v[48:51], v[168:171], v[184:187], v[48:51]
	v_mfma_f32_16x16x32_bf16 v[40:43], v[176:179], v[184:187], v[40:43]
	v_mfma_f32_16x16x32_bf16 v[32:35], v[168:171], v[196:199], v[32:35]
	v_mfma_f32_16x16x32_bf16 v[24:27], v[176:179], v[196:199], v[24:27]
	v_mfma_f32_16x16x32_bf16 v[16:19], v[168:171], v[204:207], v[16:19]
	v_mfma_f32_16x16x32_bf16 v[8:11], v[176:179], v[204:207], v[8:11]
	v_mfma_f32_16x16x32_bf16 v[4:7], v[168:171], v[212:215], v[4:7]
	v_mfma_f32_16x16x32_bf16 v[0:3], v[176:179], v[212:215], v[0:3]
	v_mfma_f32_16x16x32_bf16 v[48:51], v[172:175], v[192:195], v[48:51]
	v_mfma_f32_16x16x32_bf16 v[40:43], v[180:183], v[192:195], v[40:43]
	v_mfma_f32_16x16x32_bf16 v[32:35], v[172:175], v[200:203], v[32:35]
	v_mfma_f32_16x16x32_bf16 v[24:27], v[180:183], v[200:203], v[24:27]
	v_mfma_f32_16x16x32_bf16 v[16:19], v[172:175], v[208:211], v[16:19]
	v_mfma_f32_16x16x32_bf16 v[8:11], v[180:183], v[208:211], v[8:11]
	v_mfma_f32_16x16x32_bf16 v[4:7], v[172:175], v[216:219], v[4:7]
	v_mfma_f32_16x16x32_bf16 v[0:3], v[180:183], v[216:219], v[0:3]
	s_setprio 0
	s_barrier
	s_add_i32 s83, 0, 0x18000
	s_add_i32 s84, 0, 0x1c000
	v_add_u32_e32 v164, s83, v147
	v_add_u32_e32 v180, s84, v147
	ds_read_b128 v[152:155], v164
	ds_read_b128 v[156:159], v164 offset:1024
	ds_read_b128 v[160:163], v164 offset:2048
	ds_read_b128 v[164:167], v164 offset:3072
	ds_read_b128 v[168:171], v180
	ds_read_b128 v[172:175], v180 offset:1024
	ds_read_b128 v[176:179], v180 offset:2048
	ds_read_b128 v[180:183], v180 offset:3072
	s_add_u32 s62, s62, 0x40000
	s_addc_u32 s63, s63, 0
	s_mov_b32 m0, s66
	ds_read_b128 v[184:187], v151 offset:32768
	ds_read_b128 v[192:195], v151 offset:33792
	ds_read_b128 v[196:199], v151 offset:34816
	ds_read_b128 v[200:203], v151 offset:35840
	ds_read_b128 v[204:207], v151 offset:36864
	ds_read_b128 v[208:211], v151 offset:37888
	ds_read_b128 v[212:215], v151 offset:38912
	ds_read_b128 v[216:219], v151 offset:39936
	global_load_lds_dwordx4 v128, s[62:63]
	s_mov_b32 m0, s67
	s_nop 0
	global_load_lds_dwordx4 v132, s[62:63]
	s_waitcnt vmcnt(8)
	s_waitcnt lgkmcnt(0)
	s_barrier
	s_setprio 1
	s_waitcnt lgkmcnt(0)
	v_mfma_f32_16x16x32_bf16 v[124:127], v[152:155], v[184:187], v[124:127]
	v_mfma_f32_16x16x32_bf16 v[120:123], v[160:163], v[184:187], v[120:123]
	v_mfma_f32_16x16x32_bf16 v[116:119], v[152:155], v[196:199], v[116:119]
	v_mfma_f32_16x16x32_bf16 v[108:111], v[160:163], v[196:199], v[108:111]
	v_mfma_f32_16x16x32_bf16 v[100:103], v[152:155], v[204:207], v[100:103]
	v_mfma_f32_16x16x32_bf16 v[92:95], v[160:163], v[204:207], v[92:95]
	v_mfma_f32_16x16x32_bf16 v[84:87], v[152:155], v[212:215], v[84:87]
	v_mfma_f32_16x16x32_bf16 v[76:79], v[160:163], v[212:215], v[76:79]
	v_mfma_f32_16x16x32_bf16 v[124:127], v[156:159], v[192:195], v[124:127]
	v_mfma_f32_16x16x32_bf16 v[120:123], v[164:167], v[192:195], v[120:123]
	v_mfma_f32_16x16x32_bf16 v[116:119], v[156:159], v[200:203], v[116:119]
	v_mfma_f32_16x16x32_bf16 v[108:111], v[164:167], v[200:203], v[108:111]
	v_mfma_f32_16x16x32_bf16 v[100:103], v[156:159], v[208:211], v[100:103]
	v_mfma_f32_16x16x32_bf16 v[92:95], v[164:167], v[208:211], v[92:95]
	v_mfma_f32_16x16x32_bf16 v[84:87], v[156:159], v[216:219], v[84:87]
	v_mfma_f32_16x16x32_bf16 v[76:79], v[164:167], v[216:219], v[76:79]
	s_setprio 0
	s_setprio 1
	v_mfma_f32_16x16x32_bf16 v[112:115], v[168:171], v[184:187], v[112:115]
	v_mfma_f32_16x16x32_bf16 v[104:107], v[176:179], v[184:187], v[104:107]
	v_mfma_f32_16x16x32_bf16 v[96:99], v[168:171], v[196:199], v[96:99]
	v_mfma_f32_16x16x32_bf16 v[88:91], v[176:179], v[196:199], v[88:91]
	v_mfma_f32_16x16x32_bf16 v[80:83], v[168:171], v[204:207], v[80:83]
	v_mfma_f32_16x16x32_bf16 v[72:75], v[176:179], v[204:207], v[72:75]
	v_mfma_f32_16x16x32_bf16 v[68:71], v[168:171], v[212:215], v[68:71]
	v_mfma_f32_16x16x32_bf16 v[64:67], v[176:179], v[212:215], v[64:67]
	v_mfma_f32_16x16x32_bf16 v[112:115], v[172:175], v[192:195], v[112:115]
	v_mfma_f32_16x16x32_bf16 v[104:107], v[180:183], v[192:195], v[104:107]
	v_mfma_f32_16x16x32_bf16 v[96:99], v[172:175], v[200:203], v[96:99]
	v_mfma_f32_16x16x32_bf16 v[88:91], v[180:183], v[200:203], v[88:91]
	v_mfma_f32_16x16x32_bf16 v[80:83], v[172:175], v[208:211], v[80:83]
	v_mfma_f32_16x16x32_bf16 v[72:75], v[180:183], v[208:211], v[72:75]
	v_mfma_f32_16x16x32_bf16 v[68:71], v[172:175], v[216:219], v[68:71]
	v_mfma_f32_16x16x32_bf16 v[64:67], v[180:183], v[216:219], v[64:67]
	s_setprio 0
	s_barrier
	s_add_i32 s62, s83, s65
	s_mov_b32 m0, s62
	ds_read_b128 v[184:187], v151 offset:49152
	ds_read_b128 v[192:195], v151 offset:50176
	ds_read_b128 v[196:199], v151 offset:51200
	ds_read_b128 v[200:203], v151 offset:52224
	ds_read_b128 v[204:207], v151 offset:53248
	ds_read_b128 v[208:211], v151 offset:54272
	ds_read_b128 v[212:215], v151 offset:55296
	ds_read_b128 v[216:219], v151 offset:56320
	global_load_lds_dwordx4 v130, s[98:99]
	s_add_i32 m0, s62, 0x2000
	s_add_u32 s60, s60, 0x40080
	s_addc_u32 s61, s61, 0
	s_add_i32 s62, s84, s65
	global_load_lds_dwordx4 v134, s[98:99]
	s_mov_b32 m0, s62
	s_nop 0
	global_load_lds_dwordx4 v130, s[60:61]
	s_add_i32 m0, s62, 0x2000
	s_nop 0
	global_load_lds_dwordx4 v134, s[60:61]
	s_mov_b32 m0, s69
	s_nop 0
	global_load_lds_dwordx4 v128, s[100:101]
	s_mov_b32 m0, s70
	s_nop 0
	global_load_lds_dwordx4 v132, s[100:101]
	s_waitcnt vmcnt(8)
	s_waitcnt lgkmcnt(0)
	s_barrier
	s_setprio 1
	s_waitcnt lgkmcnt(0)
	v_mfma_f32_16x16x32_bf16 v[60:63], v[152:155], v[184:187], v[60:63]
	v_mfma_f32_16x16x32_bf16 v[56:59], v[160:163], v[184:187], v[56:59]
	v_mfma_f32_16x16x32_bf16 v[52:55], v[152:155], v[196:199], v[52:55]
	v_mfma_f32_16x16x32_bf16 v[44:47], v[160:163], v[196:199], v[44:47]
	v_mfma_f32_16x16x32_bf16 v[36:39], v[152:155], v[204:207], v[36:39]
	v_mfma_f32_16x16x32_bf16 v[28:31], v[160:163], v[204:207], v[28:31]
	v_mfma_f32_16x16x32_bf16 v[20:23], v[152:155], v[212:215], v[20:23]
	v_mfma_f32_16x16x32_bf16 v[12:15], v[160:163], v[212:215], v[12:15]
	v_mfma_f32_16x16x32_bf16 v[60:63], v[156:159], v[192:195], v[60:63]
	v_mfma_f32_16x16x32_bf16 v[56:59], v[164:167], v[192:195], v[56:59]
	v_mfma_f32_16x16x32_bf16 v[52:55], v[156:159], v[200:203], v[52:55]
	v_mfma_f32_16x16x32_bf16 v[44:47], v[164:167], v[200:203], v[44:47]
	v_mfma_f32_16x16x32_bf16 v[36:39], v[156:159], v[208:211], v[36:39]
	v_mfma_f32_16x16x32_bf16 v[28:31], v[164:167], v[208:211], v[28:31]
	v_mfma_f32_16x16x32_bf16 v[20:23], v[156:159], v[216:219], v[20:23]
	v_mfma_f32_16x16x32_bf16 v[12:15], v[164:167], v[216:219], v[12:15]
	s_setprio 0
	s_setprio 1
	v_mfma_f32_16x16x32_bf16 v[48:51], v[168:171], v[184:187], v[48:51]
	v_mfma_f32_16x16x32_bf16 v[40:43], v[176:179], v[184:187], v[40:43]
	v_mfma_f32_16x16x32_bf16 v[32:35], v[168:171], v[196:199], v[32:35]
	v_mfma_f32_16x16x32_bf16 v[24:27], v[176:179], v[196:199], v[24:27]
	v_mfma_f32_16x16x32_bf16 v[16:19], v[168:171], v[204:207], v[16:19]
	v_mfma_f32_16x16x32_bf16 v[8:11], v[176:179], v[204:207], v[8:11]
	v_mfma_f32_16x16x32_bf16 v[4:7], v[168:171], v[212:215], v[4:7]
	v_mfma_f32_16x16x32_bf16 v[0:3], v[176:179], v[212:215], v[0:3]
	v_mfma_f32_16x16x32_bf16 v[48:51], v[172:175], v[192:195], v[48:51]
	v_mfma_f32_16x16x32_bf16 v[40:43], v[180:183], v[192:195], v[40:43]
	v_mfma_f32_16x16x32_bf16 v[32:35], v[172:175], v[200:203], v[32:35]
	v_mfma_f32_16x16x32_bf16 v[24:27], v[180:183], v[200:203], v[24:27]
	v_mfma_f32_16x16x32_bf16 v[16:19], v[172:175], v[208:211], v[16:19]
	v_mfma_f32_16x16x32_bf16 v[8:11], v[180:183], v[208:211], v[8:11]
	v_mfma_f32_16x16x32_bf16 v[4:7], v[172:175], v[216:219], v[4:7]
	v_mfma_f32_16x16x32_bf16 v[0:3], v[180:183], v[216:219], v[0:3]
	s_setprio 0
	s_barrier
	s_add_i32 s82, s82, 2
	s_add_u32 s42, s42, 0x100
	s_addc_u32 s43, s43, 0
	s_add_u32 s80, s80, 0x100
	s_addc_u32 s81, s81, 0
	s_cmp_gt_u32 s82, 13
	s_cbranch_scc0 .LBB0_1053

.LBB0_1076:
	s_ashr_i32 s27, s26, 31
	s_lshl_b64 s[28:29], s[26:27], 19
	s_add_u32 s28, s40, s28
	s_addc_u32 s29, s41, s29
	s_and_b64 s[30:31], s[4:5], exec
	s_cselect_b32 s27, s29, s43
	s_cselect_b32 s55, s28, s42
	s_ashr_i32 s25, s24, 31
	s_lshl_b64 s[30:31], s[24:25], 19
	s_add_u32 s30, s53, s30
	s_addc_u32 s31, s64, s31
	s_and_b64 s[62:63], s[4:5], exec
	s_cselect_b32 s25, s31, s61
	s_cselect_b32 s79, s30, s60
	s_add_u32 s42, s42, 0x40080
	s_addc_u32 s43, s43, 0
	s_add_u32 s80, s60, 0x100
	s_addc_u32 s81, s61, 0
	s_mov_b32 s82, -2
	ds_read_b128 v[152:155], v149
	ds_read_b128 v[156:159], v149 offset:1024
	ds_read_b128 v[160:163], v149 offset:2048
	ds_read_b128 v[164:167], v149 offset:3072
	ds_read_b128 v[168:171], v150
	ds_read_b128 v[172:175], v150 offset:1024
	ds_read_b128 v[176:179], v150 offset:2048
	ds_read_b128 v[180:183], v150 offset:3072
	s_add_u32 s60, s42, 0xfffc0080
	s_addc_u32 s61, s43, -1
	s_cmp_eq_u32 s82, 12
	s_cselect_b32 s63, s27, s61
	s_cselect_b32 s62, s55, s60
	s_cselect_b32 s61, s25, s81
	s_cselect_b32 s60, s79, s80
	s_add_i32 m0, s35, 0xc000
	ds_read_b128 v[184:187], v151
	ds_read_b128 v[192:195], v151 offset:1024
	ds_read_b128 v[196:199], v151 offset:2048
	ds_read_b128 v[200:203], v151 offset:3072
	ds_read_b128 v[204:207], v151 offset:4096
	ds_read_b128 v[208:211], v151 offset:5120
	ds_read_b128 v[212:215], v151 offset:6144
	ds_read_b128 v[216:219], v151 offset:7168
	global_load_lds_dwordx4 v136, s[42:43]
	s_add_i32 m0, s35, 0xe000
	s_nop 0
	global_load_lds_dwordx4 v138, s[42:43]
	s_waitcnt vmcnt(8)
	s_waitcnt lgkmcnt(0)
	s_barrier
	s_setprio 1
	s_waitcnt lgkmcnt(0)
	v_mfma_f32_16x16x32_bf16 v[124:127], v[152:155], v[184:187], 0
	v_mfma_f32_16x16x32_bf16 v[120:123], v[160:163], v[184:187], 0
	v_mfma_f32_16x16x32_bf16 v[116:119], v[152:155], v[196:199], 0
	v_mfma_f32_16x16x32_bf16 v[108:111], v[160:163], v[196:199], 0
	v_mfma_f32_16x16x32_bf16 v[100:103], v[152:155], v[204:207], 0
	v_mfma_f32_16x16x32_bf16 v[92:95], v[160:163], v[204:207], 0
	v_mfma_f32_16x16x32_bf16 v[84:87], v[152:155], v[212:215], 0
	v_mfma_f32_16x16x32_bf16 v[76:79], v[160:163], v[212:215], 0
	v_mfma_f32_16x16x32_bf16 v[124:127], v[156:159], v[192:195], v[124:127]
	v_mfma_f32_16x16x32_bf16 v[120:123], v[164:167], v[192:195], v[120:123]
	v_mfma_f32_16x16x32_bf16 v[116:119], v[156:159], v[200:203], v[116:119]
	v_mfma_f32_16x16x32_bf16 v[108:111], v[164:167], v[200:203], v[108:111]
	v_mfma_f32_16x16x32_bf16 v[100:103], v[156:159], v[208:211], v[100:103]
	v_mfma_f32_16x16x32_bf16 v[92:95], v[164:167], v[208:211], v[92:95]
	v_mfma_f32_16x16x32_bf16 v[84:87], v[156:159], v[216:219], v[84:87]
	v_mfma_f32_16x16x32_bf16 v[76:79], v[164:167], v[216:219], v[76:79]
	s_setprio 0
	s_setprio 1
	v_mfma_f32_16x16x32_bf16 v[112:115], v[168:171], v[184:187], 0
	v_mfma_f32_16x16x32_bf16 v[104:107], v[176:179], v[184:187], 0
	v_mfma_f32_16x16x32_bf16 v[96:99], v[168:171], v[196:199], 0
	v_mfma_f32_16x16x32_bf16 v[88:91], v[176:179], v[196:199], 0
	v_mfma_f32_16x16x32_bf16 v[80:83], v[168:171], v[204:207], 0
	v_mfma_f32_16x16x32_bf16 v[72:75], v[176:179], v[204:207], 0
	v_mfma_f32_16x16x32_bf16 v[68:71], v[168:171], v[212:215], 0
	v_mfma_f32_16x16x32_bf16 v[64:67], v[176:179], v[212:215], 0
	v_mfma_f32_16x16x32_bf16 v[112:115], v[172:175], v[192:195], v[112:115]
	v_mfma_f32_16x16x32_bf16 v[104:107], v[180:183], v[192:195], v[104:107]
	v_mfma_f32_16x16x32_bf16 v[96:99], v[172:175], v[200:203], v[96:99]
	v_mfma_f32_16x16x32_bf16 v[88:91], v[180:183], v[200:203], v[88:91]
	v_mfma_f32_16x16x32_bf16 v[80:83], v[172:175], v[208:211], v[80:83]
	v_mfma_f32_16x16x32_bf16 v[72:75], v[180:183], v[208:211], v[72:75]
	v_mfma_f32_16x16x32_bf16 v[68:71], v[172:175], v[216:219], v[68:71]
	v_mfma_f32_16x16x32_bf16 v[64:67], v[180:183], v[216:219], v[64:67]
	s_setprio 0
	s_barrier
	s_add_i32 s83, s72, s65
	s_add_u32 s98, s60, 0x80
	s_addc_u32 s99, s61, 0
	s_mov_b32 m0, s83
	ds_read_b128 v[184:187], v151 offset:16384
	ds_read_b128 v[192:195], v151 offset:17408
	ds_read_b128 v[196:199], v151 offset:18432
	ds_read_b128 v[200:203], v151 offset:19456
	ds_read_b128 v[204:207], v151 offset:20480
	ds_read_b128 v[208:211], v151 offset:21504
	ds_read_b128 v[212:215], v151 offset:22528
	ds_read_b128 v[216:219], v151 offset:23552
	global_load_lds_dwordx4 v130, s[60:61]
	s_add_i32 m0, s83, 0x2000
	s_add_u32 s84, s60, 0x40000
	s_addc_u32 s85, s61, 0
	s_add_i32 s83, s73, s65
	global_load_lds_dwordx4 v134, s[60:61]
	s_mov_b32 m0, s83
	s_add_u32 s100, s62, 0x80
	s_addc_u32 s101, s63, 0
	global_load_lds_dwordx4 v130, s[84:85]
	s_add_i32 m0, s83, 0x2000
	s_nop 0
	global_load_lds_dwordx4 v134, s[84:85]
	s_mov_b32 m0, s35
	s_nop 0
	global_load_lds_dwordx4 v128, s[62:63]
	s_mov_b32 m0, s33
	s_nop 0
	global_load_lds_dwordx4 v132, s[62:63]
	s_waitcnt vmcnt(8)
	s_waitcnt lgkmcnt(0)
	s_barrier
	s_setprio 1
	s_waitcnt lgkmcnt(0)
	v_mfma_f32_16x16x32_bf16 v[60:63], v[152:155], v[184:187], 0
	v_mfma_f32_16x16x32_bf16 v[56:59], v[160:163], v[184:187], 0
	v_mfma_f32_16x16x32_bf16 v[52:55], v[152:155], v[196:199], 0
	v_mfma_f32_16x16x32_bf16 v[44:47], v[160:163], v[196:199], 0
	v_mfma_f32_16x16x32_bf16 v[36:39], v[152:155], v[204:207], 0
	v_mfma_f32_16x16x32_bf16 v[28:31], v[160:163], v[204:207], 0
	v_mfma_f32_16x16x32_bf16 v[20:23], v[152:155], v[212:215], 0
	v_mfma_f32_16x16x32_bf16 v[12:15], v[160:163], v[212:215], 0
	v_mfma_f32_16x16x32_bf16 v[60:63], v[156:159], v[192:195], v[60:63]
	v_mfma_f32_16x16x32_bf16 v[56:59], v[164:167], v[192:195], v[56:59]
	v_mfma_f32_16x16x32_bf16 v[52:55], v[156:159], v[200:203], v[52:55]
	v_mfma_f32_16x16x32_bf16 v[44:47], v[164:167], v[200:203], v[44:47]
	v_mfma_f32_16x16x32_bf16 v[36:39], v[156:159], v[208:211], v[36:39]
	v_mfma_f32_16x16x32_bf16 v[28:31], v[164:167], v[208:211], v[28:31]
	v_mfma_f32_16x16x32_bf16 v[20:23], v[156:159], v[216:219], v[20:23]
	v_mfma_f32_16x16x32_bf16 v[12:15], v[164:167], v[216:219], v[12:15]
	s_setprio 0
	s_setprio 1
	v_mfma_f32_16x16x32_bf16 v[48:51], v[168:171], v[184:187], 0
	v_mfma_f32_16x16x32_bf16 v[40:43], v[176:179], v[184:187], 0
	v_mfma_f32_16x16x32_bf16 v[32:35], v[168:171], v[196:199], 0
	v_mfma_f32_16x16x32_bf16 v[24:27], v[176:179], v[196:199], 0
	v_mfma_f32_16x16x32_bf16 v[16:19], v[168:171], v[204:207], 0
	v_mfma_f32_16x16x32_bf16 v[8:11], v[176:179], v[204:207], 0
	v_mfma_f32_16x16x32_bf16 v[4:7], v[168:171], v[212:215], 0
	v_mfma_f32_16x16x32_bf16 v[0:3], v[176:179], v[212:215], 0
	v_mfma_f32_16x16x32_bf16 v[48:51], v[172:175], v[192:195], v[48:51]
	v_mfma_f32_16x16x32_bf16 v[40:43], v[180:183], v[192:195], v[40:43]
	v_mfma_f32_16x16x32_bf16 v[32:35], v[172:175], v[200:203], v[32:35]
	v_mfma_f32_16x16x32_bf16 v[24:27], v[180:183], v[200:203], v[24:27]
	v_mfma_f32_16x16x32_bf16 v[16:19], v[172:175], v[208:211], v[16:19]
	v_mfma_f32_16x16x32_bf16 v[8:11], v[180:183], v[208:211], v[8:11]
	v_mfma_f32_16x16x32_bf16 v[4:7], v[172:175], v[216:219], v[4:7]
	v_mfma_f32_16x16x32_bf16 v[0:3], v[180:183], v[216:219], v[0:3]
	s_setprio 0
	s_barrier
	s_add_i32 s83, 0, 0x18000
	s_add_i32 s84, 0, 0x1c000
	v_add_u32_e32 v164, s83, v147
	v_add_u32_e32 v180, s84, v147
	ds_read_b128 v[152:155], v164
	ds_read_b128 v[156:159], v164 offset:1024
	ds_read_b128 v[160:163], v164 offset:2048
	ds_read_b128 v[164:167], v164 offset:3072
	ds_read_b128 v[168:171], v180
	ds_read_b128 v[172:175], v180 offset:1024
	ds_read_b128 v[176:179], v180 offset:2048
	ds_read_b128 v[180:183], v180 offset:3072
	s_add_u32 s62, s62, 0x40000
	s_addc_u32 s63, s63, 0
	s_mov_b32 m0, s66
	ds_read_b128 v[184:187], v151 offset:32768
	ds_read_b128 v[192:195], v151 offset:33792
	ds_read_b128 v[196:199], v151 offset:34816
	ds_read_b128 v[200:203], v151 offset:35840
	ds_read_b128 v[204:207], v151 offset:36864
	ds_read_b128 v[208:211], v151 offset:37888
	ds_read_b128 v[212:215], v151 offset:38912
	ds_read_b128 v[216:219], v151 offset:39936
	global_load_lds_dwordx4 v128, s[62:63]
	s_mov_b32 m0, s67
	s_nop 0
	global_load_lds_dwordx4 v132, s[62:63]
	s_waitcnt vmcnt(8)
	s_waitcnt lgkmcnt(0)
	s_barrier
	s_setprio 1
	s_waitcnt lgkmcnt(0)
	v_mfma_f32_16x16x32_bf16 v[124:127], v[152:155], v[184:187], v[124:127]
	v_mfma_f32_16x16x32_bf16 v[120:123], v[160:163], v[184:187], v[120:123]
	v_mfma_f32_16x16x32_bf16 v[116:119], v[152:155], v[196:199], v[116:119]
	v_mfma_f32_16x16x32_bf16 v[108:111], v[160:163], v[196:199], v[108:111]
	v_mfma_f32_16x16x32_bf16 v[100:103], v[152:155], v[204:207], v[100:103]
	v_mfma_f32_16x16x32_bf16 v[92:95], v[160:163], v[204:207], v[92:95]
	v_mfma_f32_16x16x32_bf16 v[84:87], v[152:155], v[212:215], v[84:87]
	v_mfma_f32_16x16x32_bf16 v[76:79], v[160:163], v[212:215], v[76:79]
	v_mfma_f32_16x16x32_bf16 v[124:127], v[156:159], v[192:195], v[124:127]
	v_mfma_f32_16x16x32_bf16 v[120:123], v[164:167], v[192:195], v[120:123]
	v_mfma_f32_16x16x32_bf16 v[116:119], v[156:159], v[200:203], v[116:119]
	v_mfma_f32_16x16x32_bf16 v[108:111], v[164:167], v[200:203], v[108:111]
	v_mfma_f32_16x16x32_bf16 v[100:103], v[156:159], v[208:211], v[100:103]
	v_mfma_f32_16x16x32_bf16 v[92:95], v[164:167], v[208:211], v[92:95]
	v_mfma_f32_16x16x32_bf16 v[84:87], v[156:159], v[216:219], v[84:87]
	v_mfma_f32_16x16x32_bf16 v[76:79], v[164:167], v[216:219], v[76:79]
	s_setprio 0
	s_setprio 1
	v_mfma_f32_16x16x32_bf16 v[112:115], v[168:171], v[184:187], v[112:115]
	v_mfma_f32_16x16x32_bf16 v[104:107], v[176:179], v[184:187], v[104:107]
	v_mfma_f32_16x16x32_bf16 v[96:99], v[168:171], v[196:199], v[96:99]
	v_mfma_f32_16x16x32_bf16 v[88:91], v[176:179], v[196:199], v[88:91]
	v_mfma_f32_16x16x32_bf16 v[80:83], v[168:171], v[204:207], v[80:83]
	v_mfma_f32_16x16x32_bf16 v[72:75], v[176:179], v[204:207], v[72:75]
	v_mfma_f32_16x16x32_bf16 v[68:71], v[168:171], v[212:215], v[68:71]
	v_mfma_f32_16x16x32_bf16 v[64:67], v[176:179], v[212:215], v[64:67]
	v_mfma_f32_16x16x32_bf16 v[112:115], v[172:175], v[192:195], v[112:115]
	v_mfma_f32_16x16x32_bf16 v[104:107], v[180:183], v[192:195], v[104:107]
	v_mfma_f32_16x16x32_bf16 v[96:99], v[172:175], v[200:203], v[96:99]
	v_mfma_f32_16x16x32_bf16 v[88:91], v[180:183], v[200:203], v[88:91]
	v_mfma_f32_16x16x32_bf16 v[80:83], v[172:175], v[208:211], v[80:83]
	v_mfma_f32_16x16x32_bf16 v[72:75], v[180:183], v[208:211], v[72:75]
	v_mfma_f32_16x16x32_bf16 v[68:71], v[172:175], v[216:219], v[68:71]
	v_mfma_f32_16x16x32_bf16 v[64:67], v[180:183], v[216:219], v[64:67]
	s_setprio 0
	s_barrier
	s_add_i32 s62, s83, s65
	s_mov_b32 m0, s62
	ds_read_b128 v[184:187], v151 offset:49152
	ds_read_b128 v[192:195], v151 offset:50176
	ds_read_b128 v[196:199], v151 offset:51200
	ds_read_b128 v[200:203], v151 offset:52224
	ds_read_b128 v[204:207], v151 offset:53248
	ds_read_b128 v[208:211], v151 offset:54272
	ds_read_b128 v[212:215], v151 offset:55296
	ds_read_b128 v[216:219], v151 offset:56320
	global_load_lds_dwordx4 v130, s[98:99]
	s_add_i32 m0, s62, 0x2000
	s_add_u32 s60, s60, 0x40080
	s_addc_u32 s61, s61, 0
	s_add_i32 s62, s84, s65
	global_load_lds_dwordx4 v134, s[98:99]
	s_mov_b32 m0, s62
	s_nop 0
	global_load_lds_dwordx4 v130, s[60:61]
	s_add_i32 m0, s62, 0x2000
	s_nop 0
	global_load_lds_dwordx4 v134, s[60:61]
	s_mov_b32 m0, s69
	s_nop 0
	global_load_lds_dwordx4 v128, s[100:101]
	s_mov_b32 m0, s70
	s_nop 0
	global_load_lds_dwordx4 v132, s[100:101]
	s_waitcnt vmcnt(8)
	s_waitcnt lgkmcnt(0)
	s_barrier
	s_setprio 1
	s_waitcnt lgkmcnt(0)
	v_mfma_f32_16x16x32_bf16 v[60:63], v[152:155], v[184:187], v[60:63]
	v_mfma_f32_16x16x32_bf16 v[56:59], v[160:163], v[184:187], v[56:59]
	v_mfma_f32_16x16x32_bf16 v[52:55], v[152:155], v[196:199], v[52:55]
	v_mfma_f32_16x16x32_bf16 v[44:47], v[160:163], v[196:199], v[44:47]
	v_mfma_f32_16x16x32_bf16 v[36:39], v[152:155], v[204:207], v[36:39]
	v_mfma_f32_16x16x32_bf16 v[28:31], v[160:163], v[204:207], v[28:31]
	v_mfma_f32_16x16x32_bf16 v[20:23], v[152:155], v[212:215], v[20:23]
	v_mfma_f32_16x16x32_bf16 v[12:15], v[160:163], v[212:215], v[12:15]
	v_mfma_f32_16x16x32_bf16 v[60:63], v[156:159], v[192:195], v[60:63]
	v_mfma_f32_16x16x32_bf16 v[56:59], v[164:167], v[192:195], v[56:59]
	v_mfma_f32_16x16x32_bf16 v[52:55], v[156:159], v[200:203], v[52:55]
	v_mfma_f32_16x16x32_bf16 v[44:47], v[164:167], v[200:203], v[44:47]
	v_mfma_f32_16x16x32_bf16 v[36:39], v[156:159], v[208:211], v[36:39]
	v_mfma_f32_16x16x32_bf16 v[28:31], v[164:167], v[208:211], v[28:31]
	v_mfma_f32_16x16x32_bf16 v[20:23], v[156:159], v[216:219], v[20:23]
	v_mfma_f32_16x16x32_bf16 v[12:15], v[164:167], v[216:219], v[12:15]
	s_setprio 0
	s_setprio 1
	v_mfma_f32_16x16x32_bf16 v[48:51], v[168:171], v[184:187], v[48:51]
	v_mfma_f32_16x16x32_bf16 v[40:43], v[176:179], v[184:187], v[40:43]
	v_mfma_f32_16x16x32_bf16 v[32:35], v[168:171], v[196:199], v[32:35]
	v_mfma_f32_16x16x32_bf16 v[24:27], v[176:179], v[196:199], v[24:27]
	v_mfma_f32_16x16x32_bf16 v[16:19], v[168:171], v[204:207], v[16:19]
	v_mfma_f32_16x16x32_bf16 v[8:11], v[176:179], v[204:207], v[8:11]
	v_mfma_f32_16x16x32_bf16 v[4:7], v[168:171], v[212:215], v[4:7]
	v_mfma_f32_16x16x32_bf16 v[0:3], v[176:179], v[212:215], v[0:3]
	v_mfma_f32_16x16x32_bf16 v[48:51], v[172:175], v[192:195], v[48:51]
	v_mfma_f32_16x16x32_bf16 v[40:43], v[180:183], v[192:195], v[40:43]
	v_mfma_f32_16x16x32_bf16 v[32:35], v[172:175], v[200:203], v[32:35]
	v_mfma_f32_16x16x32_bf16 v[24:27], v[180:183], v[200:203], v[24:27]
	v_mfma_f32_16x16x32_bf16 v[16:19], v[172:175], v[208:211], v[16:19]
	v_mfma_f32_16x16x32_bf16 v[8:11], v[180:183], v[208:211], v[8:11]
	v_mfma_f32_16x16x32_bf16 v[4:7], v[172:175], v[216:219], v[4:7]
	v_mfma_f32_16x16x32_bf16 v[0:3], v[180:183], v[216:219], v[0:3]
	s_setprio 0
	s_barrier
	s_add_i32 s82, s82, 2
	s_add_u32 s42, s42, 0x100
	s_addc_u32 s43, s43, 0
	s_add_u32 s80, s80, 0x100
	s_addc_u32 s81, s81, 0
	s_cmp_gt_u32 s82, 13
	s_cbranch_scc0 .LBB0_1077
	s_branch .Lpeel_exit6

.LBB0_1265:
	s_add_u32 s65, s18, 0x100
	s_addc_u32 s66, s19, 0
	s_mov_b32 s67, -2
	ds_read_b128 v[144:147], v151
	ds_read_b128 v[154:157], v151 offset:1024
	ds_read_b128 v[158:161], v151 offset:2048
	ds_read_b128 v[162:165], v151 offset:3072
	ds_read_b128 v[166:169], v152
	ds_read_b128 v[170:173], v152 offset:1024
	ds_read_b128 v[174:177], v152 offset:2048
	ds_read_b128 v[178:181], v152 offset:3072
	s_add_u32 s18, s16, 0x100
	s_addc_u32 s19, s17, 0
	s_cmp_eq_u32 s67, 2
	s_cselect_b32 s23, s5, s19
	s_cselect_b32 s22, s4, s18
	s_cselect_b32 s21, s15, s66
	s_cselect_b32 s20, s14, s65
	v_lshl_add_u64 v[216:217], s[16:17], 0, v[136:137]
	s_add_i32 m0, s31, 0xc000
	ds_read_b128 v[182:185], v153
	ds_read_b128 v[186:189], v153 offset:1024
	ds_read_b128 v[192:195], v153 offset:2048
	ds_read_b128 v[196:199], v153 offset:3072
	ds_read_b128 v[200:203], v153 offset:4096
	ds_read_b128 v[204:207], v153 offset:5120
	ds_read_b128 v[208:211], v153 offset:6144
	ds_read_b128 v[212:215], v153 offset:7168
	global_load_lds_dwordx4 v[216:217], off
	v_lshl_add_u64 v[216:217], s[16:17], 0, v[138:139]
	s_add_i32 m0, s31, 0xe000
	s_nop 0
	global_load_lds_dwordx4 v[216:217], off
	s_waitcnt vmcnt(8)
	s_waitcnt lgkmcnt(0)
	s_barrier
	s_setprio 1
	s_waitcnt lgkmcnt(0)
	v_mfma_f32_16x16x32_bf16 v[124:127], v[144:147], v[182:185], 0
	v_mfma_f32_16x16x32_bf16 v[120:123], v[158:161], v[182:185], 0
	v_mfma_f32_16x16x32_bf16 v[116:119], v[144:147], v[192:195], 0
	v_mfma_f32_16x16x32_bf16 v[108:111], v[158:161], v[192:195], 0
	v_mfma_f32_16x16x32_bf16 v[100:103], v[144:147], v[200:203], 0
	v_mfma_f32_16x16x32_bf16 v[92:95], v[158:161], v[200:203], 0
	v_mfma_f32_16x16x32_bf16 v[84:87], v[144:147], v[208:211], 0
	v_mfma_f32_16x16x32_bf16 v[76:79], v[158:161], v[208:211], 0
	v_mfma_f32_16x16x32_bf16 v[124:127], v[154:157], v[186:189], v[124:127]
	v_mfma_f32_16x16x32_bf16 v[120:123], v[162:165], v[186:189], v[120:123]
	v_mfma_f32_16x16x32_bf16 v[116:119], v[154:157], v[196:199], v[116:119]
	v_mfma_f32_16x16x32_bf16 v[108:111], v[162:165], v[196:199], v[108:111]
	v_mfma_f32_16x16x32_bf16 v[100:103], v[154:157], v[204:207], v[100:103]
	v_mfma_f32_16x16x32_bf16 v[92:95], v[162:165], v[204:207], v[92:95]
	v_mfma_f32_16x16x32_bf16 v[84:87], v[154:157], v[212:215], v[84:87]
	v_mfma_f32_16x16x32_bf16 v[76:79], v[162:165], v[212:215], v[76:79]
	s_setprio 0
	s_setprio 1
	v_mfma_f32_16x16x32_bf16 v[112:115], v[166:169], v[182:185], 0
	v_mfma_f32_16x16x32_bf16 v[104:107], v[174:177], v[182:185], 0
	v_mfma_f32_16x16x32_bf16 v[96:99], v[166:169], v[192:195], 0
	v_mfma_f32_16x16x32_bf16 v[88:91], v[174:177], v[192:195], 0
	v_mfma_f32_16x16x32_bf16 v[80:83], v[166:169], v[200:203], 0
	v_mfma_f32_16x16x32_bf16 v[72:75], v[174:177], v[200:203], 0
	v_mfma_f32_16x16x32_bf16 v[68:71], v[166:169], v[208:211], 0
	v_mfma_f32_16x16x32_bf16 v[64:67], v[174:177], v[208:211], 0
	v_mfma_f32_16x16x32_bf16 v[112:115], v[170:173], v[186:189], v[112:115]
	v_mfma_f32_16x16x32_bf16 v[104:107], v[178:181], v[186:189], v[104:107]
	v_mfma_f32_16x16x32_bf16 v[96:99], v[170:173], v[196:199], v[96:99]
	v_mfma_f32_16x16x32_bf16 v[88:91], v[178:181], v[196:199], v[88:91]
	v_mfma_f32_16x16x32_bf16 v[80:83], v[170:173], v[204:207], v[80:83]
	v_mfma_f32_16x16x32_bf16 v[72:75], v[178:181], v[204:207], v[72:75]
	v_mfma_f32_16x16x32_bf16 v[68:71], v[170:173], v[212:215], v[68:71]
	v_mfma_f32_16x16x32_bf16 v[64:67], v[178:181], v[212:215], v[64:67]
	s_setprio 0
	s_barrier
	s_add_i32 s16, s60, s28
	s_add_u32 s98, s20, 0x80
	s_addc_u32 s99, s21, 0
	s_mov_b32 m0, s16
	ds_read_b128 v[182:185], v153 offset:16384
	ds_read_b128 v[186:189], v153 offset:17408
	ds_read_b128 v[192:195], v153 offset:18432
	ds_read_b128 v[196:199], v153 offset:19456
	ds_read_b128 v[200:203], v153 offset:20480
	ds_read_b128 v[204:207], v153 offset:21504
	ds_read_b128 v[208:211], v153 offset:22528
	ds_read_b128 v[212:215], v153 offset:23552
	global_load_lds_dwordx4 v132, s[20:21]
	s_add_i32 m0, s16, 0x2000
	s_add_u32 s16, s20, 0x18000
	s_addc_u32 s17, s21, 0
	s_add_i32 s68, s61, s28
	global_load_lds_dwordx4 v128, s[20:21]
	s_mov_b32 m0, s68
	s_add_u32 s100, s22, 0x80
	s_addc_u32 s101, s23, 0
	global_load_lds_dwordx4 v132, s[16:17]
	s_add_i32 m0, s68, 0x2000
	s_nop 0
	global_load_lds_dwordx4 v128, s[16:17]
	s_mov_b32 m0, s31
	s_nop 0
	global_load_lds_dwordx4 v134, s[22:23]
	s_mov_b32 m0, s33
	s_nop 0
	global_load_lds_dwordx4 v130, s[22:23]
	s_waitcnt vmcnt(8)
	s_waitcnt lgkmcnt(0)
	s_barrier
	s_setprio 1
	s_waitcnt lgkmcnt(0)
	v_mfma_f32_16x16x32_bf16 v[60:63], v[144:147], v[182:185], 0
	v_mfma_f32_16x16x32_bf16 v[56:59], v[158:161], v[182:185], 0
	v_mfma_f32_16x16x32_bf16 v[52:55], v[144:147], v[192:195], 0
	v_mfma_f32_16x16x32_bf16 v[44:47], v[158:161], v[192:195], 0
	v_mfma_f32_16x16x32_bf16 v[36:39], v[144:147], v[200:203], 0
	v_mfma_f32_16x16x32_bf16 v[28:31], v[158:161], v[200:203], 0
	v_mfma_f32_16x16x32_bf16 v[20:23], v[144:147], v[208:211], 0
	v_mfma_f32_16x16x32_bf16 v[12:15], v[158:161], v[208:211], 0
	v_mfma_f32_16x16x32_bf16 v[60:63], v[154:157], v[186:189], v[60:63]
	v_mfma_f32_16x16x32_bf16 v[56:59], v[162:165], v[186:189], v[56:59]
	v_mfma_f32_16x16x32_bf16 v[52:55], v[154:157], v[196:199], v[52:55]
	v_mfma_f32_16x16x32_bf16 v[44:47], v[162:165], v[196:199], v[44:47]
	v_mfma_f32_16x16x32_bf16 v[36:39], v[154:157], v[204:207], v[36:39]
	v_mfma_f32_16x16x32_bf16 v[28:31], v[162:165], v[204:207], v[28:31]
	v_mfma_f32_16x16x32_bf16 v[20:23], v[154:157], v[212:215], v[20:23]
	v_mfma_f32_16x16x32_bf16 v[12:15], v[162:165], v[212:215], v[12:15]
	s_setprio 0
	s_setprio 1
	v_mfma_f32_16x16x32_bf16 v[48:51], v[166:169], v[182:185], 0
	v_mfma_f32_16x16x32_bf16 v[40:43], v[174:177], v[182:185], 0
	v_mfma_f32_16x16x32_bf16 v[32:35], v[166:169], v[192:195], 0
	v_mfma_f32_16x16x32_bf16 v[24:27], v[174:177], v[192:195], 0
	v_mfma_f32_16x16x32_bf16 v[16:19], v[166:169], v[200:203], 0
	v_mfma_f32_16x16x32_bf16 v[8:11], v[174:177], v[200:203], 0
	v_mfma_f32_16x16x32_bf16 v[4:7], v[166:169], v[208:211], 0
	v_mfma_f32_16x16x32_bf16 v[0:3], v[174:177], v[208:211], 0
	v_mfma_f32_16x16x32_bf16 v[48:51], v[170:173], v[186:189], v[48:51]
	v_mfma_f32_16x16x32_bf16 v[40:43], v[178:181], v[186:189], v[40:43]
	v_mfma_f32_16x16x32_bf16 v[32:35], v[170:173], v[196:199], v[32:35]
	v_mfma_f32_16x16x32_bf16 v[24:27], v[178:181], v[196:199], v[24:27]
	v_mfma_f32_16x16x32_bf16 v[16:19], v[170:173], v[204:207], v[16:19]
	v_mfma_f32_16x16x32_bf16 v[8:11], v[178:181], v[204:207], v[8:11]
	v_mfma_f32_16x16x32_bf16 v[4:7], v[170:173], v[212:215], v[4:7]
	v_mfma_f32_16x16x32_bf16 v[0:3], v[178:181], v[212:215], v[0:3]
	s_setprio 0
	s_barrier
	s_add_i32 s68, 0, 0x18000
	s_add_i32 s69, 0, 0x1c000
	v_add_u32_e32 v162, s68, v149
	v_add_u32_e32 v178, s69, v149
	ds_read_b128 v[144:147], v162
	ds_read_b128 v[154:157], v162 offset:1024
	ds_read_b128 v[158:161], v162 offset:2048
	ds_read_b128 v[162:165], v162 offset:3072
	ds_read_b128 v[166:169], v178
	ds_read_b128 v[170:173], v178 offset:1024
	ds_read_b128 v[174:177], v178 offset:2048
	ds_read_b128 v[178:181], v178 offset:3072
	s_add_u32 s16, s22, 0x18000
	s_addc_u32 s17, s23, 0
	s_mov_b32 m0, s34
	ds_read_b128 v[182:185], v153 offset:32768
	ds_read_b128 v[186:189], v153 offset:33792
	ds_read_b128 v[192:195], v153 offset:34816
	ds_read_b128 v[196:199], v153 offset:35840
	ds_read_b128 v[200:203], v153 offset:36864
	ds_read_b128 v[204:207], v153 offset:37888
	ds_read_b128 v[208:211], v153 offset:38912
	ds_read_b128 v[212:215], v153 offset:39936
	global_load_lds_dwordx4 v134, s[16:17]
	s_mov_b32 m0, s35
	s_nop 0
	global_load_lds_dwordx4 v130, s[16:17]
	s_waitcnt vmcnt(8)
	s_waitcnt lgkmcnt(0)
	s_barrier
	s_setprio 1
	s_waitcnt lgkmcnt(0)
	v_mfma_f32_16x16x32_bf16 v[124:127], v[144:147], v[182:185], v[124:127]
	v_mfma_f32_16x16x32_bf16 v[120:123], v[158:161], v[182:185], v[120:123]
	v_mfma_f32_16x16x32_bf16 v[116:119], v[144:147], v[192:195], v[116:119]
	v_mfma_f32_16x16x32_bf16 v[108:111], v[158:161], v[192:195], v[108:111]
	v_mfma_f32_16x16x32_bf16 v[100:103], v[144:147], v[200:203], v[100:103]
	v_mfma_f32_16x16x32_bf16 v[92:95], v[158:161], v[200:203], v[92:95]
	v_mfma_f32_16x16x32_bf16 v[84:87], v[144:147], v[208:211], v[84:87]
	v_mfma_f32_16x16x32_bf16 v[76:79], v[158:161], v[208:211], v[76:79]
	v_mfma_f32_16x16x32_bf16 v[124:127], v[154:157], v[186:189], v[124:127]
	v_mfma_f32_16x16x32_bf16 v[120:123], v[162:165], v[186:189], v[120:123]
	v_mfma_f32_16x16x32_bf16 v[116:119], v[154:157], v[196:199], v[116:119]
	v_mfma_f32_16x16x32_bf16 v[108:111], v[162:165], v[196:199], v[108:111]
	v_mfma_f32_16x16x32_bf16 v[100:103], v[154:157], v[204:207], v[100:103]
	v_mfma_f32_16x16x32_bf16 v[92:95], v[162:165], v[204:207], v[92:95]
	v_mfma_f32_16x16x32_bf16 v[84:87], v[154:157], v[212:215], v[84:87]
	v_mfma_f32_16x16x32_bf16 v[76:79], v[162:165], v[212:215], v[76:79]
	s_setprio 0
	s_setprio 1
	v_mfma_f32_16x16x32_bf16 v[112:115], v[166:169], v[182:185], v[112:115]
	v_mfma_f32_16x16x32_bf16 v[104:107], v[174:177], v[182:185], v[104:107]
	v_mfma_f32_16x16x32_bf16 v[96:99], v[166:169], v[192:195], v[96:99]
	v_mfma_f32_16x16x32_bf16 v[88:91], v[174:177], v[192:195], v[88:91]
	v_mfma_f32_16x16x32_bf16 v[80:83], v[166:169], v[200:203], v[80:83]
	v_mfma_f32_16x16x32_bf16 v[72:75], v[174:177], v[200:203], v[72:75]
	v_mfma_f32_16x16x32_bf16 v[68:71], v[166:169], v[208:211], v[68:71]
	v_mfma_f32_16x16x32_bf16 v[64:67], v[174:177], v[208:211], v[64:67]
	v_mfma_f32_16x16x32_bf16 v[112:115], v[170:173], v[186:189], v[112:115]
	v_mfma_f32_16x16x32_bf16 v[104:107], v[178:181], v[186:189], v[104:107]
	v_mfma_f32_16x16x32_bf16 v[96:99], v[170:173], v[196:199], v[96:99]
	v_mfma_f32_16x16x32_bf16 v[88:91], v[178:181], v[196:199], v[88:91]
	v_mfma_f32_16x16x32_bf16 v[80:83], v[170:173], v[204:207], v[80:83]
	v_mfma_f32_16x16x32_bf16 v[72:75], v[178:181], v[204:207], v[72:75]
	v_mfma_f32_16x16x32_bf16 v[68:71], v[170:173], v[212:215], v[68:71]
	v_mfma_f32_16x16x32_bf16 v[64:67], v[178:181], v[212:215], v[64:67]
	s_setprio 0
	s_barrier
	s_add_i32 s16, s68, s28
	s_mov_b32 m0, s16
	ds_read_b128 v[182:185], v153 offset:49152
	ds_read_b128 v[186:189], v153 offset:50176
	ds_read_b128 v[192:195], v153 offset:51200
	ds_read_b128 v[196:199], v153 offset:52224
	ds_read_b128 v[200:203], v153 offset:53248
	ds_read_b128 v[204:207], v153 offset:54272
	ds_read_b128 v[208:211], v153 offset:55296
	ds_read_b128 v[212:215], v153 offset:56320
	global_load_lds_dwordx4 v132, s[98:99]
	s_add_i32 m0, s16, 0x2000
	s_add_u32 s16, s20, 0x18080
	s_addc_u32 s17, s21, 0
	s_add_i32 s20, s69, s28
	global_load_lds_dwordx4 v128, s[98:99]
	s_mov_b32 m0, s20
	s_nop 0
	global_load_lds_dwordx4 v132, s[16:17]
	s_add_i32 m0, s20, 0x2000
	s_nop 0
	global_load_lds_dwordx4 v128, s[16:17]
	s_mov_b32 m0, s43
	s_nop 0
	global_load_lds_dwordx4 v134, s[100:101]
	s_mov_b32 m0, s52
	s_nop 0
	global_load_lds_dwordx4 v130, s[100:101]
	s_waitcnt vmcnt(8)
	s_waitcnt lgkmcnt(0)
	s_barrier
	s_setprio 1
	s_waitcnt lgkmcnt(0)
	v_mfma_f32_16x16x32_bf16 v[60:63], v[144:147], v[182:185], v[60:63]
	v_mfma_f32_16x16x32_bf16 v[56:59], v[158:161], v[182:185], v[56:59]
	v_mfma_f32_16x16x32_bf16 v[52:55], v[144:147], v[192:195], v[52:55]
	v_mfma_f32_16x16x32_bf16 v[44:47], v[158:161], v[192:195], v[44:47]
	v_mfma_f32_16x16x32_bf16 v[36:39], v[144:147], v[200:203], v[36:39]
	v_mfma_f32_16x16x32_bf16 v[28:31], v[158:161], v[200:203], v[28:31]
	v_mfma_f32_16x16x32_bf16 v[20:23], v[144:147], v[208:211], v[20:23]
	v_mfma_f32_16x16x32_bf16 v[12:15], v[158:161], v[208:211], v[12:15]
	v_mfma_f32_16x16x32_bf16 v[60:63], v[154:157], v[186:189], v[60:63]
	v_mfma_f32_16x16x32_bf16 v[56:59], v[162:165], v[186:189], v[56:59]
	v_mfma_f32_16x16x32_bf16 v[52:55], v[154:157], v[196:199], v[52:55]
	v_mfma_f32_16x16x32_bf16 v[44:47], v[162:165], v[196:199], v[44:47]
	v_mfma_f32_16x16x32_bf16 v[36:39], v[154:157], v[204:207], v[36:39]
	v_mfma_f32_16x16x32_bf16 v[28:31], v[162:165], v[204:207], v[28:31]
	v_mfma_f32_16x16x32_bf16 v[20:23], v[154:157], v[212:215], v[20:23]
	v_mfma_f32_16x16x32_bf16 v[12:15], v[162:165], v[212:215], v[12:15]
	s_setprio 0
	s_setprio 1
	v_mfma_f32_16x16x32_bf16 v[48:51], v[166:169], v[182:185], v[48:51]
	v_mfma_f32_16x16x32_bf16 v[40:43], v[174:177], v[182:185], v[40:43]
	v_mfma_f32_16x16x32_bf16 v[32:35], v[166:169], v[192:195], v[32:35]
	v_mfma_f32_16x16x32_bf16 v[24:27], v[174:177], v[192:195], v[24:27]
	v_mfma_f32_16x16x32_bf16 v[16:19], v[166:169], v[200:203], v[16:19]
	v_mfma_f32_16x16x32_bf16 v[8:11], v[174:177], v[200:203], v[8:11]
	v_mfma_f32_16x16x32_bf16 v[4:7], v[166:169], v[208:211], v[4:7]
	v_mfma_f32_16x16x32_bf16 v[0:3], v[174:177], v[208:211], v[0:3]
	v_mfma_f32_16x16x32_bf16 v[48:51], v[170:173], v[186:189], v[48:51]
	v_mfma_f32_16x16x32_bf16 v[40:43], v[178:181], v[186:189], v[40:43]
	v_mfma_f32_16x16x32_bf16 v[32:35], v[170:173], v[196:199], v[32:35]
	v_mfma_f32_16x16x32_bf16 v[24:27], v[178:181], v[196:199], v[24:27]
	v_mfma_f32_16x16x32_bf16 v[16:19], v[170:173], v[204:207], v[16:19]
	v_mfma_f32_16x16x32_bf16 v[8:11], v[178:181], v[204:207], v[8:11]
	v_mfma_f32_16x16x32_bf16 v[4:7], v[170:173], v[212:215], v[4:7]
	v_mfma_f32_16x16x32_bf16 v[0:3], v[178:181], v[212:215], v[0:3]
	s_setprio 0
	s_barrier
	s_add_i32 s67, s67, 2
	s_add_u32 s65, s65, 0x100
	s_addc_u32 s66, s66, 0
	s_cmp_gt_u32 s67, 3
	s_mov_b64 s[16:17], s[18:19]
	s_cbranch_scc0 .LBB0_1266
	s_branch .Lpeel_exit9
.LBB0_1266:
	ds_read_b128 v[144:147], v151
	ds_read_b128 v[154:157], v151 offset:1024
	ds_read_b128 v[158:161], v151 offset:2048
	ds_read_b128 v[162:165], v151 offset:3072
	ds_read_b128 v[166:169], v152
	ds_read_b128 v[170:173], v152 offset:1024
	ds_read_b128 v[174:177], v152 offset:2048
	ds_read_b128 v[178:181], v152 offset:3072
	s_add_u32 s18, s16, 0x100
	s_addc_u32 s19, s17, 0
	s_cmp_eq_u32 s67, 2
	s_cselect_b32 s23, s5, s19
	s_cselect_b32 s22, s4, s18
	s_cselect_b32 s21, s15, s66
	s_cselect_b32 s20, s14, s65
	v_lshl_add_u64 v[216:217], s[16:17], 0, v[136:137]
	s_add_i32 m0, s31, 0xc000
	ds_read_b128 v[182:185], v153
	ds_read_b128 v[186:189], v153 offset:1024
	ds_read_b128 v[192:195], v153 offset:2048
	ds_read_b128 v[196:199], v153 offset:3072
	ds_read_b128 v[200:203], v153 offset:4096
	ds_read_b128 v[204:207], v153 offset:5120
	ds_read_b128 v[208:211], v153 offset:6144
	ds_read_b128 v[212:215], v153 offset:7168
	global_load_lds_dwordx4 v[216:217], off
	v_lshl_add_u64 v[216:217], s[16:17], 0, v[138:139]
	s_add_i32 m0, s31, 0xe000
	s_nop 0
	global_load_lds_dwordx4 v[216:217], off
	s_waitcnt vmcnt(8)
	s_waitcnt lgkmcnt(0)
	s_barrier
	s_setprio 1
	s_waitcnt lgkmcnt(0)
	v_mfma_f32_16x16x32_bf16 v[124:127], v[144:147], v[182:185], v[124:127]
	v_mfma_f32_16x16x32_bf16 v[120:123], v[158:161], v[182:185], v[120:123]
	v_mfma_f32_16x16x32_bf16 v[116:119], v[144:147], v[192:195], v[116:119]
	v_mfma_f32_16x16x32_bf16 v[108:111], v[158:161], v[192:195], v[108:111]
	v_mfma_f32_16x16x32_bf16 v[100:103], v[144:147], v[200:203], v[100:103]
	v_mfma_f32_16x16x32_bf16 v[92:95], v[158:161], v[200:203], v[92:95]
	v_mfma_f32_16x16x32_bf16 v[84:87], v[144:147], v[208:211], v[84:87]
	v_mfma_f32_16x16x32_bf16 v[76:79], v[158:161], v[208:211], v[76:79]
	v_mfma_f32_16x16x32_bf16 v[124:127], v[154:157], v[186:189], v[124:127]
	v_mfma_f32_16x16x32_bf16 v[120:123], v[162:165], v[186:189], v[120:123]
	v_mfma_f32_16x16x32_bf16 v[116:119], v[154:157], v[196:199], v[116:119]
	v_mfma_f32_16x16x32_bf16 v[108:111], v[162:165], v[196:199], v[108:111]
	v_mfma_f32_16x16x32_bf16 v[100:103], v[154:157], v[204:207], v[100:103]
	v_mfma_f32_16x16x32_bf16 v[92:95], v[162:165], v[204:207], v[92:95]
	v_mfma_f32_16x16x32_bf16 v[84:87], v[154:157], v[212:215], v[84:87]
	v_mfma_f32_16x16x32_bf16 v[76:79], v[162:165], v[212:215], v[76:79]
	s_setprio 0
	s_setprio 1
	v_mfma_f32_16x16x32_bf16 v[112:115], v[166:169], v[182:185], v[112:115]
	v_mfma_f32_16x16x32_bf16 v[104:107], v[174:177], v[182:185], v[104:107]
	v_mfma_f32_16x16x32_bf16 v[96:99], v[166:169], v[192:195], v[96:99]
	v_mfma_f32_16x16x32_bf16 v[88:91], v[174:177], v[192:195], v[88:91]
	v_mfma_f32_16x16x32_bf16 v[80:83], v[166:169], v[200:203], v[80:83]
	v_mfma_f32_16x16x32_bf16 v[72:75], v[174:177], v[200:203], v[72:75]
	v_mfma_f32_16x16x32_bf16 v[68:71], v[166:169], v[208:211], v[68:71]
	v_mfma_f32_16x16x32_bf16 v[64:67], v[174:177], v[208:211], v[64:67]
	v_mfma_f32_16x16x32_bf16 v[112:115], v[170:173], v[186:189], v[112:115]
	v_mfma_f32_16x16x32_bf16 v[104:107], v[178:181], v[186:189], v[104:107]
	v_mfma_f32_16x16x32_bf16 v[96:99], v[170:173], v[196:199], v[96:99]
	v_mfma_f32_16x16x32_bf16 v[88:91], v[178:181], v[196:199], v[88:91]
	v_mfma_f32_16x16x32_bf16 v[80:83], v[170:173], v[204:207], v[80:83]
	v_mfma_f32_16x16x32_bf16 v[72:75], v[178:181], v[204:207], v[72:75]
	v_mfma_f32_16x16x32_bf16 v[68:71], v[170:173], v[212:215], v[68:71]
	v_mfma_f32_16x16x32_bf16 v[64:67], v[178:181], v[212:215], v[64:67]
	s_setprio 0
	s_barrier
	s_add_i32 s16, s60, s28
	s_add_u32 s98, s20, 0x80
	s_addc_u32 s99, s21, 0
	s_mov_b32 m0, s16
	ds_read_b128 v[182:185], v153 offset:16384
	ds_read_b128 v[186:189], v153 offset:17408
	ds_read_b128 v[192:195], v153 offset:18432
	ds_read_b128 v[196:199], v153 offset:19456
	ds_read_b128 v[200:203], v153 offset:20480
	ds_read_b128 v[204:207], v153 offset:21504
	ds_read_b128 v[208:211], v153 offset:22528
	ds_read_b128 v[212:215], v153 offset:23552
	global_load_lds_dwordx4 v132, s[20:21]
	s_add_i32 m0, s16, 0x2000
	s_add_u32 s16, s20, 0x18000
	s_addc_u32 s17, s21, 0
	s_add_i32 s68, s61, s28
	global_load_lds_dwordx4 v128, s[20:21]
	s_mov_b32 m0, s68
	s_add_u32 s100, s22, 0x80
	s_addc_u32 s101, s23, 0
	global_load_lds_dwordx4 v132, s[16:17]
	s_add_i32 m0, s68, 0x2000
	s_nop 0
	global_load_lds_dwordx4 v128, s[16:17]
	s_mov_b32 m0, s31
	s_nop 0
	global_load_lds_dwordx4 v134, s[22:23]
	s_mov_b32 m0, s33
	s_nop 0
	global_load_lds_dwordx4 v130, s[22:23]
	s_waitcnt vmcnt(8)
	s_waitcnt lgkmcnt(0)
	s_barrier
	s_setprio 1
	s_waitcnt lgkmcnt(0)
	v_mfma_f32_16x16x32_bf16 v[60:63], v[144:147], v[182:185], v[60:63]
	v_mfma_f32_16x16x32_bf16 v[56:59], v[158:161], v[182:185], v[56:59]
	v_mfma_f32_16x16x32_bf16 v[52:55], v[144:147], v[192:195], v[52:55]
	v_mfma_f32_16x16x32_bf16 v[44:47], v[158:161], v[192:195], v[44:47]
	v_mfma_f32_16x16x32_bf16 v[36:39], v[144:147], v[200:203], v[36:39]
	v_mfma_f32_16x16x32_bf16 v[28:31], v[158:161], v[200:203], v[28:31]
	v_mfma_f32_16x16x32_bf16 v[20:23], v[144:147], v[208:211], v[20:23]
	v_mfma_f32_16x16x32_bf16 v[12:15], v[158:161], v[208:211], v[12:15]
	v_mfma_f32_16x16x32_bf16 v[60:63], v[154:157], v[186:189], v[60:63]
	v_mfma_f32_16x16x32_bf16 v[56:59], v[162:165], v[186:189], v[56:59]
	v_mfma_f32_16x16x32_bf16 v[52:55], v[154:157], v[196:199], v[52:55]
	v_mfma_f32_16x16x32_bf16 v[44:47], v[162:165], v[196:199], v[44:47]
	v_mfma_f32_16x16x32_bf16 v[36:39], v[154:157], v[204:207], v[36:39]
	v_mfma_f32_16x16x32_bf16 v[28:31], v[162:165], v[204:207], v[28:31]
	v_mfma_f32_16x16x32_bf16 v[20:23], v[154:157], v[212:215], v[20:23]
	v_mfma_f32_16x16x32_bf16 v[12:15], v[162:165], v[212:215], v[12:15]
	s_setprio 0
	s_setprio 1
	v_mfma_f32_16x16x32_bf16 v[48:51], v[166:169], v[182:185], v[48:51]
	v_mfma_f32_16x16x32_bf16 v[40:43], v[174:177], v[182:185], v[40:43]
	v_mfma_f32_16x16x32_bf16 v[32:35], v[166:169], v[192:195], v[32:35]
	v_mfma_f32_16x16x32_bf16 v[24:27], v[174:177], v[192:195], v[24:27]
	v_mfma_f32_16x16x32_bf16 v[16:19], v[166:169], v[200:203], v[16:19]
	v_mfma_f32_16x16x32_bf16 v[8:11], v[174:177], v[200:203], v[8:11]
	v_mfma_f32_16x16x32_bf16 v[4:7], v[166:169], v[208:211], v[4:7]
	v_mfma_f32_16x16x32_bf16 v[0:3], v[174:177], v[208:211], v[0:3]
	v_mfma_f32_16x16x32_bf16 v[48:51], v[170:173], v[186:189], v[48:51]
	v_mfma_f32_16x16x32_bf16 v[40:43], v[178:181], v[186:189], v[40:43]
	v_mfma_f32_16x16x32_bf16 v[32:35], v[170:173], v[196:199], v[32:35]
	v_mfma_f32_16x16x32_bf16 v[24:27], v[178:181], v[196:199], v[24:27]
	v_mfma_f32_16x16x32_bf16 v[16:19], v[170:173], v[204:207], v[16:19]
	v_mfma_f32_16x16x32_bf16 v[8:11], v[178:181], v[204:207], v[8:11]
	v_mfma_f32_16x16x32_bf16 v[4:7], v[170:173], v[212:215], v[4:7]
	v_mfma_f32_16x16x32_bf16 v[0:3], v[178:181], v[212:215], v[0:3]
	s_setprio 0
	s_barrier
	s_add_i32 s68, 0, 0x18000
	s_add_i32 s69, 0, 0x1c000
	v_add_u32_e32 v162, s68, v149
	v_add_u32_e32 v178, s69, v149
	ds_read_b128 v[144:147], v162
	ds_read_b128 v[154:157], v162 offset:1024
	ds_read_b128 v[158:161], v162 offset:2048
	ds_read_b128 v[162:165], v162 offset:3072
	ds_read_b128 v[166:169], v178
	ds_read_b128 v[170:173], v178 offset:1024
	ds_read_b128 v[174:177], v178 offset:2048
	ds_read_b128 v[178:181], v178 offset:3072
	s_add_u32 s16, s22, 0x18000
	s_addc_u32 s17, s23, 0
	s_mov_b32 m0, s34
	ds_read_b128 v[182:185], v153 offset:32768
	ds_read_b128 v[186:189], v153 offset:33792
	ds_read_b128 v[192:195], v153 offset:34816
	ds_read_b128 v[196:199], v153 offset:35840
	ds_read_b128 v[200:203], v153 offset:36864
	ds_read_b128 v[204:207], v153 offset:37888
	ds_read_b128 v[208:211], v153 offset:38912
	ds_read_b128 v[212:215], v153 offset:39936
	global_load_lds_dwordx4 v134, s[16:17]
	s_mov_b32 m0, s35
	s_nop 0
	global_load_lds_dwordx4 v130, s[16:17]
	s_waitcnt vmcnt(8)
	s_waitcnt lgkmcnt(0)
	s_barrier
	s_setprio 1
	s_waitcnt lgkmcnt(0)
	v_mfma_f32_16x16x32_bf16 v[124:127], v[144:147], v[182:185], v[124:127]
	v_mfma_f32_16x16x32_bf16 v[120:123], v[158:161], v[182:185], v[120:123]
	v_mfma_f32_16x16x32_bf16 v[116:119], v[144:147], v[192:195], v[116:119]
	v_mfma_f32_16x16x32_bf16 v[108:111], v[158:161], v[192:195], v[108:111]
	v_mfma_f32_16x16x32_bf16 v[100:103], v[144:147], v[200:203], v[100:103]
	v_mfma_f32_16x16x32_bf16 v[92:95], v[158:161], v[200:203], v[92:95]
	v_mfma_f32_16x16x32_bf16 v[84:87], v[144:147], v[208:211], v[84:87]
	v_mfma_f32_16x16x32_bf16 v[76:79], v[158:161], v[208:211], v[76:79]
	v_mfma_f32_16x16x32_bf16 v[124:127], v[154:157], v[186:189], v[124:127]
	v_mfma_f32_16x16x32_bf16 v[120:123], v[162:165], v[186:189], v[120:123]
	v_mfma_f32_16x16x32_bf16 v[116:119], v[154:157], v[196:199], v[116:119]
	v_mfma_f32_16x16x32_bf16 v[108:111], v[162:165], v[196:199], v[108:111]
	v_mfma_f32_16x16x32_bf16 v[100:103], v[154:157], v[204:207], v[100:103]
	v_mfma_f32_16x16x32_bf16 v[92:95], v[162:165], v[204:207], v[92:95]
	v_mfma_f32_16x16x32_bf16 v[84:87], v[154:157], v[212:215], v[84:87]
	v_mfma_f32_16x16x32_bf16 v[76:79], v[162:165], v[212:215], v[76:79]
	s_setprio 0
	s_setprio 1
	v_mfma_f32_16x16x32_bf16 v[112:115], v[166:169], v[182:185], v[112:115]
	v_mfma_f32_16x16x32_bf16 v[104:107], v[174:177], v[182:185], v[104:107]
	v_mfma_f32_16x16x32_bf16 v[96:99], v[166:169], v[192:195], v[96:99]
	v_mfma_f32_16x16x32_bf16 v[88:91], v[174:177], v[192:195], v[88:91]
	v_mfma_f32_16x16x32_bf16 v[80:83], v[166:169], v[200:203], v[80:83]
	v_mfma_f32_16x16x32_bf16 v[72:75], v[174:177], v[200:203], v[72:75]
	v_mfma_f32_16x16x32_bf16 v[68:71], v[166:169], v[208:211], v[68:71]
	v_mfma_f32_16x16x32_bf16 v[64:67], v[174:177], v[208:211], v[64:67]
	v_mfma_f32_16x16x32_bf16 v[112:115], v[170:173], v[186:189], v[112:115]
	v_mfma_f32_16x16x32_bf16 v[104:107], v[178:181], v[186:189], v[104:107]
	v_mfma_f32_16x16x32_bf16 v[96:99], v[170:173], v[196:199], v[96:99]
	v_mfma_f32_16x16x32_bf16 v[88:91], v[178:181], v[196:199], v[88:91]
	v_mfma_f32_16x16x32_bf16 v[80:83], v[170:173], v[204:207], v[80:83]
	v_mfma_f32_16x16x32_bf16 v[72:75], v[178:181], v[204:207], v[72:75]
	v_mfma_f32_16x16x32_bf16 v[68:71], v[170:173], v[212:215], v[68:71]
	v_mfma_f32_16x16x32_bf16 v[64:67], v[178:181], v[212:215], v[64:67]
	s_setprio 0
	s_barrier
	s_add_i32 s16, s68, s28
	s_mov_b32 m0, s16
	ds_read_b128 v[182:185], v153 offset:49152
	ds_read_b128 v[186:189], v153 offset:50176
	ds_read_b128 v[192:195], v153 offset:51200
	ds_read_b128 v[196:199], v153 offset:52224
	ds_read_b128 v[200:203], v153 offset:53248
	ds_read_b128 v[204:207], v153 offset:54272
	ds_read_b128 v[208:211], v153 offset:55296
	ds_read_b128 v[212:215], v153 offset:56320
	global_load_lds_dwordx4 v132, s[98:99]
	s_add_i32 m0, s16, 0x2000
	s_add_u32 s16, s20, 0x18080
	s_addc_u32 s17, s21, 0
	s_add_i32 s20, s69, s28
	global_load_lds_dwordx4 v128, s[98:99]
	s_mov_b32 m0, s20
	s_nop 0
	global_load_lds_dwordx4 v132, s[16:17]
	s_add_i32 m0, s20, 0x2000
	s_nop 0
	global_load_lds_dwordx4 v128, s[16:17]
	s_mov_b32 m0, s43
	s_nop 0
	global_load_lds_dwordx4 v134, s[100:101]
	s_mov_b32 m0, s52
	s_nop 0
	global_load_lds_dwordx4 v130, s[100:101]
	s_waitcnt vmcnt(8)
	s_waitcnt lgkmcnt(0)
	s_barrier
	s_setprio 1
	s_waitcnt lgkmcnt(0)
	v_mfma_f32_16x16x32_bf16 v[60:63], v[144:147], v[182:185], v[60:63]
	v_mfma_f32_16x16x32_bf16 v[56:59], v[158:161], v[182:185], v[56:59]
	v_mfma_f32_16x16x32_bf16 v[52:55], v[144:147], v[192:195], v[52:55]
	v_mfma_f32_16x16x32_bf16 v[44:47], v[158:161], v[192:195], v[44:47]
	v_mfma_f32_16x16x32_bf16 v[36:39], v[144:147], v[200:203], v[36:39]
	v_mfma_f32_16x16x32_bf16 v[28:31], v[158:161], v[200:203], v[28:31]
	v_mfma_f32_16x16x32_bf16 v[20:23], v[144:147], v[208:211], v[20:23]
	v_mfma_f32_16x16x32_bf16 v[12:15], v[158:161], v[208:211], v[12:15]
	v_mfma_f32_16x16x32_bf16 v[60:63], v[154:157], v[186:189], v[60:63]
	v_mfma_f32_16x16x32_bf16 v[56:59], v[162:165], v[186:189], v[56:59]
	v_mfma_f32_16x16x32_bf16 v[52:55], v[154:157], v[196:199], v[52:55]
	v_mfma_f32_16x16x32_bf16 v[44:47], v[162:165], v[196:199], v[44:47]
	v_mfma_f32_16x16x32_bf16 v[36:39], v[154:157], v[204:207], v[36:39]
	v_mfma_f32_16x16x32_bf16 v[28:31], v[162:165], v[204:207], v[28:31]
	v_mfma_f32_16x16x32_bf16 v[20:23], v[154:157], v[212:215], v[20:23]
	v_mfma_f32_16x16x32_bf16 v[12:15], v[162:165], v[212:215], v[12:15]
	s_setprio 0
	s_setprio 1
	v_mfma_f32_16x16x32_bf16 v[48:51], v[166:169], v[182:185], v[48:51]
	v_mfma_f32_16x16x32_bf16 v[40:43], v[174:177], v[182:185], v[40:43]
	v_mfma_f32_16x16x32_bf16 v[32:35], v[166:169], v[192:195], v[32:35]
	v_mfma_f32_16x16x32_bf16 v[24:27], v[174:177], v[192:195], v[24:27]
	v_mfma_f32_16x16x32_bf16 v[16:19], v[166:169], v[200:203], v[16:19]
	v_mfma_f32_16x16x32_bf16 v[8:11], v[174:177], v[200:203], v[8:11]
	v_mfma_f32_16x16x32_bf16 v[4:7], v[166:169], v[208:211], v[4:7]
	v_mfma_f32_16x16x32_bf16 v[0:3], v[174:177], v[208:211], v[0:3]
	v_mfma_f32_16x16x32_bf16 v[48:51], v[170:173], v[186:189], v[48:51]
	v_mfma_f32_16x16x32_bf16 v[40:43], v[178:181], v[186:189], v[40:43]
	v_mfma_f32_16x16x32_bf16 v[32:35], v[170:173], v[196:199], v[32:35]
	v_mfma_f32_16x16x32_bf16 v[24:27], v[178:181], v[196:199], v[24:27]
	v_mfma_f32_16x16x32_bf16 v[16:19], v[170:173], v[204:207], v[16:19]
	v_mfma_f32_16x16x32_bf16 v[8:11], v[178:181], v[204:207], v[8:11]
	v_mfma_f32_16x16x32_bf16 v[4:7], v[170:173], v[212:215], v[4:7]
	v_mfma_f32_16x16x32_bf16 v[0:3], v[178:181], v[212:215], v[0:3]
	s_setprio 0
	s_barrier
	s_add_i32 s67, s67, 2
	s_add_u32 s65, s65, 0x100
	s_addc_u32 s66, s66, 0
	s_cmp_gt_u32 s67, 3
	s_mov_b64 s[16:17], s[18:19]
	s_cbranch_scc0 .LBB0_1266

.LBB0_1433:
	s_ashr_i32 s23, s22, 31
	s_lshl_b64 s[24:25], s[22:23], 19
	s_add_u32 s24, s56, s24
	s_addc_u32 s25, s57, s25
	s_and_b64 s[26:27], s[0:1], exec
	s_cselect_b32 s23, s25, s31
	s_cselect_b32 s55, s24, s30
	s_ashr_i32 s21, s20, 31
	s_lshl_b64 s[26:27], s[20:21], 19
	s_add_u32 s26, s53, s26
	s_addc_u32 s27, s60, s27
	s_and_b64 s[42:43], s[0:1], exec
	s_cselect_b32 s21, s27, s35
	s_cselect_b32 s74, s26, s34
	s_add_u32 s30, s30, 0x40080
	s_addc_u32 s31, s31, 0
	s_add_u32 s75, s34, 0x100
	s_addc_u32 s76, s35, 0
	s_mov_b32 s77, -2
	ds_read_b128 v[152:155], v149
	ds_read_b128 v[156:159], v149 offset:1024
	ds_read_b128 v[160:163], v149 offset:2048
	ds_read_b128 v[164:167], v149 offset:3072
	ds_read_b128 v[168:171], v150
	ds_read_b128 v[172:175], v150 offset:1024
	ds_read_b128 v[176:179], v150 offset:2048
	ds_read_b128 v[180:183], v150 offset:3072
	s_add_u32 s34, s30, 0xfffc0080
	s_addc_u32 s35, s31, -1
	s_cmp_eq_u32 s77, 12
	s_cselect_b32 s43, s23, s35
	s_cselect_b32 s42, s55, s34
	s_cselect_b32 s35, s21, s76
	s_cselect_b32 s34, s74, s75
	s_add_i32 m0, s29, 0xc000
	ds_read_b128 v[184:187], v151
	ds_read_b128 v[192:195], v151 offset:1024
	ds_read_b128 v[196:199], v151 offset:2048
	ds_read_b128 v[200:203], v151 offset:3072
	ds_read_b128 v[204:207], v151 offset:4096
	ds_read_b128 v[208:211], v151 offset:5120
	ds_read_b128 v[212:215], v151 offset:6144
	ds_read_b128 v[216:219], v151 offset:7168
	global_load_lds_dwordx4 v136, s[30:31]
	s_add_i32 m0, s29, 0xe000
	s_nop 0
	global_load_lds_dwordx4 v138, s[30:31]
	s_waitcnt vmcnt(8)
	s_waitcnt lgkmcnt(0)
	s_barrier
	s_setprio 1
	s_waitcnt lgkmcnt(0)
	v_mfma_f32_16x16x32_bf16 v[124:127], v[152:155], v[184:187], 0
	v_mfma_f32_16x16x32_bf16 v[120:123], v[160:163], v[184:187], 0
	v_mfma_f32_16x16x32_bf16 v[116:119], v[152:155], v[196:199], 0
	v_mfma_f32_16x16x32_bf16 v[108:111], v[160:163], v[196:199], 0
	v_mfma_f32_16x16x32_bf16 v[100:103], v[152:155], v[204:207], 0
	v_mfma_f32_16x16x32_bf16 v[92:95], v[160:163], v[204:207], 0
	v_mfma_f32_16x16x32_bf16 v[84:87], v[152:155], v[212:215], 0
	v_mfma_f32_16x16x32_bf16 v[76:79], v[160:163], v[212:215], 0
	v_mfma_f32_16x16x32_bf16 v[124:127], v[156:159], v[192:195], v[124:127]
	v_mfma_f32_16x16x32_bf16 v[120:123], v[164:167], v[192:195], v[120:123]
	v_mfma_f32_16x16x32_bf16 v[116:119], v[156:159], v[200:203], v[116:119]
	v_mfma_f32_16x16x32_bf16 v[108:111], v[164:167], v[200:203], v[108:111]
	v_mfma_f32_16x16x32_bf16 v[100:103], v[156:159], v[208:211], v[100:103]
	v_mfma_f32_16x16x32_bf16 v[92:95], v[164:167], v[208:211], v[92:95]
	v_mfma_f32_16x16x32_bf16 v[84:87], v[156:159], v[216:219], v[84:87]
	v_mfma_f32_16x16x32_bf16 v[76:79], v[164:167], v[216:219], v[76:79]
	s_setprio 0
	s_setprio 1
	v_mfma_f32_16x16x32_bf16 v[112:115], v[168:171], v[184:187], 0
	v_mfma_f32_16x16x32_bf16 v[104:107], v[176:179], v[184:187], 0
	v_mfma_f32_16x16x32_bf16 v[96:99], v[168:171], v[196:199], 0
	v_mfma_f32_16x16x32_bf16 v[88:91], v[176:179], v[196:199], 0
	v_mfma_f32_16x16x32_bf16 v[80:83], v[168:171], v[204:207], 0
	v_mfma_f32_16x16x32_bf16 v[72:75], v[176:179], v[204:207], 0
	v_mfma_f32_16x16x32_bf16 v[68:71], v[168:171], v[212:215], 0
	v_mfma_f32_16x16x32_bf16 v[64:67], v[176:179], v[212:215], 0
	v_mfma_f32_16x16x32_bf16 v[112:115], v[172:175], v[192:195], v[112:115]
	v_mfma_f32_16x16x32_bf16 v[104:107], v[180:183], v[192:195], v[104:107]
	v_mfma_f32_16x16x32_bf16 v[96:99], v[172:175], v[200:203], v[96:99]
	v_mfma_f32_16x16x32_bf16 v[88:91], v[180:183], v[200:203], v[88:91]
	v_mfma_f32_16x16x32_bf16 v[80:83], v[172:175], v[208:211], v[80:83]
	v_mfma_f32_16x16x32_bf16 v[72:75], v[180:183], v[208:211], v[72:75]
	v_mfma_f32_16x16x32_bf16 v[68:71], v[172:175], v[216:219], v[68:71]
	v_mfma_f32_16x16x32_bf16 v[64:67], v[180:183], v[216:219], v[64:67]
	s_setprio 0
	s_barrier
	s_add_i32 s79, s68, s61
	s_add_u32 s98, s34, 0x80
	s_addc_u32 s99, s35, 0
	s_mov_b32 m0, s79
	ds_read_b128 v[184:187], v151 offset:16384
	ds_read_b128 v[192:195], v151 offset:17408
	ds_read_b128 v[196:199], v151 offset:18432
	ds_read_b128 v[200:203], v151 offset:19456
	ds_read_b128 v[204:207], v151 offset:20480
	ds_read_b128 v[208:211], v151 offset:21504
	ds_read_b128 v[212:215], v151 offset:22528
	ds_read_b128 v[216:219], v151 offset:23552
	global_load_lds_dwordx4 v130, s[34:35]
	s_add_i32 m0, s79, 0x2000
	s_add_u32 s80, s34, 0x40000
	s_addc_u32 s81, s35, 0
	s_add_i32 s79, s69, s61
	global_load_lds_dwordx4 v134, s[34:35]
	s_mov_b32 m0, s79
	s_add_u32 s100, s42, 0x80
	s_addc_u32 s101, s43, 0
	global_load_lds_dwordx4 v130, s[80:81]
	s_add_i32 m0, s79, 0x2000
	s_nop 0
	global_load_lds_dwordx4 v134, s[80:81]
	s_mov_b32 m0, s29
	s_nop 0
	global_load_lds_dwordx4 v128, s[42:43]
	s_mov_b32 m0, s33
	s_nop 0
	global_load_lds_dwordx4 v132, s[42:43]
	s_waitcnt vmcnt(8)
	s_waitcnt lgkmcnt(0)
	s_barrier
	s_setprio 1
	s_waitcnt lgkmcnt(0)
	v_mfma_f32_16x16x32_bf16 v[60:63], v[152:155], v[184:187], 0
	v_mfma_f32_16x16x32_bf16 v[56:59], v[160:163], v[184:187], 0
	v_mfma_f32_16x16x32_bf16 v[52:55], v[152:155], v[196:199], 0
	v_mfma_f32_16x16x32_bf16 v[44:47], v[160:163], v[196:199], 0
	v_mfma_f32_16x16x32_bf16 v[36:39], v[152:155], v[204:207], 0
	v_mfma_f32_16x16x32_bf16 v[28:31], v[160:163], v[204:207], 0
	v_mfma_f32_16x16x32_bf16 v[20:23], v[152:155], v[212:215], 0
	v_mfma_f32_16x16x32_bf16 v[12:15], v[160:163], v[212:215], 0
	v_mfma_f32_16x16x32_bf16 v[60:63], v[156:159], v[192:195], v[60:63]
	v_mfma_f32_16x16x32_bf16 v[56:59], v[164:167], v[192:195], v[56:59]
	v_mfma_f32_16x16x32_bf16 v[52:55], v[156:159], v[200:203], v[52:55]
	v_mfma_f32_16x16x32_bf16 v[44:47], v[164:167], v[200:203], v[44:47]
	v_mfma_f32_16x16x32_bf16 v[36:39], v[156:159], v[208:211], v[36:39]
	v_mfma_f32_16x16x32_bf16 v[28:31], v[164:167], v[208:211], v[28:31]
	v_mfma_f32_16x16x32_bf16 v[20:23], v[156:159], v[216:219], v[20:23]
	v_mfma_f32_16x16x32_bf16 v[12:15], v[164:167], v[216:219], v[12:15]
	s_setprio 0
	s_setprio 1
	v_mfma_f32_16x16x32_bf16 v[48:51], v[168:171], v[184:187], 0
	v_mfma_f32_16x16x32_bf16 v[40:43], v[176:179], v[184:187], 0
	v_mfma_f32_16x16x32_bf16 v[32:35], v[168:171], v[196:199], 0
	v_mfma_f32_16x16x32_bf16 v[24:27], v[176:179], v[196:199], 0
	v_mfma_f32_16x16x32_bf16 v[16:19], v[168:171], v[204:207], 0
	v_mfma_f32_16x16x32_bf16 v[8:11], v[176:179], v[204:207], 0
	v_mfma_f32_16x16x32_bf16 v[4:7], v[168:171], v[212:215], 0
	v_mfma_f32_16x16x32_bf16 v[0:3], v[176:179], v[212:215], 0
	v_mfma_f32_16x16x32_bf16 v[48:51], v[172:175], v[192:195], v[48:51]
	v_mfma_f32_16x16x32_bf16 v[40:43], v[180:183], v[192:195], v[40:43]
	v_mfma_f32_16x16x32_bf16 v[32:35], v[172:175], v[200:203], v[32:35]
	v_mfma_f32_16x16x32_bf16 v[24:27], v[180:183], v[200:203], v[24:27]
	v_mfma_f32_16x16x32_bf16 v[16:19], v[172:175], v[208:211], v[16:19]
	v_mfma_f32_16x16x32_bf16 v[8:11], v[180:183], v[208:211], v[8:11]
	v_mfma_f32_16x16x32_bf16 v[4:7], v[172:175], v[216:219], v[4:7]
	v_mfma_f32_16x16x32_bf16 v[0:3], v[180:183], v[216:219], v[0:3]
	s_setprio 0
	s_barrier
	s_add_i32 s79, 0, 0x18000
	s_add_i32 s80, 0, 0x1c000
	v_add_u32_e32 v164, s79, v147
	v_add_u32_e32 v180, s80, v147
	ds_read_b128 v[152:155], v164
	ds_read_b128 v[156:159], v164 offset:1024
	ds_read_b128 v[160:163], v164 offset:2048
	ds_read_b128 v[164:167], v164 offset:3072
	ds_read_b128 v[168:171], v180
	ds_read_b128 v[172:175], v180 offset:1024
	ds_read_b128 v[176:179], v180 offset:2048
	ds_read_b128 v[180:183], v180 offset:3072
	s_add_u32 s42, s42, 0x40000
	s_addc_u32 s43, s43, 0
	s_mov_b32 m0, s62
	ds_read_b128 v[184:187], v151 offset:32768
	ds_read_b128 v[192:195], v151 offset:33792
	ds_read_b128 v[196:199], v151 offset:34816
	ds_read_b128 v[200:203], v151 offset:35840
	ds_read_b128 v[204:207], v151 offset:36864
	ds_read_b128 v[208:211], v151 offset:37888
	ds_read_b128 v[212:215], v151 offset:38912
	ds_read_b128 v[216:219], v151 offset:39936
	global_load_lds_dwordx4 v128, s[42:43]
	s_mov_b32 m0, s63
	s_nop 0
	global_load_lds_dwordx4 v132, s[42:43]
	s_waitcnt vmcnt(8)
	s_waitcnt lgkmcnt(0)
	s_barrier
	s_setprio 1
	s_waitcnt lgkmcnt(0)
	v_mfma_f32_16x16x32_bf16 v[124:127], v[152:155], v[184:187], v[124:127]
	v_mfma_f32_16x16x32_bf16 v[120:123], v[160:163], v[184:187], v[120:123]
	v_mfma_f32_16x16x32_bf16 v[116:119], v[152:155], v[196:199], v[116:119]
	v_mfma_f32_16x16x32_bf16 v[108:111], v[160:163], v[196:199], v[108:111]
	v_mfma_f32_16x16x32_bf16 v[100:103], v[152:155], v[204:207], v[100:103]
	v_mfma_f32_16x16x32_bf16 v[92:95], v[160:163], v[204:207], v[92:95]
	v_mfma_f32_16x16x32_bf16 v[84:87], v[152:155], v[212:215], v[84:87]
	v_mfma_f32_16x16x32_bf16 v[76:79], v[160:163], v[212:215], v[76:79]
	v_mfma_f32_16x16x32_bf16 v[124:127], v[156:159], v[192:195], v[124:127]
	v_mfma_f32_16x16x32_bf16 v[120:123], v[164:167], v[192:195], v[120:123]
	v_mfma_f32_16x16x32_bf16 v[116:119], v[156:159], v[200:203], v[116:119]
	v_mfma_f32_16x16x32_bf16 v[108:111], v[164:167], v[200:203], v[108:111]
	v_mfma_f32_16x16x32_bf16 v[100:103], v[156:159], v[208:211], v[100:103]
	v_mfma_f32_16x16x32_bf16 v[92:95], v[164:167], v[208:211], v[92:95]
	v_mfma_f32_16x16x32_bf16 v[84:87], v[156:159], v[216:219], v[84:87]
	v_mfma_f32_16x16x32_bf16 v[76:79], v[164:167], v[216:219], v[76:79]
	s_setprio 0
	s_setprio 1
	v_mfma_f32_16x16x32_bf16 v[112:115], v[168:171], v[184:187], v[112:115]
	v_mfma_f32_16x16x32_bf16 v[104:107], v[176:179], v[184:187], v[104:107]
	v_mfma_f32_16x16x32_bf16 v[96:99], v[168:171], v[196:199], v[96:99]
	v_mfma_f32_16x16x32_bf16 v[88:91], v[176:179], v[196:199], v[88:91]
	v_mfma_f32_16x16x32_bf16 v[80:83], v[168:171], v[204:207], v[80:83]
	v_mfma_f32_16x16x32_bf16 v[72:75], v[176:179], v[204:207], v[72:75]
	v_mfma_f32_16x16x32_bf16 v[68:71], v[168:171], v[212:215], v[68:71]
	v_mfma_f32_16x16x32_bf16 v[64:67], v[176:179], v[212:215], v[64:67]
	v_mfma_f32_16x16x32_bf16 v[112:115], v[172:175], v[192:195], v[112:115]
	v_mfma_f32_16x16x32_bf16 v[104:107], v[180:183], v[192:195], v[104:107]
	v_mfma_f32_16x16x32_bf16 v[96:99], v[172:175], v[200:203], v[96:99]
	v_mfma_f32_16x16x32_bf16 v[88:91], v[180:183], v[200:203], v[88:91]
	v_mfma_f32_16x16x32_bf16 v[80:83], v[172:175], v[208:211], v[80:83]
	v_mfma_f32_16x16x32_bf16 v[72:75], v[180:183], v[208:211], v[72:75]
	v_mfma_f32_16x16x32_bf16 v[68:71], v[172:175], v[216:219], v[68:71]
	v_mfma_f32_16x16x32_bf16 v[64:67], v[180:183], v[216:219], v[64:67]
	s_setprio 0
	s_barrier
	s_add_i32 s42, s79, s61
	s_mov_b32 m0, s42
	ds_read_b128 v[184:187], v151 offset:49152
	ds_read_b128 v[192:195], v151 offset:50176
	ds_read_b128 v[196:199], v151 offset:51200
	ds_read_b128 v[200:203], v151 offset:52224
	ds_read_b128 v[204:207], v151 offset:53248
	ds_read_b128 v[208:211], v151 offset:54272
	ds_read_b128 v[212:215], v151 offset:55296
	ds_read_b128 v[216:219], v151 offset:56320
	global_load_lds_dwordx4 v130, s[98:99]
	s_add_i32 m0, s42, 0x2000
	s_add_u32 s34, s34, 0x40080
	s_addc_u32 s35, s35, 0
	s_add_i32 s42, s80, s61
	global_load_lds_dwordx4 v134, s[98:99]
	s_mov_b32 m0, s42
	s_nop 0
	global_load_lds_dwordx4 v130, s[34:35]
	s_add_i32 m0, s42, 0x2000
	s_nop 0
	global_load_lds_dwordx4 v134, s[34:35]
	s_mov_b32 m0, s65
	s_nop 0
	global_load_lds_dwordx4 v128, s[100:101]
	s_mov_b32 m0, s66
	s_nop 0
	global_load_lds_dwordx4 v132, s[100:101]
	s_waitcnt vmcnt(8)
	s_waitcnt lgkmcnt(0)
	s_barrier
	s_setprio 1
	s_waitcnt lgkmcnt(0)
	v_mfma_f32_16x16x32_bf16 v[60:63], v[152:155], v[184:187], v[60:63]
	v_mfma_f32_16x16x32_bf16 v[56:59], v[160:163], v[184:187], v[56:59]
	v_mfma_f32_16x16x32_bf16 v[52:55], v[152:155], v[196:199], v[52:55]
	v_mfma_f32_16x16x32_bf16 v[44:47], v[160:163], v[196:199], v[44:47]
	v_mfma_f32_16x16x32_bf16 v[36:39], v[152:155], v[204:207], v[36:39]
	v_mfma_f32_16x16x32_bf16 v[28:31], v[160:163], v[204:207], v[28:31]
	v_mfma_f32_16x16x32_bf16 v[20:23], v[152:155], v[212:215], v[20:23]
	v_mfma_f32_16x16x32_bf16 v[12:15], v[160:163], v[212:215], v[12:15]
	v_mfma_f32_16x16x32_bf16 v[60:63], v[156:159], v[192:195], v[60:63]
	v_mfma_f32_16x16x32_bf16 v[56:59], v[164:167], v[192:195], v[56:59]
	v_mfma_f32_16x16x32_bf16 v[52:55], v[156:159], v[200:203], v[52:55]
	v_mfma_f32_16x16x32_bf16 v[44:47], v[164:167], v[200:203], v[44:47]
	v_mfma_f32_16x16x32_bf16 v[36:39], v[156:159], v[208:211], v[36:39]
	v_mfma_f32_16x16x32_bf16 v[28:31], v[164:167], v[208:211], v[28:31]
	v_mfma_f32_16x16x32_bf16 v[20:23], v[156:159], v[216:219], v[20:23]
	v_mfma_f32_16x16x32_bf16 v[12:15], v[164:167], v[216:219], v[12:15]
	s_setprio 0
	s_setprio 1
	v_mfma_f32_16x16x32_bf16 v[48:51], v[168:171], v[184:187], v[48:51]
	v_mfma_f32_16x16x32_bf16 v[40:43], v[176:179], v[184:187], v[40:43]
	v_mfma_f32_16x16x32_bf16 v[32:35], v[168:171], v[196:199], v[32:35]
	v_mfma_f32_16x16x32_bf16 v[24:27], v[176:179], v[196:199], v[24:27]
	v_mfma_f32_16x16x32_bf16 v[16:19], v[168:171], v[204:207], v[16:19]
	v_mfma_f32_16x16x32_bf16 v[8:11], v[176:179], v[204:207], v[8:11]
	v_mfma_f32_16x16x32_bf16 v[4:7], v[168:171], v[212:215], v[4:7]
	v_mfma_f32_16x16x32_bf16 v[0:3], v[176:179], v[212:215], v[0:3]
	v_mfma_f32_16x16x32_bf16 v[48:51], v[172:175], v[192:195], v[48:51]
	v_mfma_f32_16x16x32_bf16 v[40:43], v[180:183], v[192:195], v[40:43]
	v_mfma_f32_16x16x32_bf16 v[32:35], v[172:175], v[200:203], v[32:35]
	v_mfma_f32_16x16x32_bf16 v[24:27], v[180:183], v[200:203], v[24:27]
	v_mfma_f32_16x16x32_bf16 v[16:19], v[172:175], v[208:211], v[16:19]
	v_mfma_f32_16x16x32_bf16 v[8:11], v[180:183], v[208:211], v[8:11]
	v_mfma_f32_16x16x32_bf16 v[4:7], v[172:175], v[216:219], v[4:7]
	v_mfma_f32_16x16x32_bf16 v[0:3], v[180:183], v[216:219], v[0:3]
	s_setprio 0
	s_barrier
	s_add_i32 s77, s77, 2
	s_add_u32 s30, s30, 0x100
	s_addc_u32 s31, s31, 0
	s_add_u32 s75, s75, 0x100
	s_addc_u32 s76, s76, 0
	s_cmp_gt_u32 s77, 13
	s_cbranch_scc0 .LBB0_1434
	s_branch .Lpeel_exit10
.LBB0_1434:
	ds_read_b128 v[152:155], v149
	ds_read_b128 v[156:159], v149 offset:1024
	ds_read_b128 v[160:163], v149 offset:2048
	ds_read_b128 v[164:167], v149 offset:3072
	ds_read_b128 v[168:171], v150
	ds_read_b128 v[172:175], v150 offset:1024
	ds_read_b128 v[176:179], v150 offset:2048
	ds_read_b128 v[180:183], v150 offset:3072
	s_add_u32 s34, s30, 0xfffc0080
	s_addc_u32 s35, s31, -1
	s_cmp_eq_u32 s77, 12
	s_cselect_b32 s43, s23, s35
	s_cselect_b32 s42, s55, s34
	s_cselect_b32 s35, s21, s76
	s_cselect_b32 s34, s74, s75
	s_add_i32 m0, s29, 0xc000
	ds_read_b128 v[184:187], v151
	ds_read_b128 v[192:195], v151 offset:1024
	ds_read_b128 v[196:199], v151 offset:2048
	ds_read_b128 v[200:203], v151 offset:3072
	ds_read_b128 v[204:207], v151 offset:4096
	ds_read_b128 v[208:211], v151 offset:5120
	ds_read_b128 v[212:215], v151 offset:6144
	ds_read_b128 v[216:219], v151 offset:7168
	global_load_lds_dwordx4 v136, s[30:31]
	s_add_i32 m0, s29, 0xe000
	s_nop 0
	global_load_lds_dwordx4 v138, s[30:31]
	s_waitcnt vmcnt(8)
	s_waitcnt lgkmcnt(0)
	s_barrier
	s_setprio 1
	s_waitcnt lgkmcnt(0)
	v_mfma_f32_16x16x32_bf16 v[124:127], v[152:155], v[184:187], v[124:127]
	v_mfma_f32_16x16x32_bf16 v[120:123], v[160:163], v[184:187], v[120:123]
	v_mfma_f32_16x16x32_bf16 v[116:119], v[152:155], v[196:199], v[116:119]
	v_mfma_f32_16x16x32_bf16 v[108:111], v[160:163], v[196:199], v[108:111]
	v_mfma_f32_16x16x32_bf16 v[100:103], v[152:155], v[204:207], v[100:103]
	v_mfma_f32_16x16x32_bf16 v[92:95], v[160:163], v[204:207], v[92:95]
	v_mfma_f32_16x16x32_bf16 v[84:87], v[152:155], v[212:215], v[84:87]
	v_mfma_f32_16x16x32_bf16 v[76:79], v[160:163], v[212:215], v[76:79]
	v_mfma_f32_16x16x32_bf16 v[124:127], v[156:159], v[192:195], v[124:127]
	v_mfma_f32_16x16x32_bf16 v[120:123], v[164:167], v[192:195], v[120:123]
	v_mfma_f32_16x16x32_bf16 v[116:119], v[156:159], v[200:203], v[116:119]
	v_mfma_f32_16x16x32_bf16 v[108:111], v[164:167], v[200:203], v[108:111]
	v_mfma_f32_16x16x32_bf16 v[100:103], v[156:159], v[208:211], v[100:103]
	v_mfma_f32_16x16x32_bf16 v[92:95], v[164:167], v[208:211], v[92:95]
	v_mfma_f32_16x16x32_bf16 v[84:87], v[156:159], v[216:219], v[84:87]
	v_mfma_f32_16x16x32_bf16 v[76:79], v[164:167], v[216:219], v[76:79]
	s_setprio 0
	s_setprio 1
	v_mfma_f32_16x16x32_bf16 v[112:115], v[168:171], v[184:187], v[112:115]
	v_mfma_f32_16x16x32_bf16 v[104:107], v[176:179], v[184:187], v[104:107]
	v_mfma_f32_16x16x32_bf16 v[96:99], v[168:171], v[196:199], v[96:99]
	v_mfma_f32_16x16x32_bf16 v[88:91], v[176:179], v[196:199], v[88:91]
	v_mfma_f32_16x16x32_bf16 v[80:83], v[168:171], v[204:207], v[80:83]
	v_mfma_f32_16x16x32_bf16 v[72:75], v[176:179], v[204:207], v[72:75]
	v_mfma_f32_16x16x32_bf16 v[68:71], v[168:171], v[212:215], v[68:71]
	v_mfma_f32_16x16x32_bf16 v[64:67], v[176:179], v[212:215], v[64:67]
	v_mfma_f32_16x16x32_bf16 v[112:115], v[172:175], v[192:195], v[112:115]
	v_mfma_f32_16x16x32_bf16 v[104:107], v[180:183], v[192:195], v[104:107]
	v_mfma_f32_16x16x32_bf16 v[96:99], v[172:175], v[200:203], v[96:99]
	v_mfma_f32_16x16x32_bf16 v[88:91], v[180:183], v[200:203], v[88:91]
	v_mfma_f32_16x16x32_bf16 v[80:83], v[172:175], v[208:211], v[80:83]
	v_mfma_f32_16x16x32_bf16 v[72:75], v[180:183], v[208:211], v[72:75]
	v_mfma_f32_16x16x32_bf16 v[68:71], v[172:175], v[216:219], v[68:71]
	v_mfma_f32_16x16x32_bf16 v[64:67], v[180:183], v[216:219], v[64:67]
	s_setprio 0
	s_barrier
	s_add_i32 s79, s68, s61
	s_add_u32 s98, s34, 0x80
	s_addc_u32 s99, s35, 0
	s_mov_b32 m0, s79
	ds_read_b128 v[184:187], v151 offset:16384
	ds_read_b128 v[192:195], v151 offset:17408
	ds_read_b128 v[196:199], v151 offset:18432
	ds_read_b128 v[200:203], v151 offset:19456
	ds_read_b128 v[204:207], v151 offset:20480
	ds_read_b128 v[208:211], v151 offset:21504
	ds_read_b128 v[212:215], v151 offset:22528
	ds_read_b128 v[216:219], v151 offset:23552
	global_load_lds_dwordx4 v130, s[34:35]
	s_add_i32 m0, s79, 0x2000
	s_add_u32 s80, s34, 0x40000
	s_addc_u32 s81, s35, 0
	s_add_i32 s79, s69, s61
	global_load_lds_dwordx4 v134, s[34:35]
	s_mov_b32 m0, s79
	s_add_u32 s100, s42, 0x80
	s_addc_u32 s101, s43, 0
	global_load_lds_dwordx4 v130, s[80:81]
	s_add_i32 m0, s79, 0x2000
	s_nop 0
	global_load_lds_dwordx4 v134, s[80:81]
	s_mov_b32 m0, s29
	s_nop 0
	global_load_lds_dwordx4 v128, s[42:43]
	s_mov_b32 m0, s33
	s_nop 0
	global_load_lds_dwordx4 v132, s[42:43]
	s_waitcnt vmcnt(8)
	s_waitcnt lgkmcnt(0)
	s_barrier
	s_setprio 1
	s_waitcnt lgkmcnt(0)
	v_mfma_f32_16x16x32_bf16 v[60:63], v[152:155], v[184:187], v[60:63]
	v_mfma_f32_16x16x32_bf16 v[56:59], v[160:163], v[184:187], v[56:59]
	v_mfma_f32_16x16x32_bf16 v[52:55], v[152:155], v[196:199], v[52:55]
	v_mfma_f32_16x16x32_bf16 v[44:47], v[160:163], v[196:199], v[44:47]
	v_mfma_f32_16x16x32_bf16 v[36:39], v[152:155], v[204:207], v[36:39]
	v_mfma_f32_16x16x32_bf16 v[28:31], v[160:163], v[204:207], v[28:31]
	v_mfma_f32_16x16x32_bf16 v[20:23], v[152:155], v[212:215], v[20:23]
	v_mfma_f32_16x16x32_bf16 v[12:15], v[160:163], v[212:215], v[12:15]
	v_mfma_f32_16x16x32_bf16 v[60:63], v[156:159], v[192:195], v[60:63]
	v_mfma_f32_16x16x32_bf16 v[56:59], v[164:167], v[192:195], v[56:59]
	v_mfma_f32_16x16x32_bf16 v[52:55], v[156:159], v[200:203], v[52:55]
	v_mfma_f32_16x16x32_bf16 v[44:47], v[164:167], v[200:203], v[44:47]
	v_mfma_f32_16x16x32_bf16 v[36:39], v[156:159], v[208:211], v[36:39]
	v_mfma_f32_16x16x32_bf16 v[28:31], v[164:167], v[208:211], v[28:31]
	v_mfma_f32_16x16x32_bf16 v[20:23], v[156:159], v[216:219], v[20:23]
	v_mfma_f32_16x16x32_bf16 v[12:15], v[164:167], v[216:219], v[12:15]
	s_setprio 0
	s_setprio 1
	v_mfma_f32_16x16x32_bf16 v[48:51], v[168:171], v[184:187], v[48:51]
	v_mfma_f32_16x16x32_bf16 v[40:43], v[176:179], v[184:187], v[40:43]
	v_mfma_f32_16x16x32_bf16 v[32:35], v[168:171], v[196:199], v[32:35]
	v_mfma_f32_16x16x32_bf16 v[24:27], v[176:179], v[196:199], v[24:27]
	v_mfma_f32_16x16x32_bf16 v[16:19], v[168:171], v[204:207], v[16:19]
	v_mfma_f32_16x16x32_bf16 v[8:11], v[176:179], v[204:207], v[8:11]
	v_mfma_f32_16x16x32_bf16 v[4:7], v[168:171], v[212:215], v[4:7]
	v_mfma_f32_16x16x32_bf16 v[0:3], v[176:179], v[212:215], v[0:3]
	v_mfma_f32_16x16x32_bf16 v[48:51], v[172:175], v[192:195], v[48:51]
	v_mfma_f32_16x16x32_bf16 v[40:43], v[180:183], v[192:195], v[40:43]
	v_mfma_f32_16x16x32_bf16 v[32:35], v[172:175], v[200:203], v[32:35]
	v_mfma_f32_16x16x32_bf16 v[24:27], v[180:183], v[200:203], v[24:27]
	v_mfma_f32_16x16x32_bf16 v[16:19], v[172:175], v[208:211], v[16:19]
	v_mfma_f32_16x16x32_bf16 v[8:11], v[180:183], v[208:211], v[8:11]
	v_mfma_f32_16x16x32_bf16 v[4:7], v[172:175], v[216:219], v[4:7]
	v_mfma_f32_16x16x32_bf16 v[0:3], v[180:183], v[216:219], v[0:3]
	s_setprio 0
	s_barrier
	s_add_i32 s79, 0, 0x18000
	s_add_i32 s80, 0, 0x1c000
	v_add_u32_e32 v164, s79, v147
	v_add_u32_e32 v180, s80, v147
	ds_read_b128 v[152:155], v164
	ds_read_b128 v[156:159], v164 offset:1024
	ds_read_b128 v[160:163], v164 offset:2048
	ds_read_b128 v[164:167], v164 offset:3072
	ds_read_b128 v[168:171], v180
	ds_read_b128 v[172:175], v180 offset:1024
	ds_read_b128 v[176:179], v180 offset:2048
	ds_read_b128 v[180:183], v180 offset:3072
	s_add_u32 s42, s42, 0x40000
	s_addc_u32 s43, s43, 0
	s_mov_b32 m0, s62
	ds_read_b128 v[184:187], v151 offset:32768
	ds_read_b128 v[192:195], v151 offset:33792
	ds_read_b128 v[196:199], v151 offset:34816
	ds_read_b128 v[200:203], v151 offset:35840
	ds_read_b128 v[204:207], v151 offset:36864
	ds_read_b128 v[208:211], v151 offset:37888
	ds_read_b128 v[212:215], v151 offset:38912
	ds_read_b128 v[216:219], v151 offset:39936
	global_load_lds_dwordx4 v128, s[42:43]
	s_mov_b32 m0, s63
	s_nop 0
	global_load_lds_dwordx4 v132, s[42:43]
	s_waitcnt vmcnt(8)
	s_waitcnt lgkmcnt(0)
	s_barrier
	s_setprio 1
	s_waitcnt lgkmcnt(0)
	v_mfma_f32_16x16x32_bf16 v[124:127], v[152:155], v[184:187], v[124:127]
	v_mfma_f32_16x16x32_bf16 v[120:123], v[160:163], v[184:187], v[120:123]
	v_mfma_f32_16x16x32_bf16 v[116:119], v[152:155], v[196:199], v[116:119]
	v_mfma_f32_16x16x32_bf16 v[108:111], v[160:163], v[196:199], v[108:111]
	v_mfma_f32_16x16x32_bf16 v[100:103], v[152:155], v[204:207], v[100:103]
	v_mfma_f32_16x16x32_bf16 v[92:95], v[160:163], v[204:207], v[92:95]
	v_mfma_f32_16x16x32_bf16 v[84:87], v[152:155], v[212:215], v[84:87]
	v_mfma_f32_16x16x32_bf16 v[76:79], v[160:163], v[212:215], v[76:79]
	v_mfma_f32_16x16x32_bf16 v[124:127], v[156:159], v[192:195], v[124:127]
	v_mfma_f32_16x16x32_bf16 v[120:123], v[164:167], v[192:195], v[120:123]
	v_mfma_f32_16x16x32_bf16 v[116:119], v[156:159], v[200:203], v[116:119]
	v_mfma_f32_16x16x32_bf16 v[108:111], v[164:167], v[200:203], v[108:111]
	v_mfma_f32_16x16x32_bf16 v[100:103], v[156:159], v[208:211], v[100:103]
	v_mfma_f32_16x16x32_bf16 v[92:95], v[164:167], v[208:211], v[92:95]
	v_mfma_f32_16x16x32_bf16 v[84:87], v[156:159], v[216:219], v[84:87]
	v_mfma_f32_16x16x32_bf16 v[76:79], v[164:167], v[216:219], v[76:79]
	s_setprio 0
	s_setprio 1
	v_mfma_f32_16x16x32_bf16 v[112:115], v[168:171], v[184:187], v[112:115]
	v_mfma_f32_16x16x32_bf16 v[104:107], v[176:179], v[184:187], v[104:107]
	v_mfma_f32_16x16x32_bf16 v[96:99], v[168:171], v[196:199], v[96:99]
	v_mfma_f32_16x16x32_bf16 v[88:91], v[176:179], v[196:199], v[88:91]
	v_mfma_f32_16x16x32_bf16 v[80:83], v[168:171], v[204:207], v[80:83]
	v_mfma_f32_16x16x32_bf16 v[72:75], v[176:179], v[204:207], v[72:75]
	v_mfma_f32_16x16x32_bf16 v[68:71], v[168:171], v[212:215], v[68:71]
	v_mfma_f32_16x16x32_bf16 v[64:67], v[176:179], v[212:215], v[64:67]
	v_mfma_f32_16x16x32_bf16 v[112:115], v[172:175], v[192:195], v[112:115]
	v_mfma_f32_16x16x32_bf16 v[104:107], v[180:183], v[192:195], v[104:107]
	v_mfma_f32_16x16x32_bf16 v[96:99], v[172:175], v[200:203], v[96:99]
	v_mfma_f32_16x16x32_bf16 v[88:91], v[180:183], v[200:203], v[88:91]
	v_mfma_f32_16x16x32_bf16 v[80:83], v[172:175], v[208:211], v[80:83]
	v_mfma_f32_16x16x32_bf16 v[72:75], v[180:183], v[208:211], v[72:75]
	v_mfma_f32_16x16x32_bf16 v[68:71], v[172:175], v[216:219], v[68:71]
	v_mfma_f32_16x16x32_bf16 v[64:67], v[180:183], v[216:219], v[64:67]
	s_setprio 0
	s_barrier
	s_add_i32 s42, s79, s61
	s_mov_b32 m0, s42
	ds_read_b128 v[184:187], v151 offset:49152
	ds_read_b128 v[192:195], v151 offset:50176
	ds_read_b128 v[196:199], v151 offset:51200
	ds_read_b128 v[200:203], v151 offset:52224
	ds_read_b128 v[204:207], v151 offset:53248
	ds_read_b128 v[208:211], v151 offset:54272
	ds_read_b128 v[212:215], v151 offset:55296
	ds_read_b128 v[216:219], v151 offset:56320
	global_load_lds_dwordx4 v130, s[98:99]
	s_add_i32 m0, s42, 0x2000
	s_add_u32 s34, s34, 0x40080
	s_addc_u32 s35, s35, 0
	s_add_i32 s42, s80, s61
	global_load_lds_dwordx4 v134, s[98:99]
	s_mov_b32 m0, s42
	s_nop 0
	global_load_lds_dwordx4 v130, s[34:35]
	s_add_i32 m0, s42, 0x2000
	s_nop 0
	global_load_lds_dwordx4 v134, s[34:35]
	s_mov_b32 m0, s65
	s_nop 0
	global_load_lds_dwordx4 v128, s[100:101]
	s_mov_b32 m0, s66
	s_nop 0
	global_load_lds_dwordx4 v132, s[100:101]
	s_waitcnt vmcnt(8)
	s_waitcnt lgkmcnt(0)
	s_barrier
	s_setprio 1
	s_waitcnt lgkmcnt(0)
	v_mfma_f32_16x16x32_bf16 v[60:63], v[152:155], v[184:187], v[60:63]
	v_mfma_f32_16x16x32_bf16 v[56:59], v[160:163], v[184:187], v[56:59]
	v_mfma_f32_16x16x32_bf16 v[52:55], v[152:155], v[196:199], v[52:55]
	v_mfma_f32_16x16x32_bf16 v[44:47], v[160:163], v[196:199], v[44:47]
	v_mfma_f32_16x16x32_bf16 v[36:39], v[152:155], v[204:207], v[36:39]
	v_mfma_f32_16x16x32_bf16 v[28:31], v[160:163], v[204:207], v[28:31]
	v_mfma_f32_16x16x32_bf16 v[20:23], v[152:155], v[212:215], v[20:23]
	v_mfma_f32_16x16x32_bf16 v[12:15], v[160:163], v[212:215], v[12:15]
	v_mfma_f32_16x16x32_bf16 v[60:63], v[156:159], v[192:195], v[60:63]
	v_mfma_f32_16x16x32_bf16 v[56:59], v[164:167], v[192:195], v[56:59]
	v_mfma_f32_16x16x32_bf16 v[52:55], v[156:159], v[200:203], v[52:55]
	v_mfma_f32_16x16x32_bf16 v[44:47], v[164:167], v[200:203], v[44:47]
	v_mfma_f32_16x16x32_bf16 v[36:39], v[156:159], v[208:211], v[36:39]
	v_mfma_f32_16x16x32_bf16 v[28:31], v[164:167], v[208:211], v[28:31]
	v_mfma_f32_16x16x32_bf16 v[20:23], v[156:159], v[216:219], v[20:23]
	v_mfma_f32_16x16x32_bf16 v[12:15], v[164:167], v[216:219], v[12:15]
	s_setprio 0
	s_setprio 1
	v_mfma_f32_16x16x32_bf16 v[48:51], v[168:171], v[184:187], v[48:51]
	v_mfma_f32_16x16x32_bf16 v[40:43], v[176:179], v[184:187], v[40:43]
	v_mfma_f32_16x16x32_bf16 v[32:35], v[168:171], v[196:199], v[32:35]
	v_mfma_f32_16x16x32_bf16 v[24:27], v[176:179], v[196:199], v[24:27]
	v_mfma_f32_16x16x32_bf16 v[16:19], v[168:171], v[204:207], v[16:19]
	v_mfma_f32_16x16x32_bf16 v[8:11], v[176:179], v[204:207], v[8:11]
	v_mfma_f32_16x16x32_bf16 v[4:7], v[168:171], v[212:215], v[4:7]
	v_mfma_f32_16x16x32_bf16 v[0:3], v[176:179], v[212:215], v[0:3]
	v_mfma_f32_16x16x32_bf16 v[48:51], v[172:175], v[192:195], v[48:51]
	v_mfma_f32_16x16x32_bf16 v[40:43], v[180:183], v[192:195], v[40:43]
	v_mfma_f32_16x16x32_bf16 v[32:35], v[172:175], v[200:203], v[32:35]
	v_mfma_f32_16x16x32_bf16 v[24:27], v[180:183], v[200:203], v[24:27]
	v_mfma_f32_16x16x32_bf16 v[16:19], v[172:175], v[208:211], v[16:19]
	v_mfma_f32_16x16x32_bf16 v[8:11], v[180:183], v[208:211], v[8:11]
	v_mfma_f32_16x16x32_bf16 v[4:7], v[172:175], v[216:219], v[4:7]
	v_mfma_f32_16x16x32_bf16 v[0:3], v[180:183], v[216:219], v[0:3]
	s_setprio 0
	s_barrier
	s_add_i32 s77, s77, 2
	s_add_u32 s30, s30, 0x100
	s_addc_u32 s31, s31, 0
	s_add_u32 s75, s75, 0x100
	s_addc_u32 s76, s76, 0
	s_cmp_gt_u32 s77, 13
	s_cbranch_scc0 .LBB0_1434

.LBB0_1570:
	s_ashr_i32 s23, s22, 31
	s_lshl_b64 s[24:25], s[22:23], 19
	s_add_u32 s24, s58, s24
	s_addc_u32 s25, s59, s25
	s_and_b64 s[26:27], s[0:1], exec
	s_cselect_b32 s23, s25, s31
	s_cselect_b32 s54, s24, s30
	s_ashr_i32 s21, s20, 31
	s_lshl_b64 s[26:27], s[20:21], 19
	s_add_u32 s26, s61, s26
	s_addc_u32 s27, s62, s27
	s_and_b64 s[42:43], s[0:1], exec
	s_cselect_b32 s21, s27, s35
	s_cselect_b32 s55, s26, s34
	s_add_u32 s30, s30, 0x40080
	s_addc_u32 s31, s31, 0
	s_add_u32 s75, s34, 0x100
	s_addc_u32 s76, s35, 0
	s_mov_b32 s77, -2
	ds_read_b128 v[152:155], v149
	ds_read_b128 v[156:159], v149 offset:1024
	ds_read_b128 v[160:163], v149 offset:2048
	ds_read_b128 v[164:167], v149 offset:3072
	ds_read_b128 v[168:171], v150
	ds_read_b128 v[172:175], v150 offset:1024
	ds_read_b128 v[176:179], v150 offset:2048
	ds_read_b128 v[180:183], v150 offset:3072
	s_add_u32 s34, s30, 0xfffc0080
	s_addc_u32 s35, s31, -1
	s_cmp_eq_u32 s77, 12
	s_cselect_b32 s43, s23, s35
	s_cselect_b32 s42, s54, s34
	s_cselect_b32 s35, s21, s76
	s_cselect_b32 s34, s55, s75
	s_add_i32 m0, s29, 0xc000
	ds_read_b128 v[184:187], v151
	ds_read_b128 v[192:195], v151 offset:1024
	ds_read_b128 v[196:199], v151 offset:2048
	ds_read_b128 v[200:203], v151 offset:3072
	ds_read_b128 v[204:207], v151 offset:4096
	ds_read_b128 v[208:211], v151 offset:5120
	ds_read_b128 v[212:215], v151 offset:6144
	ds_read_b128 v[216:219], v151 offset:7168
	global_load_lds_dwordx4 v136, s[30:31]
	s_add_i32 m0, s29, 0xe000
	s_nop 0
	global_load_lds_dwordx4 v138, s[30:31]
	s_waitcnt vmcnt(8)
	s_waitcnt lgkmcnt(0)
	s_barrier
	s_setprio 1
	s_waitcnt lgkmcnt(0)
	v_mfma_f32_16x16x32_bf16 v[124:127], v[152:155], v[184:187], 0
	v_mfma_f32_16x16x32_bf16 v[120:123], v[160:163], v[184:187], 0
	v_mfma_f32_16x16x32_bf16 v[108:111], v[152:155], v[196:199], 0
	v_mfma_f32_16x16x32_bf16 v[104:107], v[160:163], v[196:199], 0
	v_mfma_f32_16x16x32_bf16 v[92:95], v[152:155], v[204:207], 0
	v_mfma_f32_16x16x32_bf16 v[88:91], v[160:163], v[204:207], 0
	v_mfma_f32_16x16x32_bf16 v[76:79], v[152:155], v[212:215], 0
	v_mfma_f32_16x16x32_bf16 v[72:75], v[160:163], v[212:215], 0
	v_mfma_f32_16x16x32_bf16 v[124:127], v[156:159], v[192:195], v[124:127]
	v_mfma_f32_16x16x32_bf16 v[120:123], v[164:167], v[192:195], v[120:123]
	v_mfma_f32_16x16x32_bf16 v[108:111], v[156:159], v[200:203], v[108:111]
	v_mfma_f32_16x16x32_bf16 v[104:107], v[164:167], v[200:203], v[104:107]
	v_mfma_f32_16x16x32_bf16 v[92:95], v[156:159], v[208:211], v[92:95]
	v_mfma_f32_16x16x32_bf16 v[88:91], v[164:167], v[208:211], v[88:91]
	v_mfma_f32_16x16x32_bf16 v[76:79], v[156:159], v[216:219], v[76:79]
	v_mfma_f32_16x16x32_bf16 v[72:75], v[164:167], v[216:219], v[72:75]
	s_setprio 0
	s_setprio 1
	v_mfma_f32_16x16x32_bf16 v[116:119], v[168:171], v[184:187], 0
	v_mfma_f32_16x16x32_bf16 v[112:115], v[176:179], v[184:187], 0
	v_mfma_f32_16x16x32_bf16 v[100:103], v[168:171], v[196:199], 0
	v_mfma_f32_16x16x32_bf16 v[96:99], v[176:179], v[196:199], 0
	v_mfma_f32_16x16x32_bf16 v[84:87], v[168:171], v[204:207], 0
	v_mfma_f32_16x16x32_bf16 v[80:83], v[176:179], v[204:207], 0
	v_mfma_f32_16x16x32_bf16 v[68:71], v[168:171], v[212:215], 0
	v_mfma_f32_16x16x32_bf16 v[64:67], v[176:179], v[212:215], 0
	v_mfma_f32_16x16x32_bf16 v[116:119], v[172:175], v[192:195], v[116:119]
	v_mfma_f32_16x16x32_bf16 v[112:115], v[180:183], v[192:195], v[112:115]
	v_mfma_f32_16x16x32_bf16 v[100:103], v[172:175], v[200:203], v[100:103]
	v_mfma_f32_16x16x32_bf16 v[96:99], v[180:183], v[200:203], v[96:99]
	v_mfma_f32_16x16x32_bf16 v[84:87], v[172:175], v[208:211], v[84:87]
	v_mfma_f32_16x16x32_bf16 v[80:83], v[180:183], v[208:211], v[80:83]
	v_mfma_f32_16x16x32_bf16 v[68:71], v[172:175], v[216:219], v[68:71]
	v_mfma_f32_16x16x32_bf16 v[64:67], v[180:183], v[216:219], v[64:67]
	s_setprio 0
	s_barrier
	s_add_i32 s79, s69, s63
	s_add_u32 s98, s34, 0x80
	s_addc_u32 s99, s35, 0
	s_mov_b32 m0, s79
	ds_read_b128 v[184:187], v151 offset:16384
	ds_read_b128 v[192:195], v151 offset:17408
	ds_read_b128 v[196:199], v151 offset:18432
	ds_read_b128 v[200:203], v151 offset:19456
	ds_read_b128 v[204:207], v151 offset:20480
	ds_read_b128 v[208:211], v151 offset:21504
	ds_read_b128 v[212:215], v151 offset:22528
	ds_read_b128 v[216:219], v151 offset:23552
	global_load_lds_dwordx4 v130, s[34:35]
	s_add_i32 m0, s79, 0x2000
	s_add_u32 s80, s34, 0x40000
	s_addc_u32 s81, s35, 0
	s_add_i32 s79, s70, s63
	global_load_lds_dwordx4 v134, s[34:35]
	s_mov_b32 m0, s79
	s_add_u32 s100, s42, 0x80
	s_addc_u32 s101, s43, 0
	global_load_lds_dwordx4 v130, s[80:81]
	s_add_i32 m0, s79, 0x2000
	s_nop 0
	global_load_lds_dwordx4 v134, s[80:81]
	s_mov_b32 m0, s29
	s_nop 0
	global_load_lds_dwordx4 v128, s[42:43]
	s_mov_b32 m0, s64
	s_nop 0
	global_load_lds_dwordx4 v132, s[42:43]
	s_waitcnt vmcnt(8)
	s_waitcnt lgkmcnt(0)
	s_barrier
	s_setprio 1
	s_waitcnt lgkmcnt(0)
	v_mfma_f32_16x16x32_bf16 v[60:63], v[152:155], v[184:187], 0
	v_mfma_f32_16x16x32_bf16 v[56:59], v[160:163], v[184:187], 0
	v_mfma_f32_16x16x32_bf16 v[44:47], v[152:155], v[196:199], 0
	v_mfma_f32_16x16x32_bf16 v[40:43], v[160:163], v[196:199], 0
	v_mfma_f32_16x16x32_bf16 v[28:31], v[152:155], v[204:207], 0
	v_mfma_f32_16x16x32_bf16 v[24:27], v[160:163], v[204:207], 0
	v_mfma_f32_16x16x32_bf16 v[12:15], v[152:155], v[212:215], 0
	v_mfma_f32_16x16x32_bf16 v[8:11], v[160:163], v[212:215], 0
	v_mfma_f32_16x16x32_bf16 v[60:63], v[156:159], v[192:195], v[60:63]
	v_mfma_f32_16x16x32_bf16 v[56:59], v[164:167], v[192:195], v[56:59]
	v_mfma_f32_16x16x32_bf16 v[44:47], v[156:159], v[200:203], v[44:47]
	v_mfma_f32_16x16x32_bf16 v[40:43], v[164:167], v[200:203], v[40:43]
	v_mfma_f32_16x16x32_bf16 v[28:31], v[156:159], v[208:211], v[28:31]
	v_mfma_f32_16x16x32_bf16 v[24:27], v[164:167], v[208:211], v[24:27]
	v_mfma_f32_16x16x32_bf16 v[12:15], v[156:159], v[216:219], v[12:15]
	v_mfma_f32_16x16x32_bf16 v[8:11], v[164:167], v[216:219], v[8:11]
	s_setprio 0
	s_setprio 1
	v_mfma_f32_16x16x32_bf16 v[52:55], v[168:171], v[184:187], 0
	v_mfma_f32_16x16x32_bf16 v[48:51], v[176:179], v[184:187], 0
	v_mfma_f32_16x16x32_bf16 v[36:39], v[168:171], v[196:199], 0
	v_mfma_f32_16x16x32_bf16 v[32:35], v[176:179], v[196:199], 0
	v_mfma_f32_16x16x32_bf16 v[20:23], v[168:171], v[204:207], 0
	v_mfma_f32_16x16x32_bf16 v[16:19], v[176:179], v[204:207], 0
	v_mfma_f32_16x16x32_bf16 v[4:7], v[168:171], v[212:215], 0
	v_mfma_f32_16x16x32_bf16 v[0:3], v[176:179], v[212:215], 0
	v_mfma_f32_16x16x32_bf16 v[52:55], v[172:175], v[192:195], v[52:55]
	v_mfma_f32_16x16x32_bf16 v[48:51], v[180:183], v[192:195], v[48:51]
	v_mfma_f32_16x16x32_bf16 v[36:39], v[172:175], v[200:203], v[36:39]
	v_mfma_f32_16x16x32_bf16 v[32:35], v[180:183], v[200:203], v[32:35]
	v_mfma_f32_16x16x32_bf16 v[20:23], v[172:175], v[208:211], v[20:23]
	v_mfma_f32_16x16x32_bf16 v[16:19], v[180:183], v[208:211], v[16:19]
	v_mfma_f32_16x16x32_bf16 v[4:7], v[172:175], v[216:219], v[4:7]
	v_mfma_f32_16x16x32_bf16 v[0:3], v[180:183], v[216:219], v[0:3]
	s_setprio 0
	s_barrier
	s_add_i32 s79, 0, 0x18000
	s_add_i32 s80, 0, 0x1c000
	v_add_u32_e32 v164, s79, v147
	v_add_u32_e32 v180, s80, v147
	ds_read_b128 v[152:155], v164
	ds_read_b128 v[156:159], v164 offset:1024
	ds_read_b128 v[160:163], v164 offset:2048
	ds_read_b128 v[164:167], v164 offset:3072
	ds_read_b128 v[168:171], v180
	ds_read_b128 v[172:175], v180 offset:1024
	ds_read_b128 v[176:179], v180 offset:2048
	ds_read_b128 v[180:183], v180 offset:3072
	s_add_u32 s42, s42, 0x40000
	s_addc_u32 s43, s43, 0
	s_mov_b32 m0, s65
	ds_read_b128 v[184:187], v151 offset:32768
	ds_read_b128 v[192:195], v151 offset:33792
	ds_read_b128 v[196:199], v151 offset:34816
	ds_read_b128 v[200:203], v151 offset:35840
	ds_read_b128 v[204:207], v151 offset:36864
	ds_read_b128 v[208:211], v151 offset:37888
	ds_read_b128 v[212:215], v151 offset:38912
	ds_read_b128 v[216:219], v151 offset:39936
	global_load_lds_dwordx4 v128, s[42:43]
	s_mov_b32 m0, s66
	s_nop 0
	global_load_lds_dwordx4 v132, s[42:43]
	s_waitcnt vmcnt(8)
	s_waitcnt lgkmcnt(0)
	s_barrier
	s_setprio 1
	s_waitcnt lgkmcnt(0)
	v_mfma_f32_16x16x32_bf16 v[124:127], v[152:155], v[184:187], v[124:127]
	v_mfma_f32_16x16x32_bf16 v[120:123], v[160:163], v[184:187], v[120:123]
	v_mfma_f32_16x16x32_bf16 v[108:111], v[152:155], v[196:199], v[108:111]
	v_mfma_f32_16x16x32_bf16 v[104:107], v[160:163], v[196:199], v[104:107]
	v_mfma_f32_16x16x32_bf16 v[92:95], v[152:155], v[204:207], v[92:95]
	v_mfma_f32_16x16x32_bf16 v[88:91], v[160:163], v[204:207], v[88:91]
	v_mfma_f32_16x16x32_bf16 v[76:79], v[152:155], v[212:215], v[76:79]
	v_mfma_f32_16x16x32_bf16 v[72:75], v[160:163], v[212:215], v[72:75]
	v_mfma_f32_16x16x32_bf16 v[124:127], v[156:159], v[192:195], v[124:127]
	v_mfma_f32_16x16x32_bf16 v[120:123], v[164:167], v[192:195], v[120:123]
	v_mfma_f32_16x16x32_bf16 v[108:111], v[156:159], v[200:203], v[108:111]
	v_mfma_f32_16x16x32_bf16 v[104:107], v[164:167], v[200:203], v[104:107]
	v_mfma_f32_16x16x32_bf16 v[92:95], v[156:159], v[208:211], v[92:95]
	v_mfma_f32_16x16x32_bf16 v[88:91], v[164:167], v[208:211], v[88:91]
	v_mfma_f32_16x16x32_bf16 v[76:79], v[156:159], v[216:219], v[76:79]
	v_mfma_f32_16x16x32_bf16 v[72:75], v[164:167], v[216:219], v[72:75]
	s_setprio 0
	s_setprio 1
	v_mfma_f32_16x16x32_bf16 v[116:119], v[168:171], v[184:187], v[116:119]
	v_mfma_f32_16x16x32_bf16 v[112:115], v[176:179], v[184:187], v[112:115]
	v_mfma_f32_16x16x32_bf16 v[100:103], v[168:171], v[196:199], v[100:103]
	v_mfma_f32_16x16x32_bf16 v[96:99], v[176:179], v[196:199], v[96:99]
	v_mfma_f32_16x16x32_bf16 v[84:87], v[168:171], v[204:207], v[84:87]
	v_mfma_f32_16x16x32_bf16 v[80:83], v[176:179], v[204:207], v[80:83]
	v_mfma_f32_16x16x32_bf16 v[68:71], v[168:171], v[212:215], v[68:71]
	v_mfma_f32_16x16x32_bf16 v[64:67], v[176:179], v[212:215], v[64:67]
	v_mfma_f32_16x16x32_bf16 v[116:119], v[172:175], v[192:195], v[116:119]
	v_mfma_f32_16x16x32_bf16 v[112:115], v[180:183], v[192:195], v[112:115]
	v_mfma_f32_16x16x32_bf16 v[100:103], v[172:175], v[200:203], v[100:103]
	v_mfma_f32_16x16x32_bf16 v[96:99], v[180:183], v[200:203], v[96:99]
	v_mfma_f32_16x16x32_bf16 v[84:87], v[172:175], v[208:211], v[84:87]
	v_mfma_f32_16x16x32_bf16 v[80:83], v[180:183], v[208:211], v[80:83]
	v_mfma_f32_16x16x32_bf16 v[68:71], v[172:175], v[216:219], v[68:71]
	v_mfma_f32_16x16x32_bf16 v[64:67], v[180:183], v[216:219], v[64:67]
	s_setprio 0
	s_barrier
	s_add_i32 s42, s79, s63
	s_mov_b32 m0, s42
	ds_read_b128 v[184:187], v151 offset:49152
	ds_read_b128 v[192:195], v151 offset:50176
	ds_read_b128 v[196:199], v151 offset:51200
	ds_read_b128 v[200:203], v151 offset:52224
	ds_read_b128 v[204:207], v151 offset:53248
	ds_read_b128 v[208:211], v151 offset:54272
	ds_read_b128 v[212:215], v151 offset:55296
	ds_read_b128 v[216:219], v151 offset:56320
	global_load_lds_dwordx4 v130, s[98:99]
	s_add_i32 m0, s42, 0x2000
	s_add_u32 s34, s34, 0x40080
	s_addc_u32 s35, s35, 0
	s_add_i32 s42, s80, s63
	global_load_lds_dwordx4 v134, s[98:99]
	s_mov_b32 m0, s42
	s_nop 0
	global_load_lds_dwordx4 v130, s[34:35]
	s_add_i32 m0, s42, 0x2000
	s_nop 0
	global_load_lds_dwordx4 v134, s[34:35]
	s_mov_b32 m0, s52
	s_nop 0
	global_load_lds_dwordx4 v128, s[100:101]
	s_mov_b32 m0, s53
	s_nop 0
	global_load_lds_dwordx4 v132, s[100:101]
	s_waitcnt vmcnt(8)
	s_waitcnt lgkmcnt(0)
	s_barrier
	s_setprio 1
	s_waitcnt lgkmcnt(0)
	v_mfma_f32_16x16x32_bf16 v[60:63], v[152:155], v[184:187], v[60:63]
	v_mfma_f32_16x16x32_bf16 v[56:59], v[160:163], v[184:187], v[56:59]
	v_mfma_f32_16x16x32_bf16 v[44:47], v[152:155], v[196:199], v[44:47]
	v_mfma_f32_16x16x32_bf16 v[40:43], v[160:163], v[196:199], v[40:43]
	v_mfma_f32_16x16x32_bf16 v[28:31], v[152:155], v[204:207], v[28:31]
	v_mfma_f32_16x16x32_bf16 v[24:27], v[160:163], v[204:207], v[24:27]
	v_mfma_f32_16x16x32_bf16 v[12:15], v[152:155], v[212:215], v[12:15]
	v_mfma_f32_16x16x32_bf16 v[8:11], v[160:163], v[212:215], v[8:11]
	v_mfma_f32_16x16x32_bf16 v[60:63], v[156:159], v[192:195], v[60:63]
	v_mfma_f32_16x16x32_bf16 v[56:59], v[164:167], v[192:195], v[56:59]
	v_mfma_f32_16x16x32_bf16 v[44:47], v[156:159], v[200:203], v[44:47]
	v_mfma_f32_16x16x32_bf16 v[40:43], v[164:167], v[200:203], v[40:43]
	v_mfma_f32_16x16x32_bf16 v[28:31], v[156:159], v[208:211], v[28:31]
	v_mfma_f32_16x16x32_bf16 v[24:27], v[164:167], v[208:211], v[24:27]
	v_mfma_f32_16x16x32_bf16 v[12:15], v[156:159], v[216:219], v[12:15]
	v_mfma_f32_16x16x32_bf16 v[8:11], v[164:167], v[216:219], v[8:11]
	s_setprio 0
	s_setprio 1
	v_mfma_f32_16x16x32_bf16 v[52:55], v[168:171], v[184:187], v[52:55]
	v_mfma_f32_16x16x32_bf16 v[48:51], v[176:179], v[184:187], v[48:51]
	v_mfma_f32_16x16x32_bf16 v[36:39], v[168:171], v[196:199], v[36:39]
	v_mfma_f32_16x16x32_bf16 v[32:35], v[176:179], v[196:199], v[32:35]
	v_mfma_f32_16x16x32_bf16 v[20:23], v[168:171], v[204:207], v[20:23]
	v_mfma_f32_16x16x32_bf16 v[16:19], v[176:179], v[204:207], v[16:19]
	v_mfma_f32_16x16x32_bf16 v[4:7], v[168:171], v[212:215], v[4:7]
	v_mfma_f32_16x16x32_bf16 v[0:3], v[176:179], v[212:215], v[0:3]
	v_mfma_f32_16x16x32_bf16 v[52:55], v[172:175], v[192:195], v[52:55]
	v_mfma_f32_16x16x32_bf16 v[48:51], v[180:183], v[192:195], v[48:51]
	v_mfma_f32_16x16x32_bf16 v[36:39], v[172:175], v[200:203], v[36:39]
	v_mfma_f32_16x16x32_bf16 v[32:35], v[180:183], v[200:203], v[32:35]
	v_mfma_f32_16x16x32_bf16 v[20:23], v[172:175], v[208:211], v[20:23]
	v_mfma_f32_16x16x32_bf16 v[16:19], v[180:183], v[208:211], v[16:19]
	v_mfma_f32_16x16x32_bf16 v[4:7], v[172:175], v[216:219], v[4:7]
	v_mfma_f32_16x16x32_bf16 v[0:3], v[180:183], v[216:219], v[0:3]
	s_setprio 0
	s_barrier
	s_add_i32 s77, s77, 2
	s_add_u32 s30, s30, 0x100
	s_addc_u32 s31, s31, 0
	s_add_u32 s75, s75, 0x100
	s_addc_u32 s76, s76, 0
	s_cmp_gt_u32 s77, 13
	s_cbranch_scc0 .LBB0_1571
	s_branch .Lpeel_exit11
.LBB0_1571:
	ds_read_b128 v[152:155], v149
	ds_read_b128 v[156:159], v149 offset:1024
	ds_read_b128 v[160:163], v149 offset:2048
	ds_read_b128 v[164:167], v149 offset:3072
	ds_read_b128 v[168:171], v150
	ds_read_b128 v[172:175], v150 offset:1024
	ds_read_b128 v[176:179], v150 offset:2048
	ds_read_b128 v[180:183], v150 offset:3072
	s_add_u32 s34, s30, 0xfffc0080
	s_addc_u32 s35, s31, -1
	s_cmp_eq_u32 s77, 12
	s_cselect_b32 s43, s23, s35
	s_cselect_b32 s42, s54, s34
	s_cselect_b32 s35, s21, s76
	s_cselect_b32 s34, s55, s75
	s_add_i32 m0, s29, 0xc000
	ds_read_b128 v[184:187], v151
	ds_read_b128 v[192:195], v151 offset:1024
	ds_read_b128 v[196:199], v151 offset:2048
	ds_read_b128 v[200:203], v151 offset:3072
	ds_read_b128 v[204:207], v151 offset:4096
	ds_read_b128 v[208:211], v151 offset:5120
	ds_read_b128 v[212:215], v151 offset:6144
	ds_read_b128 v[216:219], v151 offset:7168
	global_load_lds_dwordx4 v136, s[30:31]
	s_add_i32 m0, s29, 0xe000
	s_nop 0
	global_load_lds_dwordx4 v138, s[30:31]
	s_waitcnt vmcnt(8)
	s_waitcnt lgkmcnt(0)
	s_barrier
	s_setprio 1
	s_waitcnt lgkmcnt(0)
	v_mfma_f32_16x16x32_bf16 v[124:127], v[152:155], v[184:187], v[124:127]
	v_mfma_f32_16x16x32_bf16 v[120:123], v[160:163], v[184:187], v[120:123]
	v_mfma_f32_16x16x32_bf16 v[108:111], v[152:155], v[196:199], v[108:111]
	v_mfma_f32_16x16x32_bf16 v[104:107], v[160:163], v[196:199], v[104:107]
	v_mfma_f32_16x16x32_bf16 v[92:95], v[152:155], v[204:207], v[92:95]
	v_mfma_f32_16x16x32_bf16 v[88:91], v[160:163], v[204:207], v[88:91]
	v_mfma_f32_16x16x32_bf16 v[76:79], v[152:155], v[212:215], v[76:79]
	v_mfma_f32_16x16x32_bf16 v[72:75], v[160:163], v[212:215], v[72:75]
	v_mfma_f32_16x16x32_bf16 v[124:127], v[156:159], v[192:195], v[124:127]
	v_mfma_f32_16x16x32_bf16 v[120:123], v[164:167], v[192:195], v[120:123]
	v_mfma_f32_16x16x32_bf16 v[108:111], v[156:159], v[200:203], v[108:111]
	v_mfma_f32_16x16x32_bf16 v[104:107], v[164:167], v[200:203], v[104:107]
	v_mfma_f32_16x16x32_bf16 v[92:95], v[156:159], v[208:211], v[92:95]
	v_mfma_f32_16x16x32_bf16 v[88:91], v[164:167], v[208:211], v[88:91]
	v_mfma_f32_16x16x32_bf16 v[76:79], v[156:159], v[216:219], v[76:79]
	v_mfma_f32_16x16x32_bf16 v[72:75], v[164:167], v[216:219], v[72:75]
	s_setprio 0
	s_setprio 1
	v_mfma_f32_16x16x32_bf16 v[116:119], v[168:171], v[184:187], v[116:119]
	v_mfma_f32_16x16x32_bf16 v[112:115], v[176:179], v[184:187], v[112:115]
	v_mfma_f32_16x16x32_bf16 v[100:103], v[168:171], v[196:199], v[100:103]
	v_mfma_f32_16x16x32_bf16 v[96:99], v[176:179], v[196:199], v[96:99]
	v_mfma_f32_16x16x32_bf16 v[84:87], v[168:171], v[204:207], v[84:87]
	v_mfma_f32_16x16x32_bf16 v[80:83], v[176:179], v[204:207], v[80:83]
	v_mfma_f32_16x16x32_bf16 v[68:71], v[168:171], v[212:215], v[68:71]
	v_mfma_f32_16x16x32_bf16 v[64:67], v[176:179], v[212:215], v[64:67]
	v_mfma_f32_16x16x32_bf16 v[116:119], v[172:175], v[192:195], v[116:119]
	v_mfma_f32_16x16x32_bf16 v[112:115], v[180:183], v[192:195], v[112:115]
	v_mfma_f32_16x16x32_bf16 v[100:103], v[172:175], v[200:203], v[100:103]
	v_mfma_f32_16x16x32_bf16 v[96:99], v[180:183], v[200:203], v[96:99]
	v_mfma_f32_16x16x32_bf16 v[84:87], v[172:175], v[208:211], v[84:87]
	v_mfma_f32_16x16x32_bf16 v[80:83], v[180:183], v[208:211], v[80:83]
	v_mfma_f32_16x16x32_bf16 v[68:71], v[172:175], v[216:219], v[68:71]
	v_mfma_f32_16x16x32_bf16 v[64:67], v[180:183], v[216:219], v[64:67]
	s_setprio 0
	s_barrier
	s_add_i32 s79, s69, s63
	s_add_u32 s98, s34, 0x80
	s_addc_u32 s99, s35, 0
	s_mov_b32 m0, s79
	ds_read_b128 v[184:187], v151 offset:16384
	ds_read_b128 v[192:195], v151 offset:17408
	ds_read_b128 v[196:199], v151 offset:18432
	ds_read_b128 v[200:203], v151 offset:19456
	ds_read_b128 v[204:207], v151 offset:20480
	ds_read_b128 v[208:211], v151 offset:21504
	ds_read_b128 v[212:215], v151 offset:22528
	ds_read_b128 v[216:219], v151 offset:23552
	global_load_lds_dwordx4 v130, s[34:35]
	s_add_i32 m0, s79, 0x2000
	s_add_u32 s80, s34, 0x40000
	s_addc_u32 s81, s35, 0
	s_add_i32 s79, s70, s63
	global_load_lds_dwordx4 v134, s[34:35]
	s_mov_b32 m0, s79
	s_add_u32 s100, s42, 0x80
	s_addc_u32 s101, s43, 0
	global_load_lds_dwordx4 v130, s[80:81]
	s_add_i32 m0, s79, 0x2000
	s_nop 0
	global_load_lds_dwordx4 v134, s[80:81]
	s_mov_b32 m0, s29
	s_nop 0
	global_load_lds_dwordx4 v128, s[42:43]
	s_mov_b32 m0, s64
	s_nop 0
	global_load_lds_dwordx4 v132, s[42:43]
	s_waitcnt vmcnt(8)
	s_waitcnt lgkmcnt(0)
	s_barrier
	s_setprio 1
	s_waitcnt lgkmcnt(0)
	v_mfma_f32_16x16x32_bf16 v[60:63], v[152:155], v[184:187], v[60:63]
	v_mfma_f32_16x16x32_bf16 v[56:59], v[160:163], v[184:187], v[56:59]
	v_mfma_f32_16x16x32_bf16 v[44:47], v[152:155], v[196:199], v[44:47]
	v_mfma_f32_16x16x32_bf16 v[40:43], v[160:163], v[196:199], v[40:43]
	v_mfma_f32_16x16x32_bf16 v[28:31], v[152:155], v[204:207], v[28:31]
	v_mfma_f32_16x16x32_bf16 v[24:27], v[160:163], v[204:207], v[24:27]
	v_mfma_f32_16x16x32_bf16 v[12:15], v[152:155], v[212:215], v[12:15]
	v_mfma_f32_16x16x32_bf16 v[8:11], v[160:163], v[212:215], v[8:11]
	v_mfma_f32_16x16x32_bf16 v[60:63], v[156:159], v[192:195], v[60:63]
	v_mfma_f32_16x16x32_bf16 v[56:59], v[164:167], v[192:195], v[56:59]
	v_mfma_f32_16x16x32_bf16 v[44:47], v[156:159], v[200:203], v[44:47]
	v_mfma_f32_16x16x32_bf16 v[40:43], v[164:167], v[200:203], v[40:43]
	v_mfma_f32_16x16x32_bf16 v[28:31], v[156:159], v[208:211], v[28:31]
	v_mfma_f32_16x16x32_bf16 v[24:27], v[164:167], v[208:211], v[24:27]
	v_mfma_f32_16x16x32_bf16 v[12:15], v[156:159], v[216:219], v[12:15]
	v_mfma_f32_16x16x32_bf16 v[8:11], v[164:167], v[216:219], v[8:11]
	s_setprio 0
	s_setprio 1
	v_mfma_f32_16x16x32_bf16 v[52:55], v[168:171], v[184:187], v[52:55]
	v_mfma_f32_16x16x32_bf16 v[48:51], v[176:179], v[184:187], v[48:51]
	v_mfma_f32_16x16x32_bf16 v[36:39], v[168:171], v[196:199], v[36:39]
	v_mfma_f32_16x16x32_bf16 v[32:35], v[176:179], v[196:199], v[32:35]
	v_mfma_f32_16x16x32_bf16 v[20:23], v[168:171], v[204:207], v[20:23]
	v_mfma_f32_16x16x32_bf16 v[16:19], v[176:179], v[204:207], v[16:19]
	v_mfma_f32_16x16x32_bf16 v[4:7], v[168:171], v[212:215], v[4:7]
	v_mfma_f32_16x16x32_bf16 v[0:3], v[176:179], v[212:215], v[0:3]
	v_mfma_f32_16x16x32_bf16 v[52:55], v[172:175], v[192:195], v[52:55]
	v_mfma_f32_16x16x32_bf16 v[48:51], v[180:183], v[192:195], v[48:51]
	v_mfma_f32_16x16x32_bf16 v[36:39], v[172:175], v[200:203], v[36:39]
	v_mfma_f32_16x16x32_bf16 v[32:35], v[180:183], v[200:203], v[32:35]
	v_mfma_f32_16x16x32_bf16 v[20:23], v[172:175], v[208:211], v[20:23]
	v_mfma_f32_16x16x32_bf16 v[16:19], v[180:183], v[208:211], v[16:19]
	v_mfma_f32_16x16x32_bf16 v[4:7], v[172:175], v[216:219], v[4:7]
	v_mfma_f32_16x16x32_bf16 v[0:3], v[180:183], v[216:219], v[0:3]
	s_setprio 0
	s_barrier
	s_add_i32 s79, 0, 0x18000
	s_add_i32 s80, 0, 0x1c000
	v_add_u32_e32 v164, s79, v147
	v_add_u32_e32 v180, s80, v147
	ds_read_b128 v[152:155], v164
	ds_read_b128 v[156:159], v164 offset:1024
	ds_read_b128 v[160:163], v164 offset:2048
	ds_read_b128 v[164:167], v164 offset:3072
	ds_read_b128 v[168:171], v180
	ds_read_b128 v[172:175], v180 offset:1024
	ds_read_b128 v[176:179], v180 offset:2048
	ds_read_b128 v[180:183], v180 offset:3072
	s_add_u32 s42, s42, 0x40000
	s_addc_u32 s43, s43, 0
	s_mov_b32 m0, s65
	ds_read_b128 v[184:187], v151 offset:32768
	ds_read_b128 v[192:195], v151 offset:33792
	ds_read_b128 v[196:199], v151 offset:34816
	ds_read_b128 v[200:203], v151 offset:35840
	ds_read_b128 v[204:207], v151 offset:36864
	ds_read_b128 v[208:211], v151 offset:37888
	ds_read_b128 v[212:215], v151 offset:38912
	ds_read_b128 v[216:219], v151 offset:39936
	global_load_lds_dwordx4 v128, s[42:43]
	s_mov_b32 m0, s66
	s_nop 0
	global_load_lds_dwordx4 v132, s[42:43]
	s_waitcnt vmcnt(8)
	s_waitcnt lgkmcnt(0)
	s_barrier
	s_setprio 1
	s_waitcnt lgkmcnt(0)
	v_mfma_f32_16x16x32_bf16 v[124:127], v[152:155], v[184:187], v[124:127]
	v_mfma_f32_16x16x32_bf16 v[120:123], v[160:163], v[184:187], v[120:123]
	v_mfma_f32_16x16x32_bf16 v[108:111], v[152:155], v[196:199], v[108:111]
	v_mfma_f32_16x16x32_bf16 v[104:107], v[160:163], v[196:199], v[104:107]
	v_mfma_f32_16x16x32_bf16 v[92:95], v[152:155], v[204:207], v[92:95]
	v_mfma_f32_16x16x32_bf16 v[88:91], v[160:163], v[204:207], v[88:91]
	v_mfma_f32_16x16x32_bf16 v[76:79], v[152:155], v[212:215], v[76:79]
	v_mfma_f32_16x16x32_bf16 v[72:75], v[160:163], v[212:215], v[72:75]
	v_mfma_f32_16x16x32_bf16 v[124:127], v[156:159], v[192:195], v[124:127]
	v_mfma_f32_16x16x32_bf16 v[120:123], v[164:167], v[192:195], v[120:123]
	v_mfma_f32_16x16x32_bf16 v[108:111], v[156:159], v[200:203], v[108:111]
	v_mfma_f32_16x16x32_bf16 v[104:107], v[164:167], v[200:203], v[104:107]
	v_mfma_f32_16x16x32_bf16 v[92:95], v[156:159], v[208:211], v[92:95]
	v_mfma_f32_16x16x32_bf16 v[88:91], v[164:167], v[208:211], v[88:91]
	v_mfma_f32_16x16x32_bf16 v[76:79], v[156:159], v[216:219], v[76:79]
	v_mfma_f32_16x16x32_bf16 v[72:75], v[164:167], v[216:219], v[72:75]
	s_setprio 0
	s_setprio 1
	v_mfma_f32_16x16x32_bf16 v[116:119], v[168:171], v[184:187], v[116:119]
	v_mfma_f32_16x16x32_bf16 v[112:115], v[176:179], v[184:187], v[112:115]
	v_mfma_f32_16x16x32_bf16 v[100:103], v[168:171], v[196:199], v[100:103]
	v_mfma_f32_16x16x32_bf16 v[96:99], v[176:179], v[196:199], v[96:99]
	v_mfma_f32_16x16x32_bf16 v[84:87], v[168:171], v[204:207], v[84:87]
	v_mfma_f32_16x16x32_bf16 v[80:83], v[176:179], v[204:207], v[80:83]
	v_mfma_f32_16x16x32_bf16 v[68:71], v[168:171], v[212:215], v[68:71]
	v_mfma_f32_16x16x32_bf16 v[64:67], v[176:179], v[212:215], v[64:67]
	v_mfma_f32_16x16x32_bf16 v[116:119], v[172:175], v[192:195], v[116:119]
	v_mfma_f32_16x16x32_bf16 v[112:115], v[180:183], v[192:195], v[112:115]
	v_mfma_f32_16x16x32_bf16 v[100:103], v[172:175], v[200:203], v[100:103]
	v_mfma_f32_16x16x32_bf16 v[96:99], v[180:183], v[200:203], v[96:99]
	v_mfma_f32_16x16x32_bf16 v[84:87], v[172:175], v[208:211], v[84:87]
	v_mfma_f32_16x16x32_bf16 v[80:83], v[180:183], v[208:211], v[80:83]
	v_mfma_f32_16x16x32_bf16 v[68:71], v[172:175], v[216:219], v[68:71]
	v_mfma_f32_16x16x32_bf16 v[64:67], v[180:183], v[216:219], v[64:67]
	s_setprio 0
	s_barrier
	s_add_i32 s42, s79, s63
	s_mov_b32 m0, s42
	ds_read_b128 v[184:187], v151 offset:49152
	ds_read_b128 v[192:195], v151 offset:50176
	ds_read_b128 v[196:199], v151 offset:51200
	ds_read_b128 v[200:203], v151 offset:52224
	ds_read_b128 v[204:207], v151 offset:53248
	ds_read_b128 v[208:211], v151 offset:54272
	ds_read_b128 v[212:215], v151 offset:55296
	ds_read_b128 v[216:219], v151 offset:56320
	global_load_lds_dwordx4 v130, s[98:99]
	s_add_i32 m0, s42, 0x2000
	s_add_u32 s34, s34, 0x40080
	s_addc_u32 s35, s35, 0
	s_add_i32 s42, s80, s63
	global_load_lds_dwordx4 v134, s[98:99]
	s_mov_b32 m0, s42
	s_nop 0
	global_load_lds_dwordx4 v130, s[34:35]
	s_add_i32 m0, s42, 0x2000
	s_nop 0
	global_load_lds_dwordx4 v134, s[34:35]
	s_mov_b32 m0, s52
	s_nop 0
	global_load_lds_dwordx4 v128, s[100:101]
	s_mov_b32 m0, s53
	s_nop 0
	global_load_lds_dwordx4 v132, s[100:101]
	s_waitcnt vmcnt(8)
	s_waitcnt lgkmcnt(0)
	s_barrier
	s_setprio 1
	s_waitcnt lgkmcnt(0)
	v_mfma_f32_16x16x32_bf16 v[60:63], v[152:155], v[184:187], v[60:63]
	v_mfma_f32_16x16x32_bf16 v[56:59], v[160:163], v[184:187], v[56:59]
	v_mfma_f32_16x16x32_bf16 v[44:47], v[152:155], v[196:199], v[44:47]
	v_mfma_f32_16x16x32_bf16 v[40:43], v[160:163], v[196:199], v[40:43]
	v_mfma_f32_16x16x32_bf16 v[28:31], v[152:155], v[204:207], v[28:31]
	v_mfma_f32_16x16x32_bf16 v[24:27], v[160:163], v[204:207], v[24:27]
	v_mfma_f32_16x16x32_bf16 v[12:15], v[152:155], v[212:215], v[12:15]
	v_mfma_f32_16x16x32_bf16 v[8:11], v[160:163], v[212:215], v[8:11]
	v_mfma_f32_16x16x32_bf16 v[60:63], v[156:159], v[192:195], v[60:63]
	v_mfma_f32_16x16x32_bf16 v[56:59], v[164:167], v[192:195], v[56:59]
	v_mfma_f32_16x16x32_bf16 v[44:47], v[156:159], v[200:203], v[44:47]
	v_mfma_f32_16x16x32_bf16 v[40:43], v[164:167], v[200:203], v[40:43]
	v_mfma_f32_16x16x32_bf16 v[28:31], v[156:159], v[208:211], v[28:31]
	v_mfma_f32_16x16x32_bf16 v[24:27], v[164:167], v[208:211], v[24:27]
	v_mfma_f32_16x16x32_bf16 v[12:15], v[156:159], v[216:219], v[12:15]
	v_mfma_f32_16x16x32_bf16 v[8:11], v[164:167], v[216:219], v[8:11]
	s_setprio 0
	s_setprio 1
	v_mfma_f32_16x16x32_bf16 v[52:55], v[168:171], v[184:187], v[52:55]
	v_mfma_f32_16x16x32_bf16 v[48:51], v[176:179], v[184:187], v[48:51]
	v_mfma_f32_16x16x32_bf16 v[36:39], v[168:171], v[196:199], v[36:39]
	v_mfma_f32_16x16x32_bf16 v[32:35], v[176:179], v[196:199], v[32:35]
	v_mfma_f32_16x16x32_bf16 v[20:23], v[168:171], v[204:207], v[20:23]
	v_mfma_f32_16x16x32_bf16 v[16:19], v[176:179], v[204:207], v[16:19]
	v_mfma_f32_16x16x32_bf16 v[4:7], v[168:171], v[212:215], v[4:7]
	v_mfma_f32_16x16x32_bf16 v[0:3], v[176:179], v[212:215], v[0:3]
	v_mfma_f32_16x16x32_bf16 v[52:55], v[172:175], v[192:195], v[52:55]
	v_mfma_f32_16x16x32_bf16 v[48:51], v[180:183], v[192:195], v[48:51]
	v_mfma_f32_16x16x32_bf16 v[36:39], v[172:175], v[200:203], v[36:39]
	v_mfma_f32_16x16x32_bf16 v[32:35], v[180:183], v[200:203], v[32:35]
	v_mfma_f32_16x16x32_bf16 v[20:23], v[172:175], v[208:211], v[20:23]
	v_mfma_f32_16x16x32_bf16 v[16:19], v[180:183], v[208:211], v[16:19]
	v_mfma_f32_16x16x32_bf16 v[4:7], v[172:175], v[216:219], v[4:7]
	v_mfma_f32_16x16x32_bf16 v[0:3], v[180:183], v[216:219], v[0:3]
	s_setprio 0
	s_barrier
	s_add_i32 s77, s77, 2
	s_add_u32 s30, s30, 0x100
	s_addc_u32 s31, s31, 0
	s_add_u32 s75, s75, 0x100
	s_addc_u32 s76, s76, 0
	s_cmp_gt_u32 s77, 13
	s_cbranch_scc0 .LBB0_1571

.LBB0_1649:
	s_ashr_i32 s23, s22, 31
	s_lshl_b64 s[24:25], s[22:23], 21
	s_add_u32 s24, s56, s24
	s_addc_u32 s25, s57, s25
	s_and_b64 s[26:27], s[0:1], exec
	s_cselect_b32 s23, s25, s31
	s_cselect_b32 s55, s24, s30
	s_ashr_i32 s21, s20, 31
	s_lshl_b64 s[26:27], s[20:21], 21
	s_add_u32 s26, s53, s26
	s_addc_u32 s27, s58, s27
	s_and_b64 s[42:43], s[0:1], exec
	s_cselect_b32 s21, s27, s35
	s_cselect_b32 s72, s26, s34
	s_add_u32 s30, s30, 0x100080
	s_addc_u32 s31, s31, 0
	s_add_u32 s73, s34, 0x100
	s_addc_u32 s74, s35, 0
	s_mov_b32 s75, -2
	ds_read_b128 v[152:155], v149
	ds_read_b128 v[156:159], v149 offset:1024
	ds_read_b128 v[160:163], v149 offset:2048
	ds_read_b128 v[164:167], v149 offset:3072
	ds_read_b128 v[168:171], v150
	ds_read_b128 v[172:175], v150 offset:1024
	ds_read_b128 v[176:179], v150 offset:2048
	ds_read_b128 v[180:183], v150 offset:3072
	s_add_u32 s34, s30, 0xfff00080
	s_addc_u32 s35, s31, -1
	s_cmp_eq_u32 s75, 60
	s_cselect_b32 s43, s23, s35
	s_cselect_b32 s42, s55, s34
	s_cselect_b32 s35, s21, s74
	s_cselect_b32 s34, s72, s73
	s_add_i32 m0, s29, 0xc000
	ds_read_b128 v[184:187], v151
	ds_read_b128 v[192:195], v151 offset:1024
	ds_read_b128 v[196:199], v151 offset:2048
	ds_read_b128 v[200:203], v151 offset:3072
	ds_read_b128 v[204:207], v151 offset:4096
	ds_read_b128 v[208:211], v151 offset:5120
	ds_read_b128 v[212:215], v151 offset:6144
	ds_read_b128 v[216:219], v151 offset:7168
	global_load_lds_dwordx4 v136, s[30:31]
	s_add_i32 m0, s29, 0xe000
	s_nop 0
	global_load_lds_dwordx4 v138, s[30:31]
	s_waitcnt vmcnt(8)
	s_waitcnt lgkmcnt(0)
	s_barrier
	s_setprio 1
	s_waitcnt lgkmcnt(0)
	v_mfma_f32_16x16x32_bf16 v[124:127], v[152:155], v[184:187], 0
	v_mfma_f32_16x16x32_bf16 v[120:123], v[160:163], v[184:187], 0
	v_mfma_f32_16x16x32_bf16 v[116:119], v[152:155], v[196:199], 0
	v_mfma_f32_16x16x32_bf16 v[108:111], v[160:163], v[196:199], 0
	v_mfma_f32_16x16x32_bf16 v[100:103], v[152:155], v[204:207], 0
	v_mfma_f32_16x16x32_bf16 v[92:95], v[160:163], v[204:207], 0
	v_mfma_f32_16x16x32_bf16 v[84:87], v[152:155], v[212:215], 0
	v_mfma_f32_16x16x32_bf16 v[76:79], v[160:163], v[212:215], 0
	v_mfma_f32_16x16x32_bf16 v[124:127], v[156:159], v[192:195], v[124:127]
	v_mfma_f32_16x16x32_bf16 v[120:123], v[164:167], v[192:195], v[120:123]
	v_mfma_f32_16x16x32_bf16 v[116:119], v[156:159], v[200:203], v[116:119]
	v_mfma_f32_16x16x32_bf16 v[108:111], v[164:167], v[200:203], v[108:111]
	v_mfma_f32_16x16x32_bf16 v[100:103], v[156:159], v[208:211], v[100:103]
	v_mfma_f32_16x16x32_bf16 v[92:95], v[164:167], v[208:211], v[92:95]
	v_mfma_f32_16x16x32_bf16 v[84:87], v[156:159], v[216:219], v[84:87]
	v_mfma_f32_16x16x32_bf16 v[76:79], v[164:167], v[216:219], v[76:79]
	s_setprio 0
	s_setprio 1
	v_mfma_f32_16x16x32_bf16 v[112:115], v[168:171], v[184:187], 0
	v_mfma_f32_16x16x32_bf16 v[104:107], v[176:179], v[184:187], 0
	v_mfma_f32_16x16x32_bf16 v[96:99], v[168:171], v[196:199], 0
	v_mfma_f32_16x16x32_bf16 v[88:91], v[176:179], v[196:199], 0
	v_mfma_f32_16x16x32_bf16 v[80:83], v[168:171], v[204:207], 0
	v_mfma_f32_16x16x32_bf16 v[72:75], v[176:179], v[204:207], 0
	v_mfma_f32_16x16x32_bf16 v[68:71], v[168:171], v[212:215], 0
	v_mfma_f32_16x16x32_bf16 v[64:67], v[176:179], v[212:215], 0
	v_mfma_f32_16x16x32_bf16 v[112:115], v[172:175], v[192:195], v[112:115]
	v_mfma_f32_16x16x32_bf16 v[104:107], v[180:183], v[192:195], v[104:107]
	v_mfma_f32_16x16x32_bf16 v[96:99], v[172:175], v[200:203], v[96:99]
	v_mfma_f32_16x16x32_bf16 v[88:91], v[180:183], v[200:203], v[88:91]
	v_mfma_f32_16x16x32_bf16 v[80:83], v[172:175], v[208:211], v[80:83]
	v_mfma_f32_16x16x32_bf16 v[72:75], v[180:183], v[208:211], v[72:75]
	v_mfma_f32_16x16x32_bf16 v[68:71], v[172:175], v[216:219], v[68:71]
	v_mfma_f32_16x16x32_bf16 v[64:67], v[180:183], v[216:219], v[64:67]
	s_setprio 0
	s_barrier
	s_add_i32 s76, s66, s59
	s_add_u32 s98, s34, 0x80
	s_addc_u32 s99, s35, 0
	s_mov_b32 m0, s76
	ds_read_b128 v[184:187], v151 offset:16384
	ds_read_b128 v[192:195], v151 offset:17408
	ds_read_b128 v[196:199], v151 offset:18432
	ds_read_b128 v[200:203], v151 offset:19456
	ds_read_b128 v[204:207], v151 offset:20480
	ds_read_b128 v[208:211], v151 offset:21504
	ds_read_b128 v[212:215], v151 offset:22528
	ds_read_b128 v[216:219], v151 offset:23552
	global_load_lds_dwordx4 v130, s[34:35]
	s_add_i32 m0, s76, 0x2000
	s_add_u32 s76, s34, 0x100000
	s_addc_u32 s77, s35, 0
	s_add_i32 s79, s67, s59
	global_load_lds_dwordx4 v134, s[34:35]
	s_mov_b32 m0, s79
	s_add_u32 s100, s42, 0x80
	s_addc_u32 s101, s43, 0
	global_load_lds_dwordx4 v130, s[76:77]
	s_add_i32 m0, s79, 0x2000
	s_nop 0
	global_load_lds_dwordx4 v134, s[76:77]
	s_mov_b32 m0, s29
	s_nop 0
	global_load_lds_dwordx4 v128, s[42:43]
	s_mov_b32 m0, s33
	s_nop 0
	global_load_lds_dwordx4 v132, s[42:43]
	s_waitcnt vmcnt(8)
	s_waitcnt lgkmcnt(0)
	s_barrier
	s_setprio 1
	s_waitcnt lgkmcnt(0)
	v_mfma_f32_16x16x32_bf16 v[60:63], v[152:155], v[184:187], 0
	v_mfma_f32_16x16x32_bf16 v[56:59], v[160:163], v[184:187], 0
	v_mfma_f32_16x16x32_bf16 v[52:55], v[152:155], v[196:199], 0
	v_mfma_f32_16x16x32_bf16 v[44:47], v[160:163], v[196:199], 0
	v_mfma_f32_16x16x32_bf16 v[36:39], v[152:155], v[204:207], 0
	v_mfma_f32_16x16x32_bf16 v[28:31], v[160:163], v[204:207], 0
	v_mfma_f32_16x16x32_bf16 v[20:23], v[152:155], v[212:215], 0
	v_mfma_f32_16x16x32_bf16 v[12:15], v[160:163], v[212:215], 0
	v_mfma_f32_16x16x32_bf16 v[60:63], v[156:159], v[192:195], v[60:63]
	v_mfma_f32_16x16x32_bf16 v[56:59], v[164:167], v[192:195], v[56:59]
	v_mfma_f32_16x16x32_bf16 v[52:55], v[156:159], v[200:203], v[52:55]
	v_mfma_f32_16x16x32_bf16 v[44:47], v[164:167], v[200:203], v[44:47]
	v_mfma_f32_16x16x32_bf16 v[36:39], v[156:159], v[208:211], v[36:39]
	v_mfma_f32_16x16x32_bf16 v[28:31], v[164:167], v[208:211], v[28:31]
	v_mfma_f32_16x16x32_bf16 v[20:23], v[156:159], v[216:219], v[20:23]
	v_mfma_f32_16x16x32_bf16 v[12:15], v[164:167], v[216:219], v[12:15]
	s_setprio 0
	s_setprio 1
	v_mfma_f32_16x16x32_bf16 v[48:51], v[168:171], v[184:187], 0
	v_mfma_f32_16x16x32_bf16 v[40:43], v[176:179], v[184:187], 0
	v_mfma_f32_16x16x32_bf16 v[32:35], v[168:171], v[196:199], 0
	v_mfma_f32_16x16x32_bf16 v[24:27], v[176:179], v[196:199], 0
	v_mfma_f32_16x16x32_bf16 v[16:19], v[168:171], v[204:207], 0
	v_mfma_f32_16x16x32_bf16 v[8:11], v[176:179], v[204:207], 0
	v_mfma_f32_16x16x32_bf16 v[4:7], v[168:171], v[212:215], 0
	v_mfma_f32_16x16x32_bf16 v[0:3], v[176:179], v[212:215], 0
	v_mfma_f32_16x16x32_bf16 v[48:51], v[172:175], v[192:195], v[48:51]
	v_mfma_f32_16x16x32_bf16 v[40:43], v[180:183], v[192:195], v[40:43]
	v_mfma_f32_16x16x32_bf16 v[32:35], v[172:175], v[200:203], v[32:35]
	v_mfma_f32_16x16x32_bf16 v[24:27], v[180:183], v[200:203], v[24:27]
	v_mfma_f32_16x16x32_bf16 v[16:19], v[172:175], v[208:211], v[16:19]
	v_mfma_f32_16x16x32_bf16 v[8:11], v[180:183], v[208:211], v[8:11]
	v_mfma_f32_16x16x32_bf16 v[4:7], v[172:175], v[216:219], v[4:7]
	v_mfma_f32_16x16x32_bf16 v[0:3], v[180:183], v[216:219], v[0:3]
	s_setprio 0
	s_barrier
	s_add_i32 s76, 0, 0x18000
	s_add_i32 s77, 0, 0x1c000
	v_add_u32_e32 v164, s76, v147
	v_add_u32_e32 v180, s77, v147
	ds_read_b128 v[152:155], v164
	ds_read_b128 v[156:159], v164 offset:1024
	ds_read_b128 v[160:163], v164 offset:2048
	ds_read_b128 v[164:167], v164 offset:3072
	ds_read_b128 v[168:171], v180
	ds_read_b128 v[172:175], v180 offset:1024
	ds_read_b128 v[176:179], v180 offset:2048
	ds_read_b128 v[180:183], v180 offset:3072
	s_add_u32 s42, s42, 0x100000
	s_addc_u32 s43, s43, 0
	s_mov_b32 m0, s60
	ds_read_b128 v[184:187], v151 offset:32768
	ds_read_b128 v[192:195], v151 offset:33792
	ds_read_b128 v[196:199], v151 offset:34816
	ds_read_b128 v[200:203], v151 offset:35840
	ds_read_b128 v[204:207], v151 offset:36864
	ds_read_b128 v[208:211], v151 offset:37888
	ds_read_b128 v[212:215], v151 offset:38912
	ds_read_b128 v[216:219], v151 offset:39936
	global_load_lds_dwordx4 v128, s[42:43]
	s_mov_b32 m0, s61
	s_nop 0
	global_load_lds_dwordx4 v132, s[42:43]
	s_waitcnt vmcnt(8)
	s_waitcnt lgkmcnt(0)
	s_barrier
	s_setprio 1
	s_waitcnt lgkmcnt(0)
	v_mfma_f32_16x16x32_bf16 v[124:127], v[152:155], v[184:187], v[124:127]
	v_mfma_f32_16x16x32_bf16 v[120:123], v[160:163], v[184:187], v[120:123]
	v_mfma_f32_16x16x32_bf16 v[116:119], v[152:155], v[196:199], v[116:119]
	v_mfma_f32_16x16x32_bf16 v[108:111], v[160:163], v[196:199], v[108:111]
	v_mfma_f32_16x16x32_bf16 v[100:103], v[152:155], v[204:207], v[100:103]
	v_mfma_f32_16x16x32_bf16 v[92:95], v[160:163], v[204:207], v[92:95]
	v_mfma_f32_16x16x32_bf16 v[84:87], v[152:155], v[212:215], v[84:87]
	v_mfma_f32_16x16x32_bf16 v[76:79], v[160:163], v[212:215], v[76:79]
	v_mfma_f32_16x16x32_bf16 v[124:127], v[156:159], v[192:195], v[124:127]
	v_mfma_f32_16x16x32_bf16 v[120:123], v[164:167], v[192:195], v[120:123]
	v_mfma_f32_16x16x32_bf16 v[116:119], v[156:159], v[200:203], v[116:119]
	v_mfma_f32_16x16x32_bf16 v[108:111], v[164:167], v[200:203], v[108:111]
	v_mfma_f32_16x16x32_bf16 v[100:103], v[156:159], v[208:211], v[100:103]
	v_mfma_f32_16x16x32_bf16 v[92:95], v[164:167], v[208:211], v[92:95]
	v_mfma_f32_16x16x32_bf16 v[84:87], v[156:159], v[216:219], v[84:87]
	v_mfma_f32_16x16x32_bf16 v[76:79], v[164:167], v[216:219], v[76:79]
	s_setprio 0
	s_setprio 1
	v_mfma_f32_16x16x32_bf16 v[112:115], v[168:171], v[184:187], v[112:115]
	v_mfma_f32_16x16x32_bf16 v[104:107], v[176:179], v[184:187], v[104:107]
	v_mfma_f32_16x16x32_bf16 v[96:99], v[168:171], v[196:199], v[96:99]
	v_mfma_f32_16x16x32_bf16 v[88:91], v[176:179], v[196:199], v[88:91]
	v_mfma_f32_16x16x32_bf16 v[80:83], v[168:171], v[204:207], v[80:83]
	v_mfma_f32_16x16x32_bf16 v[72:75], v[176:179], v[204:207], v[72:75]
	v_mfma_f32_16x16x32_bf16 v[68:71], v[168:171], v[212:215], v[68:71]
	v_mfma_f32_16x16x32_bf16 v[64:67], v[176:179], v[212:215], v[64:67]
	v_mfma_f32_16x16x32_bf16 v[112:115], v[172:175], v[192:195], v[112:115]
	v_mfma_f32_16x16x32_bf16 v[104:107], v[180:183], v[192:195], v[104:107]
	v_mfma_f32_16x16x32_bf16 v[96:99], v[172:175], v[200:203], v[96:99]
	v_mfma_f32_16x16x32_bf16 v[88:91], v[180:183], v[200:203], v[88:91]
	v_mfma_f32_16x16x32_bf16 v[80:83], v[172:175], v[208:211], v[80:83]
	v_mfma_f32_16x16x32_bf16 v[72:75], v[180:183], v[208:211], v[72:75]
	v_mfma_f32_16x16x32_bf16 v[68:71], v[172:175], v[216:219], v[68:71]
	v_mfma_f32_16x16x32_bf16 v[64:67], v[180:183], v[216:219], v[64:67]
	s_setprio 0
	s_barrier
	s_add_i32 s42, s76, s59
	s_mov_b32 m0, s42
	ds_read_b128 v[184:187], v151 offset:49152
	ds_read_b128 v[192:195], v151 offset:50176
	ds_read_b128 v[196:199], v151 offset:51200
	ds_read_b128 v[200:203], v151 offset:52224
	ds_read_b128 v[204:207], v151 offset:53248
	ds_read_b128 v[208:211], v151 offset:54272
	ds_read_b128 v[212:215], v151 offset:55296
	ds_read_b128 v[216:219], v151 offset:56320
	global_load_lds_dwordx4 v130, s[98:99]
	s_add_i32 m0, s42, 0x2000
	s_add_u32 s34, s34, 0x100080
	s_addc_u32 s35, s35, 0
	s_add_i32 s42, s77, s59
	global_load_lds_dwordx4 v134, s[98:99]
	s_mov_b32 m0, s42
	s_nop 0
	global_load_lds_dwordx4 v130, s[34:35]
	s_add_i32 m0, s42, 0x2000
	s_nop 0
	global_load_lds_dwordx4 v134, s[34:35]
	s_mov_b32 m0, s63
	s_nop 0
	global_load_lds_dwordx4 v128, s[100:101]
	s_mov_b32 m0, s64
	s_nop 0
	global_load_lds_dwordx4 v132, s[100:101]
	s_waitcnt vmcnt(8)
	s_waitcnt lgkmcnt(0)
	s_barrier
	s_setprio 1
	s_waitcnt lgkmcnt(0)
	v_mfma_f32_16x16x32_bf16 v[60:63], v[152:155], v[184:187], v[60:63]
	v_mfma_f32_16x16x32_bf16 v[56:59], v[160:163], v[184:187], v[56:59]
	v_mfma_f32_16x16x32_bf16 v[52:55], v[152:155], v[196:199], v[52:55]
	v_mfma_f32_16x16x32_bf16 v[44:47], v[160:163], v[196:199], v[44:47]
	v_mfma_f32_16x16x32_bf16 v[36:39], v[152:155], v[204:207], v[36:39]
	v_mfma_f32_16x16x32_bf16 v[28:31], v[160:163], v[204:207], v[28:31]
	v_mfma_f32_16x16x32_bf16 v[20:23], v[152:155], v[212:215], v[20:23]
	v_mfma_f32_16x16x32_bf16 v[12:15], v[160:163], v[212:215], v[12:15]
	v_mfma_f32_16x16x32_bf16 v[60:63], v[156:159], v[192:195], v[60:63]
	v_mfma_f32_16x16x32_bf16 v[56:59], v[164:167], v[192:195], v[56:59]
	v_mfma_f32_16x16x32_bf16 v[52:55], v[156:159], v[200:203], v[52:55]
	v_mfma_f32_16x16x32_bf16 v[44:47], v[164:167], v[200:203], v[44:47]
	v_mfma_f32_16x16x32_bf16 v[36:39], v[156:159], v[208:211], v[36:39]
	v_mfma_f32_16x16x32_bf16 v[28:31], v[164:167], v[208:211], v[28:31]
	v_mfma_f32_16x16x32_bf16 v[20:23], v[156:159], v[216:219], v[20:23]
	v_mfma_f32_16x16x32_bf16 v[12:15], v[164:167], v[216:219], v[12:15]
	s_setprio 0
	s_setprio 1
	v_mfma_f32_16x16x32_bf16 v[48:51], v[168:171], v[184:187], v[48:51]
	v_mfma_f32_16x16x32_bf16 v[40:43], v[176:179], v[184:187], v[40:43]
	v_mfma_f32_16x16x32_bf16 v[32:35], v[168:171], v[196:199], v[32:35]
	v_mfma_f32_16x16x32_bf16 v[24:27], v[176:179], v[196:199], v[24:27]
	v_mfma_f32_16x16x32_bf16 v[16:19], v[168:171], v[204:207], v[16:19]
	v_mfma_f32_16x16x32_bf16 v[8:11], v[176:179], v[204:207], v[8:11]
	v_mfma_f32_16x16x32_bf16 v[4:7], v[168:171], v[212:215], v[4:7]
	v_mfma_f32_16x16x32_bf16 v[0:3], v[176:179], v[212:215], v[0:3]
	v_mfma_f32_16x16x32_bf16 v[48:51], v[172:175], v[192:195], v[48:51]
	v_mfma_f32_16x16x32_bf16 v[40:43], v[180:183], v[192:195], v[40:43]
	v_mfma_f32_16x16x32_bf16 v[32:35], v[172:175], v[200:203], v[32:35]
	v_mfma_f32_16x16x32_bf16 v[24:27], v[180:183], v[200:203], v[24:27]
	v_mfma_f32_16x16x32_bf16 v[16:19], v[172:175], v[208:211], v[16:19]
	v_mfma_f32_16x16x32_bf16 v[8:11], v[180:183], v[208:211], v[8:11]
	v_mfma_f32_16x16x32_bf16 v[4:7], v[172:175], v[216:219], v[4:7]
	v_mfma_f32_16x16x32_bf16 v[0:3], v[180:183], v[216:219], v[0:3]
	s_setprio 0
	s_barrier
	s_add_i32 s75, s75, 2
	s_add_u32 s30, s30, 0x100
	s_addc_u32 s31, s31, 0
	s_add_u32 s73, s73, 0x100
	s_addc_u32 s74, s74, 0
	s_cmp_gt_u32 s75, 61
	s_cbranch_scc0 .LBB0_1650
	s_branch .Lpeel_exit12
.LBB0_1650:
	ds_read_b128 v[152:155], v149
	ds_read_b128 v[156:159], v149 offset:1024
	ds_read_b128 v[160:163], v149 offset:2048
	ds_read_b128 v[164:167], v149 offset:3072
	ds_read_b128 v[168:171], v150
	ds_read_b128 v[172:175], v150 offset:1024
	ds_read_b128 v[176:179], v150 offset:2048
	ds_read_b128 v[180:183], v150 offset:3072
	s_add_u32 s34, s30, 0xfff00080
	s_addc_u32 s35, s31, -1
	s_cmp_eq_u32 s75, 60
	s_cselect_b32 s43, s23, s35
	s_cselect_b32 s42, s55, s34
	s_cselect_b32 s35, s21, s74
	s_cselect_b32 s34, s72, s73
	s_add_i32 m0, s29, 0xc000
	ds_read_b128 v[184:187], v151
	ds_read_b128 v[192:195], v151 offset:1024
	ds_read_b128 v[196:199], v151 offset:2048
	ds_read_b128 v[200:203], v151 offset:3072
	ds_read_b128 v[204:207], v151 offset:4096
	ds_read_b128 v[208:211], v151 offset:5120
	ds_read_b128 v[212:215], v151 offset:6144
	ds_read_b128 v[216:219], v151 offset:7168
	global_load_lds_dwordx4 v136, s[30:31]
	s_add_i32 m0, s29, 0xe000
	s_nop 0
	global_load_lds_dwordx4 v138, s[30:31]
	s_waitcnt vmcnt(8)
	s_waitcnt lgkmcnt(0)
	s_barrier
	s_setprio 1
	s_waitcnt lgkmcnt(0)
	v_mfma_f32_16x16x32_bf16 v[124:127], v[152:155], v[184:187], v[124:127]
	v_mfma_f32_16x16x32_bf16 v[120:123], v[160:163], v[184:187], v[120:123]
	v_mfma_f32_16x16x32_bf16 v[116:119], v[152:155], v[196:199], v[116:119]
	v_mfma_f32_16x16x32_bf16 v[108:111], v[160:163], v[196:199], v[108:111]
	v_mfma_f32_16x16x32_bf16 v[100:103], v[152:155], v[204:207], v[100:103]
	v_mfma_f32_16x16x32_bf16 v[92:95], v[160:163], v[204:207], v[92:95]
	v_mfma_f32_16x16x32_bf16 v[84:87], v[152:155], v[212:215], v[84:87]
	v_mfma_f32_16x16x32_bf16 v[76:79], v[160:163], v[212:215], v[76:79]
	v_mfma_f32_16x16x32_bf16 v[124:127], v[156:159], v[192:195], v[124:127]
	v_mfma_f32_16x16x32_bf16 v[120:123], v[164:167], v[192:195], v[120:123]
	v_mfma_f32_16x16x32_bf16 v[116:119], v[156:159], v[200:203], v[116:119]
	v_mfma_f32_16x16x32_bf16 v[108:111], v[164:167], v[200:203], v[108:111]
	v_mfma_f32_16x16x32_bf16 v[100:103], v[156:159], v[208:211], v[100:103]
	v_mfma_f32_16x16x32_bf16 v[92:95], v[164:167], v[208:211], v[92:95]
	v_mfma_f32_16x16x32_bf16 v[84:87], v[156:159], v[216:219], v[84:87]
	v_mfma_f32_16x16x32_bf16 v[76:79], v[164:167], v[216:219], v[76:79]
	s_setprio 0
	s_setprio 1
	v_mfma_f32_16x16x32_bf16 v[112:115], v[168:171], v[184:187], v[112:115]
	v_mfma_f32_16x16x32_bf16 v[104:107], v[176:179], v[184:187], v[104:107]
	v_mfma_f32_16x16x32_bf16 v[96:99], v[168:171], v[196:199], v[96:99]
	v_mfma_f32_16x16x32_bf16 v[88:91], v[176:179], v[196:199], v[88:91]
	v_mfma_f32_16x16x32_bf16 v[80:83], v[168:171], v[204:207], v[80:83]
	v_mfma_f32_16x16x32_bf16 v[72:75], v[176:179], v[204:207], v[72:75]
	v_mfma_f32_16x16x32_bf16 v[68:71], v[168:171], v[212:215], v[68:71]
	v_mfma_f32_16x16x32_bf16 v[64:67], v[176:179], v[212:215], v[64:67]
	v_mfma_f32_16x16x32_bf16 v[112:115], v[172:175], v[192:195], v[112:115]
	v_mfma_f32_16x16x32_bf16 v[104:107], v[180:183], v[192:195], v[104:107]
	v_mfma_f32_16x16x32_bf16 v[96:99], v[172:175], v[200:203], v[96:99]
	v_mfma_f32_16x16x32_bf16 v[88:91], v[180:183], v[200:203], v[88:91]
	v_mfma_f32_16x16x32_bf16 v[80:83], v[172:175], v[208:211], v[80:83]
	v_mfma_f32_16x16x32_bf16 v[72:75], v[180:183], v[208:211], v[72:75]
	v_mfma_f32_16x16x32_bf16 v[68:71], v[172:175], v[216:219], v[68:71]
	v_mfma_f32_16x16x32_bf16 v[64:67], v[180:183], v[216:219], v[64:67]
	s_setprio 0
	s_barrier
	s_add_i32 s76, s66, s59
	s_add_u32 s98, s34, 0x80
	s_addc_u32 s99, s35, 0
	s_mov_b32 m0, s76
	ds_read_b128 v[184:187], v151 offset:16384
	ds_read_b128 v[192:195], v151 offset:17408
	ds_read_b128 v[196:199], v151 offset:18432
	ds_read_b128 v[200:203], v151 offset:19456
	ds_read_b128 v[204:207], v151 offset:20480
	ds_read_b128 v[208:211], v151 offset:21504
	ds_read_b128 v[212:215], v151 offset:22528
	ds_read_b128 v[216:219], v151 offset:23552
	global_load_lds_dwordx4 v130, s[34:35]
	s_add_i32 m0, s76, 0x2000
	s_add_u32 s76, s34, 0x100000
	s_addc_u32 s77, s35, 0
	s_add_i32 s79, s67, s59
	global_load_lds_dwordx4 v134, s[34:35]
	s_mov_b32 m0, s79
	s_add_u32 s100, s42, 0x80
	s_addc_u32 s101, s43, 0
	global_load_lds_dwordx4 v130, s[76:77]
	s_add_i32 m0, s79, 0x2000
	s_nop 0
	global_load_lds_dwordx4 v134, s[76:77]
	s_mov_b32 m0, s29
	s_nop 0
	global_load_lds_dwordx4 v128, s[42:43]
	s_mov_b32 m0, s33
	s_nop 0
	global_load_lds_dwordx4 v132, s[42:43]
	s_waitcnt vmcnt(8)
	s_waitcnt lgkmcnt(0)
	s_barrier
	s_setprio 1
	s_waitcnt lgkmcnt(0)
	v_mfma_f32_16x16x32_bf16 v[60:63], v[152:155], v[184:187], v[60:63]
	v_mfma_f32_16x16x32_bf16 v[56:59], v[160:163], v[184:187], v[56:59]
	v_mfma_f32_16x16x32_bf16 v[52:55], v[152:155], v[196:199], v[52:55]
	v_mfma_f32_16x16x32_bf16 v[44:47], v[160:163], v[196:199], v[44:47]
	v_mfma_f32_16x16x32_bf16 v[36:39], v[152:155], v[204:207], v[36:39]
	v_mfma_f32_16x16x32_bf16 v[28:31], v[160:163], v[204:207], v[28:31]
	v_mfma_f32_16x16x32_bf16 v[20:23], v[152:155], v[212:215], v[20:23]
	v_mfma_f32_16x16x32_bf16 v[12:15], v[160:163], v[212:215], v[12:15]
	v_mfma_f32_16x16x32_bf16 v[60:63], v[156:159], v[192:195], v[60:63]
	v_mfma_f32_16x16x32_bf16 v[56:59], v[164:167], v[192:195], v[56:59]
	v_mfma_f32_16x16x32_bf16 v[52:55], v[156:159], v[200:203], v[52:55]
	v_mfma_f32_16x16x32_bf16 v[44:47], v[164:167], v[200:203], v[44:47]
	v_mfma_f32_16x16x32_bf16 v[36:39], v[156:159], v[208:211], v[36:39]
	v_mfma_f32_16x16x32_bf16 v[28:31], v[164:167], v[208:211], v[28:31]
	v_mfma_f32_16x16x32_bf16 v[20:23], v[156:159], v[216:219], v[20:23]
	v_mfma_f32_16x16x32_bf16 v[12:15], v[164:167], v[216:219], v[12:15]
	s_setprio 0
	s_setprio 1
	v_mfma_f32_16x16x32_bf16 v[48:51], v[168:171], v[184:187], v[48:51]
	v_mfma_f32_16x16x32_bf16 v[40:43], v[176:179], v[184:187], v[40:43]
	v_mfma_f32_16x16x32_bf16 v[32:35], v[168:171], v[196:199], v[32:35]
	v_mfma_f32_16x16x32_bf16 v[24:27], v[176:179], v[196:199], v[24:27]
	v_mfma_f32_16x16x32_bf16 v[16:19], v[168:171], v[204:207], v[16:19]
	v_mfma_f32_16x16x32_bf16 v[8:11], v[176:179], v[204:207], v[8:11]
	v_mfma_f32_16x16x32_bf16 v[4:7], v[168:171], v[212:215], v[4:7]
	v_mfma_f32_16x16x32_bf16 v[0:3], v[176:179], v[212:215], v[0:3]
	v_mfma_f32_16x16x32_bf16 v[48:51], v[172:175], v[192:195], v[48:51]
	v_mfma_f32_16x16x32_bf16 v[40:43], v[180:183], v[192:195], v[40:43]
	v_mfma_f32_16x16x32_bf16 v[32:35], v[172:175], v[200:203], v[32:35]
	v_mfma_f32_16x16x32_bf16 v[24:27], v[180:183], v[200:203], v[24:27]
	v_mfma_f32_16x16x32_bf16 v[16:19], v[172:175], v[208:211], v[16:19]
	v_mfma_f32_16x16x32_bf16 v[8:11], v[180:183], v[208:211], v[8:11]
	v_mfma_f32_16x16x32_bf16 v[4:7], v[172:175], v[216:219], v[4:7]
	v_mfma_f32_16x16x32_bf16 v[0:3], v[180:183], v[216:219], v[0:3]
	s_setprio 0
	s_barrier
	s_add_i32 s76, 0, 0x18000
	s_add_i32 s77, 0, 0x1c000
	v_add_u32_e32 v164, s76, v147
	v_add_u32_e32 v180, s77, v147
	ds_read_b128 v[152:155], v164
	ds_read_b128 v[156:159], v164 offset:1024
	ds_read_b128 v[160:163], v164 offset:2048
	ds_read_b128 v[164:167], v164 offset:3072
	ds_read_b128 v[168:171], v180
	ds_read_b128 v[172:175], v180 offset:1024
	ds_read_b128 v[176:179], v180 offset:2048
	ds_read_b128 v[180:183], v180 offset:3072
	s_add_u32 s42, s42, 0x100000
	s_addc_u32 s43, s43, 0
	s_mov_b32 m0, s60
	ds_read_b128 v[184:187], v151 offset:32768
	ds_read_b128 v[192:195], v151 offset:33792
	ds_read_b128 v[196:199], v151 offset:34816
	ds_read_b128 v[200:203], v151 offset:35840
	ds_read_b128 v[204:207], v151 offset:36864
	ds_read_b128 v[208:211], v151 offset:37888
	ds_read_b128 v[212:215], v151 offset:38912
	ds_read_b128 v[216:219], v151 offset:39936
	global_load_lds_dwordx4 v128, s[42:43]
	s_mov_b32 m0, s61
	s_nop 0
	global_load_lds_dwordx4 v132, s[42:43]
	s_waitcnt vmcnt(8)
	s_waitcnt lgkmcnt(0)
	s_barrier
	s_setprio 1
	s_waitcnt lgkmcnt(0)
	v_mfma_f32_16x16x32_bf16 v[124:127], v[152:155], v[184:187], v[124:127]
	v_mfma_f32_16x16x32_bf16 v[120:123], v[160:163], v[184:187], v[120:123]
	v_mfma_f32_16x16x32_bf16 v[116:119], v[152:155], v[196:199], v[116:119]
	v_mfma_f32_16x16x32_bf16 v[108:111], v[160:163], v[196:199], v[108:111]
	v_mfma_f32_16x16x32_bf16 v[100:103], v[152:155], v[204:207], v[100:103]
	v_mfma_f32_16x16x32_bf16 v[92:95], v[160:163], v[204:207], v[92:95]
	v_mfma_f32_16x16x32_bf16 v[84:87], v[152:155], v[212:215], v[84:87]
	v_mfma_f32_16x16x32_bf16 v[76:79], v[160:163], v[212:215], v[76:79]
	v_mfma_f32_16x16x32_bf16 v[124:127], v[156:159], v[192:195], v[124:127]
	v_mfma_f32_16x16x32_bf16 v[120:123], v[164:167], v[192:195], v[120:123]
	v_mfma_f32_16x16x32_bf16 v[116:119], v[156:159], v[200:203], v[116:119]
	v_mfma_f32_16x16x32_bf16 v[108:111], v[164:167], v[200:203], v[108:111]
	v_mfma_f32_16x16x32_bf16 v[100:103], v[156:159], v[208:211], v[100:103]
	v_mfma_f32_16x16x32_bf16 v[92:95], v[164:167], v[208:211], v[92:95]
	v_mfma_f32_16x16x32_bf16 v[84:87], v[156:159], v[216:219], v[84:87]
	v_mfma_f32_16x16x32_bf16 v[76:79], v[164:167], v[216:219], v[76:79]
	s_setprio 0
	s_setprio 1
	v_mfma_f32_16x16x32_bf16 v[112:115], v[168:171], v[184:187], v[112:115]
	v_mfma_f32_16x16x32_bf16 v[104:107], v[176:179], v[184:187], v[104:107]
	v_mfma_f32_16x16x32_bf16 v[96:99], v[168:171], v[196:199], v[96:99]
	v_mfma_f32_16x16x32_bf16 v[88:91], v[176:179], v[196:199], v[88:91]
	v_mfma_f32_16x16x32_bf16 v[80:83], v[168:171], v[204:207], v[80:83]
	v_mfma_f32_16x16x32_bf16 v[72:75], v[176:179], v[204:207], v[72:75]
	v_mfma_f32_16x16x32_bf16 v[68:71], v[168:171], v[212:215], v[68:71]
	v_mfma_f32_16x16x32_bf16 v[64:67], v[176:179], v[212:215], v[64:67]
	v_mfma_f32_16x16x32_bf16 v[112:115], v[172:175], v[192:195], v[112:115]
	v_mfma_f32_16x16x32_bf16 v[104:107], v[180:183], v[192:195], v[104:107]
	v_mfma_f32_16x16x32_bf16 v[96:99], v[172:175], v[200:203], v[96:99]
	v_mfma_f32_16x16x32_bf16 v[88:91], v[180:183], v[200:203], v[88:91]
	v_mfma_f32_16x16x32_bf16 v[80:83], v[172:175], v[208:211], v[80:83]
	v_mfma_f32_16x16x32_bf16 v[72:75], v[180:183], v[208:211], v[72:75]
	v_mfma_f32_16x16x32_bf16 v[68:71], v[172:175], v[216:219], v[68:71]
	v_mfma_f32_16x16x32_bf16 v[64:67], v[180:183], v[216:219], v[64:67]
	s_setprio 0
	s_barrier
	s_add_i32 s42, s76, s59
	s_mov_b32 m0, s42
	ds_read_b128 v[184:187], v151 offset:49152
	ds_read_b128 v[192:195], v151 offset:50176
	ds_read_b128 v[196:199], v151 offset:51200
	ds_read_b128 v[200:203], v151 offset:52224
	ds_read_b128 v[204:207], v151 offset:53248
	ds_read_b128 v[208:211], v151 offset:54272
	ds_read_b128 v[212:215], v151 offset:55296
	ds_read_b128 v[216:219], v151 offset:56320
	global_load_lds_dwordx4 v130, s[98:99]
	s_add_i32 m0, s42, 0x2000
	s_add_u32 s34, s34, 0x100080
	s_addc_u32 s35, s35, 0
	s_add_i32 s42, s77, s59
	global_load_lds_dwordx4 v134, s[98:99]
	s_mov_b32 m0, s42
	s_nop 0
	global_load_lds_dwordx4 v130, s[34:35]
	s_add_i32 m0, s42, 0x2000
	s_nop 0
	global_load_lds_dwordx4 v134, s[34:35]
	s_mov_b32 m0, s63
	s_nop 0
	global_load_lds_dwordx4 v128, s[100:101]
	s_mov_b32 m0, s64
	s_nop 0
	global_load_lds_dwordx4 v132, s[100:101]
	s_waitcnt vmcnt(8)
	s_waitcnt lgkmcnt(0)
	s_barrier
	s_setprio 1
	s_waitcnt lgkmcnt(0)
	v_mfma_f32_16x16x32_bf16 v[60:63], v[152:155], v[184:187], v[60:63]
	v_mfma_f32_16x16x32_bf16 v[56:59], v[160:163], v[184:187], v[56:59]
	v_mfma_f32_16x16x32_bf16 v[52:55], v[152:155], v[196:199], v[52:55]
	v_mfma_f32_16x16x32_bf16 v[44:47], v[160:163], v[196:199], v[44:47]
	v_mfma_f32_16x16x32_bf16 v[36:39], v[152:155], v[204:207], v[36:39]
	v_mfma_f32_16x16x32_bf16 v[28:31], v[160:163], v[204:207], v[28:31]
	v_mfma_f32_16x16x32_bf16 v[20:23], v[152:155], v[212:215], v[20:23]
	v_mfma_f32_16x16x32_bf16 v[12:15], v[160:163], v[212:215], v[12:15]
	v_mfma_f32_16x16x32_bf16 v[60:63], v[156:159], v[192:195], v[60:63]
	v_mfma_f32_16x16x32_bf16 v[56:59], v[164:167], v[192:195], v[56:59]
	v_mfma_f32_16x16x32_bf16 v[52:55], v[156:159], v[200:203], v[52:55]
	v_mfma_f32_16x16x32_bf16 v[44:47], v[164:167], v[200:203], v[44:47]
	v_mfma_f32_16x16x32_bf16 v[36:39], v[156:159], v[208:211], v[36:39]
	v_mfma_f32_16x16x32_bf16 v[28:31], v[164:167], v[208:211], v[28:31]
	v_mfma_f32_16x16x32_bf16 v[20:23], v[156:159], v[216:219], v[20:23]
	v_mfma_f32_16x16x32_bf16 v[12:15], v[164:167], v[216:219], v[12:15]
	s_setprio 0
	s_setprio 1
	v_mfma_f32_16x16x32_bf16 v[48:51], v[168:171], v[184:187], v[48:51]
	v_mfma_f32_16x16x32_bf16 v[40:43], v[176:179], v[184:187], v[40:43]
	v_mfma_f32_16x16x32_bf16 v[32:35], v[168:171], v[196:199], v[32:35]
	v_mfma_f32_16x16x32_bf16 v[24:27], v[176:179], v[196:199], v[24:27]
	v_mfma_f32_16x16x32_bf16 v[16:19], v[168:171], v[204:207], v[16:19]
	v_mfma_f32_16x16x32_bf16 v[8:11], v[176:179], v[204:207], v[8:11]
	v_mfma_f32_16x16x32_bf16 v[4:7], v[168:171], v[212:215], v[4:7]
	v_mfma_f32_16x16x32_bf16 v[0:3], v[176:179], v[212:215], v[0:3]
	v_mfma_f32_16x16x32_bf16 v[48:51], v[172:175], v[192:195], v[48:51]
	v_mfma_f32_16x16x32_bf16 v[40:43], v[180:183], v[192:195], v[40:43]
	v_mfma_f32_16x16x32_bf16 v[32:35], v[172:175], v[200:203], v[32:35]
	v_mfma_f32_16x16x32_bf16 v[24:27], v[180:183], v[200:203], v[24:27]
	v_mfma_f32_16x16x32_bf16 v[16:19], v[172:175], v[208:211], v[16:19]
	v_mfma_f32_16x16x32_bf16 v[8:11], v[180:183], v[208:211], v[8:11]
	v_mfma_f32_16x16x32_bf16 v[4:7], v[172:175], v[216:219], v[4:7]
	v_mfma_f32_16x16x32_bf16 v[0:3], v[180:183], v[216:219], v[0:3]
	s_setprio 0
	s_barrier
	s_add_i32 s75, s75, 2
	s_add_u32 s30, s30, 0x100
	s_addc_u32 s31, s31, 0
	s_add_u32 s73, s73, 0x100
	s_addc_u32 s74, s74, 0
	s_cmp_gt_u32 s75, 61
	s_cbranch_scc0 .LBB0_1650
